# SwiGLU epilogue from registers (transposed MFMA acc, no LDS staging); P2 GLA-gate unit loads batched; LayerNorm before FFN-down keeps rows un-normalized + per-row mean/rstd, FFN-down epilogue re-appli
# speedup vs baseline: 1.0325x; 1.0288x over previous
_Z4mega6Params:
	s_load_dwordx16 s[48:63], s[0:1], 0x100
	s_load_dword s36, s[0:1], 0x150
	s_load_dwordx2 s[96:97], s[0:1], 0x148
	s_mov_b32 s30, s2
	s_add_u32 s2, s0, 0x148
	s_addc_u32 s3, s1, 0
	v_cmp_gt_u32_e32 vcc, 2, v0
	s_and_saveexec_b64 s[4:5], vcc
	v_lshl_add_u32 v1, v0, 2, 0
	v_add_u32_e32 v1, 0x20000, v1
	v_mov_b32_e32 v2, 0
	ds_write_b32 v1, v2
	s_or_b64 exec, exec, s[4:5]
	s_load_dwordx16 s[64:79], s[0:1], 0x0
	s_waitcnt lgkmcnt(0)
	s_barrier
	v_writelane_b32 v255, s48, 40
	v_writelane_b32 v255, s49, 41
	s_add_u32 s34, s62, 0xf71a000
	s_getreg_b32 s4, hwreg(HW_REG_XCC_ID, 0, 4)
	s_addc_u32 s35, s63, 0
	s_and_b32 s37, s4, 15
	v_cmp_eq_u32_e64 s[38:39], 0, v0
	s_and_saveexec_b64 s[4:5], s[38:39]
	s_cbranch_execz .LBB0_5
	s_mov_b64 s[6:7], exec
	v_mbcnt_lo_u32_b32 v1, s6, 0
	v_mbcnt_hi_u32_b32 v1, s7, v1
	v_cmp_eq_u32_e32 vcc, 0, v1
	s_and_b64 s[8:9], exec, vcc
	s_mov_b64 exec, s[8:9]
	s_cbranch_execz .LBB0_5
	s_lshl_b32 s8, s37, 8
	s_bcnt1_i32_b64 s6, s[6:7]
	v_mov_b32_e32 v1, s8
	v_mov_b32_e32 v2, s6
	global_atomic_add v1, v2, s[34:35] offset:1024

.LBB0_683:
	s_movk_i32 s0, 0xfff
	v_cmp_lt_i32_e32 vcc, s0, v1
	s_and_saveexec_b64 s[0:1], vcc
	s_xor_b64 s[36:37], exec, s[0:1]
	s_cbranch_execz .LBB0_718
	s_movk_i32 s0, 0x11ff
	v_cmp_lt_u32_e32 vcc, s0, v1
	s_and_saveexec_b64 s[0:1], vcc
	s_xor_b64 s[86:87], exec, s[0:1]
	s_cbranch_execz .LBB0_695
	s_movk_i32 s0, 0x127f
	v_cmp_lt_u32_e32 vcc, s0, v1
	s_and_saveexec_b64 s[0:1], vcc
	s_xor_b64 s[72:73], exec, s[0:1]
	s_cbranch_execz .LBB0_689
	v_add_u32_e32 v2, 0xffffed80, v1
	v_lshrrev_b32_e32 v26, 4, v2
	v_lshlrev_b32_e32 v86, 7, v26
	v_readlane_b32 s0, v254, 7
	v_lshlrev_b64 v[2:3], 6, v[86:87]
	v_readlane_b32 s1, v254, 8
	v_mov_b32_e32 v105, v87
	s_nop 0
	v_lshl_add_u64 v[2:3], s[0:1], 0, v[2:3]
	v_lshl_add_u64 v[4:5], v[2:3], 0, v[104:105]
	v_mov_b32_e32 v107, v87
	v_mov_b32_e32 v109, v87
	v_mov_b32_e32 v111, v87
	v_mov_b32_e32 v113, v87
	global_load_dword v186, v[4:5], off
	global_load_dword v187, v[4:5], off offset:1024
	global_load_dword v188, v[4:5], off offset:2048
	global_load_dword v189, v[4:5], off offset:3072
	v_lshl_add_u64 v[212:213], v[2:3], 0, v[106:107]
	v_lshl_add_u64 v[214:215], v[2:3], 0, v[108:109]
	v_lshl_add_u64 v[216:217], v[2:3], 0, v[110:111]
	v_lshl_add_u64 v[218:219], v[2:3], 0, v[112:113]
	global_load_dword v190, v[212:213], off
	global_load_dword v191, v[214:215], off
	global_load_dword v192, v[216:217], off
	global_load_dword v193, v[218:219], off
	v_readlane_b32 s98, v253, 63
	v_readlane_b32 s99, v254, 0
	v_and_b32_e32 v194, 0x1e0, v148
	v_or_b32_e32 v194, v194, v130
	v_and_b32_e32 v194, 0x1fe, v194
	v_or_b32_e32 v195, v135, v86
	v_lshlrev_b32_e32 v194, 1, v194
	s_nop 1
	v_lshl_or_b32 v196, v195, 10, v194
	v_add_u32_e32 v197, 0x800, v196
	v_add_u32_e32 v198, 0x1000, v196
	v_add_u32_e32 v199, 0x1800, v196
	v_add_u32_e32 v200, 0x2000, v196
	v_add_u32_e32 v201, 0x2800, v196
	v_add_u32_e32 v202, 0x3000, v196
	v_add_u32_e32 v203, 0x3800, v196
	global_load_dword v204, v196, s[98:99]
	global_load_dword v205, v197, s[98:99]
	global_load_dword v206, v198, s[98:99]
	global_load_dword v207, v199, s[98:99]
	global_load_dword v208, v200, s[98:99]
	global_load_dword v209, v201, s[98:99]
	global_load_dword v210, v202, s[98:99]
	global_load_dword v211, v203, s[98:99]
	v_readlane_b32 s98, v254, 1
	v_readlane_b32 s99, v254, 2
	s_nop 4
	global_load_dword v220, v196, s[98:99]
	global_load_dword v221, v197, s[98:99]
	global_load_dword v222, v198, s[98:99]
	global_load_dword v223, v199, s[98:99]
	global_load_dword v224, v200, s[98:99]
	global_load_dword v225, v201, s[98:99]
	global_load_dword v226, v202, s[98:99]
	global_load_dword v227, v203, s[98:99]
	s_barrier
	v_mov_b32_e32 v107, v87
	v_mov_b32_e32 v109, v87
	v_mov_b32_e32 v111, v87
	v_mov_b32_e32 v113, v87
	v_and_b32_e32 v24, 0x1e0, v148
	s_mov_b64 s[4:5], s[10:11]
	s_mov_b64 s[10:11], s[24:25]
	s_mov_b64 s[38:39], s[20:21]
	v_or_b32_e32 v25, v24, v130
	s_mov_b64 s[2:3], s[18:19]
	v_readlane_b32 s16, v253, 0
	v_readlane_b32 s17, v253, 1
	v_readlane_b32 s26, v253, 10
	s_movk_i32 s26, 0x2000
	v_readlane_b32 s27, v253, 11
	s_movk_i32 s27, 0x4000
	s_movk_i32 s0, 0x5000
	v_readlane_b32 s18, v253, 2
	v_readlane_b32 s19, v253, 3
	v_readlane_b32 s20, v253, 4
	v_readlane_b32 s21, v253, 5
	v_readlane_b32 s22, v253, 6
	v_readlane_b32 s23, v253, 7
	v_readlane_b32 s24, v253, 8
	v_readlane_b32 s25, v253, 9
	v_readlane_b32 s28, v253, 12
	v_readlane_b32 s29, v253, 13
	v_readlane_b32 s30, v253, 14
	v_readlane_b32 s31, v253, 15
	s_waitcnt vmcnt(16)
	ds_write2st64_b32 v132, v186, v187 offset1:4
	ds_write2st64_b32 v132, v188, v189 offset0:8 offset1:12
	ds_write2st64_b32 v132, v190, v191 offset0:16 offset1:20
	ds_write2st64_b32 v132, v192, v193 offset0:24 offset1:28
	v_mov_b32_e32 v3, v87
	v_lshlrev_b32_e32 v2, 2, v25
	v_lshl_add_u64 v[4:5], s[16:17], 0, v[2:3]
	v_add_co_u32_e32 v6, vcc, s93, v4
	s_waitcnt lgkmcnt(0)
	s_nop 0
	v_addc_co_u32_e32 v7, vcc, 0, v5, vcc
	v_add_co_u32_e32 v8, vcc, s26, v4
	s_barrier
	s_nop 0
	v_addc_co_u32_e32 v9, vcc, 0, v5, vcc
	global_load_dword v28, v2, s[16:17]
	global_load_dword v29, v2, s[16:17] offset:2048
	global_load_dword v30, v[8:9], off offset:-4096
	global_load_dword v31, v[6:7], off offset:2048
	global_load_dword v23, v[8:9], off
	global_load_dword v27, v[8:9], off offset:2048
	v_add_co_u32_e32 v6, vcc, s88, v4
	s_nop 1
	v_addc_co_u32_e32 v7, vcc, 0, v5, vcc
	v_add_co_u32_e32 v8, vcc, s27, v4
	s_nop 1
	v_addc_co_u32_e32 v9, vcc, 0, v5, vcc
	global_load_dword v14, v[8:9], off offset:-4096
	global_load_dword v15, v[6:7], off offset:2048
	global_load_dword v10, v[8:9], off
	global_load_dword v11, v[8:9], off offset:2048
	v_add_co_u32_e32 v6, vcc, s0, v4
	s_movk_i32 s0, 0x6000
	s_nop 0
	v_addc_co_u32_e32 v7, vcc, 0, v5, vcc
	v_add_co_u32_e32 v8, vcc, s0, v4
	s_movk_i32 s0, 0x7000
	s_nop 0
	v_addc_co_u32_e32 v9, vcc, 0, v5, vcc
	v_add_co_u32_e32 v4, vcc, s0, v4
	global_load_dword v12, v[8:9], off offset:-4096
	global_load_dword v13, v[6:7], off offset:2048
	s_nop 0
	global_load_dword v6, v[8:9], off
	global_load_dword v7, v[8:9], off offset:2048
	v_addc_co_u32_e32 v5, vcc, 0, v5, vcc
	global_load_dword v8, v[4:5], off
	global_load_dword v9, v[4:5], off offset:2048
	global_load_dword v33, v2, s[18:19]
	ds_read_b128 v[2:5], v131
	ds_read_b128 v[16:19], v131 offset:16
	ds_read_b128 v[34:37], v131 offset:32
	ds_read_b128 v[38:41], v131 offset:48
	s_mov_b64 s[18:19], s[2:3]
	s_waitcnt vmcnt(0) lgkmcnt(3)
	v_fma_f32 v2, v28, v2, v33
	v_fmac_f32_e32 v2, v29, v3
	v_fmac_f32_e32 v2, v30, v4
	v_fmac_f32_e32 v2, v31, v5
	s_waitcnt lgkmcnt(2)
	v_fmac_f32_e32 v2, v23, v16
	v_fmac_f32_e32 v2, v27, v17
	v_fmac_f32_e32 v2, v14, v18
	v_fmac_f32_e32 v2, v15, v19
	s_waitcnt lgkmcnt(1)
	v_fmac_f32_e32 v2, v10, v34
	v_fmac_f32_e32 v2, v11, v35
	v_fmac_f32_e32 v2, v12, v36
	v_fmac_f32_e32 v2, v13, v37
	s_waitcnt lgkmcnt(0)
	v_fmac_f32_e32 v2, v6, v38
	v_fmac_f32_e32 v2, v7, v39
	v_fmac_f32_e32 v2, v8, v40
	v_fmac_f32_e32 v2, v9, v41
	v_min_f32_e32 v3, 0, v2
	v_mul_f32_e64 v2, |v2|, s89
	v_exp_f32_e32 v2, v2
	ds_read_b128 v[18:21], v131 offset:320
	v_add_f32_e32 v2, 1.0, v2
	v_cmp_gt_f32_e32 vcc, s90, v2
	s_nop 1
	v_cndmask_b32_e64 v4, 0, 32, vcc
	v_ldexp_f32 v2, v2, v4
	v_log_f32_e32 v2, v2
	s_nop 0
	v_mul_f32_e32 v4, 0x3f317217, v2
	v_fma_f32 v4, v2, s91, -v4
	v_fmac_f32_e32 v4, 0x3377d1cf, v2
	v_fmac_f32_e32 v4, 0x3f317217, v2
	v_cmp_lt_f32_e64 s[0:1], |v2|, s97
	s_nop 1
	v_cndmask_b32_e64 v2, v2, v4, s[0:1]
	v_cndmask_b32_e32 v4, 0, v151, vcc
	v_sub_f32_e32 v2, v2, v4
	v_sub_f32_e32 v32, v3, v2
	ds_read_b128 v[2:5], v131 offset:64
	v_fma_f32 v16, v32, s84, 0
	s_waitcnt lgkmcnt(0)
	v_fma_f32 v17, v28, v2, v33
	v_fmac_f32_e32 v17, v29, v3
	v_fmac_f32_e32 v17, v30, v4
	v_fmac_f32_e32 v17, v31, v5
	ds_read_b128 v[2:5], v131 offset:80
	s_waitcnt lgkmcnt(0)
	v_fmac_f32_e32 v17, v23, v2
	v_fmac_f32_e32 v17, v27, v3
	v_fmac_f32_e32 v17, v14, v4
	v_fmac_f32_e32 v17, v15, v5
	ds_read_b128 v[2:5], v131 offset:96
	s_waitcnt lgkmcnt(0)
	v_fmac_f32_e32 v17, v10, v2
	v_fmac_f32_e32 v17, v11, v3
	v_fmac_f32_e32 v17, v12, v4
	v_fmac_f32_e32 v17, v13, v5
	ds_read_b128 v[2:5], v131 offset:112
	s_waitcnt lgkmcnt(0)
	v_fmac_f32_e32 v17, v6, v2
	v_fmac_f32_e32 v17, v7, v3
	v_fmac_f32_e32 v17, v8, v4
	v_fmac_f32_e32 v17, v9, v5
	v_mul_f32_e64 v3, |v17|, s89
	v_exp_f32_e32 v3, v3
	v_min_f32_e32 v2, 0, v17
	v_add_f32_e32 v3, 1.0, v3
	v_cmp_gt_f32_e32 vcc, s90, v3
	s_nop 1
	v_cndmask_b32_e64 v4, 0, 32, vcc
	v_ldexp_f32 v3, v3, v4
	v_log_f32_e32 v3, v3
	s_nop 0
	v_mul_f32_e32 v4, 0x3f317217, v3
	v_fma_f32 v4, v3, s91, -v4
	v_fmac_f32_e32 v4, 0x3377d1cf, v3
	v_fmac_f32_e32 v4, 0x3f317217, v3
	v_cmp_lt_f32_e64 s[0:1], |v3|, s97
	s_nop 1
	v_cndmask_b32_e64 v3, v3, v4, s[0:1]
	v_cndmask_b32_e32 v4, 0, v151, vcc
	v_sub_f32_e32 v3, v3, v4
	v_sub_f32_e32 v34, v2, v3
	ds_read_b128 v[2:5], v131 offset:128
	v_fmac_f32_e32 v16, 0x3d800000, v34
	s_waitcnt lgkmcnt(0)
	v_fma_f32 v17, v28, v2, v33
	v_fmac_f32_e32 v17, v29, v3
	v_fmac_f32_e32 v17, v30, v4
	v_fmac_f32_e32 v17, v31, v5
	ds_read_b128 v[2:5], v131 offset:144
	s_waitcnt lgkmcnt(0)
	v_fmac_f32_e32 v17, v23, v2
	v_fmac_f32_e32 v17, v27, v3
	v_fmac_f32_e32 v17, v14, v4
	v_fmac_f32_e32 v17, v15, v5
	ds_read_b128 v[2:5], v131 offset:160
	s_waitcnt lgkmcnt(0)
	v_fmac_f32_e32 v17, v10, v2
	v_fmac_f32_e32 v17, v11, v3
	v_fmac_f32_e32 v17, v12, v4
	v_fmac_f32_e32 v17, v13, v5
	ds_read_b128 v[2:5], v131 offset:176
	s_waitcnt lgkmcnt(0)
	v_fmac_f32_e32 v17, v6, v2
	v_fmac_f32_e32 v17, v7, v3
	v_fmac_f32_e32 v17, v8, v4
	v_fmac_f32_e32 v17, v9, v5
	v_mul_f32_e64 v3, |v17|, s89
	v_exp_f32_e32 v3, v3
	v_min_f32_e32 v2, 0, v17
	v_add_f32_e32 v3, 1.0, v3
	v_cmp_gt_f32_e32 vcc, s90, v3
	s_nop 1
	v_cndmask_b32_e64 v4, 0, 32, vcc
	v_ldexp_f32 v3, v3, v4
	v_log_f32_e32 v3, v3
	s_nop 0
	v_mul_f32_e32 v4, 0x3f317217, v3
	v_fma_f32 v4, v3, s91, -v4
	v_fmac_f32_e32 v4, 0x3377d1cf, v3
	v_fmac_f32_e32 v4, 0x3f317217, v3
	v_cmp_lt_f32_e64 s[0:1], |v3|, s97
	s_nop 1
	v_cndmask_b32_e64 v3, v3, v4, s[0:1]
	v_cndmask_b32_e32 v4, 0, v151, vcc
	v_sub_f32_e32 v3, v3, v4
	v_sub_f32_e32 v35, v2, v3
	ds_read_b128 v[2:5], v131 offset:192
	v_fmac_f32_e32 v16, 0x3d800000, v35
	s_waitcnt lgkmcnt(0)
	v_fma_f32 v17, v28, v2, v33
	v_fmac_f32_e32 v17, v29, v3
	v_fmac_f32_e32 v17, v30, v4
	v_fmac_f32_e32 v17, v31, v5
	ds_read_b128 v[2:5], v131 offset:208
	s_waitcnt lgkmcnt(0)
	v_fmac_f32_e32 v17, v23, v2
	v_fmac_f32_e32 v17, v27, v3
	v_fmac_f32_e32 v17, v14, v4
	v_fmac_f32_e32 v17, v15, v5
	ds_read_b128 v[2:5], v131 offset:224
	s_waitcnt lgkmcnt(0)
	v_fmac_f32_e32 v17, v10, v2
	v_fmac_f32_e32 v17, v11, v3
	v_fmac_f32_e32 v17, v12, v4
	v_fmac_f32_e32 v17, v13, v5
	ds_read_b128 v[2:5], v131 offset:240
	s_waitcnt lgkmcnt(0)
	v_fmac_f32_e32 v17, v6, v2
	v_fmac_f32_e32 v17, v7, v3
	v_fmac_f32_e32 v17, v8, v4
	v_fmac_f32_e32 v17, v9, v5
	v_mul_f32_e64 v3, |v17|, s89
	v_exp_f32_e32 v3, v3
	v_min_f32_e32 v2, 0, v17
	v_add_f32_e32 v3, 1.0, v3
	v_cmp_gt_f32_e32 vcc, s90, v3
	s_nop 1
	v_cndmask_b32_e64 v4, 0, 32, vcc
	v_ldexp_f32 v3, v3, v4
	v_log_f32_e32 v3, v3
	s_nop 0
	v_mul_f32_e32 v4, 0x3f317217, v3
	v_fma_f32 v4, v3, s91, -v4
	v_fmac_f32_e32 v4, 0x3377d1cf, v3
	v_fmac_f32_e32 v4, 0x3f317217, v3
	v_cmp_lt_f32_e64 s[0:1], |v3|, s97
	s_nop 1
	v_cndmask_b32_e64 v3, v3, v4, s[0:1]
	v_cndmask_b32_e32 v4, 0, v151, vcc
	v_sub_f32_e32 v3, v3, v4
	v_sub_f32_e32 v36, v2, v3
	ds_read_b128 v[2:5], v131 offset:256
	v_fmac_f32_e32 v16, 0x3d800000, v36
	s_waitcnt lgkmcnt(0)
	v_fma_f32 v17, v28, v2, v33
	v_fmac_f32_e32 v17, v29, v3
	v_fmac_f32_e32 v17, v30, v4
	v_fmac_f32_e32 v17, v31, v5
	ds_read_b128 v[2:5], v131 offset:272
	s_waitcnt lgkmcnt(0)
	v_fmac_f32_e32 v17, v23, v2
	v_fmac_f32_e32 v17, v27, v3
	v_pk_mul_f32 v[2:3], v[14:15], v[4:5]
	s_nop 0
	v_add_f32_e32 v2, v17, v2
	v_add_f32_e32 v17, v2, v3
	ds_read_b128 v[2:5], v131 offset:288
	s_waitcnt lgkmcnt(0)
	v_pk_mul_f32 v[2:3], v[10:11], v[2:3]
	s_nop 0
	v_add_f32_e32 v2, v17, v2
	v_add_f32_e32 v17, v2, v3
	v_pk_mul_f32 v[2:3], v[12:13], v[4:5]
	s_nop 0
	v_add_f32_e32 v2, v17, v2
	v_add_f32_e32 v17, v2, v3
	ds_read_b128 v[2:5], v131 offset:304
	s_waitcnt lgkmcnt(0)
	v_pk_mul_f32 v[2:3], v[6:7], v[2:3]
	s_nop 0
	v_add_f32_e32 v2, v17, v2
	v_add_f32_e32 v17, v2, v3
	v_pk_mul_f32 v[2:3], v[8:9], v[4:5]
	s_nop 0
	v_add_f32_e32 v2, v17, v2
	v_add_f32_e32 v3, v2, v3
	v_min_f32_e32 v2, 0, v3
	v_mul_f32_e64 v3, |v3|, s89
	v_exp_f32_e32 v3, v3
	s_nop 0
	v_add_f32_e32 v3, 1.0, v3
	v_cmp_gt_f32_e32 vcc, s90, v3
	s_nop 1
	v_cndmask_b32_e64 v4, 0, 32, vcc
	v_ldexp_f32 v3, v3, v4
	v_log_f32_e32 v3, v3
	s_nop 0
	v_mul_f32_e32 v4, 0x3f317217, v3
	v_fma_f32 v4, v3, s91, -v4
	v_fmac_f32_e32 v4, 0x3377d1cf, v3
	v_fmac_f32_e32 v4, 0x3f317217, v3
	v_cmp_lt_f32_e64 s[0:1], |v3|, s97
	s_nop 1
	v_cndmask_b32_e64 v3, v3, v4, s[0:1]
	v_cndmask_b32_e32 v4, 0, v151, vcc
	v_sub_f32_e32 v4, v3, v4
	v_fma_f32 v3, v28, v18, v33
	v_fmac_f32_e32 v3, v29, v19
	v_fmac_f32_e32 v3, v30, v20
	v_fmac_f32_e32 v3, v31, v21
	ds_read_b128 v[18:21], v131 offset:336
	s_waitcnt lgkmcnt(0)
	v_fmac_f32_e32 v3, v23, v18
	v_fmac_f32_e32 v3, v27, v19
	v_pk_mul_f32 v[18:19], v[14:15], v[20:21]
	s_nop 0
	v_add_f32_e32 v3, v3, v18
	v_add_f32_e32 v3, v3, v19
	ds_read_b128 v[18:21], v131 offset:352
	s_waitcnt lgkmcnt(0)
	v_pk_mul_f32 v[18:19], v[10:11], v[18:19]
	s_nop 0
	v_add_f32_e32 v3, v3, v18
	v_add_f32_e32 v3, v3, v19
	v_pk_mul_f32 v[18:19], v[12:13], v[20:21]
	s_nop 0
	v_add_f32_e32 v3, v3, v18
	v_add_f32_e32 v3, v3, v19
	ds_read_b128 v[18:21], v131 offset:368
	s_waitcnt lgkmcnt(0)
	v_pk_mul_f32 v[18:19], v[6:7], v[18:19]
	s_nop 0
	v_add_f32_e32 v3, v3, v18
	v_add_f32_e32 v3, v3, v19
	v_pk_mul_f32 v[18:19], v[8:9], v[20:21]
	s_nop 0
	v_add_f32_e32 v3, v3, v18
	v_add_f32_e32 v5, v3, v19
	v_min_f32_e32 v3, 0, v5
	v_mul_f32_e64 v5, |v5|, s89
	v_exp_f32_e32 v5, v5
	s_nop 0
	v_add_f32_e32 v5, 1.0, v5
	v_cmp_gt_f32_e32 vcc, s90, v5
	s_nop 1
	v_cndmask_b32_e64 v17, 0, 32, vcc
	v_ldexp_f32 v5, v5, v17
	v_log_f32_e32 v5, v5
	s_nop 0
	v_mul_f32_e32 v17, 0x3f317217, v5
	v_fma_f32 v17, v5, s91, -v17
	v_fmac_f32_e32 v17, 0x3377d1cf, v5
	v_fmac_f32_e32 v17, 0x3f317217, v5
	v_cmp_lt_f32_e64 s[0:1], |v5|, s97
	s_nop 1
	v_cndmask_b32_e64 v5, v5, v17, s[0:1]
	v_cndmask_b32_e32 v17, 0, v151, vcc
	v_sub_f32_e32 v5, v5, v17
	v_pk_add_f32 v[2:3], v[2:3], v[4:5] neg_lo:[0,1] neg_hi:[0,1]
	s_nop 0
	v_pk_mul_f32 v[2:3], v[2:3], s[84:85] op_sel_hi:[1,0]
	s_nop 0
	v_add_f32_e32 v4, v16, v2
	ds_read_b128 v[16:19], v131 offset:384
	v_add_f32_e32 v22, v4, v3
	s_waitcnt lgkmcnt(0)
	v_fma_f32 v20, v28, v16, v33
	v_fmac_f32_e32 v20, v29, v17
	v_fmac_f32_e32 v20, v30, v18
	v_fmac_f32_e32 v20, v31, v19
	ds_read_b128 v[16:19], v131 offset:400
	s_waitcnt lgkmcnt(0)
	v_fmac_f32_e32 v20, v23, v16
	v_fmac_f32_e32 v20, v27, v17
	v_pk_mul_f32 v[4:5], v[14:15], v[18:19]
	ds_read_b128 v[16:19], v131 offset:416
	v_add_f32_e32 v4, v20, v4
	v_add_f32_e32 v20, v4, v5
	s_waitcnt lgkmcnt(0)
	v_pk_mul_f32 v[4:5], v[10:11], v[16:17]
	s_nop 0
	v_add_f32_e32 v4, v20, v4
	v_add_f32_e32 v16, v4, v5
	v_pk_mul_f32 v[4:5], v[12:13], v[18:19]
	s_nop 0
	v_add_f32_e32 v4, v16, v4
	ds_read_b128 v[16:19], v131 offset:432
	v_add_f32_e32 v20, v4, v5
	s_waitcnt lgkmcnt(0)
	v_pk_mul_f32 v[4:5], v[6:7], v[16:17]
	s_nop 0
	v_add_f32_e32 v4, v20, v4
	v_add_f32_e32 v16, v4, v5
	v_pk_mul_f32 v[4:5], v[8:9], v[18:19]
	s_nop 0
	v_add_f32_e32 v4, v16, v4
	v_add_f32_e32 v5, v4, v5
	v_min_f32_e32 v4, 0, v5
	v_mul_f32_e64 v5, |v5|, s89
	v_exp_f32_e32 v5, v5
	s_nop 0
	v_add_f32_e32 v5, 1.0, v5
	v_cmp_gt_f32_e32 vcc, s90, v5
	s_nop 1
	v_cndmask_b32_e64 v16, 0, 32, vcc
	v_ldexp_f32 v5, v5, v16
	v_log_f32_e32 v5, v5
	s_nop 0
	v_mul_f32_e32 v16, 0x3f317217, v5
	v_fma_f32 v16, v5, s91, -v16
	v_fmac_f32_e32 v16, 0x3377d1cf, v5
	v_fmac_f32_e32 v16, 0x3f317217, v5
	v_cmp_lt_f32_e64 s[0:1], |v5|, s97
	s_nop 1
	v_cndmask_b32_e64 v5, v5, v16, s[0:1]
	v_cndmask_b32_e32 v16, 0, v151, vcc
	v_sub_f32_e32 v20, v5, v16
	ds_read_b128 v[16:19], v131 offset:448
	s_waitcnt lgkmcnt(0)
	v_fma_f32 v5, v28, v16, v33
	v_fmac_f32_e32 v5, v29, v17
	v_fmac_f32_e32 v5, v30, v18
	v_fmac_f32_e32 v5, v31, v19
	ds_read_b128 v[16:19], v131 offset:464
	s_waitcnt lgkmcnt(0)
	v_fmac_f32_e32 v5, v23, v16
	v_fmac_f32_e32 v5, v27, v17
	v_pk_mul_f32 v[16:17], v[14:15], v[18:19]
	s_nop 0
	v_add_f32_e32 v5, v5, v16
	v_add_f32_e32 v5, v5, v17
	ds_read_b128 v[16:19], v131 offset:480
	s_waitcnt lgkmcnt(0)
	v_pk_mul_f32 v[16:17], v[10:11], v[16:17]
	s_nop 0
	v_add_f32_e32 v5, v5, v16
	v_add_f32_e32 v5, v5, v17
	v_pk_mul_f32 v[16:17], v[12:13], v[18:19]
	s_nop 0
	v_add_f32_e32 v5, v5, v16
	v_add_f32_e32 v5, v5, v17
	ds_read_b128 v[16:19], v131 offset:496
	s_waitcnt lgkmcnt(0)
	v_pk_mul_f32 v[16:17], v[6:7], v[16:17]
	s_nop 0
	v_add_f32_e32 v5, v5, v16
	v_add_f32_e32 v5, v5, v17
	v_pk_mul_f32 v[16:17], v[8:9], v[18:19]
	s_nop 0
	v_add_f32_e32 v5, v5, v16
	v_add_f32_e32 v16, v5, v17
	v_min_f32_e32 v5, 0, v16
	v_mul_f32_e64 v16, |v16|, s89
	v_exp_f32_e32 v16, v16
	s_nop 0
	v_add_f32_e32 v16, 1.0, v16
	v_cmp_gt_f32_e32 vcc, s90, v16
	s_nop 1
	v_cndmask_b32_e64 v17, 0, 32, vcc
	v_ldexp_f32 v16, v16, v17
	v_log_f32_e32 v16, v16
	s_nop 0
	v_mul_f32_e32 v17, 0x3f317217, v16
	v_fma_f32 v17, v16, s91, -v17
	v_fmac_f32_e32 v17, 0x3377d1cf, v16
	v_fmac_f32_e32 v17, 0x3f317217, v16
	v_cmp_lt_f32_e64 s[0:1], |v16|, s97
	s_nop 1
	v_cndmask_b32_e64 v16, v16, v17, s[0:1]
	v_cndmask_b32_e32 v17, 0, v151, vcc
	v_sub_f32_e32 v21, v16, v17
	v_pk_add_f32 v[4:5], v[4:5], v[20:21] neg_lo:[0,1] neg_hi:[0,1]
	s_nop 0
	v_pk_mul_f32 v[4:5], v[4:5], s[84:85] op_sel_hi:[1,0]
	s_nop 0
	v_add_f32_e32 v16, v22, v4
	v_add_f32_e32 v22, v16, v5
	ds_read_b128 v[16:19], v131 offset:512
	s_waitcnt lgkmcnt(0)
	v_fma_f32 v20, v28, v16, v33
	v_fmac_f32_e32 v20, v29, v17
	v_fmac_f32_e32 v20, v30, v18
	v_fmac_f32_e32 v20, v31, v19
	ds_read_b128 v[16:19], v131 offset:528
	s_waitcnt lgkmcnt(0)
	v_fmac_f32_e32 v20, v23, v16
	v_fmac_f32_e32 v20, v27, v17
	v_pk_mul_f32 v[16:17], v[14:15], v[18:19]
	s_nop 0
	v_add_f32_e32 v16, v20, v16
	v_add_f32_e32 v20, v16, v17
	ds_read_b128 v[16:19], v131 offset:544
	s_waitcnt lgkmcnt(0)
	v_pk_mul_f32 v[16:17], v[10:11], v[16:17]
	s_nop 0
	v_add_f32_e32 v16, v20, v16
	v_add_f32_e32 v20, v16, v17
	v_pk_mul_f32 v[16:17], v[12:13], v[18:19]
	s_nop 0
	v_add_f32_e32 v16, v20, v16
	v_add_f32_e32 v20, v16, v17
	ds_read_b128 v[16:19], v131 offset:560
	s_waitcnt lgkmcnt(0)
	v_pk_mul_f32 v[16:17], v[6:7], v[16:17]
	s_nop 0
	v_add_f32_e32 v16, v20, v16
	v_add_f32_e32 v20, v16, v17
	v_pk_mul_f32 v[16:17], v[8:9], v[18:19]
	s_nop 0
	v_add_f32_e32 v16, v20, v16
	v_add_f32_e32 v17, v16, v17
	v_min_f32_e32 v16, 0, v17
	v_mul_f32_e64 v17, |v17|, s89
	v_exp_f32_e32 v17, v17
	s_nop 0
	v_add_f32_e32 v17, 1.0, v17
	v_cmp_gt_f32_e32 vcc, s90, v17
	s_nop 1
	v_cndmask_b32_e64 v18, 0, 32, vcc
	v_ldexp_f32 v17, v17, v18
	v_log_f32_e32 v17, v17
	s_nop 0
	v_mul_f32_e32 v18, 0x3f317217, v17
	v_fma_f32 v18, v17, s91, -v18
	v_fmac_f32_e32 v18, 0x3377d1cf, v17
	v_fmac_f32_e32 v18, 0x3f317217, v17
	v_cmp_lt_f32_e64 s[0:1], |v17|, s97
	s_nop 1
	v_cndmask_b32_e64 v17, v17, v18, s[0:1]
	v_cndmask_b32_e32 v18, 0, v151, vcc
	v_sub_f32_e32 v38, v17, v18
	ds_read_b128 v[18:21], v131 offset:576
	s_waitcnt lgkmcnt(0)
	v_fma_f32 v17, v28, v18, v33
	v_fmac_f32_e32 v17, v29, v19
	v_fmac_f32_e32 v17, v30, v20
	v_fmac_f32_e32 v17, v31, v21
	ds_read_b128 v[18:21], v131 offset:592
	s_waitcnt lgkmcnt(0)
	v_fmac_f32_e32 v17, v23, v18
	v_fmac_f32_e32 v17, v27, v19
	v_pk_mul_f32 v[18:19], v[14:15], v[20:21]
	s_nop 0
	v_add_f32_e32 v17, v17, v18
	v_add_f32_e32 v17, v17, v19
	ds_read_b128 v[18:21], v131 offset:608
	s_waitcnt lgkmcnt(0)
	v_pk_mul_f32 v[18:19], v[10:11], v[18:19]
	s_nop 0
	v_add_f32_e32 v17, v17, v18
	v_add_f32_e32 v17, v17, v19
	v_pk_mul_f32 v[18:19], v[12:13], v[20:21]
	s_nop 0
	v_add_f32_e32 v17, v17, v18
	v_add_f32_e32 v17, v17, v19
	ds_read_b128 v[18:21], v131 offset:624
	s_waitcnt lgkmcnt(0)
	v_pk_mul_f32 v[18:19], v[6:7], v[18:19]
	s_nop 0
	v_add_f32_e32 v17, v17, v18
	v_add_f32_e32 v17, v17, v19
	v_pk_mul_f32 v[18:19], v[8:9], v[20:21]
	s_nop 0
	v_add_f32_e32 v17, v17, v18
	v_add_f32_e32 v18, v17, v19
	v_min_f32_e32 v17, 0, v18
	v_mul_f32_e64 v18, |v18|, s89
	v_exp_f32_e32 v18, v18
	s_nop 0
	v_add_f32_e32 v18, 1.0, v18
	v_cmp_gt_f32_e32 vcc, s90, v18
	s_nop 1
	v_cndmask_b32_e64 v19, 0, 32, vcc
	v_ldexp_f32 v18, v18, v19
	v_log_f32_e32 v18, v18
	s_nop 0
	v_mul_f32_e32 v19, 0x3f317217, v18
	v_fma_f32 v19, v18, s91, -v19
	v_fmac_f32_e32 v19, 0x3377d1cf, v18
	v_fmac_f32_e32 v19, 0x3f317217, v18
	v_cmp_lt_f32_e64 s[0:1], |v18|, s97
	s_nop 1
	v_cndmask_b32_e64 v18, v18, v19, s[0:1]
	v_cndmask_b32_e32 v19, 0, v151, vcc
	v_sub_f32_e32 v39, v18, v19
	v_pk_add_f32 v[16:17], v[16:17], v[38:39] neg_lo:[0,1] neg_hi:[0,1]
	ds_read_b128 v[38:41], v131 offset:704
	v_pk_mul_f32 v[16:17], v[16:17], s[84:85] op_sel_hi:[1,0]
	s_nop 0
	v_add_f32_e32 v18, v22, v16
	v_add_f32_e32 v22, v18, v17
	ds_read_b128 v[18:21], v131 offset:640
	s_waitcnt lgkmcnt(0)
	v_fma_f32 v37, v28, v18, v33
	v_fmac_f32_e32 v37, v29, v19
	v_fmac_f32_e32 v37, v30, v20
	v_fmac_f32_e32 v37, v31, v21
	ds_read_b128 v[18:21], v131 offset:656
	s_waitcnt lgkmcnt(0)
	v_fmac_f32_e32 v37, v23, v18
	v_fmac_f32_e32 v37, v27, v19
	v_pk_mul_f32 v[18:19], v[14:15], v[20:21]
	s_nop 0
	v_add_f32_e32 v18, v37, v18
	v_add_f32_e32 v37, v18, v19
	ds_read_b128 v[18:21], v131 offset:672
	s_waitcnt lgkmcnt(0)
	v_pk_mul_f32 v[18:19], v[10:11], v[18:19]
	s_nop 0
	v_add_f32_e32 v18, v37, v18
	v_add_f32_e32 v37, v18, v19
	v_pk_mul_f32 v[18:19], v[12:13], v[20:21]
	s_nop 0
	v_add_f32_e32 v18, v37, v18
	v_add_f32_e32 v37, v18, v19
	ds_read_b128 v[18:21], v131 offset:688
	s_waitcnt lgkmcnt(0)
	v_pk_mul_f32 v[18:19], v[6:7], v[18:19]
	s_nop 0
	v_add_f32_e32 v18, v37, v18
	v_add_f32_e32 v37, v18, v19
	v_pk_mul_f32 v[18:19], v[8:9], v[20:21]
	s_nop 0
	v_add_f32_e32 v18, v37, v18
	v_add_f32_e32 v19, v18, v19
	v_min_f32_e32 v18, 0, v19
	v_mul_f32_e64 v19, |v19|, s89
	v_exp_f32_e32 v19, v19
	s_nop 0
	v_add_f32_e32 v19, 1.0, v19
	v_cmp_gt_f32_e32 vcc, s90, v19
	s_nop 1
	v_cndmask_b32_e64 v20, 0, 32, vcc
	v_ldexp_f32 v19, v19, v20
	v_log_f32_e32 v19, v19
	s_nop 0
	v_mul_f32_e32 v20, 0x3f317217, v19
	v_fma_f32 v20, v19, s91, -v20
	v_fmac_f32_e32 v20, 0x3377d1cf, v19
	v_fmac_f32_e32 v20, 0x3f317217, v19
	v_cmp_lt_f32_e64 s[0:1], |v19|, s97
	s_nop 1
	v_cndmask_b32_e64 v19, v19, v20, s[0:1]
	v_cndmask_b32_e32 v20, 0, v151, vcc
	v_sub_f32_e32 v20, v19, v20
	v_fma_f32 v19, v28, v38, v33
	v_fmac_f32_e32 v19, v29, v39
	v_fmac_f32_e32 v19, v30, v40
	v_fmac_f32_e32 v19, v31, v41
	ds_read_b128 v[38:41], v131 offset:720
	s_waitcnt lgkmcnt(0)
	v_fmac_f32_e32 v19, v23, v38
	v_fmac_f32_e32 v19, v27, v39
	v_pk_mul_f32 v[38:39], v[14:15], v[40:41]
	s_nop 0
	v_add_f32_e32 v19, v19, v38
	v_add_f32_e32 v19, v19, v39
	ds_read_b128 v[38:41], v131 offset:736
	s_waitcnt lgkmcnt(0)
	v_pk_mul_f32 v[38:39], v[10:11], v[38:39]
	s_nop 0
	v_add_f32_e32 v19, v19, v38
	v_add_f32_e32 v19, v19, v39
	v_pk_mul_f32 v[38:39], v[12:13], v[40:41]
	s_nop 0
	v_add_f32_e32 v19, v19, v38
	v_add_f32_e32 v19, v19, v39
	ds_read_b128 v[38:41], v131 offset:752
	s_waitcnt lgkmcnt(0)
	v_pk_mul_f32 v[38:39], v[6:7], v[38:39]
	s_nop 0
	v_add_f32_e32 v19, v19, v38
	v_add_f32_e32 v19, v19, v39
	v_pk_mul_f32 v[38:39], v[8:9], v[40:41]
	s_nop 0
	v_add_f32_e32 v19, v19, v38
	v_add_f32_e32 v21, v19, v39
	v_min_f32_e32 v19, 0, v21
	v_mul_f32_e64 v21, |v21|, s89
	v_exp_f32_e32 v21, v21
	ds_read_b128 v[38:41], v131 offset:768
	v_add_f32_e32 v21, 1.0, v21
	v_cmp_gt_f32_e32 vcc, s90, v21
	s_nop 1
	v_cndmask_b32_e64 v37, 0, 32, vcc
	v_ldexp_f32 v21, v21, v37
	v_log_f32_e32 v21, v21
	s_nop 0
	v_mul_f32_e32 v37, 0x3f317217, v21
	v_fma_f32 v37, v21, s91, -v37
	v_fmac_f32_e32 v37, 0x3377d1cf, v21
	v_fmac_f32_e32 v37, 0x3f317217, v21
	v_cmp_lt_f32_e64 s[0:1], |v21|, s97
	s_nop 1
	v_cndmask_b32_e64 v21, v21, v37, s[0:1]
	v_cndmask_b32_e32 v37, 0, v151, vcc
	v_sub_f32_e32 v21, v21, v37
	s_waitcnt lgkmcnt(0)
	v_fma_f32 v37, v28, v38, v33
	v_fmac_f32_e32 v37, v29, v39
	v_fmac_f32_e32 v37, v30, v40
	v_fmac_f32_e32 v37, v31, v41
	ds_read_b128 v[38:41], v131 offset:784
	v_pk_add_f32 v[18:19], v[18:19], v[20:21] neg_lo:[0,1] neg_hi:[0,1]
	s_waitcnt lgkmcnt(0)
	v_fmac_f32_e32 v37, v23, v38
	v_pk_mul_f32 v[18:19], v[18:19], s[84:85] op_sel_hi:[1,0]
	v_fmac_f32_e32 v37, v27, v39
	v_add_f32_e32 v20, v22, v18
	v_add_f32_e32 v22, v20, v19
	v_pk_mul_f32 v[20:21], v[14:15], v[40:41]
	ds_read_b128 v[38:41], v131 offset:800
	v_add_f32_e32 v20, v37, v20
	v_add_f32_e32 v37, v20, v21
	s_waitcnt lgkmcnt(0)
	v_pk_mul_f32 v[20:21], v[10:11], v[38:39]
	s_nop 0
	v_add_f32_e32 v20, v37, v20
	v_add_f32_e32 v37, v20, v21
	v_pk_mul_f32 v[20:21], v[12:13], v[40:41]
	ds_read_b128 v[38:41], v131 offset:816
	v_add_f32_e32 v20, v37, v20
	v_add_f32_e32 v37, v20, v21
	s_waitcnt lgkmcnt(0)
	v_pk_mul_f32 v[20:21], v[6:7], v[38:39]
	s_nop 0
	v_add_f32_e32 v20, v37, v20
	v_add_f32_e32 v37, v20, v21
	v_pk_mul_f32 v[20:21], v[8:9], v[40:41]
	ds_read_b128 v[38:41], v131 offset:832
	v_add_f32_e32 v20, v37, v20
	v_add_f32_e32 v21, v20, v21
	v_min_f32_e32 v20, 0, v21
	v_mul_f32_e64 v21, |v21|, s89
	v_exp_f32_e32 v21, v21
	s_nop 0
	v_add_f32_e32 v21, 1.0, v21
	v_cmp_gt_f32_e32 vcc, s90, v21
	s_nop 1
	v_cndmask_b32_e64 v37, 0, 32, vcc
	v_ldexp_f32 v21, v21, v37
	v_log_f32_e32 v21, v21
	s_nop 0
	v_mul_f32_e32 v37, 0x3f317217, v21
	v_fma_f32 v37, v21, s91, -v37
	v_fmac_f32_e32 v37, 0x3377d1cf, v21
	v_fmac_f32_e32 v37, 0x3f317217, v21
	v_cmp_lt_f32_e64 s[0:1], |v21|, s97
	s_nop 1
	v_cndmask_b32_e64 v21, v21, v37, s[0:1]
	v_cndmask_b32_e32 v37, 0, v151, vcc
	v_sub_f32_e32 v42, v21, v37
	s_waitcnt lgkmcnt(0)
	v_fma_f32 v21, v28, v38, v33
	v_fmac_f32_e32 v21, v29, v39
	v_fmac_f32_e32 v21, v30, v40
	v_fmac_f32_e32 v21, v31, v41
	ds_read_b128 v[38:41], v131 offset:848
	s_waitcnt lgkmcnt(0)
	v_fmac_f32_e32 v21, v23, v38
	v_fmac_f32_e32 v21, v27, v39
	v_pk_mul_f32 v[38:39], v[14:15], v[40:41]
	s_nop 0
	v_add_f32_e32 v21, v21, v38
	v_add_f32_e32 v21, v21, v39
	ds_read_b128 v[38:41], v131 offset:864
	s_waitcnt lgkmcnt(0)
	v_pk_mul_f32 v[38:39], v[10:11], v[38:39]
	s_nop 0
	v_add_f32_e32 v21, v21, v38
	v_add_f32_e32 v21, v21, v39
	v_pk_mul_f32 v[38:39], v[12:13], v[40:41]
	s_nop 0
	v_add_f32_e32 v21, v21, v38
	v_add_f32_e32 v21, v21, v39
	ds_read_b128 v[38:41], v131 offset:880
	s_waitcnt lgkmcnt(0)
	v_pk_mul_f32 v[38:39], v[6:7], v[38:39]
	s_nop 0
	v_add_f32_e32 v21, v21, v38
	v_add_f32_e32 v21, v21, v39
	v_pk_mul_f32 v[38:39], v[8:9], v[40:41]
	s_nop 0
	v_add_f32_e32 v21, v21, v38
	v_add_f32_e32 v37, v21, v39
	v_min_f32_e32 v21, 0, v37
	v_mul_f32_e64 v37, |v37|, s89
	v_exp_f32_e32 v37, v37
	s_nop 0
	v_add_f32_e32 v37, 1.0, v37
	v_cmp_gt_f32_e32 vcc, s90, v37
	s_nop 1
	v_cndmask_b32_e64 v38, 0, 32, vcc
	v_ldexp_f32 v37, v37, v38
	v_log_f32_e32 v37, v37
	s_nop 0
	v_mul_f32_e32 v38, 0x3f317217, v37
	v_fma_f32 v38, v37, s91, -v38
	v_fmac_f32_e32 v38, 0x3377d1cf, v37
	v_fmac_f32_e32 v38, 0x3f317217, v37
	v_cmp_lt_f32_e64 s[0:1], |v37|, s97
	s_nop 1
	v_cndmask_b32_e64 v37, v37, v38, s[0:1]
	v_cndmask_b32_e32 v38, 0, v151, vcc
	v_sub_f32_e32 v43, v37, v38
	ds_read_b128 v[38:41], v131 offset:896
	v_pk_add_f32 v[20:21], v[20:21], v[42:43] neg_lo:[0,1] neg_hi:[0,1]
	s_nop 0
	v_pk_mul_f32 v[20:21], v[20:21], s[84:85] op_sel_hi:[1,0]
	s_nop 0
	v_add_f32_e32 v22, v22, v20
	v_add_f32_e32 v37, v22, v21
	s_waitcnt lgkmcnt(0)
	v_fma_f32 v22, v28, v38, v33
	v_fmac_f32_e32 v22, v29, v39
	v_fmac_f32_e32 v22, v30, v40
	v_fmac_f32_e32 v22, v31, v41
	ds_read_b128 v[38:41], v131 offset:912
	s_waitcnt lgkmcnt(0)
	v_fmac_f32_e32 v22, v23, v38
	v_fmac_f32_e32 v22, v27, v39
	v_pk_mul_f32 v[38:39], v[14:15], v[40:41]
	s_nop 0
	v_add_f32_e32 v22, v22, v38
	v_add_f32_e32 v22, v22, v39
	ds_read_b128 v[38:41], v131 offset:928
	s_waitcnt lgkmcnt(0)
	v_pk_mul_f32 v[38:39], v[10:11], v[38:39]
	s_nop 0
	v_add_f32_e32 v22, v22, v38
	v_add_f32_e32 v22, v22, v39
	v_pk_mul_f32 v[38:39], v[12:13], v[40:41]
	s_nop 0
	v_add_f32_e32 v22, v22, v38
	v_add_f32_e32 v22, v22, v39
	ds_read_b128 v[38:41], v131 offset:944
	s_waitcnt lgkmcnt(0)
	v_pk_mul_f32 v[38:39], v[6:7], v[38:39]
	s_nop 0
	v_add_f32_e32 v22, v22, v38
	v_add_f32_e32 v22, v22, v39
	v_pk_mul_f32 v[38:39], v[8:9], v[40:41]
	s_nop 0
	v_add_f32_e32 v22, v22, v38
	v_add_f32_e32 v38, v22, v39
	v_min_f32_e32 v22, 0, v38
	v_mul_f32_e64 v38, |v38|, s89
	v_exp_f32_e32 v38, v38
	s_nop 0
	v_add_f32_e32 v38, 1.0, v38
	v_cmp_gt_f32_e32 vcc, s90, v38
	s_nop 1
	v_cndmask_b32_e64 v39, 0, 32, vcc
	v_ldexp_f32 v38, v38, v39
	v_log_f32_e32 v38, v38
	s_nop 0
	v_mul_f32_e32 v39, 0x3f317217, v38
	v_fma_f32 v39, v38, s91, -v39
	v_fmac_f32_e32 v39, 0x3377d1cf, v38
	v_fmac_f32_e32 v39, 0x3f317217, v38
	v_cmp_lt_f32_e64 s[0:1], |v38|, s97
	s_nop 1
	v_cndmask_b32_e64 v38, v38, v39, s[0:1]
	v_cndmask_b32_e32 v39, 0, v151, vcc
	v_sub_f32_e32 v42, v38, v39
	ds_read_b128 v[38:41], v131 offset:960
	s_waitcnt lgkmcnt(0)
	v_fmac_f32_e32 v33, v28, v38
	v_fmac_f32_e32 v33, v29, v39
	v_fmac_f32_e32 v33, v30, v40
	v_fmac_f32_e32 v33, v31, v41
	ds_read_b128 v[28:31], v131 offset:976
	s_waitcnt lgkmcnt(0)
	v_fmac_f32_e32 v33, v23, v28
	v_fmac_f32_e32 v33, v27, v29
	v_pk_mul_f32 v[14:15], v[14:15], v[30:31]
	ds_read_b128 v[28:31], v131 offset:992
	v_add_f32_e32 v14, v33, v14
	v_add_f32_e32 v14, v14, v15
	s_waitcnt lgkmcnt(0)
	v_pk_mul_f32 v[10:11], v[10:11], v[28:29]
	s_nop 0
	v_add_f32_e32 v10, v14, v10
	v_add_f32_e32 v14, v10, v11
	v_pk_mul_f32 v[10:11], v[12:13], v[30:31]
	s_nop 0
	v_add_f32_e32 v10, v14, v10
	v_add_f32_e32 v14, v10, v11
	ds_read_b128 v[10:13], v131 offset:1008
	s_waitcnt lgkmcnt(0)
	v_pk_mul_f32 v[6:7], v[6:7], v[10:11]
	s_nop 0
	v_add_f32_e32 v6, v14, v6
	v_add_f32_e32 v10, v6, v7
	v_pk_mul_f32 v[6:7], v[8:9], v[12:13]
	s_nop 0
	v_add_f32_e32 v6, v10, v6
	v_add_f32_e32 v6, v6, v7
	v_min_f32_e32 v23, 0, v6
	v_mul_f32_e64 v6, |v6|, s89
	v_exp_f32_e32 v6, v6
	s_nop 0
	v_add_f32_e32 v6, 1.0, v6
	v_cmp_gt_f32_e32 vcc, s90, v6
	s_nop 1
	v_cndmask_b32_e64 v7, 0, 32, vcc
	v_ldexp_f32 v6, v6, v7
	v_log_f32_e32 v6, v6
	s_nop 0
	v_mul_f32_e32 v7, 0x3f317217, v6
	v_fma_f32 v7, v6, s91, -v7
	v_fmac_f32_e32 v7, 0x3377d1cf, v6
	v_fmac_f32_e32 v7, 0x3f317217, v6
	v_cmp_lt_f32_e64 s[0:1], |v6|, s97
	s_nop 1
	v_cndmask_b32_e64 v6, v6, v7, s[0:1]
	v_cndmask_b32_e32 v7, 0, v151, vcc
	v_sub_f32_e32 v43, v6, v7
	v_pk_add_f32 v[6:7], v[22:23], v[42:43] neg_lo:[0,1] neg_hi:[0,1]
	s_nop 0
	v_pk_mul_f32 v[6:7], v[6:7], s[84:85] op_sel_hi:[1,0]
	s_nop 0
	v_add_f32_e32 v8, v37, v6
	v_add_f32_e32 v8, v8, v7
	ds_write_b32 v132, v8 offset:8192
	s_waitcnt lgkmcnt(0)
	s_barrier
	ds_read2_b32 v[8:9], v152 offset1:32
	ds_read2_b32 v[10:11], v152 offset0:64 offset1:96
	s_waitcnt lgkmcnt(1)
	v_add_f32_e32 v8, 0, v8
	v_add_f32_e32 v12, v8, v9
	s_waitcnt lgkmcnt(0)
	v_add_f32_e32 v12, v12, v10
	v_add_f32_e32 v42, v12, v11
	ds_read2_b32 v[12:13], v152 offset0:128 offset1:160
	ds_read_b32 v14, v133 offset:8960
	s_and_saveexec_b64 s[0:1], s[2:3]
	s_cbranch_execz .LBB0_688
	ds_read_b32 v15, v133 offset:9088
	s_waitcnt lgkmcnt(2)
	v_add_f32_e32 v22, v42, v12
	v_mul_f32_e32 v23, 0x3fb8aa3b, v42
	v_add_f32_e32 v22, v22, v13
	s_waitcnt lgkmcnt(1)
	v_add_f32_e32 v22, v22, v14
	v_exp_f32_e32 v28, v23
	s_waitcnt lgkmcnt(0)
	v_add_f32_e32 v15, v22, v15
	v_lshl_or_b32 v22, v26, 9, v25
	v_mov_b32_e32 v23, v87
	v_readlane_b32 s2, v254, 51
	v_lshlrev_b64 v[22:23], 2, v[22:23]
	v_readlane_b32 s3, v254, 52
	s_nop 1
	v_lshl_add_u64 v[26:27], s[2:3], 0, v[22:23]
	global_store_dword v[26:27], v28, off
	v_mul_f32_e32 v26, 0x3fb8aa3b, v15
	v_sub_f32_e32 v15, v15, v42
	v_mul_f32_e32 v15, 0x3fb8aa3b, v15
	v_readlane_b32 s2, v254, 53
	v_exp_f32_e32 v28, v26
	v_exp_f32_e32 v15, v15
	v_readlane_b32 s3, v254, 54
	s_nop 1
	v_lshl_add_u64 v[26:27], s[2:3], 0, v[22:23]
	v_readlane_b32 s2, v254, 55
	v_readlane_b32 s3, v254, 56
	global_store_dword v[26:27], v28, off
	s_nop 0
	v_lshl_add_u64 v[22:23], s[2:3], 0, v[22:23]
	global_store_dword v[22:23], v15, off
.LBB0_688:
	s_or_b64 exec, exec, s[0:1]
	v_cndmask_b32_e64 v8, v8, 0, s[18:19]
	v_add_f32_e32 v9, v9, v8
	s_mov_b64 s[20:21], s[38:39]
	v_cndmask_b32_e64 v8, v8, v9, s[20:21]
	v_add_f32_e32 v9, v10, v8
	s_mov_b64 s[24:25], s[10:11]
	v_cndmask_b32_e64 v8, v8, v9, s[24:25]
	v_add_f32_e32 v9, v11, v8
	s_mov_b64 s[10:11], s[4:5]
	v_cndmask_b32_e64 v8, v8, v9, s[10:11]
	v_readlane_b32 s22, v255, 15
	s_waitcnt lgkmcnt(1)
	v_add_f32_e32 v9, v12, v8
	v_readlane_b32 s23, v255, 16
	v_readlane_b32 s4, v255, 17
	v_readlane_b32 s5, v255, 18
	v_cndmask_b32_e64 v8, v8, v9, s[22:23]
	v_add_f32_e32 v9, v13, v8
	v_cndmask_b32_e64 v8, v8, v9, s[4:5]
	v_readlane_b32 s0, v254, 61
	s_waitcnt lgkmcnt(0)
	v_add_f32_e32 v9, v14, v8
	v_readlane_b32 s1, v254, 62
	v_mul_f32_e32 v15, 0x3d800000, v32
	v_mul_f32_e32 v22, 0x3d800000, v34
	v_cndmask_b32_e64 v8, v8, v9, s[0:1]
	v_add_f32_e32 v8, v15, v8
	v_sub_f32_e32 v9, v8, v42
	v_mul_f32_e32 v9, 0x3fb8aa3b, v9
	v_exp_f32_e32 v12, v9
	v_sub_f32_e32 v9, v42, v8
	v_mul_f32_e32 v9, 0x3fb8aa3b, v9
	v_add_f32_e32 v8, v22, v8
	v_exp_f32_e32 v13, v9
	v_sub_f32_e32 v9, v8, v42
	v_mul_f32_e32 v9, 0x3fb8aa3b, v9
	v_mul_f32_e32 v23, 0x3d800000, v35
	v_exp_f32_e32 v41, v9
	v_sub_f32_e32 v9, v42, v8
	v_mul_f32_e32 v9, 0x3fb8aa3b, v9
	v_add_f32_e32 v8, v23, v8
	v_exp_f32_e32 v40, v9
	v_sub_f32_e32 v9, v8, v42
	v_mul_f32_e32 v9, 0x3fb8aa3b, v9
	v_mul_f32_e32 v26, 0x3d800000, v36
	v_exp_f32_e32 v36, v9
	v_sub_f32_e32 v9, v42, v8
	v_mul_f32_e32 v9, 0x3fb8aa3b, v9
	v_add_f32_e32 v8, v26, v8
	v_exp_f32_e32 v37, v9
	v_sub_f32_e32 v9, v8, v42
	v_mul_f32_e32 v9, 0x3fb8aa3b, v9
	v_add_f32_e32 v2, v2, v8
	v_exp_f32_e32 v39, v9
	v_sub_f32_e32 v9, v42, v8
	v_sub_f32_e32 v8, v2, v42
	v_mul_f32_e32 v8, 0x3fb8aa3b, v8
	v_exp_f32_e32 v32, v8
	v_sub_f32_e32 v8, v42, v2
	v_add_f32_e32 v2, v3, v2
	v_sub_f32_e32 v3, v2, v42
	v_mul_f32_e32 v3, 0x3fb8aa3b, v3
	v_exp_f32_e32 v35, v3
	v_sub_f32_e32 v3, v42, v2
	v_mul_f32_e32 v3, 0x3fb8aa3b, v3
	v_add_f32_e32 v2, v4, v2
	v_exp_f32_e32 v34, v3
	v_sub_f32_e32 v3, v2, v42
	v_mul_f32_e32 v3, 0x3fb8aa3b, v3
	v_exp_f32_e32 v28, v3
	v_sub_f32_e32 v3, v42, v2
	v_mul_f32_e32 v3, 0x3fb8aa3b, v3
	v_add_f32_e32 v2, v5, v2
	v_exp_f32_e32 v29, v3
	v_sub_f32_e32 v3, v2, v42
	v_mul_f32_e32 v3, 0x3fb8aa3b, v3
	v_exp_f32_e32 v31, v3
	v_sub_f32_e32 v3, v42, v2
	v_mul_f32_e32 v3, 0x3fb8aa3b, v3
	v_add_f32_e32 v2, v16, v2
	v_exp_f32_e32 v30, v3
	v_sub_f32_e32 v3, v2, v42
	v_mul_f32_e32 v3, 0x3fb8aa3b, v3
	v_exp_f32_e32 v22, v3
	v_sub_f32_e32 v3, v42, v2
	v_mul_f32_e32 v3, 0x3fb8aa3b, v3
	v_add_f32_e32 v2, v17, v2
	v_exp_f32_e32 v23, v3
	v_sub_f32_e32 v3, v2, v42
	v_mul_f32_e32 v3, 0x3fb8aa3b, v3
	v_exp_f32_e32 v27, v3
	v_sub_f32_e32 v3, v42, v2
	v_mul_f32_e32 v3, 0x3fb8aa3b, v3
	v_add_f32_e32 v2, v18, v2
	v_exp_f32_e32 v26, v3
	v_sub_f32_e32 v3, v2, v42
	v_mul_f32_e32 v3, 0x3fb8aa3b, v3
	v_exp_f32_e32 v14, v3
	v_sub_f32_e32 v3, v42, v2
	v_mul_f32_e32 v3, 0x3fb8aa3b, v3
	v_add_f32_e32 v2, v19, v2
	v_exp_f32_e32 v15, v3
	v_sub_f32_e32 v3, v2, v42
	v_mul_f32_e32 v3, 0x3fb8aa3b, v3
	v_exp_f32_e32 v17, v3
	v_sub_f32_e32 v3, v42, v2
	v_mul_f32_e32 v3, 0x3fb8aa3b, v3
	v_add_f32_e32 v2, v20, v2
	v_exp_f32_e32 v16, v3
	v_sub_f32_e32 v3, v2, v42
	v_mul_f32_e32 v8, 0x3fb8aa3b, v8
	v_mul_f32_e32 v3, 0x3fb8aa3b, v3
	v_exp_f32_e32 v33, v8
	v_exp_f32_e32 v8, v3
	v_sub_f32_e32 v3, v42, v2
	v_mul_f32_e32 v9, 0x3fb8aa3b, v9
	v_mul_f32_e32 v3, 0x3fb8aa3b, v3
	v_add_f32_e32 v2, v21, v2
	v_exp_f32_e32 v38, v9
	v_exp_f32_e32 v9, v3
	v_sub_f32_e32 v3, v2, v42
	v_mul_f32_e32 v3, 0x3fb8aa3b, v3
	v_exp_f32_e32 v11, v3
	v_sub_f32_e32 v3, v42, v2
	v_mul_f32_e32 v3, 0x3fb8aa3b, v3
	v_add_f32_e32 v2, v6, v2
	v_exp_f32_e32 v10, v3
	v_sub_f32_e32 v3, v2, v42
	v_mul_f32_e32 v3, 0x3fb8aa3b, v3
	v_exp_f32_e32 v4, v3
	v_sub_f32_e32 v3, v42, v2
	v_mul_f32_e32 v3, 0x3fb8aa3b, v3
	v_add_f32_e32 v2, v7, v2
	v_exp_f32_e32 v5, v3
	v_sub_f32_e32 v3, v2, v42
	v_mul_f32_e32 v3, 0x3fb8aa3b, v3
	v_exp_f32_e32 v6, v3
	v_sub_f32_e32 v2, v42, v2
	v_cndmask_b32_e64 v3, v12, v41, s[8:9]
	v_mul_f32_e32 v2, 0x3fb8aa3b, v2
	v_cndmask_b32_e64 v18, v13, v40, s[8:9]
	v_mov_b32_dpp v3, v3 quad_perm:[1,0,3,2] row_mask:0xf bank_mask:0xf bound_ctrl:1
	v_exp_f32_e32 v7, v2
	s_waitcnt vmcnt(0)
	v_or_b32_e32 v2, v135, v86
	v_and_b32_e32 v20, 0x1fe, v25
	v_mov_b32_dpp v18, v18 quad_perm:[1,0,3,2] row_mask:0xf bank_mask:0xf bound_ctrl:1
	v_cndmask_b32_e64 v12, v3, v12, s[8:9]
	v_cndmask_b32_e64 v25, v41, v3, s[8:9]
	v_mov_b32_e32 v3, v87
	v_cndmask_b32_e64 v41, v18, v13, s[8:9]
	v_cndmask_b32_e64 v40, v40, v18, s[8:9]
	v_lshlrev_b64 v[18:19], 10, v[2:3]
	v_lshlrev_b32_e32 v13, 1, v20
	v_readlane_b32 s0, v253, 63
	v_readlane_b32 s2, v254, 1
	v_or_b32_e32 v18, v18, v13
	v_readlane_b32 s1, v254, 0
	v_readlane_b32 s3, v254, 2
	v_cndmask_b32_e64 v42, v37, v38, s[8:9]
	v_lshl_add_u64 v[20:21], s[0:1], 0, v[18:19]
	v_lshl_add_u64 v[18:19], s[2:3], 0, v[18:19]
	v_mov_b32_e32 v3, v204
	v_mov_b32_e32 v44, v220
	v_cndmask_b32_e64 v43, v36, v39, s[8:9]
	s_waitcnt vmcnt(0)
	v_lshlrev_b32_e32 v45, 16, v44
	v_and_b32_e32 v44, 0xffff0000, v44
	v_mul_f32_e32 v40, v40, v44
	v_lshlrev_b32_e32 v44, 16, v3
	v_and_b32_e32 v3, 0xffff0000, v3
	v_mul_f32_e32 v12, v12, v44
	v_mul_f32_e32 v3, v25, v3
	v_mul_f32_e32 v41, v41, v45
	v_cvt_pk_bf16_f32 v3, v12, v3
	global_store_dword v[20:21], v3, off
	v_cvt_pk_bf16_f32 v3, v41, v40
	global_store_dword v[18:19], v3, off
	v_mov_b32_dpp v18, v43 quad_perm:[1,0,3,2] row_mask:0xf bank_mask:0xf bound_ctrl:1
	v_mov_b32_dpp v19, v42 quad_perm:[1,0,3,2] row_mask:0xf bank_mask:0xf bound_ctrl:1
	v_cndmask_b32_e64 v25, v18, v36, s[8:9]
	v_cndmask_b32_e64 v36, v39, v18, s[8:9]
	v_cndmask_b32_e64 v37, v19, v37, s[8:9]
	v_cndmask_b32_e64 v38, v38, v19, s[8:9]
	v_or_b32_e32 v18, 2, v2
	v_mov_b32_e32 v19, v87
	v_lshlrev_b64 v[18:19], 10, v[18:19]
	v_cndmask_b32_e64 v3, v41, v40, s[8:9]
	v_or_b32_e32 v18, v18, v13
	v_lshl_add_u64 v[20:21], s[0:1], 0, v[18:19]
	v_mov_b32_dpp v12, v3 quad_perm:[1,0,3,2] row_mask:0xf bank_mask:0xf bound_ctrl:1
	v_lshl_add_u64 v[18:19], s[2:3], 0, v[18:19]
	v_cndmask_b32_e64 v3, v12, v41, s[8:9]
	v_mov_b32_e32 v41, v205
	v_mov_b32_e32 v42, v221
	v_cndmask_b32_e64 v12, v40, v12, s[8:9]
	v_cndmask_b32_e64 v39, v33, v34, s[8:9]
	v_cndmask_b32_e64 v40, v32, v35, s[8:9]
	s_nop 0
	v_lshlrev_b32_e32 v43, 16, v42
	v_and_b32_e32 v42, 0xffff0000, v42
	v_mul_f32_e32 v38, v38, v42
	v_lshlrev_b32_e32 v42, 16, v41
	v_and_b32_e32 v41, 0xffff0000, v41
	v_mul_f32_e32 v25, v25, v42
	v_mul_f32_e32 v36, v36, v41
	v_mul_f32_e32 v37, v37, v43
	v_cvt_pk_bf16_f32 v25, v25, v36
	global_store_dword v[20:21], v25, off
	v_cvt_pk_bf16_f32 v20, v37, v38
	global_store_dword v[18:19], v20, off
	v_mov_b32_dpp v21, v39 quad_perm:[1,0,3,2] row_mask:0xf bank_mask:0xf bound_ctrl:1
	v_mov_b32_dpp v20, v40 quad_perm:[1,0,3,2] row_mask:0xf bank_mask:0xf bound_ctrl:1
	v_cndmask_b32_e64 v25, v20, v32, s[8:9]
	v_cndmask_b32_e64 v35, v35, v20, s[8:9]
	v_cndmask_b32_e64 v36, v21, v33, s[8:9]
	v_cndmask_b32_e64 v34, v34, v21, s[8:9]
	v_or_b32_e32 v20, 4, v2
	v_mov_b32_e32 v21, v87
	v_lshlrev_b64 v[20:21], 10, v[20:21]
	v_or_b32_e32 v20, v20, v13
	v_lshl_add_u64 v[32:33], s[0:1], 0, v[20:21]
	v_lshl_add_u64 v[20:21], s[2:3], 0, v[20:21]
	v_mov_b32_e32 v39, v206
	v_mov_b32_e32 v40, v222
	v_cndmask_b32_e64 v18, v37, v38, s[8:9]
	s_nop 0
	v_lshlrev_b32_e32 v41, 16, v40
	v_and_b32_e32 v40, 0xffff0000, v40
	v_mul_f32_e32 v34, v34, v40
	v_lshlrev_b32_e32 v40, 16, v39
	v_and_b32_e32 v39, 0xffff0000, v39
	v_mul_f32_e32 v25, v25, v40
	v_mul_f32_e32 v35, v35, v39
	v_mul_f32_e32 v36, v36, v41
	v_cvt_pk_bf16_f32 v25, v25, v35
	v_mov_b32_dpp v19, v18 quad_perm:[1,0,3,2] row_mask:0xf bank_mask:0xf bound_ctrl:1
	global_store_dword v[32:33], v25, off
	v_cvt_pk_bf16_f32 v25, v36, v34
	v_cndmask_b32_e64 v18, v19, v37, s[8:9]
	v_cndmask_b32_e64 v19, v38, v19, s[8:9]
	v_cndmask_b32_e64 v37, v29, v30, s[8:9]
	v_cndmask_b32_e64 v38, v28, v31, s[8:9]
	global_store_dword v[20:21], v25, off
	v_cndmask_b32_e64 v20, v36, v34, s[8:9]
	v_mov_b32_dpp v25, v38 quad_perm:[1,0,3,2] row_mask:0xf bank_mask:0xf bound_ctrl:1
	v_mov_b32_dpp v32, v37 quad_perm:[1,0,3,2] row_mask:0xf bank_mask:0xf bound_ctrl:1
	v_mov_b32_dpp v21, v20 quad_perm:[1,0,3,2] row_mask:0xf bank_mask:0xf bound_ctrl:1
	v_cndmask_b32_e64 v20, v21, v36, s[8:9]
	v_cndmask_b32_e64 v21, v34, v21, s[8:9]
	v_cndmask_b32_e64 v33, v25, v28, s[8:9]
	v_cndmask_b32_e64 v34, v32, v29, s[8:9]
	v_or_b32_e32 v28, 6, v2
	v_mov_b32_e32 v29, v87
	v_lshlrev_b64 v[28:29], 10, v[28:29]
	v_or_b32_e32 v28, v28, v13
	v_cndmask_b32_e64 v25, v31, v25, s[8:9]
	v_cndmask_b32_e64 v32, v30, v32, s[8:9]
	v_lshl_add_u64 v[30:31], s[0:1], 0, v[28:29]
	v_lshl_add_u64 v[28:29], s[2:3], 0, v[28:29]
	v_mov_b32_e32 v37, v207
	v_mov_b32_e32 v38, v223
	v_cndmask_b32_e64 v35, v23, v26, s[8:9]
	v_cndmask_b32_e64 v36, v22, v27, s[8:9]
	s_nop 0
	v_lshlrev_b32_e32 v39, 16, v38
	v_and_b32_e32 v38, 0xffff0000, v38
	v_mul_f32_e32 v32, v32, v38
	v_lshlrev_b32_e32 v38, 16, v37
	v_and_b32_e32 v37, 0xffff0000, v37
	v_mul_f32_e32 v33, v33, v38
	v_mul_f32_e32 v25, v25, v37
	v_mul_f32_e32 v34, v34, v39
	v_cvt_pk_bf16_f32 v25, v33, v25
	global_store_dword v[30:31], v25, off
	v_cvt_pk_bf16_f32 v25, v34, v32
	global_store_dword v[28:29], v25, off
	v_cndmask_b32_e64 v25, v34, v32, s[8:9]
	v_mov_b32_dpp v29, v36 quad_perm:[1,0,3,2] row_mask:0xf bank_mask:0xf bound_ctrl:1
	v_mov_b32_dpp v30, v35 quad_perm:[1,0,3,2] row_mask:0xf bank_mask:0xf bound_ctrl:1
	v_mov_b32_dpp v28, v25 quad_perm:[1,0,3,2] row_mask:0xf bank_mask:0xf bound_ctrl:1
	v_cndmask_b32_e64 v25, v28, v34, s[8:9]
	v_cndmask_b32_e64 v28, v32, v28, s[8:9]
	v_cndmask_b32_e64 v31, v29, v22, s[8:9]
	v_cndmask_b32_e64 v32, v30, v23, s[8:9]
	v_or_b32_e32 v22, 8, v2
	v_mov_b32_e32 v23, v87
	v_lshlrev_b64 v[22:23], 10, v[22:23]
	v_or_b32_e32 v22, v22, v13
	v_cndmask_b32_e64 v29, v27, v29, s[8:9]
	v_cndmask_b32_e64 v30, v26, v30, s[8:9]
	v_lshl_add_u64 v[26:27], s[0:1], 0, v[22:23]
	v_lshl_add_u64 v[22:23], s[2:3], 0, v[22:23]
	v_mov_b32_e32 v35, v208
	v_mov_b32_e32 v36, v224
	v_cndmask_b32_e64 v33, v15, v16, s[8:9]
	v_cndmask_b32_e64 v34, v14, v17, s[8:9]
	s_nop 0
	v_lshlrev_b32_e32 v37, 16, v36
	v_and_b32_e32 v36, 0xffff0000, v36
	v_mul_f32_e32 v30, v30, v36
	v_lshlrev_b32_e32 v36, 16, v35
	v_and_b32_e32 v35, 0xffff0000, v35
	v_mul_f32_e32 v31, v31, v36
	v_mul_f32_e32 v29, v29, v35
	v_mul_f32_e32 v32, v32, v37
	v_cvt_pk_bf16_f32 v29, v31, v29
	global_store_dword v[26:27], v29, off
	v_cvt_pk_bf16_f32 v26, v32, v30
	global_store_dword v[22:23], v26, off
	v_cndmask_b32_e64 v22, v32, v30, s[8:9]
	v_mov_b32_dpp v26, v34 quad_perm:[1,0,3,2] row_mask:0xf bank_mask:0xf bound_ctrl:1
	v_mov_b32_dpp v27, v33 quad_perm:[1,0,3,2] row_mask:0xf bank_mask:0xf bound_ctrl:1
	v_mov_b32_dpp v23, v22 quad_perm:[1,0,3,2] row_mask:0xf bank_mask:0xf bound_ctrl:1
	v_cndmask_b32_e64 v22, v23, v32, s[8:9]
	v_cndmask_b32_e64 v23, v30, v23, s[8:9]
	v_cndmask_b32_e64 v29, v26, v14, s[8:9]
	v_cndmask_b32_e64 v30, v27, v15, s[8:9]
	v_or_b32_e32 v14, 10, v2
	v_mov_b32_e32 v15, v87
	v_lshlrev_b64 v[14:15], 10, v[14:15]
	v_or_b32_e32 v14, v14, v13
	v_cndmask_b32_e64 v26, v17, v26, s[8:9]
	v_cndmask_b32_e64 v27, v16, v27, s[8:9]
	v_lshl_add_u64 v[16:17], s[0:1], 0, v[14:15]
	v_lshl_add_u64 v[14:15], s[2:3], 0, v[14:15]
	v_mov_b32_e32 v33, v209
	v_mov_b32_e32 v34, v225
	v_cndmask_b32_e64 v31, v9, v10, s[8:9]
	v_cndmask_b32_e64 v32, v8, v11, s[8:9]
	s_nop 0
	v_lshlrev_b32_e32 v35, 16, v34
	v_and_b32_e32 v34, 0xffff0000, v34
	v_mul_f32_e32 v27, v27, v34
	v_lshlrev_b32_e32 v34, 16, v33
	v_and_b32_e32 v33, 0xffff0000, v33
	v_mul_f32_e32 v29, v29, v34
	v_mul_f32_e32 v26, v26, v33
	v_mul_f32_e32 v30, v30, v35
	v_cvt_pk_bf16_f32 v26, v29, v26
	global_store_dword v[16:17], v26, off
	v_cvt_pk_bf16_f32 v16, v30, v27
	global_store_dword v[14:15], v16, off
	v_cndmask_b32_e64 v14, v30, v27, s[8:9]
	v_mov_b32_dpp v16, v32 quad_perm:[1,0,3,2] row_mask:0xf bank_mask:0xf bound_ctrl:1
	v_mov_b32_dpp v17, v31 quad_perm:[1,0,3,2] row_mask:0xf bank_mask:0xf bound_ctrl:1
	v_mov_b32_dpp v15, v14 quad_perm:[1,0,3,2] row_mask:0xf bank_mask:0xf bound_ctrl:1
	v_cndmask_b32_e64 v14, v15, v30, s[8:9]
	v_cndmask_b32_e64 v15, v27, v15, s[8:9]
	v_cndmask_b32_e64 v26, v16, v8, s[8:9]
	v_cndmask_b32_e64 v27, v17, v9, s[8:9]
	v_or_b32_e32 v8, 12, v2
	v_mov_b32_e32 v9, v87
	v_lshlrev_b64 v[8:9], 10, v[8:9]
	v_or_b32_e32 v8, v8, v13
	v_cndmask_b32_e64 v16, v11, v16, s[8:9]
	v_cndmask_b32_e64 v17, v10, v17, s[8:9]
	v_lshl_add_u64 v[10:11], s[0:1], 0, v[8:9]
	v_lshl_add_u64 v[8:9], s[2:3], 0, v[8:9]
	v_mov_b32_e32 v31, v210
	v_mov_b32_e32 v32, v226
	v_cndmask_b32_e64 v29, v5, v7, s[8:9]
	v_cndmask_b32_e64 v30, v4, v6, s[8:9]
	s_nop 0
	v_lshlrev_b32_e32 v33, 16, v32
	v_and_b32_e32 v32, 0xffff0000, v32
	v_mul_f32_e32 v17, v17, v32
	v_lshlrev_b32_e32 v32, 16, v31
	v_and_b32_e32 v31, 0xffff0000, v31
	v_mul_f32_e32 v26, v26, v32
	v_mul_f32_e32 v16, v16, v31
	v_mul_f32_e32 v27, v27, v33
	v_cvt_pk_bf16_f32 v16, v26, v16
	global_store_dword v[10:11], v16, off
	v_cvt_pk_bf16_f32 v10, v27, v17
	global_store_dword v[8:9], v10, off
	v_cndmask_b32_e64 v8, v27, v17, s[8:9]
	v_mov_b32_dpp v9, v29 quad_perm:[1,0,3,2] row_mask:0xf bank_mask:0xf bound_ctrl:1
	s_nop 0
	v_mov_b32_dpp v8, v8 quad_perm:[1,0,3,2] row_mask:0xf bank_mask:0xf bound_ctrl:1
	v_cndmask_b32_e64 v10, v8, v27, s[8:9]
	v_cndmask_b32_e64 v11, v17, v8, s[8:9]
	v_mov_b32_dpp v8, v30 quad_perm:[1,0,3,2] row_mask:0xf bank_mask:0xf bound_ctrl:1
	v_cndmask_b32_e64 v16, v8, v4, s[8:9]
	v_cndmask_b32_e64 v17, v9, v5, s[8:9]
	v_or_b32_e32 v4, 14, v2
	v_mov_b32_e32 v5, v87
	v_lshlrev_b64 v[4:5], 10, v[4:5]
	v_or_b32_e32 v4, v4, v13
	v_cndmask_b32_e64 v8, v6, v8, s[8:9]
	v_cndmask_b32_e64 v9, v7, v9, s[8:9]
	v_lshl_add_u64 v[6:7], s[0:1], 0, v[4:5]
	v_lshl_add_u64 v[4:5], s[2:3], 0, v[4:5]
	v_mov_b32_e32 v2, v211
	v_mov_b32_e32 v13, v227
	s_nop 0
	v_lshlrev_b32_e32 v26, 16, v13
	v_and_b32_e32 v13, 0xffff0000, v13
	v_mul_f32_e32 v9, v9, v13
	v_lshlrev_b32_e32 v13, 16, v2
	v_and_b32_e32 v2, 0xffff0000, v2
	v_mul_f32_e32 v13, v16, v13
	v_mul_f32_e32 v2, v8, v2
	v_mul_f32_e32 v17, v17, v26
	v_cvt_pk_bf16_f32 v2, v13, v2
	global_store_dword v[6:7], v2, off
	v_cvt_pk_bf16_f32 v2, v17, v9
	global_store_dword v[4:5], v2, off
	v_cvt_pk_bf16_f32 v4, v10, v11
	v_or_b32_e32 v10, v86, v134
	v_lshrrev_b32_e32 v10, 3, v10
	v_cndmask_b32_e64 v2, v17, v9, s[8:9]
	v_lshl_add_u32 v86, v24, 6, v10
	v_lshlrev_b64 v[10:11], 9, v[86:87]
	v_mov_b32_dpp v2, v2 quad_perm:[1,0,3,2] row_mask:0xf bank_mask:0xf bound_ctrl:1
	v_cndmask_b32_e64 v13, v9, v2, s[8:9]
	v_cvt_pk_bf16_f32 v6, v3, v12
	v_cvt_pk_bf16_f32 v7, v18, v19
	v_cvt_pk_bf16_f32 v8, v20, v21
	v_cvt_pk_bf16_f32 v9, v25, v28
	v_lshl_add_u64 v[10:11], v[88:89], 0, v[10:11]
	v_or_b32_e32 v86, 1, v86
	v_cndmask_b32_e64 v5, v2, v17, s[8:9]
	global_store_dwordx4 v[10:11], v[6:9], off
	v_cvt_pk_bf16_f32 v2, v22, v23
	v_cvt_pk_bf16_f32 v3, v14, v15
	v_lshlrev_b64 v[6:7], 9, v[86:87]
	v_cvt_pk_bf16_f32 v5, v5, v13
	v_lshl_add_u64 v[6:7], v[88:89], 0, v[6:7]
	global_store_dwordx4 v[6:7], v[2:5], off

.LBB0_780:
	s_movk_i32 s6, 0x7ff
	v_cmp_lt_i32_e32 vcc, s6, v66
	s_and_saveexec_b64 s[6:7], vcc
	s_xor_b64 s[6:7], exec, s[6:7]
	s_cbranch_execz .LBB0_782
	s_movk_i32 s11, 0x80
	v_add_u32_e32 v2, 0xfffff800, v66
	v_bfe_u32 v86, v66, 1, 2
	v_and_or_b32 v67, v77, s11, v1
	v_lshrrev_b32_e32 v87, 3, v2
	v_lshlrev_b32_e32 v2, 6, v67
	v_lshlrev_b32_e32 v3, 14, v86
	v_or3_b32 v89, v3, v2, v68
	v_lshlrev_b32_e32 v90, 4, v87
	v_lshl_or_b32 v88, v86, 13, v68
	v_add_u32_e32 v70, v89, v90
	v_lshlrev_b64 v[2:3], 9, v[70:71]
	v_add_u32_e32 v70, v88, v90
	v_lshlrev_b64 v[6:7], 9, v[70:71]
	v_lshl_add_u64 v[2:3], v[72:73], 0, v[2:3]
	v_lshl_add_u64 v[6:7], v[74:75], 0, v[6:7]
	s_mov_b64 vcc, 0x1000
	v_lshl_add_u64 v[100:101], v[2:3], 0, vcc
	s_mov_b64 vcc, 0x1000
	v_lshl_add_u64 v[102:103], v[6:7], 0, vcc
	s_mov_b64 vcc, 0x101000
	v_lshl_add_u64 v[104:105], v[6:7], 0, vcc
	s_mov_b64 vcc, 0x201000
	v_lshl_add_u64 v[106:107], v[6:7], 0, vcc
	s_mov_b64 vcc, 0x301000
	v_lshl_add_u64 v[108:109], v[6:7], 0, vcc
	global_load_dwordx4 v[112:115], v[100:101], off offset:-4096
	global_load_dwordx4 v[116:119], v[100:101], off offset:-3072
	global_load_dwordx4 v[144:147], v[102:103], off offset:-4096
	global_load_dwordx4 v[148:151], v[104:105], off offset:-4096
	global_load_dwordx4 v[152:155], v[106:107], off offset:-4096
	global_load_dwordx4 v[156:159], v[108:109], off offset:-4096
	global_load_dwordx4 v[120:123], v[100:101], off offset:-2048
	global_load_dwordx4 v[124:127], v[100:101], off offset:-1024
	global_load_dwordx4 v[128:131], v[100:101], off
	global_load_dwordx4 v[132:135], v[100:101], off offset:1024
	global_load_dwordx4 v[136:139], v[100:101], off offset:2048
	global_load_dwordx4 v[140:143], v[100:101], off offset:3072
	global_load_dwordx4 v[160:163], v[102:103], off offset:-3072
	global_load_dwordx4 v[164:167], v[104:105], off offset:-3072
	global_load_dwordx4 v[168:171], v[106:107], off offset:-3072
	global_load_dwordx4 v[172:175], v[108:109], off offset:-3072
	global_load_dwordx4 v[176:179], v[102:103], off offset:-2048
	global_load_dwordx4 v[180:183], v[104:105], off offset:-2048
	global_load_dwordx4 v[184:187], v[106:107], off offset:-2048
	global_load_dwordx4 v[188:191], v[108:109], off offset:-2048
	s_waitcnt vmcnt(17)
	v_mfma_f32_32x32x16_bf16 v[50:65], v[144:147], v[112:115], 0
	global_load_dwordx4 v[144:147], v[102:103], off offset:-1024
	s_waitcnt vmcnt(17)
	v_mfma_f32_32x32x16_bf16 v[34:49], v[148:151], v[112:115], 0
	global_load_dwordx4 v[148:151], v[104:105], off offset:-1024
	s_waitcnt vmcnt(17)
	v_mfma_f32_32x32x16_bf16 v[18:33], v[152:155], v[112:115], 0
	global_load_dwordx4 v[152:155], v[106:107], off offset:-1024
	s_waitcnt vmcnt(17)
	v_mfma_f32_32x32x16_bf16 v[2:17], v[156:159], v[112:115], 0
	global_load_dwordx4 v[156:159], v[108:109], off offset:-1024
	s_waitcnt vmcnt(11)
	v_mfma_f32_32x32x16_bf16 v[50:65], v[160:163], v[116:119], v[50:65]
	global_load_dwordx4 v[160:163], v[102:103], off
	s_waitcnt vmcnt(11)
	v_mfma_f32_32x32x16_bf16 v[34:49], v[164:167], v[116:119], v[34:49]
	global_load_dwordx4 v[164:167], v[104:105], off
	s_waitcnt vmcnt(11)
	v_mfma_f32_32x32x16_bf16 v[18:33], v[168:171], v[116:119], v[18:33]
	global_load_dwordx4 v[168:171], v[106:107], off
	s_waitcnt vmcnt(11)
	v_mfma_f32_32x32x16_bf16 v[2:17], v[172:175], v[116:119], v[2:17]
	global_load_dwordx4 v[172:175], v[108:109], off
	s_waitcnt vmcnt(11)
	v_mfma_f32_32x32x16_bf16 v[50:65], v[176:179], v[120:123], v[50:65]
	global_load_dwordx4 v[176:179], v[102:103], off offset:1024
	s_waitcnt vmcnt(11)
	v_mfma_f32_32x32x16_bf16 v[34:49], v[180:183], v[120:123], v[34:49]
	global_load_dwordx4 v[180:183], v[104:105], off offset:1024
	s_waitcnt vmcnt(11)
	v_mfma_f32_32x32x16_bf16 v[18:33], v[184:187], v[120:123], v[18:33]
	global_load_dwordx4 v[184:187], v[106:107], off offset:1024
	s_waitcnt vmcnt(11)
	v_mfma_f32_32x32x16_bf16 v[2:17], v[188:191], v[120:123], v[2:17]
	global_load_dwordx4 v[188:191], v[108:109], off offset:1024
	s_waitcnt vmcnt(11)
	v_mfma_f32_32x32x16_bf16 v[50:65], v[144:147], v[124:127], v[50:65]
	global_load_dwordx4 v[144:147], v[102:103], off offset:2048
	s_waitcnt vmcnt(11)
	v_mfma_f32_32x32x16_bf16 v[34:49], v[148:151], v[124:127], v[34:49]
	global_load_dwordx4 v[148:151], v[104:105], off offset:2048
	s_waitcnt vmcnt(11)
	v_mfma_f32_32x32x16_bf16 v[18:33], v[152:155], v[124:127], v[18:33]
	global_load_dwordx4 v[152:155], v[106:107], off offset:2048
	s_waitcnt vmcnt(11)
	v_mfma_f32_32x32x16_bf16 v[2:17], v[156:159], v[124:127], v[2:17]
	global_load_dwordx4 v[156:159], v[108:109], off offset:2048
	s_waitcnt vmcnt(11)
	v_mfma_f32_32x32x16_bf16 v[50:65], v[160:163], v[128:131], v[50:65]
	global_load_dwordx4 v[160:163], v[102:103], off offset:3072
	s_waitcnt vmcnt(11)
	v_mfma_f32_32x32x16_bf16 v[34:49], v[164:167], v[128:131], v[34:49]
	global_load_dwordx4 v[164:167], v[104:105], off offset:3072
	s_waitcnt vmcnt(11)
	v_mfma_f32_32x32x16_bf16 v[18:33], v[168:171], v[128:131], v[18:33]
	global_load_dwordx4 v[168:171], v[106:107], off offset:3072
	s_waitcnt vmcnt(11)
	v_mfma_f32_32x32x16_bf16 v[2:17], v[172:175], v[128:131], v[2:17]
	global_load_dwordx4 v[172:175], v[108:109], off offset:3072
	s_waitcnt vmcnt(11)
	v_mfma_f32_32x32x16_bf16 v[50:65], v[176:179], v[132:135], v[50:65]
	s_waitcnt vmcnt(10)
	v_mfma_f32_32x32x16_bf16 v[34:49], v[180:183], v[132:135], v[34:49]
	s_waitcnt vmcnt(9)
	v_mfma_f32_32x32x16_bf16 v[18:33], v[184:187], v[132:135], v[18:33]
	s_waitcnt vmcnt(8)
	v_mfma_f32_32x32x16_bf16 v[2:17], v[188:191], v[132:135], v[2:17]
	s_waitcnt vmcnt(7)
	v_mfma_f32_32x32x16_bf16 v[50:65], v[144:147], v[136:139], v[50:65]
	s_waitcnt vmcnt(6)
	v_mfma_f32_32x32x16_bf16 v[34:49], v[148:151], v[136:139], v[34:49]
	s_waitcnt vmcnt(5)
	v_mfma_f32_32x32x16_bf16 v[18:33], v[152:155], v[136:139], v[18:33]
	s_waitcnt vmcnt(4)
	v_mfma_f32_32x32x16_bf16 v[2:17], v[156:159], v[136:139], v[2:17]
	s_waitcnt vmcnt(3)
	v_mfma_f32_32x32x16_bf16 v[50:65], v[160:163], v[140:143], v[50:65]
	s_waitcnt vmcnt(2)
	v_mfma_f32_32x32x16_bf16 v[34:49], v[164:167], v[140:143], v[34:49]
	s_waitcnt vmcnt(1)
	v_mfma_f32_32x32x16_bf16 v[18:33], v[168:171], v[140:143], v[18:33]
	s_waitcnt vmcnt(0)
	v_mfma_f32_32x32x16_bf16 v[2:17], v[172:175], v[140:143], v[2:17]
	s_movk_i32 s11, 0x1000
	v_lshl_or_b32 v70, v87, 2, v86
	v_lshlrev_b64 v[86:87], 16, v[70:71]
	v_lshl_add_u64 v[86:87], s[68:69], 0, v[86:87]
	v_lshl_or_b32 v70, v67, 8, v85
	v_lshl_add_u64 v[192:193], v[86:87], 0, v[70:71]
	s_mov_b64 vcc, 0x1000
	v_lshl_add_u64 v[194:195], v[192:193], 0, vcc
	s_nop 7
	s_nop 7
	v_cvt_pk_bf16_f32 v196, v50, v51
	v_cvt_pk_bf16_f32 v197, v52, v53
	global_store_dwordx2 v[192:193], v[196:197], off
	v_cvt_pk_bf16_f32 v198, v54, v55
	v_cvt_pk_bf16_f32 v199, v56, v57
	global_store_dwordx2 v[192:193], v[198:199], off offset:512
	v_cvt_pk_bf16_f32 v200, v58, v59
	v_cvt_pk_bf16_f32 v201, v60, v61
	global_store_dwordx2 v[192:193], v[200:201], off offset:1024
	v_cvt_pk_bf16_f32 v202, v62, v63
	v_cvt_pk_bf16_f32 v203, v64, v65
	global_store_dwordx2 v[192:193], v[202:203], off offset:1536
	v_cvt_pk_bf16_f32 v196, v34, v35
	v_cvt_pk_bf16_f32 v197, v36, v37
	global_store_dwordx2 v[192:193], v[196:197], off offset:2048
	v_cvt_pk_bf16_f32 v198, v38, v39
	v_cvt_pk_bf16_f32 v199, v40, v41
	global_store_dwordx2 v[192:193], v[198:199], off offset:2560
	v_cvt_pk_bf16_f32 v200, v42, v43
	v_cvt_pk_bf16_f32 v201, v44, v45
	global_store_dwordx2 v[192:193], v[200:201], off offset:3072
	v_cvt_pk_bf16_f32 v202, v46, v47
	v_cvt_pk_bf16_f32 v203, v48, v49
	global_store_dwordx2 v[192:193], v[202:203], off offset:3584
	v_cvt_pk_bf16_f32 v196, v18, v19
	v_cvt_pk_bf16_f32 v197, v20, v21
	global_store_dwordx2 v[194:195], v[196:197], off
	v_cvt_pk_bf16_f32 v198, v22, v23
	v_cvt_pk_bf16_f32 v199, v24, v25
	global_store_dwordx2 v[194:195], v[198:199], off offset:512
	v_cvt_pk_bf16_f32 v200, v26, v27
	v_cvt_pk_bf16_f32 v201, v28, v29
	global_store_dwordx2 v[194:195], v[200:201], off offset:1024
	v_cvt_pk_bf16_f32 v202, v30, v31
	v_cvt_pk_bf16_f32 v203, v32, v33
	global_store_dwordx2 v[194:195], v[202:203], off offset:1536
	v_cvt_pk_bf16_f32 v196, v2, v3
	v_cvt_pk_bf16_f32 v197, v4, v5
	global_store_dwordx2 v[194:195], v[196:197], off offset:2048
	v_cvt_pk_bf16_f32 v198, v6, v7
	v_cvt_pk_bf16_f32 v199, v8, v9
	global_store_dwordx2 v[194:195], v[198:199], off offset:2560
	v_cvt_pk_bf16_f32 v200, v10, v11
	v_cvt_pk_bf16_f32 v201, v12, v13
	global_store_dwordx2 v[194:195], v[200:201], off offset:3072
	v_cvt_pk_bf16_f32 v202, v14, v15
	v_cvt_pk_bf16_f32 v203, v16, v17
	global_store_dwordx2 v[194:195], v[202:203], off offset:3584
	s_nop 0
	s_nop 0
	s_nop 0
	s_nop 0
	s_nop 0
	s_nop 0
.LBB0_782:
	s_andn2_saveexec_b64 s[6:7], s[6:7]
	s_cbranch_execz .LBB0_779
	v_and_b32_e32 v4, 15, v66
	v_lshlrev_b32_e32 v2, 10, v66
	v_and_b32_e32 v54, 0xffffff80, v84
	v_and_or_b32 v70, v2, s10, v69
	v_lshlrev_b32_e32 v2, 16, v4
	v_mov_b32_e32 v3, v71
	v_lshl_add_u64 v[34:35], s[2:3], 0, v[2:3]
	v_ashrrev_i32_e32 v2, 4, v54
	v_ashrrev_i32_e32 v3, 31, v2
	v_lshlrev_b64 v[30:31], 1, v[2:3]
	v_lshl_add_u64 v[2:3], v[30:31], 0, v[70:71]
	v_or_b32_e32 v36, v54, v76
	v_lshlrev_b64 v[2:3], 9, v[2:3]
	v_lshlrev_b32_e32 v46, 12, v4
	v_lshl_add_u64 v[2:3], v[78:79], 0, v[2:3]
	v_ashrrev_i32_e32 v37, 31, v36
	v_mov_b32_e32 v47, v71
	global_load_dwordx4 v[18:21], v[2:3], off
	v_lshl_add_u64 v[2:3], v[36:37], 2, v[34:35]
	v_or_b32_e32 v30, v30, v68
	v_or_b32_e32 v48, 0x800, v46
	v_mov_b32_e32 v49, v71
	global_load_dwordx4 v[22:25], v[2:3], off offset:16
	global_load_dwordx4 v[26:29], v[2:3], off
	v_lshl_add_u64 v[2:3], v[30:31], 0, v[46:47]
	v_lshl_add_u64 v[30:31], v[30:31], 0, v[48:49]
	v_lshlrev_b64 v[2:3], 9, v[2:3]
	v_lshlrev_b64 v[30:31], 9, v[30:31]
	v_lshl_add_u64 v[2:3], v[80:81], 0, v[2:3]
	v_lshl_add_u64 v[30:31], v[80:81], 0, v[30:31]
	global_load_dwordx4 v[2:5], v[2:3], off
	v_or_b32_e32 v37, 16, v54
	global_load_dwordx4 v[30:33], v[30:31], off
	v_ashrrev_i32_e32 v67, 31, v66
	s_waitcnt vmcnt(1)
	v_lshlrev_b32_e32 v6, 16, v2
	v_and_b32_e32 v7, 0xffff0000, v2
	s_waitcnt vmcnt(0)
	v_lshlrev_b32_e32 v38, 16, v30
	v_and_b32_e32 v39, 0xffff0000, v30
	v_pk_mul_f32 v[6:7], v[26:27], v[6:7]
	v_pk_mul_f32 v[26:27], v[26:27], v[38:39]
	v_ashrrev_i32_e32 v38, 4, v37
	v_ashrrev_i32_e32 v39, 31, v38
	v_lshlrev_b64 v[52:53], 1, v[38:39]
	v_lshl_add_u64 v[38:39], v[52:53], 0, v[70:71]
	v_or_b32_e32 v52, v52, v68
	v_lshl_add_u64 v[56:57], v[52:53], 0, v[46:47]
	v_lshlrev_b64 v[38:39], 9, v[38:39]
	v_ashrrev_i32_e32 v37, 31, v54
	v_lshlrev_b64 v[56:57], 9, v[56:57]
	v_lshl_add_u64 v[38:39], v[78:79], 0, v[38:39]
	v_lshl_add_u64 v[50:51], v[36:37], 2, v[34:35]
	v_lshl_add_u64 v[56:57], v[80:81], 0, v[56:57]
	global_load_dwordx4 v[38:41], v[38:39], off
	s_nop 0
	global_load_dwordx4 v[34:37], v[50:51], off offset:80
	global_load_dwordx4 v[42:45], v[50:51], off offset:64
	v_cvt_pk_bf16_f32 v2, v6, v7
	global_load_dwordx4 v[56:59], v[56:57], off
	v_lshlrev_b32_e32 v6, 16, v3
	v_and_b32_e32 v7, 0xffff0000, v3
	v_pk_mul_f32 v[6:7], v[28:29], v[6:7]
	v_lshl_add_u64 v[52:53], v[52:53], 0, v[48:49]
	v_cvt_pk_bf16_f32 v3, v6, v7
	v_lshlrev_b32_e32 v6, 16, v4
	v_and_b32_e32 v7, 0xffff0000, v4
	v_pk_mul_f32 v[6:7], v[22:23], v[6:7]
	v_lshlrev_b64 v[52:53], 9, v[52:53]
	v_cvt_pk_bf16_f32 v4, v6, v7
	v_lshlrev_b32_e32 v6, 16, v5
	v_and_b32_e32 v7, 0xffff0000, v5
	v_pk_mul_f32 v[6:7], v[24:25], v[6:7]
	v_lshl_add_u64 v[52:53], v[80:81], 0, v[52:53]
	v_cvt_pk_bf16_f32 v5, v6, v7
	v_lshlrev_b32_e32 v30, 16, v31
	v_and_b32_e32 v31, 0xffff0000, v31
	v_mfma_f32_32x32x16_bf16 v[2:17], v[18:21], v[2:5], 0
	v_mul_f32_e64 v28, v28, v30
	v_mul_f32_e64 v29, v29, v31
	v_cvt_pk_bf16_f32 v26, v26, v27
	v_cvt_pk_bf16_f32 v27, v28, v29
	v_lshlrev_b32_e32 v28, 16, v32
	v_and_b32_e32 v29, 0xffff0000, v32
	v_pk_mul_f32 v[22:23], v[22:23], v[28:29]
	s_waitcnt vmcnt(0)
	v_lshlrev_b32_e32 v60, 16, v56
	v_and_b32_e32 v61, 0xffff0000, v56
	v_pk_mul_f32 v[60:61], v[42:43], v[60:61]
	v_cvt_pk_bf16_f32 v28, v22, v23
	v_cvt_pk_bf16_f32 v56, v60, v61
	v_lshlrev_b32_e32 v60, 16, v57
	v_and_b32_e32 v61, 0xffff0000, v57
	v_pk_mul_f32 v[60:61], v[44:45], v[60:61]
	v_lshlrev_b32_e32 v22, 16, v33
	v_cvt_pk_bf16_f32 v57, v60, v61
	v_lshlrev_b32_e32 v60, 16, v58
	v_and_b32_e32 v61, 0xffff0000, v58
	v_pk_mul_f32 v[60:61], v[34:35], v[60:61]
	v_and_b32_e32 v23, 0xffff0000, v33
	v_cvt_pk_bf16_f32 v58, v60, v61
	v_lshlrev_b32_e32 v60, 16, v59
	v_and_b32_e32 v61, 0xffff0000, v59
	v_pk_mul_f32 v[60:61], v[36:37], v[60:61]
	v_pk_mul_f32 v[22:23], v[24:25], v[22:23]
	v_cvt_pk_bf16_f32 v59, v60, v61
	v_cvt_pk_bf16_f32 v29, v22, v23
	s_nop 0
	v_mfma_f32_32x32x16_bf16 v[2:17], v[38:41], v[56:59], v[2:17]
	global_load_dwordx4 v[56:59], v[52:53], off
	s_waitcnt vmcnt(0)
	v_lshlrev_b32_e32 v52, 16, v56
	v_and_b32_e32 v53, 0xffff0000, v56
	v_mul_f32_e64 v42, v42, v52
	v_mul_f32_e64 v43, v43, v53
	v_lshlrev_b32_e32 v52, 16, v57
	v_and_b32_e32 v53, 0xffff0000, v57
	v_pk_mul_f32 v[44:45], v[44:45], v[52:53]
	v_cvt_pk_bf16_f32 v42, v42, v43
	v_cvt_pk_bf16_f32 v43, v44, v45
	v_lshlrev_b32_e32 v44, 16, v58
	v_and_b32_e32 v45, 0xffff0000, v58
	v_pk_mul_f32 v[34:35], v[34:35], v[44:45]
	v_mfma_f32_32x32x16_bf16 v[18:33], v[18:21], v[26:29], 0
	v_cvt_pk_bf16_f32 v44, v34, v35
	v_lshlrev_b32_e32 v34, 16, v59
	v_and_b32_e32 v35, 0xffff0000, v59
	v_mul_f32_e64 v34, v36, v34
	v_mul_f32_e64 v35, v37, v35
	v_cvt_pk_bf16_f32 v45, v34, v35
	v_or_b32_e32 v34, 32, v54
	v_ashrrev_i32_e32 v34, 4, v34
	v_ashrrev_i32_e32 v35, 31, v34
	v_lshlrev_b64 v[52:53], 1, v[34:35]
	v_lshl_add_u64 v[34:35], v[52:53], 0, v[70:71]
	v_or_b32_e32 v52, v52, v68
	v_lshl_add_u64 v[56:57], v[52:53], 0, v[46:47]
	v_lshlrev_b64 v[34:35], 9, v[34:35]
	v_lshlrev_b64 v[56:57], 9, v[56:57]
	v_lshl_add_u64 v[34:35], v[78:79], 0, v[34:35]
	v_lshl_add_u64 v[56:57], v[80:81], 0, v[56:57]
	v_mfma_f32_32x32x16_bf16 v[18:33], v[38:41], v[42:45], v[18:33]
	global_load_dwordx4 v[34:37], v[34:35], off
	s_nop 0
	global_load_dwordx4 v[38:41], v[50:51], off offset:144
	global_load_dwordx4 v[42:45], v[50:51], off offset:128
	v_lshl_add_u64 v[52:53], v[52:53], 0, v[48:49]
	global_load_dwordx4 v[56:59], v[56:57], off
	v_lshlrev_b64 v[52:53], 9, v[52:53]
	v_lshl_add_u64 v[52:53], v[80:81], 0, v[52:53]
	s_waitcnt vmcnt(0)
	v_lshlrev_b32_e32 v60, 16, v56
	v_and_b32_e32 v61, 0xffff0000, v56
	v_pk_mul_f32 v[60:61], v[42:43], v[60:61]
	s_nop 0
	v_cvt_pk_bf16_f32 v56, v60, v61
	v_lshlrev_b32_e32 v60, 16, v57
	v_and_b32_e32 v61, 0xffff0000, v57
	v_pk_mul_f32 v[60:61], v[44:45], v[60:61]
	s_nop 0
	v_cvt_pk_bf16_f32 v57, v60, v61
	v_lshlrev_b32_e32 v60, 16, v58
	v_and_b32_e32 v61, 0xffff0000, v58
	v_pk_mul_f32 v[60:61], v[38:39], v[60:61]
	s_nop 0
	v_cvt_pk_bf16_f32 v58, v60, v61
	v_lshlrev_b32_e32 v60, 16, v59
	v_and_b32_e32 v61, 0xffff0000, v59
	v_pk_mul_f32 v[60:61], v[40:41], v[60:61]
	s_nop 0
	v_cvt_pk_bf16_f32 v59, v60, v61
	s_nop 1
	v_mfma_f32_32x32x16_bf16 v[2:17], v[34:37], v[56:59], v[2:17]
	global_load_dwordx4 v[56:59], v[52:53], off
	s_waitcnt vmcnt(0)
	v_lshlrev_b32_e32 v52, 16, v56
	v_and_b32_e32 v53, 0xffff0000, v56
	v_mul_f32_e64 v42, v42, v52
	v_mul_f32_e64 v43, v43, v53
	v_lshlrev_b32_e32 v52, 16, v57
	v_and_b32_e32 v53, 0xffff0000, v57
	v_pk_mul_f32 v[44:45], v[44:45], v[52:53]
	v_cvt_pk_bf16_f32 v42, v42, v43
	v_cvt_pk_bf16_f32 v43, v44, v45
	v_lshlrev_b32_e32 v44, 16, v58
	v_and_b32_e32 v45, 0xffff0000, v58
	v_pk_mul_f32 v[38:39], v[38:39], v[44:45]
	s_nop 0
	v_cvt_pk_bf16_f32 v44, v38, v39
	v_lshlrev_b32_e32 v38, 16, v59
	v_and_b32_e32 v39, 0xffff0000, v59
	v_pk_mul_f32 v[38:39], v[40:41], v[38:39]
	s_nop 0
	v_cvt_pk_bf16_f32 v45, v38, v39
	s_nop 1
	v_mfma_f32_32x32x16_bf16 v[18:33], v[34:37], v[42:45], v[18:33]
	v_or_b32_e32 v34, 48, v54
	v_ashrrev_i32_e32 v34, 4, v34
	v_ashrrev_i32_e32 v35, 31, v34
	v_lshlrev_b64 v[52:53], 1, v[34:35]
	v_lshl_add_u64 v[34:35], v[52:53], 0, v[70:71]
	v_or_b32_e32 v52, v52, v68
	v_lshl_add_u64 v[56:57], v[52:53], 0, v[46:47]
	v_lshlrev_b64 v[34:35], 9, v[34:35]
	v_lshlrev_b64 v[56:57], 9, v[56:57]
	v_lshl_add_u64 v[34:35], v[78:79], 0, v[34:35]
	v_lshl_add_u64 v[56:57], v[80:81], 0, v[56:57]
	global_load_dwordx4 v[34:37], v[34:35], off
	s_nop 0
	global_load_dwordx4 v[38:41], v[50:51], off offset:208
	global_load_dwordx4 v[42:45], v[50:51], off offset:192
	v_lshl_add_u64 v[52:53], v[52:53], 0, v[48:49]
	global_load_dwordx4 v[56:59], v[56:57], off
	v_lshlrev_b64 v[52:53], 9, v[52:53]
	v_lshl_add_u64 v[52:53], v[80:81], 0, v[52:53]
	s_waitcnt vmcnt(0)
	v_lshlrev_b32_e32 v60, 16, v56
	v_and_b32_e32 v61, 0xffff0000, v56
	v_pk_mul_f32 v[60:61], v[42:43], v[60:61]
	s_nop 0
	v_cvt_pk_bf16_f32 v56, v60, v61
	v_lshlrev_b32_e32 v60, 16, v57
	v_and_b32_e32 v61, 0xffff0000, v57
	v_pk_mul_f32 v[60:61], v[44:45], v[60:61]
	s_nop 0
	v_cvt_pk_bf16_f32 v57, v60, v61
	v_lshlrev_b32_e32 v60, 16, v58
	v_and_b32_e32 v61, 0xffff0000, v58
	v_pk_mul_f32 v[60:61], v[38:39], v[60:61]
	s_nop 0
	v_cvt_pk_bf16_f32 v58, v60, v61
	v_lshlrev_b32_e32 v60, 16, v59
	v_and_b32_e32 v61, 0xffff0000, v59
	v_pk_mul_f32 v[60:61], v[40:41], v[60:61]
	s_nop 0
	v_cvt_pk_bf16_f32 v59, v60, v61
	s_nop 1
	v_mfma_f32_32x32x16_bf16 v[2:17], v[34:37], v[56:59], v[2:17]
	global_load_dwordx4 v[56:59], v[52:53], off
	s_waitcnt vmcnt(0)
	v_lshlrev_b32_e32 v52, 16, v56
	v_and_b32_e32 v53, 0xffff0000, v56
	v_mul_f32_e64 v42, v42, v52
	v_mul_f32_e64 v43, v43, v53
	v_lshlrev_b32_e32 v52, 16, v57
	v_and_b32_e32 v53, 0xffff0000, v57
	v_pk_mul_f32 v[44:45], v[44:45], v[52:53]
	v_cvt_pk_bf16_f32 v42, v42, v43
	v_cvt_pk_bf16_f32 v43, v44, v45
	v_lshlrev_b32_e32 v44, 16, v58
	v_and_b32_e32 v45, 0xffff0000, v58
	v_pk_mul_f32 v[38:39], v[38:39], v[44:45]
	s_nop 0
	v_cvt_pk_bf16_f32 v44, v38, v39
	v_lshlrev_b32_e32 v38, 16, v59
	v_and_b32_e32 v39, 0xffff0000, v59
	v_pk_mul_f32 v[38:39], v[40:41], v[38:39]
	s_nop 0
	v_cvt_pk_bf16_f32 v45, v38, v39
	s_nop 1
	v_mfma_f32_32x32x16_bf16 v[18:33], v[34:37], v[42:45], v[18:33]
	v_or_b32_e32 v34, 64, v54
	v_ashrrev_i32_e32 v34, 4, v34
	v_ashrrev_i32_e32 v35, 31, v34
	v_lshlrev_b64 v[52:53], 1, v[34:35]
	v_lshl_add_u64 v[34:35], v[52:53], 0, v[70:71]
	v_or_b32_e32 v52, v52, v68
	v_lshl_add_u64 v[56:57], v[52:53], 0, v[46:47]
	v_lshlrev_b64 v[34:35], 9, v[34:35]
	v_lshlrev_b64 v[56:57], 9, v[56:57]
	v_lshl_add_u64 v[34:35], v[78:79], 0, v[34:35]
	v_lshl_add_u64 v[56:57], v[80:81], 0, v[56:57]
	global_load_dwordx4 v[34:37], v[34:35], off
	s_nop 0
	global_load_dwordx4 v[38:41], v[50:51], off offset:272
	global_load_dwordx4 v[42:45], v[50:51], off offset:256
	v_lshl_add_u64 v[52:53], v[52:53], 0, v[48:49]
	global_load_dwordx4 v[56:59], v[56:57], off
	v_lshlrev_b64 v[52:53], 9, v[52:53]
	v_lshl_add_u64 v[52:53], v[80:81], 0, v[52:53]
	s_waitcnt vmcnt(0)
	v_lshlrev_b32_e32 v60, 16, v56
	v_and_b32_e32 v61, 0xffff0000, v56
	v_pk_mul_f32 v[60:61], v[42:43], v[60:61]
	s_nop 0
	v_cvt_pk_bf16_f32 v56, v60, v61
	v_lshlrev_b32_e32 v60, 16, v57
	v_and_b32_e32 v61, 0xffff0000, v57
	v_pk_mul_f32 v[60:61], v[44:45], v[60:61]
	s_nop 0
	v_cvt_pk_bf16_f32 v57, v60, v61
	v_lshlrev_b32_e32 v60, 16, v58
	v_and_b32_e32 v61, 0xffff0000, v58
	v_pk_mul_f32 v[60:61], v[38:39], v[60:61]
	s_nop 0
	v_cvt_pk_bf16_f32 v58, v60, v61
	v_lshlrev_b32_e32 v60, 16, v59
	v_and_b32_e32 v61, 0xffff0000, v59
	v_pk_mul_f32 v[60:61], v[40:41], v[60:61]
	s_nop 0
	v_cvt_pk_bf16_f32 v59, v60, v61
	s_nop 1
	v_mfma_f32_32x32x16_bf16 v[2:17], v[34:37], v[56:59], v[2:17]
	global_load_dwordx4 v[56:59], v[52:53], off
	s_waitcnt vmcnt(0)
	v_lshlrev_b32_e32 v52, 16, v56
	v_and_b32_e32 v53, 0xffff0000, v56
	v_mul_f32_e64 v42, v42, v52
	v_mul_f32_e64 v43, v43, v53
	v_lshlrev_b32_e32 v52, 16, v57
	v_and_b32_e32 v53, 0xffff0000, v57
	v_pk_mul_f32 v[44:45], v[44:45], v[52:53]
	v_cvt_pk_bf16_f32 v42, v42, v43
	v_cvt_pk_bf16_f32 v43, v44, v45
	v_lshlrev_b32_e32 v44, 16, v58
	v_and_b32_e32 v45, 0xffff0000, v58
	v_pk_mul_f32 v[38:39], v[38:39], v[44:45]
	s_nop 0
	v_cvt_pk_bf16_f32 v44, v38, v39
	v_lshlrev_b32_e32 v38, 16, v59
	v_and_b32_e32 v39, 0xffff0000, v59
	v_pk_mul_f32 v[38:39], v[40:41], v[38:39]
	s_nop 0
	v_cvt_pk_bf16_f32 v45, v38, v39
	s_nop 1
	v_mfma_f32_32x32x16_bf16 v[18:33], v[34:37], v[42:45], v[18:33]
	v_or_b32_e32 v34, 0x50, v54
	v_ashrrev_i32_e32 v34, 4, v34
	v_ashrrev_i32_e32 v35, 31, v34
	v_lshlrev_b64 v[52:53], 1, v[34:35]
	v_lshl_add_u64 v[34:35], v[52:53], 0, v[70:71]
	v_or_b32_e32 v52, v52, v68
	v_lshl_add_u64 v[56:57], v[52:53], 0, v[46:47]
	v_lshlrev_b64 v[34:35], 9, v[34:35]
	v_lshlrev_b64 v[56:57], 9, v[56:57]
	v_lshl_add_u64 v[34:35], v[78:79], 0, v[34:35]
	v_lshl_add_u64 v[56:57], v[80:81], 0, v[56:57]
	global_load_dwordx4 v[34:37], v[34:35], off
	s_nop 0
	global_load_dwordx4 v[38:41], v[50:51], off offset:336
	global_load_dwordx4 v[42:45], v[50:51], off offset:320
	v_lshl_add_u64 v[52:53], v[52:53], 0, v[48:49]
	global_load_dwordx4 v[56:59], v[56:57], off
	v_lshlrev_b64 v[52:53], 9, v[52:53]
	v_lshl_add_u64 v[52:53], v[80:81], 0, v[52:53]
	s_waitcnt vmcnt(0)
	v_lshlrev_b32_e32 v60, 16, v56
	v_and_b32_e32 v61, 0xffff0000, v56
	v_pk_mul_f32 v[60:61], v[42:43], v[60:61]
	s_nop 0
	v_cvt_pk_bf16_f32 v56, v60, v61
	v_lshlrev_b32_e32 v60, 16, v57
	v_and_b32_e32 v61, 0xffff0000, v57
	v_pk_mul_f32 v[60:61], v[44:45], v[60:61]
	s_nop 0
	v_cvt_pk_bf16_f32 v57, v60, v61
	v_lshlrev_b32_e32 v60, 16, v58
	v_and_b32_e32 v61, 0xffff0000, v58
	v_pk_mul_f32 v[60:61], v[38:39], v[60:61]
	s_nop 0
	v_cvt_pk_bf16_f32 v58, v60, v61
	v_lshlrev_b32_e32 v60, 16, v59
	v_and_b32_e32 v61, 0xffff0000, v59
	v_pk_mul_f32 v[60:61], v[40:41], v[60:61]
	s_nop 0
	v_cvt_pk_bf16_f32 v59, v60, v61
	s_nop 1
	v_mfma_f32_32x32x16_bf16 v[2:17], v[34:37], v[56:59], v[2:17]
	global_load_dwordx4 v[56:59], v[52:53], off
	s_waitcnt vmcnt(0)
	v_lshlrev_b32_e32 v52, 16, v56
	v_and_b32_e32 v53, 0xffff0000, v56
	v_mul_f32_e64 v42, v42, v52
	v_mul_f32_e64 v43, v43, v53
	v_lshlrev_b32_e32 v52, 16, v57
	v_and_b32_e32 v53, 0xffff0000, v57
	v_pk_mul_f32 v[44:45], v[44:45], v[52:53]
	v_cvt_pk_bf16_f32 v42, v42, v43
	v_cvt_pk_bf16_f32 v43, v44, v45
	v_lshlrev_b32_e32 v44, 16, v58
	v_and_b32_e32 v45, 0xffff0000, v58
	v_pk_mul_f32 v[38:39], v[38:39], v[44:45]
	s_nop 0
	v_cvt_pk_bf16_f32 v44, v38, v39
	v_lshlrev_b32_e32 v38, 16, v59
	v_and_b32_e32 v39, 0xffff0000, v59
	v_pk_mul_f32 v[38:39], v[40:41], v[38:39]
	s_nop 0
	v_cvt_pk_bf16_f32 v45, v38, v39
	s_nop 1
	v_mfma_f32_32x32x16_bf16 v[18:33], v[34:37], v[42:45], v[18:33]
	v_or_b32_e32 v34, 0x60, v54
	v_ashrrev_i32_e32 v34, 4, v34
	v_ashrrev_i32_e32 v35, 31, v34
	v_lshlrev_b64 v[52:53], 1, v[34:35]
	v_lshl_add_u64 v[34:35], v[52:53], 0, v[70:71]
	v_or_b32_e32 v52, v52, v68
	v_lshl_add_u64 v[56:57], v[52:53], 0, v[46:47]
	v_lshlrev_b64 v[34:35], 9, v[34:35]
	v_lshlrev_b64 v[56:57], 9, v[56:57]
	v_lshl_add_u64 v[34:35], v[78:79], 0, v[34:35]
	v_lshl_add_u64 v[56:57], v[80:81], 0, v[56:57]
	global_load_dwordx4 v[34:37], v[34:35], off
	s_nop 0
	global_load_dwordx4 v[38:41], v[50:51], off offset:400
	global_load_dwordx4 v[42:45], v[50:51], off offset:384
	v_lshl_add_u64 v[52:53], v[52:53], 0, v[48:49]
	global_load_dwordx4 v[56:59], v[56:57], off
	v_lshlrev_b64 v[52:53], 9, v[52:53]
	v_lshl_add_u64 v[52:53], v[80:81], 0, v[52:53]
	s_waitcnt vmcnt(0)
	v_lshlrev_b32_e32 v60, 16, v56
	v_and_b32_e32 v61, 0xffff0000, v56
	v_pk_mul_f32 v[60:61], v[42:43], v[60:61]
	s_nop 0
	v_cvt_pk_bf16_f32 v56, v60, v61
	v_lshlrev_b32_e32 v60, 16, v57
	v_and_b32_e32 v61, 0xffff0000, v57
	v_pk_mul_f32 v[60:61], v[44:45], v[60:61]
	s_nop 0
	v_cvt_pk_bf16_f32 v57, v60, v61
	v_lshlrev_b32_e32 v60, 16, v58
	v_and_b32_e32 v61, 0xffff0000, v58
	v_pk_mul_f32 v[60:61], v[38:39], v[60:61]
	s_nop 0
	v_cvt_pk_bf16_f32 v58, v60, v61
	v_lshlrev_b32_e32 v60, 16, v59
	v_and_b32_e32 v61, 0xffff0000, v59
	v_pk_mul_f32 v[60:61], v[40:41], v[60:61]
	s_nop 0
	v_cvt_pk_bf16_f32 v59, v60, v61
	s_nop 1
	v_mfma_f32_32x32x16_bf16 v[2:17], v[34:37], v[56:59], v[2:17]
	global_load_dwordx4 v[56:59], v[52:53], off
	s_waitcnt vmcnt(0)
	v_lshlrev_b32_e32 v52, 16, v56
	v_and_b32_e32 v53, 0xffff0000, v56
	v_mul_f32_e64 v42, v42, v52
	v_mul_f32_e64 v43, v43, v53
	v_lshlrev_b32_e32 v52, 16, v57
	v_and_b32_e32 v53, 0xffff0000, v57
	v_pk_mul_f32 v[44:45], v[44:45], v[52:53]
	v_cvt_pk_bf16_f32 v42, v42, v43
	v_cvt_pk_bf16_f32 v43, v44, v45
	v_lshlrev_b32_e32 v44, 16, v58
	v_and_b32_e32 v45, 0xffff0000, v58
	v_pk_mul_f32 v[38:39], v[38:39], v[44:45]
	s_nop 0
	v_cvt_pk_bf16_f32 v44, v38, v39
	v_lshlrev_b32_e32 v38, 16, v59
	v_and_b32_e32 v39, 0xffff0000, v59
	v_pk_mul_f32 v[38:39], v[40:41], v[38:39]
	s_nop 0
	v_cvt_pk_bf16_f32 v45, v38, v39
	s_nop 1
	v_mfma_f32_32x32x16_bf16 v[18:33], v[34:37], v[42:45], v[18:33]
	v_or_b32_e32 v34, 0x70, v54
	v_ashrrev_i32_e32 v34, 4, v34
	v_ashrrev_i32_e32 v35, 31, v34
	v_lshlrev_b64 v[54:55], 1, v[34:35]
	v_lshl_add_u64 v[34:35], v[54:55], 0, v[70:71]
	v_or_b32_e32 v54, v54, v68
	v_lshl_add_u64 v[46:47], v[54:55], 0, v[46:47]
	v_lshlrev_b64 v[34:35], 9, v[34:35]
	v_lshlrev_b64 v[46:47], 9, v[46:47]
	v_lshl_add_u64 v[34:35], v[78:79], 0, v[34:35]
	v_lshl_add_u64 v[46:47], v[80:81], 0, v[46:47]
	global_load_dwordx4 v[34:37], v[34:35], off
	s_nop 0
	global_load_dwordx4 v[38:41], v[50:51], off offset:464
	global_load_dwordx4 v[42:45], v[50:51], off offset:448
	s_nop 0
	global_load_dwordx4 v[50:53], v[46:47], off
	s_waitcnt vmcnt(0)
	v_lshlrev_b32_e32 v46, 16, v50
	v_and_b32_e32 v47, 0xffff0000, v50
	v_pk_mul_f32 v[46:47], v[42:43], v[46:47]
	s_nop 0
	v_cvt_pk_bf16_f32 v50, v46, v47
	v_lshlrev_b32_e32 v46, 16, v51
	v_and_b32_e32 v47, 0xffff0000, v51
	v_pk_mul_f32 v[46:47], v[44:45], v[46:47]
	s_nop 0
	v_cvt_pk_bf16_f32 v51, v46, v47
	v_lshlrev_b32_e32 v46, 16, v52
	v_and_b32_e32 v47, 0xffff0000, v52
	v_pk_mul_f32 v[46:47], v[38:39], v[46:47]
	s_nop 0
	v_cvt_pk_bf16_f32 v52, v46, v47
	v_lshlrev_b32_e32 v46, 16, v53
	v_and_b32_e32 v47, 0xffff0000, v53
	v_pk_mul_f32 v[46:47], v[40:41], v[46:47]
	s_nop 0
	v_cvt_pk_bf16_f32 v53, v46, v47
	v_lshl_add_u64 v[46:47], v[54:55], 0, v[48:49]
	v_lshlrev_b64 v[46:47], 9, v[46:47]
	v_lshl_add_u64 v[46:47], v[80:81], 0, v[46:47]
	global_load_dwordx4 v[46:49], v[46:47], off
	v_mfma_f32_32x32x16_bf16 v[2:17], v[34:37], v[50:53], v[2:17]
	s_waitcnt vmcnt(0)
	v_lshlrev_b32_e32 v50, 16, v46
	v_and_b32_e32 v51, 0xffff0000, v46
	v_lshlrev_b32_e32 v46, 16, v47
	v_and_b32_e32 v47, 0xffff0000, v47
	v_pk_mul_f32 v[42:43], v[42:43], v[50:51]
	v_pk_mul_f32 v[44:45], v[44:45], v[46:47]
	v_cvt_pk_bf16_f32 v42, v42, v43
	v_cvt_pk_bf16_f32 v43, v44, v45
	v_lshlrev_b32_e32 v44, 16, v48
	v_and_b32_e32 v45, 0xffff0000, v48
	v_pk_mul_f32 v[38:39], v[38:39], v[44:45]
	v_cvt_pk_bf16_f32 v2, v2, v3
	v_cvt_pk_bf16_f32 v44, v38, v39
	v_lshlrev_b32_e32 v38, 16, v49
	v_and_b32_e32 v39, 0xffff0000, v49
	v_pk_mul_f32 v[38:39], v[40:41], v[38:39]
	v_cvt_pk_bf16_f32 v3, v4, v5
	v_cvt_pk_bf16_f32 v45, v38, v39
	s_nop 1
	v_mfma_f32_32x32x16_bf16 v[18:33], v[34:37], v[42:45], v[18:33]
	v_lshlrev_b64 v[34:35], 14, v[66:67]
	v_lshl_add_u64 v[4:5], v[82:83], 0, v[34:35]
	global_store_dwordx2 v[4:5], v[2:3], off
	v_cvt_pk_bf16_f32 v2, v6, v7
	v_cvt_pk_bf16_f32 v3, v8, v9
	global_store_dwordx2 v[4:5], v[2:3], off offset:512
	v_cvt_pk_bf16_f32 v2, v10, v11
	v_cvt_pk_bf16_f32 v3, v12, v13
	global_store_dwordx2 v[4:5], v[2:3], off offset:1024
	v_cvt_pk_bf16_f32 v2, v14, v15
	v_cvt_pk_bf16_f32 v3, v16, v17
	global_store_dwordx2 v[4:5], v[2:3], off offset:1536
	v_add_co_u32_e32 v4, vcc, s10, v4
	v_cvt_pk_bf16_f32 v2, v18, v19
	v_cvt_pk_bf16_f32 v3, v20, v21
	v_addc_co_u32_e32 v5, vcc, 0, v5, vcc
	global_store_dwordx2 v[4:5], v[2:3], off
	v_cvt_pk_bf16_f32 v2, v22, v23
	v_cvt_pk_bf16_f32 v3, v24, v25
	global_store_dwordx2 v[4:5], v[2:3], off offset:512
	v_cvt_pk_bf16_f32 v2, v26, v27
	v_cvt_pk_bf16_f32 v3, v28, v29
	global_store_dwordx2 v[4:5], v[2:3], off offset:1024
	v_cvt_pk_bf16_f32 v2, v30, v31
	v_cvt_pk_bf16_f32 v3, v32, v33
	global_store_dwordx2 v[4:5], v[2:3], off offset:1536
	s_branch .LBB0_779

.LBB0_1106:
	v_mbcnt_lo_u32_b32 v148, -1, 0
	v_mbcnt_hi_u32_b32 v148, -1, v148
	v_xor_b32_e32 v149, 32, v148
	v_lshlrev_b32_e32 v149, 2, v149
	v_mov_b32_e32 v150, 0x3727c5ac
	v_lshlrev_b32_e32 v151, 3, v148
	global_load_dwordx4 v[64:67], v[12:13], off
	global_load_dwordx4 v[68:71], v[12:13], off offset:1024
	global_load_dwordx4 v[72:75], v[12:13], off offset:2048
	global_load_dwordx4 v[76:79], v[12:13], off offset:3072
	global_load_dwordx4 v[80:83], v[14:15], off
	global_load_dwordx4 v[84:87], v[14:15], off offset:1024
	global_load_dwordx4 v[88:91], v[14:15], off offset:2048
	global_load_dwordx4 v[92:95], v[14:15], off offset:3072
	v_ashrrev_i32_e32 v159, 31, v16
	v_mov_b32_e32 v158, v16
	v_lshlrev_b64 v[158:159], 12, v[158:159]
	v_lshl_add_u64 v[152:153], v[10:11], 0, v[158:159]
	global_load_dwordx4 v[96:99], v[152:153], off
	global_load_dwordx4 v[100:103], v[152:153], off offset:1024
	global_load_dwordx4 v[104:107], v[152:153], off offset:2048
	global_load_dwordx4 v[108:111], v[152:153], off offset:3072
	s_add_i32 s99, s3, s96
	s_cmpk_lt_i32 s99, 0x800
	s_cselect_b32 s99, s2, 0
	v_add_u32_e32 v156, s99, v16
	v_ashrrev_i32_e32 v159, 31, v156
	v_mov_b32_e32 v158, v156
	v_lshlrev_b64 v[158:159], 12, v[158:159]
	v_lshl_add_u64 v[154:155], v[10:11], 0, v[158:159]
	global_load_dwordx4 v[112:115], v[154:155], off
	global_load_dwordx4 v[116:119], v[154:155], off offset:1024
	global_load_dwordx4 v[120:123], v[154:155], off offset:2048
	global_load_dwordx4 v[124:127], v[154:155], off offset:3072
	s_waitcnt vmcnt(4)
	s_branch .Lln_p7_procA
.Lln_p7_loopA:
	s_add_i32 s99, s3, s96
	s_cmpk_lt_i32 s99, 0x800
	s_cselect_b32 s99, s2, 0
	v_add_u32_e32 v156, s99, v16
	v_ashrrev_i32_e32 v159, 31, v156
	v_mov_b32_e32 v158, v156
	v_lshlrev_b64 v[158:159], 12, v[158:159]
	v_lshl_add_u64 v[154:155], v[10:11], 0, v[158:159]
	global_load_dwordx4 v[112:115], v[154:155], off
	global_load_dwordx4 v[116:119], v[154:155], off offset:1024
	global_load_dwordx4 v[120:123], v[154:155], off offset:2048
	global_load_dwordx4 v[124:127], v[154:155], off offset:3072
	s_waitcnt vmcnt(9)
.Lln_p7_procA:
	v_add_f32_e32 v128, v96, v97
	v_add_f32_e32 v129, v100, v101
	v_add_f32_e32 v130, v104, v105
	v_add_f32_e32 v131, v108, v109
	v_add_f32_e32 v128, v98, v128
	v_add_f32_e32 v129, v102, v129
	v_add_f32_e32 v130, v106, v130
	v_add_f32_e32 v131, v110, v131
	v_add_f32_e32 v128, v99, v128
	v_add_f32_e32 v129, v103, v129
	v_add_f32_e32 v130, v107, v130
	v_add_f32_e32 v131, v111, v131
	v_add_f32_e32 v132, v128, v129
	v_add_f32_e32 v132, v132, v130
	v_add_f32_e32 v132, v132, v131
	s_nop 1
	v_add_f32_dpp v132, v132, v132 quad_perm:[1,0,3,2] row_mask:0xf bank_mask:0xf
	s_nop 1
	v_add_f32_dpp v132, v132, v132 quad_perm:[2,3,0,1] row_mask:0xf bank_mask:0xf
	s_nop 1
	v_add_f32_dpp v132, v132, v132 row_half_mirror row_mask:0xf bank_mask:0xf
	s_nop 1
	v_add_f32_dpp v132, v132, v132 row_mirror row_mask:0xf bank_mask:0xf
	ds_swizzle_b32 v147, v132 offset:0x401f
	s_waitcnt lgkmcnt(0)
	v_add_f32_e32 v132, v132, v147
	ds_bpermute_b32 v147, v149, v132
	s_waitcnt lgkmcnt(0)
	v_add_f32_e32 v132, v132, v147
	v_mul_f32_e32 v133, 0x3a800000, v132
	v_sub_f32_e32 v96, v96, v133
	v_sub_f32_e32 v97, v97, v133
	v_sub_f32_e32 v98, v98, v133
	v_sub_f32_e32 v99, v99, v133
	v_sub_f32_e32 v100, v100, v133
	v_sub_f32_e32 v101, v101, v133
	v_sub_f32_e32 v102, v102, v133
	v_sub_f32_e32 v103, v103, v133
	v_sub_f32_e32 v104, v104, v133
	v_sub_f32_e32 v105, v105, v133
	v_sub_f32_e32 v106, v106, v133
	v_sub_f32_e32 v107, v107, v133
	v_sub_f32_e32 v108, v108, v133
	v_sub_f32_e32 v109, v109, v133
	v_sub_f32_e32 v110, v110, v133
	v_sub_f32_e32 v111, v111, v133
	v_mul_f32_e32 v134, v96, v96
	v_mul_f32_e32 v135, v97, v97
	v_add_f32_e32 v134, v134, v135
	v_mul_f32_e32 v135, v98, v98
	v_add_f32_e32 v134, v135, v134
	v_mul_f32_e32 v135, v99, v99
	v_add_f32_e32 v134, v135, v134
	v_mul_f32_e32 v135, v100, v100
	v_add_f32_e32 v134, v135, v134
	v_mul_f32_e32 v135, v101, v101
	v_add_f32_e32 v134, v135, v134
	v_mul_f32_e32 v135, v102, v102
	v_add_f32_e32 v134, v135, v134
	v_mul_f32_e32 v135, v103, v103
	v_add_f32_e32 v134, v135, v134
	v_mul_f32_e32 v135, v104, v104
	v_add_f32_e32 v134, v135, v134
	v_mul_f32_e32 v135, v105, v105
	v_add_f32_e32 v134, v135, v134
	v_mul_f32_e32 v135, v106, v106
	v_add_f32_e32 v134, v135, v134
	v_mul_f32_e32 v135, v107, v107
	v_add_f32_e32 v134, v135, v134
	v_mul_f32_e32 v135, v108, v108
	v_add_f32_e32 v134, v135, v134
	v_mul_f32_e32 v135, v109, v109
	v_add_f32_e32 v134, v135, v134
	v_mul_f32_e32 v135, v110, v110
	v_add_f32_e32 v134, v135, v134
	v_mul_f32_e32 v135, v111, v111
	v_add_f32_e32 v134, v135, v134
	s_nop 1
	v_add_f32_dpp v134, v134, v134 quad_perm:[1,0,3,2] row_mask:0xf bank_mask:0xf
	s_nop 1
	v_add_f32_dpp v134, v134, v134 quad_perm:[2,3,0,1] row_mask:0xf bank_mask:0xf
	s_nop 1
	v_add_f32_dpp v134, v134, v134 row_half_mirror row_mask:0xf bank_mask:0xf
	s_nop 1
	v_add_f32_dpp v134, v134, v134 row_mirror row_mask:0xf bank_mask:0xf
	ds_swizzle_b32 v147, v134 offset:0x401f
	s_waitcnt lgkmcnt(0)
	v_add_f32_e32 v134, v134, v147
	ds_bpermute_b32 v147, v149, v134
	s_waitcnt lgkmcnt(0)
	v_add_f32_e32 v134, v134, v147
	v_fmamk_f32 v134, v134, 0x3a800000, v150
	v_rsq_f32_e32 v134, v134
	s_nop 0
	v_mul_f32_e32 v96, v96, v134
	v_mul_f32_e32 v97, v97, v134
	v_mul_f32_e32 v98, v98, v134
	v_mul_f32_e32 v99, v99, v134
	v_mul_f32_e32 v100, v100, v134
	v_mul_f32_e32 v101, v101, v134
	v_mul_f32_e32 v102, v102, v134
	v_mul_f32_e32 v103, v103, v134
	v_mul_f32_e32 v104, v104, v134
	v_mul_f32_e32 v105, v105, v134
	v_mul_f32_e32 v106, v106, v134
	v_mul_f32_e32 v107, v107, v134
	v_mul_f32_e32 v108, v108, v134
	v_mul_f32_e32 v109, v109, v134
	v_mul_f32_e32 v110, v110, v134
	v_mul_f32_e32 v111, v111, v134
	v_fma_f32 v96, v64, v96, v80
	v_fma_f32 v97, v65, v97, v81
	v_fma_f32 v98, v66, v98, v82
	v_fma_f32 v99, v67, v99, v83
	v_fma_f32 v100, v68, v100, v84
	v_fma_f32 v101, v69, v101, v85
	v_fma_f32 v102, v70, v102, v86
	v_fma_f32 v103, v71, v103, v87
	v_fma_f32 v104, v72, v104, v88
	v_fma_f32 v105, v73, v105, v89
	v_fma_f32 v106, v74, v106, v90
	v_fma_f32 v107, v75, v107, v91
	v_fma_f32 v108, v76, v108, v92
	v_fma_f32 v109, v77, v109, v93
	v_fma_f32 v110, v78, v110, v94
	v_fma_f32 v111, v79, v111, v95
	v_lshlrev_b32_e32 v162, 3, v16
	v_add_u32_e32 v162, 0xf000000, v162
	v_mov_b32_e32 v164, v133
	v_mov_b32_e32 v165, v134
	s_mov_b64 exec, 1
	global_store_dwordx2 v162, v[164:165], s[62:63]
	s_mov_b64 exec, -1
	v_ashrrev_i32_e32 v159, 31, v16
	v_mov_b32_e32 v158, v16
	v_lshlrev_b64 v[158:159], 11, v[158:159]
	v_lshl_add_u64 v[160:161], s[60:61], 0, v[158:159]
	v_mov_b32_e32 v158, v151
	v_mov_b32_e32 v159, 0
	v_lshl_add_u64 v[160:161], v[160:161], 0, v[158:159]
	v_cvt_pk_bf16_f32 v136, v96, v97
	v_cvt_pk_bf16_f32 v137, v98, v99
	v_cvt_pk_bf16_f32 v138, v100, v101
	v_cvt_pk_bf16_f32 v139, v102, v103
	v_cvt_pk_bf16_f32 v140, v104, v105
	v_cvt_pk_bf16_f32 v141, v106, v107
	v_cvt_pk_bf16_f32 v142, v108, v109
	v_cvt_pk_bf16_f32 v143, v110, v111
	global_store_dwordx2 v[160:161], v[136:137], off
	global_store_dwordx2 v[160:161], v[138:139], off offset:512
	global_store_dwordx2 v[160:161], v[140:141], off offset:1024
	global_store_dwordx2 v[160:161], v[142:143], off offset:1536
	v_mov_b32_e32 v16, v156
	v_mov_b32_e32 v152, v154
	v_mov_b32_e32 v153, v155
	s_add_i32 s3, s3, s96
	s_cmpk_lt_i32 s3, 0x800
	s_cbranch_scc0 .LBB0_1114
	s_add_i32 s99, s3, s96
	s_cmpk_lt_i32 s99, 0x800
	s_cselect_b32 s99, s2, 0
	v_add_u32_e32 v156, s99, v16
	v_ashrrev_i32_e32 v159, 31, v156
	v_mov_b32_e32 v158, v156
	v_lshlrev_b64 v[158:159], 12, v[158:159]
	v_lshl_add_u64 v[154:155], v[10:11], 0, v[158:159]
	global_load_dwordx4 v[96:99], v[154:155], off
	global_load_dwordx4 v[100:103], v[154:155], off offset:1024
	global_load_dwordx4 v[104:107], v[154:155], off offset:2048
	global_load_dwordx4 v[108:111], v[154:155], off offset:3072
	s_waitcnt vmcnt(9)
	v_add_f32_e32 v128, v112, v113
	v_add_f32_e32 v129, v116, v117
	v_add_f32_e32 v130, v120, v121
	v_add_f32_e32 v131, v124, v125
	v_add_f32_e32 v128, v114, v128
	v_add_f32_e32 v129, v118, v129
	v_add_f32_e32 v130, v122, v130
	v_add_f32_e32 v131, v126, v131
	v_add_f32_e32 v128, v115, v128
	v_add_f32_e32 v129, v119, v129
	v_add_f32_e32 v130, v123, v130
	v_add_f32_e32 v131, v127, v131
	v_add_f32_e32 v132, v128, v129
	v_add_f32_e32 v132, v132, v130
	v_add_f32_e32 v132, v132, v131
	s_nop 1
	v_add_f32_dpp v132, v132, v132 quad_perm:[1,0,3,2] row_mask:0xf bank_mask:0xf
	s_nop 1
	v_add_f32_dpp v132, v132, v132 quad_perm:[2,3,0,1] row_mask:0xf bank_mask:0xf
	s_nop 1
	v_add_f32_dpp v132, v132, v132 row_half_mirror row_mask:0xf bank_mask:0xf
	s_nop 1
	v_add_f32_dpp v132, v132, v132 row_mirror row_mask:0xf bank_mask:0xf
	ds_swizzle_b32 v147, v132 offset:0x401f
	s_waitcnt lgkmcnt(0)
	v_add_f32_e32 v132, v132, v147
	ds_bpermute_b32 v147, v149, v132
	s_waitcnt lgkmcnt(0)
	v_add_f32_e32 v132, v132, v147
	v_mul_f32_e32 v133, 0x3a800000, v132
	v_sub_f32_e32 v112, v112, v133
	v_sub_f32_e32 v113, v113, v133
	v_sub_f32_e32 v114, v114, v133
	v_sub_f32_e32 v115, v115, v133
	v_sub_f32_e32 v116, v116, v133
	v_sub_f32_e32 v117, v117, v133
	v_sub_f32_e32 v118, v118, v133
	v_sub_f32_e32 v119, v119, v133
	v_sub_f32_e32 v120, v120, v133
	v_sub_f32_e32 v121, v121, v133
	v_sub_f32_e32 v122, v122, v133
	v_sub_f32_e32 v123, v123, v133
	v_sub_f32_e32 v124, v124, v133
	v_sub_f32_e32 v125, v125, v133
	v_sub_f32_e32 v126, v126, v133
	v_sub_f32_e32 v127, v127, v133
	v_mul_f32_e32 v134, v112, v112
	v_mul_f32_e32 v135, v113, v113
	v_add_f32_e32 v134, v134, v135
	v_mul_f32_e32 v135, v114, v114
	v_add_f32_e32 v134, v135, v134
	v_mul_f32_e32 v135, v115, v115
	v_add_f32_e32 v134, v135, v134
	v_mul_f32_e32 v135, v116, v116
	v_add_f32_e32 v134, v135, v134
	v_mul_f32_e32 v135, v117, v117
	v_add_f32_e32 v134, v135, v134
	v_mul_f32_e32 v135, v118, v118
	v_add_f32_e32 v134, v135, v134
	v_mul_f32_e32 v135, v119, v119
	v_add_f32_e32 v134, v135, v134
	v_mul_f32_e32 v135, v120, v120
	v_add_f32_e32 v134, v135, v134
	v_mul_f32_e32 v135, v121, v121
	v_add_f32_e32 v134, v135, v134
	v_mul_f32_e32 v135, v122, v122
	v_add_f32_e32 v134, v135, v134
	v_mul_f32_e32 v135, v123, v123
	v_add_f32_e32 v134, v135, v134
	v_mul_f32_e32 v135, v124, v124
	v_add_f32_e32 v134, v135, v134
	v_mul_f32_e32 v135, v125, v125
	v_add_f32_e32 v134, v135, v134
	v_mul_f32_e32 v135, v126, v126
	v_add_f32_e32 v134, v135, v134
	v_mul_f32_e32 v135, v127, v127
	v_add_f32_e32 v134, v135, v134
	s_nop 1
	v_add_f32_dpp v134, v134, v134 quad_perm:[1,0,3,2] row_mask:0xf bank_mask:0xf
	s_nop 1
	v_add_f32_dpp v134, v134, v134 quad_perm:[2,3,0,1] row_mask:0xf bank_mask:0xf
	s_nop 1
	v_add_f32_dpp v134, v134, v134 row_half_mirror row_mask:0xf bank_mask:0xf
	s_nop 1
	v_add_f32_dpp v134, v134, v134 row_mirror row_mask:0xf bank_mask:0xf
	ds_swizzle_b32 v147, v134 offset:0x401f
	s_waitcnt lgkmcnt(0)
	v_add_f32_e32 v134, v134, v147
	ds_bpermute_b32 v147, v149, v134
	s_waitcnt lgkmcnt(0)
	v_add_f32_e32 v134, v134, v147
	v_fmamk_f32 v134, v134, 0x3a800000, v150
	v_rsq_f32_e32 v134, v134
	s_nop 0
	v_mul_f32_e32 v112, v112, v134
	v_mul_f32_e32 v113, v113, v134
	v_mul_f32_e32 v114, v114, v134
	v_mul_f32_e32 v115, v115, v134
	v_mul_f32_e32 v116, v116, v134
	v_mul_f32_e32 v117, v117, v134
	v_mul_f32_e32 v118, v118, v134
	v_mul_f32_e32 v119, v119, v134
	v_mul_f32_e32 v120, v120, v134
	v_mul_f32_e32 v121, v121, v134
	v_mul_f32_e32 v122, v122, v134
	v_mul_f32_e32 v123, v123, v134
	v_mul_f32_e32 v124, v124, v134
	v_mul_f32_e32 v125, v125, v134
	v_mul_f32_e32 v126, v126, v134
	v_mul_f32_e32 v127, v127, v134
	v_fma_f32 v112, v64, v112, v80
	v_fma_f32 v113, v65, v113, v81
	v_fma_f32 v114, v66, v114, v82
	v_fma_f32 v115, v67, v115, v83
	v_fma_f32 v116, v68, v116, v84
	v_fma_f32 v117, v69, v117, v85
	v_fma_f32 v118, v70, v118, v86
	v_fma_f32 v119, v71, v119, v87
	v_fma_f32 v120, v72, v120, v88
	v_fma_f32 v121, v73, v121, v89
	v_fma_f32 v122, v74, v122, v90
	v_fma_f32 v123, v75, v123, v91
	v_fma_f32 v124, v76, v124, v92
	v_fma_f32 v125, v77, v125, v93
	v_fma_f32 v126, v78, v126, v94
	v_fma_f32 v127, v79, v127, v95
	v_lshlrev_b32_e32 v162, 3, v16
	v_add_u32_e32 v162, 0xf000000, v162
	v_mov_b32_e32 v164, v133
	v_mov_b32_e32 v165, v134
	s_mov_b64 exec, 1
	global_store_dwordx2 v162, v[164:165], s[62:63]
	s_mov_b64 exec, -1
	v_ashrrev_i32_e32 v159, 31, v16
	v_mov_b32_e32 v158, v16
	v_lshlrev_b64 v[158:159], 11, v[158:159]
	v_lshl_add_u64 v[160:161], s[60:61], 0, v[158:159]
	v_mov_b32_e32 v158, v151
	v_mov_b32_e32 v159, 0
	v_lshl_add_u64 v[160:161], v[160:161], 0, v[158:159]
	v_cvt_pk_bf16_f32 v136, v112, v113
	v_cvt_pk_bf16_f32 v137, v114, v115
	v_cvt_pk_bf16_f32 v138, v116, v117
	v_cvt_pk_bf16_f32 v139, v118, v119
	v_cvt_pk_bf16_f32 v140, v120, v121
	v_cvt_pk_bf16_f32 v141, v122, v123
	v_cvt_pk_bf16_f32 v142, v124, v125
	v_cvt_pk_bf16_f32 v143, v126, v127
	global_store_dwordx2 v[160:161], v[136:137], off
	global_store_dwordx2 v[160:161], v[138:139], off offset:512
	global_store_dwordx2 v[160:161], v[140:141], off offset:1024
	global_store_dwordx2 v[160:161], v[142:143], off offset:1536
	v_mov_b32_e32 v16, v156
	v_mov_b32_e32 v152, v154
	v_mov_b32_e32 v153, v155
	s_add_i32 s3, s3, s96
	s_cmpk_lt_i32 s3, 0x800
	s_cbranch_scc0 .LBB0_1114
	s_branch .Lln_p7_loopA

.LBB0_1175:
	v_add_u32_e32 v169, s35, v161
	ds_read_b128 v[172:175], v169 offset:32768
	ds_read_b128 v[176:179], v169 offset:33792
	ds_read_b128 v[180:183], v169 offset:34816
	ds_read_b128 v[184:187], v169 offset:35840
	v_add_u32_e32 v170, s70, v142
	v_lshl_add_u64 v[224:225], v[138:139], 0, s[0:1]
	v_readfirstlane_b32 s75, v170
	v_add_u32_e32 v171, 0x2000, v170
	v_add_u32_e32 v165, s37, v161
	v_add_u32_e32 v166, s43, v162
	v_add_u32_e32 v167, s46, v162
	v_add_u32_e32 v168, s47, v162
	v_lshl_add_u64 v[220:221], v[224:225], 0, s[8:9]
	s_mov_b32 m0, s75
	v_lshl_add_u64 v[246:247], v[140:141], 0, s[0:1]
	v_readfirstlane_b32 s75, v171
	ds_read_b128 v[188:191], v165
	ds_read_b128 v[192:195], v165 offset:1024
	ds_read_b128 v[196:199], v166
	ds_read_b128 v[200:203], v166 offset:1024
	ds_read_b128 v[204:207], v167
	ds_read_b128 v[208:211], v167 offset:1024
	ds_read_b128 v[212:215], v168
	ds_read_b128 v[216:219], v168 offset:1024
	global_load_lds_dwordx4 v[220:221], off
	v_lshl_add_u64 v[220:221], v[246:247], 0, s[8:9]
	s_mov_b32 m0, s75
	s_nop 0
	global_load_lds_dwordx4 v[220:221], off
	s_waitcnt lgkmcnt(8)
	s_barrier
	s_waitcnt lgkmcnt(0)
	s_setprio 1
	s_waitcnt lgkmcnt(0)
	v_mfma_f32_16x16x32_bf16 v[126:129], v[172:175], v[188:191], v[126:129]
	v_mfma_f32_16x16x32_bf16 v[122:125], v[180:183], v[188:191], v[122:125]
	v_mfma_f32_16x16x32_bf16 v[118:121], v[172:175], v[196:199], v[118:121]
	v_mfma_f32_16x16x32_bf16 v[114:117], v[180:183], v[196:199], v[114:117]
	v_mfma_f32_16x16x32_bf16 v[110:113], v[172:175], v[204:207], v[110:113]
	v_mfma_f32_16x16x32_bf16 v[106:109], v[180:183], v[204:207], v[106:109]
	v_mfma_f32_16x16x32_bf16 v[102:105], v[172:175], v[212:215], v[102:105]
	v_mfma_f32_16x16x32_bf16 v[98:101], v[180:183], v[212:215], v[98:101]
	v_mfma_f32_16x16x32_bf16 v[126:129], v[176:179], v[192:195], v[126:129]
	v_mfma_f32_16x16x32_bf16 v[122:125], v[184:187], v[192:195], v[122:125]
	v_mfma_f32_16x16x32_bf16 v[118:121], v[176:179], v[200:203], v[118:121]
	v_mfma_f32_16x16x32_bf16 v[114:117], v[184:187], v[200:203], v[114:117]
	v_mfma_f32_16x16x32_bf16 v[110:113], v[176:179], v[208:211], v[110:113]
	v_mfma_f32_16x16x32_bf16 v[106:109], v[184:187], v[208:211], v[106:109]
	v_mfma_f32_16x16x32_bf16 v[102:105], v[176:179], v[216:219], v[102:105]
	v_mfma_f32_16x16x32_bf16 v[98:101], v[184:187], v[216:219], v[98:101]
	s_setprio 0
	s_barrier
	v_lshl_add_u64 v[248:249], v[134:135], 0, s[0:1]
	v_readfirstlane_b32 s75, v144
	v_lshl_add_u64 v[238:239], v[248:249], 0, s[10:11]
	s_mov_b32 m0, s75
	v_lshl_add_u64 v[250:251], v[136:137], 0, s[0:1]
	v_readfirstlane_b32 s75, v145
	ds_read_b128 v[220:223], v169 offset:49152
	ds_read_b128 v[226:229], v169 offset:50176
	ds_read_b128 v[230:233], v169 offset:51200
	ds_read_b128 v[234:237], v169 offset:52224
	global_load_lds_dwordx4 v[238:239], off
	v_lshl_add_u64 v[238:239], v[250:251], 0, s[10:11]
	s_mov_b32 m0, s75
	s_nop 0
	global_load_lds_dwordx4 v[238:239], off
	s_barrier
	s_waitcnt lgkmcnt(0)
	s_setprio 1
	s_waitcnt lgkmcnt(0)
	v_mfma_f32_16x16x32_bf16 v[94:97], v[220:223], v[188:191], v[94:97]
	v_mfma_f32_16x16x32_bf16 v[90:93], v[230:233], v[188:191], v[90:93]
	v_mfma_f32_16x16x32_bf16 v[82:85], v[220:223], v[196:199], v[82:85]
	v_mfma_f32_16x16x32_bf16 v[66:69], v[230:233], v[196:199], v[66:69]
	v_mfma_f32_16x16x32_bf16 v[62:65], v[220:223], v[204:207], v[62:65]
	v_mfma_f32_16x16x32_bf16 v[58:61], v[230:233], v[204:207], v[58:61]
	v_mfma_f32_16x16x32_bf16 v[54:57], v[220:223], v[212:215], v[54:57]
	v_mfma_f32_16x16x32_bf16 v[50:53], v[230:233], v[212:215], v[50:53]
	v_mfma_f32_16x16x32_bf16 v[94:97], v[226:229], v[192:195], v[94:97]
	v_mfma_f32_16x16x32_bf16 v[90:93], v[234:237], v[192:195], v[90:93]
	v_mfma_f32_16x16x32_bf16 v[82:85], v[226:229], v[200:203], v[82:85]
	v_mfma_f32_16x16x32_bf16 v[66:69], v[234:237], v[200:203], v[66:69]
	v_mfma_f32_16x16x32_bf16 v[62:65], v[226:229], v[208:211], v[62:65]
	v_mfma_f32_16x16x32_bf16 v[58:61], v[234:237], v[208:211], v[58:61]
	v_mfma_f32_16x16x32_bf16 v[54:57], v[226:229], v[216:219], v[54:57]
	v_mfma_f32_16x16x32_bf16 v[50:53], v[234:237], v[216:219], v[50:53]
	s_setprio 0
	v_readfirstlane_b32 s75, v143
	v_lshl_add_u64 v[238:239], v[224:225], 0, s[12:13]
	s_mov_b32 m0, s75
	v_readfirstlane_b32 s75, v146
	s_barrier
	ds_read_b128 v[188:191], v165 offset:16384
	ds_read_b128 v[192:195], v165 offset:17408
	ds_read_b128 v[196:199], v166 offset:16384
	ds_read_b128 v[200:203], v166 offset:17408
	ds_read_b128 v[204:207], v167 offset:16384
	ds_read_b128 v[208:211], v167 offset:17408
	ds_read_b128 v[212:215], v168 offset:16384
	ds_read_b128 v[216:219], v168 offset:17408
	global_load_lds_dwordx4 v[238:239], off
	v_lshl_add_u64 v[238:239], v[246:247], 0, s[12:13]
	s_mov_b32 m0, s75
	s_nop 0
	global_load_lds_dwordx4 v[238:239], off
	s_barrier
	s_waitcnt lgkmcnt(0)
	s_setprio 1
	s_waitcnt lgkmcnt(0)
	v_mfma_f32_16x16x32_bf16 v[46:49], v[172:175], v[188:191], v[46:49]
	v_mfma_f32_16x16x32_bf16 v[42:45], v[180:183], v[188:191], v[42:45]
	v_mfma_f32_16x16x32_bf16 v[38:41], v[172:175], v[196:199], v[38:41]
	v_mfma_f32_16x16x32_bf16 v[34:37], v[180:183], v[196:199], v[34:37]
	v_mfma_f32_16x16x32_bf16 v[30:33], v[172:175], v[204:207], v[30:33]
	v_mfma_f32_16x16x32_bf16 v[26:29], v[180:183], v[204:207], v[26:29]
	v_mfma_f32_16x16x32_bf16 v[22:25], v[172:175], v[212:215], v[22:25]
	v_mfma_f32_16x16x32_bf16 v[18:21], v[180:183], v[212:215], v[18:21]
	v_mfma_f32_16x16x32_bf16 v[46:49], v[176:179], v[192:195], v[46:49]
	v_mfma_f32_16x16x32_bf16 v[42:45], v[184:187], v[192:195], v[42:45]
	v_mfma_f32_16x16x32_bf16 v[38:41], v[176:179], v[200:203], v[38:41]
	v_mfma_f32_16x16x32_bf16 v[34:37], v[184:187], v[200:203], v[34:37]
	v_mfma_f32_16x16x32_bf16 v[30:33], v[176:179], v[208:211], v[30:33]
	v_mfma_f32_16x16x32_bf16 v[26:29], v[184:187], v[208:211], v[26:29]
	v_mfma_f32_16x16x32_bf16 v[22:25], v[176:179], v[216:219], v[22:25]
	v_mfma_f32_16x16x32_bf16 v[18:21], v[184:187], v[216:219], v[18:21]
	s_setprio 0
	s_barrier
	v_readfirstlane_b32 s75, v147
	v_lshl_add_u64 v[172:173], v[248:249], 0, s[16:17]
	s_mov_b32 m0, s75
	v_readfirstlane_b32 s75, v148
	global_load_lds_dwordx4 v[172:173], off
	v_lshl_add_u64 v[172:173], v[250:251], 0, s[16:17]
	s_mov_b32 m0, s75
	s_nop 0
	global_load_lds_dwordx4 v[172:173], off
	s_waitcnt vmcnt(6)
	s_barrier
	s_setprio 1
	v_mfma_f32_16x16x32_bf16 v[14:17], v[220:223], v[188:191], v[14:17]
	v_mfma_f32_16x16x32_bf16 v[10:13], v[230:233], v[188:191], v[10:13]
	v_mfma_f32_16x16x32_bf16 v[6:9], v[220:223], v[196:199], v[6:9]
	v_mfma_f32_16x16x32_bf16 v[2:5], v[230:233], v[196:199], v[2:5]
	v_mfma_f32_16x16x32_bf16 v[70:73], v[220:223], v[204:207], v[70:73]
	v_mfma_f32_16x16x32_bf16 v[74:77], v[230:233], v[204:207], v[74:77]
	v_mfma_f32_16x16x32_bf16 v[78:81], v[220:223], v[212:215], v[78:81]
	v_mfma_f32_16x16x32_bf16 v[86:89], v[230:233], v[212:215], v[86:89]
	v_mfma_f32_16x16x32_bf16 v[14:17], v[226:229], v[192:195], v[14:17]
	v_mfma_f32_16x16x32_bf16 v[10:13], v[234:237], v[192:195], v[10:13]
	v_mfma_f32_16x16x32_bf16 v[6:9], v[226:229], v[200:203], v[6:9]
	v_mfma_f32_16x16x32_bf16 v[2:5], v[234:237], v[200:203], v[2:5]
	v_mfma_f32_16x16x32_bf16 v[70:73], v[226:229], v[208:211], v[70:73]
	v_mfma_f32_16x16x32_bf16 v[74:77], v[234:237], v[208:211], v[74:77]
	v_mfma_f32_16x16x32_bf16 v[78:81], v[226:229], v[216:219], v[78:81]
	v_mfma_f32_16x16x32_bf16 v[86:89], v[234:237], v[216:219], v[86:89]
	s_setprio 0
	s_barrier
	ds_read_b128 v[178:181], v154
	ds_read_b128 v[182:185], v154 offset:1024
	ds_read_b128 v[186:189], v154 offset:2048
	ds_read_b128 v[190:193], v154 offset:3072
	v_readfirstlane_b32 s75, v149
	v_add_u32_e32 v172, s43, v163
	v_add_u32_e32 v173, s46, v163
	v_add_u32_e32 v174, s47, v163
	v_lshl_add_u64 v[176:177], v[224:225], 0, s[20:21]
	s_mov_b32 m0, s75
	v_readfirstlane_b32 s75, v150
	ds_read_b128 v[194:197], v153
	ds_read_b128 v[198:201], v153 offset:1024
	ds_read_b128 v[202:205], v172
	ds_read_b128 v[206:209], v172 offset:1024
	ds_read_b128 v[210:213], v173
	ds_read_b128 v[214:217], v173 offset:1024
	ds_read_b128 v[218:221], v174
	ds_read_b128 v[226:229], v174 offset:1024
	global_load_lds_dwordx4 v[176:177], off
	v_lshl_add_u64 v[176:177], v[246:247], 0, s[20:21]
	s_mov_b32 m0, s75
	s_nop 0
	global_load_lds_dwordx4 v[176:177], off
	s_waitcnt lgkmcnt(8)
	s_barrier
	s_waitcnt lgkmcnt(0)
	s_setprio 1
	s_waitcnt lgkmcnt(0)
	v_mfma_f32_16x16x32_bf16 v[126:129], v[178:181], v[194:197], v[126:129]
	v_mfma_f32_16x16x32_bf16 v[122:125], v[186:189], v[194:197], v[122:125]
	v_mfma_f32_16x16x32_bf16 v[118:121], v[178:181], v[202:205], v[118:121]
	v_mfma_f32_16x16x32_bf16 v[114:117], v[186:189], v[202:205], v[114:117]
	v_mfma_f32_16x16x32_bf16 v[110:113], v[178:181], v[210:213], v[110:113]
	v_mfma_f32_16x16x32_bf16 v[106:109], v[186:189], v[210:213], v[106:109]
	v_mfma_f32_16x16x32_bf16 v[102:105], v[178:181], v[218:221], v[102:105]
	v_mfma_f32_16x16x32_bf16 v[98:101], v[186:189], v[218:221], v[98:101]
	v_mfma_f32_16x16x32_bf16 v[126:129], v[182:185], v[198:201], v[126:129]
	v_mfma_f32_16x16x32_bf16 v[122:125], v[190:193], v[198:201], v[122:125]
	v_mfma_f32_16x16x32_bf16 v[118:121], v[182:185], v[206:209], v[118:121]
	v_mfma_f32_16x16x32_bf16 v[114:117], v[190:193], v[206:209], v[114:117]
	v_mfma_f32_16x16x32_bf16 v[110:113], v[182:185], v[214:217], v[110:113]
	v_mfma_f32_16x16x32_bf16 v[106:109], v[190:193], v[214:217], v[106:109]
	v_mfma_f32_16x16x32_bf16 v[102:105], v[182:185], v[226:229], v[102:105]
	v_mfma_f32_16x16x32_bf16 v[98:101], v[190:193], v[226:229], v[98:101]
	s_setprio 0
	s_barrier
	v_readfirstlane_b32 s75, v155
	v_lshl_add_u64 v[176:177], v[248:249], 0, s[22:23]
	s_mov_b32 m0, s75
	v_readfirstlane_b32 s75, v156
	ds_read_b128 v[230:233], v152
	ds_read_b128 v[234:237], v152 offset:1024
	ds_read_b128 v[238:241], v152 offset:2048
	ds_read_b128 v[242:245], v152 offset:3072
	global_load_lds_dwordx4 v[176:177], off
	v_lshl_add_u64 v[176:177], v[250:251], 0, s[22:23]
	s_mov_b32 m0, s75
	s_nop 0
	global_load_lds_dwordx4 v[176:177], off
	s_barrier
	s_waitcnt lgkmcnt(0)
	s_setprio 1
	s_waitcnt lgkmcnt(0)
	v_mfma_f32_16x16x32_bf16 v[94:97], v[230:233], v[194:197], v[94:97]
	v_mfma_f32_16x16x32_bf16 v[90:93], v[238:241], v[194:197], v[90:93]
	v_mfma_f32_16x16x32_bf16 v[82:85], v[230:233], v[202:205], v[82:85]
	v_mfma_f32_16x16x32_bf16 v[66:69], v[238:241], v[202:205], v[66:69]
	v_mfma_f32_16x16x32_bf16 v[62:65], v[230:233], v[210:213], v[62:65]
	v_mfma_f32_16x16x32_bf16 v[58:61], v[238:241], v[210:213], v[58:61]
	v_mfma_f32_16x16x32_bf16 v[54:57], v[230:233], v[218:221], v[54:57]
	v_mfma_f32_16x16x32_bf16 v[50:53], v[238:241], v[218:221], v[50:53]
	v_mfma_f32_16x16x32_bf16 v[94:97], v[234:237], v[198:201], v[94:97]
	v_mfma_f32_16x16x32_bf16 v[90:93], v[242:245], v[198:201], v[90:93]
	v_mfma_f32_16x16x32_bf16 v[82:85], v[234:237], v[206:209], v[82:85]
	v_mfma_f32_16x16x32_bf16 v[66:69], v[242:245], v[206:209], v[66:69]
	v_mfma_f32_16x16x32_bf16 v[62:65], v[234:237], v[214:217], v[62:65]
	v_mfma_f32_16x16x32_bf16 v[58:61], v[242:245], v[214:217], v[58:61]
	v_mfma_f32_16x16x32_bf16 v[54:57], v[234:237], v[226:229], v[54:57]
	v_mfma_f32_16x16x32_bf16 v[50:53], v[242:245], v[226:229], v[50:53]
	s_setprio 0
	v_readfirstlane_b32 s75, v157
	v_add_u32_e32 v175, s43, v164
	v_add_u32_e32 v176, s46, v164
	v_add_u32_e32 v177, s47, v164
	v_lshl_add_u64 v[222:223], v[224:225], 0, s[24:25]
	s_mov_b32 m0, s75
	v_readfirstlane_b32 s75, v158
	s_barrier
	ds_read_b128 v[194:197], v151
	ds_read_b128 v[198:201], v151 offset:1024
	ds_read_b128 v[202:205], v175
	ds_read_b128 v[206:209], v175 offset:1024
	ds_read_b128 v[210:213], v176
	ds_read_b128 v[214:217], v176 offset:1024
	ds_read_b128 v[218:221], v177
	ds_read_b128 v[226:229], v177 offset:1024
	global_load_lds_dwordx4 v[222:223], off
	v_lshl_add_u64 v[222:223], v[246:247], 0, s[24:25]
	s_mov_b32 m0, s75
	s_nop 0
	global_load_lds_dwordx4 v[222:223], off
	s_barrier
	s_waitcnt lgkmcnt(0)
	s_setprio 1
	s_waitcnt lgkmcnt(0)
	v_mfma_f32_16x16x32_bf16 v[46:49], v[178:181], v[194:197], v[46:49]
	v_mfma_f32_16x16x32_bf16 v[42:45], v[186:189], v[194:197], v[42:45]
	v_mfma_f32_16x16x32_bf16 v[38:41], v[178:181], v[202:205], v[38:41]
	v_mfma_f32_16x16x32_bf16 v[34:37], v[186:189], v[202:205], v[34:37]
	v_mfma_f32_16x16x32_bf16 v[30:33], v[178:181], v[210:213], v[30:33]
	v_mfma_f32_16x16x32_bf16 v[26:29], v[186:189], v[210:213], v[26:29]
	v_mfma_f32_16x16x32_bf16 v[22:25], v[178:181], v[218:221], v[22:25]
	v_mfma_f32_16x16x32_bf16 v[18:21], v[186:189], v[218:221], v[18:21]
	v_mfma_f32_16x16x32_bf16 v[46:49], v[182:185], v[198:201], v[46:49]
	v_mfma_f32_16x16x32_bf16 v[42:45], v[190:193], v[198:201], v[42:45]
	v_mfma_f32_16x16x32_bf16 v[38:41], v[182:185], v[206:209], v[38:41]
	v_mfma_f32_16x16x32_bf16 v[34:37], v[190:193], v[206:209], v[34:37]
	v_mfma_f32_16x16x32_bf16 v[30:33], v[182:185], v[214:217], v[30:33]
	v_mfma_f32_16x16x32_bf16 v[26:29], v[190:193], v[214:217], v[26:29]
	v_mfma_f32_16x16x32_bf16 v[22:25], v[182:185], v[226:229], v[22:25]
	v_mfma_f32_16x16x32_bf16 v[18:21], v[190:193], v[226:229], v[18:21]
	s_setprio 0
	s_barrier
	v_readfirstlane_b32 s75, v159
	v_lshl_add_u64 v[178:179], v[248:249], 0, s[26:27]
	s_mov_b32 m0, s75
	v_readfirstlane_b32 s75, v160
	global_load_lds_dwordx4 v[178:179], off
	v_lshl_add_u64 v[178:179], v[250:251], 0, s[26:27]
	s_mov_b32 m0, s75
	s_nop 0
	global_load_lds_dwordx4 v[178:179], off
	s_waitcnt vmcnt(6)
	s_barrier
	s_setprio 1
	v_mfma_f32_16x16x32_bf16 v[14:17], v[230:233], v[194:197], v[14:17]
	v_mfma_f32_16x16x32_bf16 v[10:13], v[238:241], v[194:197], v[10:13]
	v_mfma_f32_16x16x32_bf16 v[6:9], v[230:233], v[202:205], v[6:9]
	v_mfma_f32_16x16x32_bf16 v[2:5], v[238:241], v[202:205], v[2:5]
	v_mfma_f32_16x16x32_bf16 v[70:73], v[230:233], v[210:213], v[70:73]
	v_mfma_f32_16x16x32_bf16 v[74:77], v[238:241], v[210:213], v[74:77]
	v_mfma_f32_16x16x32_bf16 v[78:81], v[230:233], v[218:221], v[78:81]
	v_mfma_f32_16x16x32_bf16 v[86:89], v[238:241], v[218:221], v[86:89]
	v_mfma_f32_16x16x32_bf16 v[14:17], v[234:237], v[198:201], v[14:17]
	v_mfma_f32_16x16x32_bf16 v[10:13], v[242:245], v[198:201], v[10:13]
	v_mfma_f32_16x16x32_bf16 v[6:9], v[234:237], v[206:209], v[6:9]
	v_mfma_f32_16x16x32_bf16 v[2:5], v[242:245], v[206:209], v[2:5]
	v_mfma_f32_16x16x32_bf16 v[70:73], v[234:237], v[214:217], v[70:73]
	v_mfma_f32_16x16x32_bf16 v[74:77], v[242:245], v[214:217], v[74:77]
	v_mfma_f32_16x16x32_bf16 v[78:81], v[234:237], v[226:229], v[78:81]
	v_mfma_f32_16x16x32_bf16 v[86:89], v[242:245], v[226:229], v[86:89]
	s_setprio 0
	s_add_i32 s74, s74, 2
	s_add_u32 s0, s0, 0x100
	s_addc_u32 s1, s1, 0
	s_cmp_lt_u32 s74, 12
	s_barrier
	s_cbranch_scc1 .LBB0_1175
	s_or_b32 s0, s34, 0x80
	s_ashr_i32 s1, s0, 31
	s_lshl_b64 s[46:47], s[0:1], 11
	s_add_u32 s46, s60, s46
	s_addc_u32 s47, s61, s47
	v_lshl_add_u64 v[202:203], v[130:131], 1, s[46:47]
	v_readfirstlane_b32 s1, v170
	v_lshl_add_u64 v[202:203], v[202:203], 0, s[28:29]
	s_mov_b32 m0, s1
	v_lshl_add_u64 v[132:133], v[132:133], 1, s[46:47]
	v_readfirstlane_b32 s1, v171
	ds_read_b128 v[134:137], v169 offset:32768
	ds_read_b128 v[138:141], v169 offset:33792
	ds_read_b128 v[142:145], v169 offset:34816
	ds_read_b128 v[146:149], v169 offset:35840
	ds_read_b128 v[156:159], v165
	ds_read_b128 v[160:163], v165 offset:1024
	ds_read_b128 v[178:181], v166
	ds_read_b128 v[182:185], v166 offset:1024
	ds_read_b128 v[186:189], v167
	ds_read_b128 v[190:193], v167 offset:1024
	ds_read_b128 v[194:197], v168
	ds_read_b128 v[198:201], v168 offset:1024
	global_load_lds_dwordx4 v[202:203], off
	v_lshl_add_u64 v[132:133], v[132:133], 0, s[28:29]
	s_mov_b32 m0, s1
	s_nop 0
	global_load_lds_dwordx4 v[132:133], off
	s_barrier
	s_waitcnt lgkmcnt(0)
	s_setprio 1
	s_waitcnt lgkmcnt(0)
	v_mfma_f32_16x16x32_bf16 v[126:129], v[134:137], v[156:159], v[126:129]
	v_mfma_f32_16x16x32_bf16 v[122:125], v[142:145], v[156:159], v[122:125]
	v_mfma_f32_16x16x32_bf16 v[118:121], v[134:137], v[178:181], v[118:121]
	v_mfma_f32_16x16x32_bf16 v[114:117], v[142:145], v[178:181], v[114:117]
	v_mfma_f32_16x16x32_bf16 v[110:113], v[134:137], v[186:189], v[110:113]
	v_mfma_f32_16x16x32_bf16 v[126:129], v[138:141], v[160:163], v[126:129]
	v_mfma_f32_16x16x32_bf16 v[122:125], v[146:149], v[160:163], v[122:125]
	v_mfma_f32_16x16x32_bf16 v[118:121], v[138:141], v[182:185], v[118:121]
	v_mfma_f32_16x16x32_bf16 v[114:117], v[146:149], v[182:185], v[114:117]
	v_mfma_f32_16x16x32_bf16 v[110:113], v[138:141], v[190:193], v[110:113]
	v_mfma_f32_16x16x32_bf16 v[106:109], v[142:145], v[186:189], v[106:109]
	v_mfma_f32_16x16x32_bf16 v[102:105], v[134:137], v[194:197], v[102:105]
	v_mfma_f32_16x16x32_bf16 v[98:101], v[142:145], v[194:197], v[98:101]
	v_mfma_f32_16x16x32_bf16 v[202:205], v[146:149], v[190:193], v[106:109]
	v_mfma_f32_16x16x32_bf16 v[206:209], v[138:141], v[198:201], v[102:105]
	v_mfma_f32_16x16x32_bf16 v[210:213], v[146:149], v[198:201], v[98:101]
	s_setprio 0
	s_barrier
	s_nop 2
	ds_read_b128 v[98:101], v169 offset:49152
	ds_read_b128 v[102:105], v169 offset:50176
	ds_read_b128 v[106:109], v169 offset:51200
	ds_read_b128 v[214:217], v169 offset:52224
	s_barrier
	s_waitcnt lgkmcnt(0)
	s_setprio 1
	s_waitcnt lgkmcnt(0)
	v_mfma_f32_16x16x32_bf16 v[94:97], v[98:101], v[156:159], v[94:97]
	v_mfma_f32_16x16x32_bf16 v[90:93], v[106:109], v[156:159], v[90:93]
	v_mfma_f32_16x16x32_bf16 v[82:85], v[98:101], v[178:181], v[82:85]
	v_mfma_f32_16x16x32_bf16 v[62:65], v[98:101], v[186:189], v[62:65]
	v_mfma_f32_16x16x32_bf16 v[58:61], v[106:109], v[186:189], v[58:61]
	v_mfma_f32_16x16x32_bf16 v[54:57], v[98:101], v[194:197], v[54:57]
	v_mfma_f32_16x16x32_bf16 v[50:53], v[106:109], v[194:197], v[50:53]
	v_mfma_f32_16x16x32_bf16 v[94:97], v[102:105], v[160:163], v[94:97]
	v_mfma_f32_16x16x32_bf16 v[90:93], v[214:217], v[160:163], v[90:93]
	v_mfma_f32_16x16x32_bf16 v[82:85], v[102:105], v[182:185], v[82:85]
	v_mfma_f32_16x16x32_bf16 v[66:69], v[106:109], v[178:181], v[66:69]
	v_mfma_f32_16x16x32_bf16 v[62:65], v[102:105], v[190:193], v[62:65]
	v_mfma_f32_16x16x32_bf16 v[58:61], v[214:217], v[190:193], v[58:61]
	v_mfma_f32_16x16x32_bf16 v[54:57], v[102:105], v[198:201], v[54:57]
	v_mfma_f32_16x16x32_bf16 v[50:53], v[214:217], v[198:201], v[50:53]
	v_mfma_f32_16x16x32_bf16 v[156:159], v[214:217], v[182:185], v[66:69]
	s_setprio 0
	s_barrier
	s_nop 0
	ds_read_b128 v[66:69], v165 offset:16384
	ds_read_b128 v[160:163], v165 offset:17408
	ds_read_b128 v[178:181], v166 offset:16384
	ds_read_b128 v[182:185], v166 offset:17408
	ds_read_b128 v[186:189], v167 offset:16384
	ds_read_b128 v[164:167], v167 offset:17408
	ds_read_b128 v[190:193], v168 offset:16384
	ds_read_b128 v[168:171], v168 offset:17408
	s_waitcnt vmcnt(4)
	s_barrier
	s_waitcnt lgkmcnt(0)
	s_setprio 1
	s_waitcnt lgkmcnt(0)
	v_mfma_f32_16x16x32_bf16 v[46:49], v[134:137], v[66:69], v[46:49]
	v_mfma_f32_16x16x32_bf16 v[42:45], v[142:145], v[66:69], v[42:45]
	v_mfma_f32_16x16x32_bf16 v[30:33], v[134:137], v[186:189], v[30:33]
	v_mfma_f32_16x16x32_bf16 v[26:29], v[142:145], v[186:189], v[26:29]
	v_mfma_f32_16x16x32_bf16 v[22:25], v[134:137], v[190:193], v[22:25]
	v_mfma_f32_16x16x32_bf16 v[18:21], v[142:145], v[190:193], v[18:21]
	v_mfma_f32_16x16x32_bf16 v[46:49], v[138:141], v[160:163], v[46:49]
	v_mfma_f32_16x16x32_bf16 v[42:45], v[146:149], v[160:163], v[42:45]
	v_mfma_f32_16x16x32_bf16 v[38:41], v[134:137], v[178:181], v[38:41]
	v_mfma_f32_16x16x32_bf16 v[34:37], v[142:145], v[178:181], v[34:37]
	v_mfma_f32_16x16x32_bf16 v[30:33], v[138:141], v[164:167], v[30:33]
	v_mfma_f32_16x16x32_bf16 v[26:29], v[146:149], v[164:167], v[26:29]
	v_mfma_f32_16x16x32_bf16 v[22:25], v[138:141], v[168:171], v[22:25]
	v_mfma_f32_16x16x32_bf16 v[18:21], v[146:149], v[168:171], v[18:21]
	v_mfma_f32_16x16x32_bf16 v[194:197], v[138:141], v[182:185], v[38:41]
	v_mfma_f32_16x16x32_bf16 v[198:201], v[146:149], v[182:185], v[34:37]
	s_setprio 0
	s_setprio 1
	v_mfma_f32_16x16x32_bf16 v[2:5], v[106:109], v[178:181], v[2:5]
	v_mfma_f32_16x16x32_bf16 v[136:139], v[214:217], v[182:185], v[2:5]
	v_mfma_f32_16x16x32_bf16 v[2:5], v[98:101], v[186:189], v[70:73]
	v_mfma_f32_16x16x32_bf16 v[140:143], v[102:105], v[164:167], v[2:5]
	v_mfma_f32_16x16x32_bf16 v[2:5], v[106:109], v[186:189], v[74:77]
	v_mfma_f32_16x16x32_bf16 v[14:17], v[98:101], v[66:69], v[14:17]
	v_mfma_f32_16x16x32_bf16 v[10:13], v[106:109], v[66:69], v[10:13]
	v_mfma_f32_16x16x32_bf16 v[144:147], v[214:217], v[164:167], v[2:5]
	v_mfma_f32_16x16x32_bf16 v[2:5], v[98:101], v[190:193], v[78:81]
	v_mfma_f32_16x16x32_bf16 v[14:17], v[102:105], v[160:163], v[14:17]
	v_mfma_f32_16x16x32_bf16 v[10:13], v[214:217], v[160:163], v[10:13]
	v_mfma_f32_16x16x32_bf16 v[6:9], v[98:101], v[178:181], v[6:9]
	v_mfma_f32_16x16x32_bf16 v[160:163], v[102:105], v[168:171], v[2:5]
	v_mfma_f32_16x16x32_bf16 v[2:5], v[106:109], v[190:193], v[86:89]
	v_mfma_f32_16x16x32_bf16 v[132:135], v[102:105], v[182:185], v[6:9]
	v_mfma_f32_16x16x32_bf16 v[164:167], v[214:217], v[168:171], v[2:5]
	s_setprio 0
	s_barrier
	s_nop 3
	ds_read_b128 v[2:5], v154
	ds_read_b128 v[6:9], v154 offset:1024
	ds_read_b128 v[168:171], v154 offset:2048
	ds_read_b128 v[178:181], v154 offset:3072
	ds_read_b128 v[34:37], v153
	ds_read_b128 v[38:41], v153 offset:1024
	ds_read_b128 v[78:81], v172
	ds_read_b128 v[86:89], v172 offset:1024
	ds_read_b128 v[182:185], v173
	ds_read_b128 v[186:189], v173 offset:1024
	ds_read_b128 v[190:193], v174
	ds_read_b128 v[214:217], v174 offset:1024
	s_waitcnt vmcnt(2)
	s_barrier
	s_waitcnt lgkmcnt(0)
	s_setprio 1
	s_waitcnt lgkmcnt(0)
	v_mfma_f32_16x16x32_bf16 v[66:69], v[2:5], v[34:37], v[126:129]
	v_mfma_f32_16x16x32_bf16 v[126:129], v[6:9], v[38:41], v[66:69]
	v_mfma_f32_16x16x32_bf16 v[66:69], v[168:171], v[34:37], v[122:125]
	v_mfma_f32_16x16x32_bf16 v[98:101], v[178:181], v[38:41], v[66:69]
	v_mfma_f32_16x16x32_bf16 v[66:69], v[2:5], v[78:81], v[118:121]
	v_mfma_f32_16x16x32_bf16 v[102:105], v[6:9], v[86:89], v[66:69]
	v_mfma_f32_16x16x32_bf16 v[66:69], v[168:171], v[78:81], v[114:117]
	v_mfma_f32_16x16x32_bf16 v[106:109], v[178:181], v[86:89], v[66:69]
	v_mfma_f32_16x16x32_bf16 v[66:69], v[2:5], v[182:185], v[110:113]
	v_mfma_f32_16x16x32_bf16 v[110:113], v[6:9], v[186:189], v[66:69]
	v_mfma_f32_16x16x32_bf16 v[66:69], v[168:171], v[182:185], v[202:205]
	v_mfma_f32_16x16x32_bf16 v[114:117], v[178:181], v[186:189], v[66:69]
	v_mfma_f32_16x16x32_bf16 v[66:69], v[2:5], v[190:193], v[206:209]
	v_mfma_f32_16x16x32_bf16 v[118:121], v[6:9], v[214:217], v[66:69]
	v_mfma_f32_16x16x32_bf16 v[66:69], v[168:171], v[190:193], v[210:213]
	v_mfma_f32_16x16x32_bf16 v[122:125], v[178:181], v[214:217], v[66:69]
	s_setprio 0
	s_barrier
	ds_read_b128 v[202:205], v152
	ds_read_b128 v[206:209], v152 offset:1024
	ds_read_b128 v[210:213], v152 offset:2048
	ds_read_b128 v[152:155], v152 offset:3072
	s_waitcnt vmcnt(0)
	s_barrier
	s_waitcnt lgkmcnt(0)
	s_setprio 1
	s_waitcnt lgkmcnt(0)
	v_mfma_f32_16x16x32_bf16 v[66:69], v[202:205], v[34:37], v[94:97]
	v_mfma_f32_16x16x32_bf16 v[34:37], v[210:213], v[34:37], v[90:93]
	v_mfma_f32_16x16x32_bf16 v[70:73], v[152:155], v[38:41], v[34:37]
	v_mfma_f32_16x16x32_bf16 v[34:37], v[202:205], v[78:81], v[82:85]
	v_mfma_f32_16x16x32_bf16 v[74:77], v[206:209], v[86:89], v[34:37]
	v_mfma_f32_16x16x32_bf16 v[34:37], v[210:213], v[78:81], v[156:159]
	v_mfma_f32_16x16x32_bf16 v[78:81], v[152:155], v[86:89], v[34:37]
	v_mfma_f32_16x16x32_bf16 v[34:37], v[202:205], v[182:185], v[62:65]
	v_mfma_f32_16x16x32_bf16 v[82:85], v[206:209], v[186:189], v[34:37]
	v_mfma_f32_16x16x32_bf16 v[34:37], v[210:213], v[182:185], v[58:61]
	v_mfma_f32_16x16x32_bf16 v[86:89], v[152:155], v[186:189], v[34:37]
	v_mfma_f32_16x16x32_bf16 v[34:37], v[202:205], v[190:193], v[54:57]
	v_mfma_f32_16x16x32_bf16 v[90:93], v[206:209], v[214:217], v[34:37]
	v_mfma_f32_16x16x32_bf16 v[34:37], v[210:213], v[190:193], v[50:53]
	v_mfma_f32_16x16x32_bf16 v[66:69], v[206:209], v[38:41], v[66:69]
	v_mfma_f32_16x16x32_bf16 v[94:97], v[152:155], v[214:217], v[34:37]
	s_setprio 0
	s_barrier
	ds_read_b128 v[156:159], v151
	ds_read_b128 v[148:151], v151 offset:1024
	ds_read_b128 v[182:185], v175
	ds_read_b128 v[172:175], v175 offset:1024
	ds_read_b128 v[186:189], v176
	ds_read_b128 v[190:193], v176 offset:1024
	ds_read_b128 v[214:217], v177
	ds_read_b128 v[218:221], v177 offset:1024
	s_barrier
	s_waitcnt lgkmcnt(0)
	s_setprio 1
	s_waitcnt lgkmcnt(0)
	v_mfma_f32_16x16x32_bf16 v[34:37], v[2:5], v[156:159], v[46:49]
	v_mfma_f32_16x16x32_bf16 v[38:41], v[168:171], v[156:159], v[42:45]
	v_mfma_f32_16x16x32_bf16 v[42:45], v[2:5], v[182:185], v[194:197]
	v_mfma_f32_16x16x32_bf16 v[30:33], v[2:5], v[186:189], v[30:33]
	v_mfma_f32_16x16x32_bf16 v[2:5], v[2:5], v[214:217], v[22:25]
	v_mfma_f32_16x16x32_bf16 v[46:49], v[168:171], v[182:185], v[198:201]
	v_mfma_f32_16x16x32_bf16 v[26:29], v[168:171], v[186:189], v[26:29]
	v_mfma_f32_16x16x32_bf16 v[58:61], v[6:9], v[218:221], v[2:5]
	v_mfma_f32_16x16x32_bf16 v[2:5], v[168:171], v[214:217], v[18:21]
	v_mfma_f32_16x16x32_bf16 v[34:37], v[6:9], v[148:151], v[34:37]
	v_mfma_f32_16x16x32_bf16 v[38:41], v[178:181], v[148:151], v[38:41]
	v_mfma_f32_16x16x32_bf16 v[42:45], v[6:9], v[172:175], v[42:45]
	v_mfma_f32_16x16x32_bf16 v[46:49], v[178:181], v[172:175], v[46:49]
	v_mfma_f32_16x16x32_bf16 v[50:53], v[6:9], v[190:193], v[30:33]
	v_mfma_f32_16x16x32_bf16 v[54:57], v[178:181], v[190:193], v[26:29]
	v_mfma_f32_16x16x32_bf16 v[62:65], v[178:181], v[218:221], v[2:5]
	s_setprio 0
	s_setprio 1
	v_mfma_f32_16x16x32_bf16 v[2:5], v[202:205], v[156:159], v[14:17]
	v_mfma_f32_16x16x32_bf16 v[6:9], v[210:213], v[156:159], v[10:13]
	v_mfma_f32_16x16x32_bf16 v[10:13], v[202:205], v[182:185], v[132:135]
	v_mfma_f32_16x16x32_bf16 v[14:17], v[210:213], v[182:185], v[136:139]
	v_mfma_f32_16x16x32_bf16 v[18:21], v[202:205], v[186:189], v[140:143]
	v_mfma_f32_16x16x32_bf16 v[22:25], v[210:213], v[186:189], v[144:147]
	v_mfma_f32_16x16x32_bf16 v[26:29], v[202:205], v[214:217], v[160:163]
	v_mfma_f32_16x16x32_bf16 v[30:33], v[210:213], v[214:217], v[164:167]
	v_mfma_f32_16x16x32_bf16 v[2:5], v[206:209], v[148:151], v[2:5]
	v_mfma_f32_16x16x32_bf16 v[6:9], v[152:155], v[148:151], v[6:9]
	v_mfma_f32_16x16x32_bf16 v[10:13], v[206:209], v[172:175], v[10:13]
	v_mfma_f32_16x16x32_bf16 v[14:17], v[152:155], v[172:175], v[14:17]
	v_mfma_f32_16x16x32_bf16 v[18:21], v[206:209], v[190:193], v[18:21]
	v_mfma_f32_16x16x32_bf16 v[22:25], v[152:155], v[190:193], v[22:25]
	v_mfma_f32_16x16x32_bf16 v[26:29], v[206:209], v[218:221], v[26:29]
	v_mfma_f32_16x16x32_bf16 v[30:33], v[152:155], v[218:221], v[30:33]
	s_setprio 0
	s_cmpk_gt_u32 s39, 0xff
	s_barrier
	s_cbranch_scc1 .LBB0_1178
	s_barrier

.LBB0_1180:
	v_and_b32_e32 v132, 15, v0
	v_lshrrev_b32_e32 v133, 8, v0
	v_lshl_add_u32 v132, v133, 6, v132
	v_add_u32_e32 v132, s34, v132
	v_mul_u32_u24_e32 v132, 0x1600, v132
	v_bfe_u32 v133, v0, 4, 4
	s_lshl_b32 s1, s73, 8
	v_lshl_add_u32 v132, v133, 3, v132
	v_add_u32_e32 v140, s1, v132
	v_mul_f32_e32 v132, 0xbfb8aa3b, v126
	v_mul_f32_e32 v133, 0xbfb8aa3b, v127
	v_mul_f32_e32 v134, 0xbfb8aa3b, v128
	v_mul_f32_e32 v135, 0xbfb8aa3b, v129
	v_mul_f32_e32 v136, 0xbfb8aa3b, v66
	v_mul_f32_e32 v137, 0xbfb8aa3b, v67
	v_mul_f32_e32 v138, 0xbfb8aa3b, v68
	v_mul_f32_e32 v139, 0xbfb8aa3b, v69
	v_exp_f32_e32 v132, v132
	v_exp_f32_e32 v133, v133
	v_exp_f32_e32 v134, v134
	v_exp_f32_e32 v135, v135
	v_exp_f32_e32 v136, v136
	v_exp_f32_e32 v137, v137
	v_exp_f32_e32 v138, v138
	v_exp_f32_e32 v139, v139
	v_add_f32_e32 v132, 1.0, v132
	v_add_f32_e32 v133, 1.0, v133
	v_add_f32_e32 v134, 1.0, v134
	v_add_f32_e32 v135, 1.0, v135
	v_add_f32_e32 v136, 1.0, v136
	v_add_f32_e32 v137, 1.0, v137
	v_add_f32_e32 v138, 1.0, v138
	v_add_f32_e32 v139, 1.0, v139
	v_rcp_f32_e32 v132, v132
	v_rcp_f32_e32 v133, v133
	v_rcp_f32_e32 v134, v134
	v_rcp_f32_e32 v135, v135
	v_rcp_f32_e32 v136, v136
	v_rcp_f32_e32 v137, v137
	v_rcp_f32_e32 v138, v138
	v_rcp_f32_e32 v139, v139
	v_pk_mul_f32 v[126:127], v[126:127], v[132:133]
	v_pk_mul_f32 v[128:129], v[128:129], v[134:135]
	v_pk_mul_f32 v[66:67], v[66:67], v[136:137]
	v_pk_mul_f32 v[68:69], v[68:69], v[138:139]
	v_pk_mul_f32 v[126:127], v[98:99], v[126:127]
	v_pk_mul_f32 v[128:129], v[100:101], v[128:129]
	v_pk_mul_f32 v[66:67], v[70:71], v[66:67]
	v_pk_mul_f32 v[68:69], v[72:73], v[68:69]
	v_cvt_pk_bf16_f32 v126, v126, v127
	v_cvt_pk_bf16_f32 v127, v128, v129
	v_cvt_pk_bf16_f32 v66, v66, v67
	v_cvt_pk_bf16_f32 v67, v68, v69
	global_store_dwordx2 v140, v[126:127], s[94:95]
	global_store_dwordx2 v140, v[66:67], s[94:95] offset:128
	v_add_u32_e32 v142, 0x16000, v140
	v_mul_f32_e32 v132, 0xbfb8aa3b, v102
	v_mul_f32_e32 v133, 0xbfb8aa3b, v103
	v_mul_f32_e32 v134, 0xbfb8aa3b, v104
	v_mul_f32_e32 v135, 0xbfb8aa3b, v105
	v_mul_f32_e32 v136, 0xbfb8aa3b, v74
	v_mul_f32_e32 v137, 0xbfb8aa3b, v75
	v_mul_f32_e32 v138, 0xbfb8aa3b, v76
	v_mul_f32_e32 v139, 0xbfb8aa3b, v77
	v_exp_f32_e32 v132, v132
	v_exp_f32_e32 v133, v133
	v_exp_f32_e32 v134, v134
	v_exp_f32_e32 v135, v135
	v_exp_f32_e32 v136, v136
	v_exp_f32_e32 v137, v137
	v_exp_f32_e32 v138, v138
	v_exp_f32_e32 v139, v139
	v_add_f32_e32 v132, 1.0, v132
	v_add_f32_e32 v133, 1.0, v133
	v_add_f32_e32 v134, 1.0, v134
	v_add_f32_e32 v135, 1.0, v135
	v_add_f32_e32 v136, 1.0, v136
	v_add_f32_e32 v137, 1.0, v137
	v_add_f32_e32 v138, 1.0, v138
	v_add_f32_e32 v139, 1.0, v139
	v_rcp_f32_e32 v132, v132
	v_rcp_f32_e32 v133, v133
	v_rcp_f32_e32 v134, v134
	v_rcp_f32_e32 v135, v135
	v_rcp_f32_e32 v136, v136
	v_rcp_f32_e32 v137, v137
	v_rcp_f32_e32 v138, v138
	v_rcp_f32_e32 v139, v139
	v_pk_mul_f32 v[102:103], v[102:103], v[132:133]
	v_pk_mul_f32 v[104:105], v[104:105], v[134:135]
	v_pk_mul_f32 v[74:75], v[74:75], v[136:137]
	v_pk_mul_f32 v[76:77], v[76:77], v[138:139]
	v_pk_mul_f32 v[102:103], v[106:107], v[102:103]
	v_pk_mul_f32 v[104:105], v[108:109], v[104:105]
	v_pk_mul_f32 v[74:75], v[78:79], v[74:75]
	v_pk_mul_f32 v[76:77], v[80:81], v[76:77]
	v_cvt_pk_bf16_f32 v102, v102, v103
	v_cvt_pk_bf16_f32 v103, v104, v105
	v_cvt_pk_bf16_f32 v74, v74, v75
	v_cvt_pk_bf16_f32 v75, v76, v77
	global_store_dwordx2 v142, v[102:103], s[94:95]
	global_store_dwordx2 v142, v[74:75], s[94:95] offset:128
	v_add_u32_e32 v141, 0x2c000, v140
	v_mul_f32_e32 v132, 0xbfb8aa3b, v110
	v_mul_f32_e32 v133, 0xbfb8aa3b, v111
	v_mul_f32_e32 v134, 0xbfb8aa3b, v112
	v_mul_f32_e32 v135, 0xbfb8aa3b, v113
	v_mul_f32_e32 v136, 0xbfb8aa3b, v82
	v_mul_f32_e32 v137, 0xbfb8aa3b, v83
	v_mul_f32_e32 v138, 0xbfb8aa3b, v84
	v_mul_f32_e32 v139, 0xbfb8aa3b, v85
	v_exp_f32_e32 v132, v132
	v_exp_f32_e32 v133, v133
	v_exp_f32_e32 v134, v134
	v_exp_f32_e32 v135, v135
	v_exp_f32_e32 v136, v136
	v_exp_f32_e32 v137, v137
	v_exp_f32_e32 v138, v138
	v_exp_f32_e32 v139, v139
	v_add_f32_e32 v132, 1.0, v132
	v_add_f32_e32 v133, 1.0, v133
	v_add_f32_e32 v134, 1.0, v134
	v_add_f32_e32 v135, 1.0, v135
	v_add_f32_e32 v136, 1.0, v136
	v_add_f32_e32 v137, 1.0, v137
	v_add_f32_e32 v138, 1.0, v138
	v_add_f32_e32 v139, 1.0, v139
	v_rcp_f32_e32 v132, v132
	v_rcp_f32_e32 v133, v133
	v_rcp_f32_e32 v134, v134
	v_rcp_f32_e32 v135, v135
	v_rcp_f32_e32 v136, v136
	v_rcp_f32_e32 v137, v137
	v_rcp_f32_e32 v138, v138
	v_rcp_f32_e32 v139, v139
	v_pk_mul_f32 v[110:111], v[110:111], v[132:133]
	v_pk_mul_f32 v[112:113], v[112:113], v[134:135]
	v_pk_mul_f32 v[82:83], v[82:83], v[136:137]
	v_pk_mul_f32 v[84:85], v[84:85], v[138:139]
	v_pk_mul_f32 v[110:111], v[114:115], v[110:111]
	v_pk_mul_f32 v[112:113], v[116:117], v[112:113]
	v_pk_mul_f32 v[82:83], v[86:87], v[82:83]
	v_pk_mul_f32 v[84:85], v[88:89], v[84:85]
	v_cvt_pk_bf16_f32 v110, v110, v111
	v_cvt_pk_bf16_f32 v111, v112, v113
	v_cvt_pk_bf16_f32 v82, v82, v83
	v_cvt_pk_bf16_f32 v83, v84, v85
	global_store_dwordx2 v141, v[110:111], s[94:95]
	global_store_dwordx2 v141, v[82:83], s[94:95] offset:128
	v_add_u32_e32 v142, 0x42000, v140
	v_mul_f32_e32 v132, 0xbfb8aa3b, v118
	v_mul_f32_e32 v133, 0xbfb8aa3b, v119
	v_mul_f32_e32 v134, 0xbfb8aa3b, v120
	v_mul_f32_e32 v135, 0xbfb8aa3b, v121
	v_mul_f32_e32 v136, 0xbfb8aa3b, v90
	v_mul_f32_e32 v137, 0xbfb8aa3b, v91
	v_mul_f32_e32 v138, 0xbfb8aa3b, v92
	v_mul_f32_e32 v139, 0xbfb8aa3b, v93
	v_exp_f32_e32 v132, v132
	v_exp_f32_e32 v133, v133
	v_exp_f32_e32 v134, v134
	v_exp_f32_e32 v135, v135
	v_exp_f32_e32 v136, v136
	v_exp_f32_e32 v137, v137
	v_exp_f32_e32 v138, v138
	v_exp_f32_e32 v139, v139
	v_add_f32_e32 v132, 1.0, v132
	v_add_f32_e32 v133, 1.0, v133
	v_add_f32_e32 v134, 1.0, v134
	v_add_f32_e32 v135, 1.0, v135
	v_add_f32_e32 v136, 1.0, v136
	v_add_f32_e32 v137, 1.0, v137
	v_add_f32_e32 v138, 1.0, v138
	v_add_f32_e32 v139, 1.0, v139
	v_rcp_f32_e32 v132, v132
	v_rcp_f32_e32 v133, v133
	v_rcp_f32_e32 v134, v134
	v_rcp_f32_e32 v135, v135
	v_rcp_f32_e32 v136, v136
	v_rcp_f32_e32 v137, v137
	v_rcp_f32_e32 v138, v138
	v_rcp_f32_e32 v139, v139
	v_pk_mul_f32 v[118:119], v[118:119], v[132:133]
	v_pk_mul_f32 v[120:121], v[120:121], v[134:135]
	v_pk_mul_f32 v[90:91], v[90:91], v[136:137]
	v_pk_mul_f32 v[92:93], v[92:93], v[138:139]
	v_pk_mul_f32 v[118:119], v[122:123], v[118:119]
	v_pk_mul_f32 v[120:121], v[124:125], v[120:121]
	v_pk_mul_f32 v[90:91], v[94:95], v[90:91]
	v_pk_mul_f32 v[92:93], v[96:97], v[92:93]
	v_cvt_pk_bf16_f32 v118, v118, v119
	v_cvt_pk_bf16_f32 v119, v120, v121
	v_cvt_pk_bf16_f32 v90, v90, v91
	v_cvt_pk_bf16_f32 v91, v92, v93
	global_store_dwordx2 v142, v[118:119], s[94:95]
	global_store_dwordx2 v142, v[90:91], s[94:95] offset:128
	v_add_u32_e32 v141, 0xb0000, v140
	v_mul_f32_e32 v132, 0xbfb8aa3b, v34
	v_mul_f32_e32 v133, 0xbfb8aa3b, v35
	v_mul_f32_e32 v134, 0xbfb8aa3b, v36
	v_mul_f32_e32 v135, 0xbfb8aa3b, v37
	v_mul_f32_e32 v136, 0xbfb8aa3b, v2
	v_mul_f32_e32 v137, 0xbfb8aa3b, v3
	v_mul_f32_e32 v138, 0xbfb8aa3b, v4
	v_mul_f32_e32 v139, 0xbfb8aa3b, v5
	v_exp_f32_e32 v132, v132
	v_exp_f32_e32 v133, v133
	v_exp_f32_e32 v134, v134
	v_exp_f32_e32 v135, v135
	v_exp_f32_e32 v136, v136
	v_exp_f32_e32 v137, v137
	v_exp_f32_e32 v138, v138
	v_exp_f32_e32 v139, v139
	v_add_f32_e32 v132, 1.0, v132
	v_add_f32_e32 v133, 1.0, v133
	v_add_f32_e32 v134, 1.0, v134
	v_add_f32_e32 v135, 1.0, v135
	v_add_f32_e32 v136, 1.0, v136
	v_add_f32_e32 v137, 1.0, v137
	v_add_f32_e32 v138, 1.0, v138
	v_add_f32_e32 v139, 1.0, v139
	v_rcp_f32_e32 v132, v132
	v_rcp_f32_e32 v133, v133
	v_rcp_f32_e32 v134, v134
	v_rcp_f32_e32 v135, v135
	v_rcp_f32_e32 v136, v136
	v_rcp_f32_e32 v137, v137
	v_rcp_f32_e32 v138, v138
	v_rcp_f32_e32 v139, v139
	v_pk_mul_f32 v[34:35], v[34:35], v[132:133]
	v_pk_mul_f32 v[36:37], v[36:37], v[134:135]
	v_pk_mul_f32 v[2:3], v[2:3], v[136:137]
	v_pk_mul_f32 v[4:5], v[4:5], v[138:139]
	v_pk_mul_f32 v[34:35], v[38:39], v[34:35]
	v_pk_mul_f32 v[36:37], v[40:41], v[36:37]
	v_pk_mul_f32 v[2:3], v[6:7], v[2:3]
	v_pk_mul_f32 v[4:5], v[8:9], v[4:5]
	v_cvt_pk_bf16_f32 v34, v34, v35
	v_cvt_pk_bf16_f32 v35, v36, v37
	v_cvt_pk_bf16_f32 v2, v2, v3
	v_cvt_pk_bf16_f32 v3, v4, v5
	global_store_dwordx2 v141, v[34:35], s[94:95]
	global_store_dwordx2 v141, v[2:3], s[94:95] offset:128
	v_add_u32_e32 v142, 0xc6000, v140
	v_mul_f32_e32 v132, 0xbfb8aa3b, v42
	v_mul_f32_e32 v133, 0xbfb8aa3b, v43
	v_mul_f32_e32 v134, 0xbfb8aa3b, v44
	v_mul_f32_e32 v135, 0xbfb8aa3b, v45
	v_mul_f32_e32 v136, 0xbfb8aa3b, v10
	v_mul_f32_e32 v137, 0xbfb8aa3b, v11
	v_mul_f32_e32 v138, 0xbfb8aa3b, v12
	v_mul_f32_e32 v139, 0xbfb8aa3b, v13
	v_exp_f32_e32 v132, v132
	v_exp_f32_e32 v133, v133
	v_exp_f32_e32 v134, v134
	v_exp_f32_e32 v135, v135
	v_exp_f32_e32 v136, v136
	v_exp_f32_e32 v137, v137
	v_exp_f32_e32 v138, v138
	v_exp_f32_e32 v139, v139
	v_add_f32_e32 v132, 1.0, v132
	v_add_f32_e32 v133, 1.0, v133
	v_add_f32_e32 v134, 1.0, v134
	v_add_f32_e32 v135, 1.0, v135
	v_add_f32_e32 v136, 1.0, v136
	v_add_f32_e32 v137, 1.0, v137
	v_add_f32_e32 v138, 1.0, v138
	v_add_f32_e32 v139, 1.0, v139
	v_rcp_f32_e32 v132, v132
	v_rcp_f32_e32 v133, v133
	v_rcp_f32_e32 v134, v134
	v_rcp_f32_e32 v135, v135
	v_rcp_f32_e32 v136, v136
	v_rcp_f32_e32 v137, v137
	v_rcp_f32_e32 v138, v138
	v_rcp_f32_e32 v139, v139
	v_pk_mul_f32 v[42:43], v[42:43], v[132:133]
	v_pk_mul_f32 v[44:45], v[44:45], v[134:135]
	v_pk_mul_f32 v[10:11], v[10:11], v[136:137]
	v_pk_mul_f32 v[12:13], v[12:13], v[138:139]
	v_pk_mul_f32 v[42:43], v[46:47], v[42:43]
	v_pk_mul_f32 v[44:45], v[48:49], v[44:45]
	v_pk_mul_f32 v[10:11], v[14:15], v[10:11]
	v_pk_mul_f32 v[12:13], v[16:17], v[12:13]
	v_cvt_pk_bf16_f32 v42, v42, v43
	v_cvt_pk_bf16_f32 v43, v44, v45
	v_cvt_pk_bf16_f32 v10, v10, v11
	v_cvt_pk_bf16_f32 v11, v12, v13
	global_store_dwordx2 v142, v[42:43], s[94:95]
	global_store_dwordx2 v142, v[10:11], s[94:95] offset:128
	v_add_u32_e32 v141, 0xdc000, v140
	v_mul_f32_e32 v132, 0xbfb8aa3b, v50
	v_mul_f32_e32 v133, 0xbfb8aa3b, v51
	v_mul_f32_e32 v134, 0xbfb8aa3b, v52
	v_mul_f32_e32 v135, 0xbfb8aa3b, v53
	v_mul_f32_e32 v136, 0xbfb8aa3b, v18
	v_mul_f32_e32 v137, 0xbfb8aa3b, v19
	v_mul_f32_e32 v138, 0xbfb8aa3b, v20
	v_mul_f32_e32 v139, 0xbfb8aa3b, v21
	v_exp_f32_e32 v132, v132
	v_exp_f32_e32 v133, v133
	v_exp_f32_e32 v134, v134
	v_exp_f32_e32 v135, v135
	v_exp_f32_e32 v136, v136
	v_exp_f32_e32 v137, v137
	v_exp_f32_e32 v138, v138
	v_exp_f32_e32 v139, v139
	v_add_f32_e32 v132, 1.0, v132
	v_add_f32_e32 v133, 1.0, v133
	v_add_f32_e32 v134, 1.0, v134
	v_add_f32_e32 v135, 1.0, v135
	v_add_f32_e32 v136, 1.0, v136
	v_add_f32_e32 v137, 1.0, v137
	v_add_f32_e32 v138, 1.0, v138
	v_add_f32_e32 v139, 1.0, v139
	v_rcp_f32_e32 v132, v132
	v_rcp_f32_e32 v133, v133
	v_rcp_f32_e32 v134, v134
	v_rcp_f32_e32 v135, v135
	v_rcp_f32_e32 v136, v136
	v_rcp_f32_e32 v137, v137
	v_rcp_f32_e32 v138, v138
	v_rcp_f32_e32 v139, v139
	v_pk_mul_f32 v[50:51], v[50:51], v[132:133]
	v_pk_mul_f32 v[52:53], v[52:53], v[134:135]
	v_pk_mul_f32 v[18:19], v[18:19], v[136:137]
	v_pk_mul_f32 v[20:21], v[20:21], v[138:139]
	v_pk_mul_f32 v[50:51], v[54:55], v[50:51]
	v_pk_mul_f32 v[52:53], v[56:57], v[52:53]
	v_pk_mul_f32 v[18:19], v[22:23], v[18:19]
	v_pk_mul_f32 v[20:21], v[24:25], v[20:21]
	v_cvt_pk_bf16_f32 v50, v50, v51
	v_cvt_pk_bf16_f32 v51, v52, v53
	v_cvt_pk_bf16_f32 v18, v18, v19
	v_cvt_pk_bf16_f32 v19, v20, v21
	global_store_dwordx2 v141, v[50:51], s[94:95]
	global_store_dwordx2 v141, v[18:19], s[94:95] offset:128
	v_add_u32_e32 v142, 0xf2000, v140
	v_mul_f32_e32 v132, 0xbfb8aa3b, v58
	v_mul_f32_e32 v133, 0xbfb8aa3b, v59
	v_mul_f32_e32 v134, 0xbfb8aa3b, v60
	v_mul_f32_e32 v135, 0xbfb8aa3b, v61
	v_mul_f32_e32 v136, 0xbfb8aa3b, v26
	v_mul_f32_e32 v137, 0xbfb8aa3b, v27
	v_mul_f32_e32 v138, 0xbfb8aa3b, v28
	v_mul_f32_e32 v139, 0xbfb8aa3b, v29
	v_exp_f32_e32 v132, v132
	v_exp_f32_e32 v133, v133
	v_exp_f32_e32 v134, v134
	v_exp_f32_e32 v135, v135
	v_exp_f32_e32 v136, v136
	v_exp_f32_e32 v137, v137
	v_exp_f32_e32 v138, v138
	v_exp_f32_e32 v139, v139
	v_add_f32_e32 v132, 1.0, v132
	v_add_f32_e32 v133, 1.0, v133
	v_add_f32_e32 v134, 1.0, v134
	v_add_f32_e32 v135, 1.0, v135
	v_add_f32_e32 v136, 1.0, v136
	v_add_f32_e32 v137, 1.0, v137
	v_add_f32_e32 v138, 1.0, v138
	v_add_f32_e32 v139, 1.0, v139
	v_rcp_f32_e32 v132, v132
	v_rcp_f32_e32 v133, v133
	v_rcp_f32_e32 v134, v134
	v_rcp_f32_e32 v135, v135
	v_rcp_f32_e32 v136, v136
	v_rcp_f32_e32 v137, v137
	v_rcp_f32_e32 v138, v138
	v_rcp_f32_e32 v139, v139
	v_pk_mul_f32 v[58:59], v[58:59], v[132:133]
	v_pk_mul_f32 v[60:61], v[60:61], v[134:135]
	v_pk_mul_f32 v[26:27], v[26:27], v[136:137]
	v_pk_mul_f32 v[28:29], v[28:29], v[138:139]
	v_pk_mul_f32 v[58:59], v[62:63], v[58:59]
	v_pk_mul_f32 v[60:61], v[64:65], v[60:61]
	v_pk_mul_f32 v[26:27], v[30:31], v[26:27]
	v_pk_mul_f32 v[28:29], v[32:33], v[28:29]
	v_cvt_pk_bf16_f32 v58, v58, v59
	v_cvt_pk_bf16_f32 v59, v60, v61
	v_cvt_pk_bf16_f32 v26, v26, v27
	v_cvt_pk_bf16_f32 v27, v28, v29
	global_store_dwordx2 v142, v[58:59], s[94:95]
	global_store_dwordx2 v142, v[26:27], s[94:95] offset:128
	s_waitcnt lgkmcnt(0)
	s_mov_b64 s[46:47], 0
	s_andn2_b64 vcc, exec, s[30:31]
	s_mov_b32 s0, s72
	s_barrier
	s_cbranch_vccnz .LBB0_1168
	s_branch .LBB0_1191

.LBB0_1460:
	v_and_b32_e32 v246, 15, v0
	v_lshlrev_b32_e32 v246, 5, v246
	s_lshl_b32 s98, s46, 2
	v_mov_b32_e32 v247, 0
	v_add_u32_e32 v246, s98, v246
	v_lshrrev_b32_e32 v244, 4, v0
	v_add_u32_e32 v244, s73, v244
	v_mov_b32_e32 v245, 0
	v_lshlrev_b32_e32 v244, 3, v244
	v_readlane_b32 s98, v253, 8
	v_readlane_b32 s99, v253, 9
	s_nop 1
	v_lshl_add_u64 v[240:241], s[98:99], 0, v[246:247]
	v_readlane_b32 s98, v253, 10
	v_readlane_b32 s99, v253, 11
	s_nop 1
	v_lshl_add_u64 v[242:243], s[98:99], 0, v[246:247]
	s_add_u32 s98, s62, 0xf000000
	s_addc_u32 s99, s63, 0
	v_lshl_add_u64 v[238:239], s[98:99], 0, v[244:245]
	v_lshlrev_b32_e32 v130, 3, v153
	v_and_b32_e32 v190, 0x78, v130
	v_ashrrev_i32_e32 v152, 4, v153
	v_lshrrev_b32_e32 v130, 1, v153
	v_and_b32_e32 v191, 0x60, v130
	v_or_b32_e32 v130, 4, v190
	v_lshlrev_b32_e32 v132, 2, v152
	v_bitop3_b32 v133, v132, v190, 48 bitop3:0x6c
	v_bitop3_b32 v132, v132, v130, 48 bitop3:0x6c
	v_lshlrev_b32_e32 v134, 9, v152
	v_lshlrev_b32_e32 v132, 2, v132
	v_add_u32_e32 v151, 32, v152
	v_lshlrev_b32_e32 v133, 2, v133
	v_add3_u32 v148, s64, v132, v134
	v_lshlrev_b32_e32 v132, 2, v151
	v_add3_u32 v147, s64, v133, v134
	v_bitop3_b32 v133, v132, v190, 48 bitop3:0x6c
	v_bitop3_b32 v132, v132, v130, 48 bitop3:0x6c
	v_lshlrev_b32_e32 v134, 9, v151
	v_lshlrev_b32_e32 v132, 2, v132
	v_add_u32_e32 v150, 64, v152
	v_lshlrev_b32_e32 v133, 2, v133
	v_add3_u32 v145, s64, v132, v134
	v_lshlrev_b32_e32 v132, 2, v150
	v_add3_u32 v146, s64, v133, v134
	v_bitop3_b32 v133, v132, v190, 48 bitop3:0x6c
	v_bitop3_b32 v132, v132, v130, 48 bitop3:0x6c
	v_lshlrev_b32_e32 v134, 9, v150
	v_lshlrev_b32_e32 v132, 2, v132
	v_add_u32_e32 v149, 0x60, v152
	v_lshlrev_b32_e32 v133, 2, v133
	v_add3_u32 v143, s64, v132, v134
	v_lshlrev_b32_e32 v132, 2, v149
	v_add3_u32 v144, s64, v133, v134
	v_bitop3_b32 v133, v132, v190, 48 bitop3:0x6c
	v_bitop3_b32 v130, v132, v130, 48 bitop3:0x6c
	v_lshlrev_b32_e32 v133, 2, v133
	v_lshlrev_b32_e32 v134, 9, v149
	v_lshlrev_b32_e32 v130, 2, v130
	s_lshl_b64 s[50:51], s[46:47], 2
	v_add3_u32 v141, s64, v133, v134
	v_add3_u32 v140, s64, v130, v134
	v_add_u32_e32 v134, s73, v152
	s_add_u32 s52, s66, s50
	s_addc_u32 s53, s67, s51
	v_lshlrev_b32_e32 v130, 2, v190
	v_ashrrev_i32_e32 v135, 31, v134
	v_lshl_add_u64 v[132:133], s[52:53], 0, v[130:131]
	v_lshlrev_b64 v[134:135], 12, v[134:135]
	v_lshl_add_u64 v[136:137], v[132:133], 0, v[134:135]
	global_load_dwordx2 v[194:195], v[238:239], off offset:0
	global_load_dwordx2 v[196:197], v[238:239], off offset:256
	global_load_dwordx2 v[198:199], v[238:239], off offset:512
	global_load_dwordx2 v[200:201], v[238:239], off offset:768
	global_load_dwordx4 v[202:205], v[240:241], off offset:0
	global_load_dwordx4 v[206:209], v[240:241], off offset:16
	global_load_dwordx4 v[210:213], v[242:243], off offset:0
	global_load_dwordx4 v[214:217], v[242:243], off offset:16
	global_load_dwordx4 v[154:157], v[136:137], off offset:16
	global_load_dwordx4 v[158:161], v[136:137], off
	v_lshl_add_u64 v[136:137], v[134:135], 0, s[36:37]
	v_lshl_add_u64 v[138:139], v[132:133], 0, v[136:137]
	global_load_dwordx4 v[162:165], v[138:139], off offset:16
	global_load_dwordx4 v[166:169], v[138:139], off
	v_lshl_add_u64 v[138:139], v[134:135], 0, s[38:39]
	v_lshl_add_u64 v[174:175], v[132:133], 0, v[138:139]
	global_load_dwordx4 v[170:173], v[174:175], off offset:16
	s_nop 0
	global_load_dwordx4 v[174:177], v[174:175], off
	v_lshl_add_u64 v[186:187], v[134:135], 0, s[40:41]
	v_lshl_add_u64 v[182:183], v[132:133], 0, v[186:187]
	global_load_dwordx4 v[178:181], v[182:183], off offset:16
	s_nop 0
	global_load_dwordx4 v[182:185], v[182:183], off
	v_bfe_u32 v189, v153, 4, 2
	v_and_b32_e32 v188, 15, v153
	v_lshlrev_b32_e32 v193, 4, v189
	v_lshlrev_b32_e32 v153, 7, v153
	v_or_b32_e32 v192, v191, v188
	v_bitop3_b32 v188, v191, v193, v188 bitop3:0x36
	v_and_b32_e32 v153, 0xffff8000, v153
	v_lshlrev_b32_e32 v188, 2, v188
	v_lshl_or_b32 v189, v189, 11, v153
	v_add3_u32 v153, s64, v188, v189
	ds_write2st64_b32 v153, v126, v127 offset1:2
	ds_write2st64_b32 v153, v128, v129 offset0:4 offset1:6
	v_bitop3_b32 v126, v192, v193, 16 bitop3:0x36
	v_lshlrev_b32_e32 v126, 2, v126
	v_add3_u32 v126, s64, v126, v189
	ds_write2st64_b32 v126, v98, v99 offset1:2
	ds_write2st64_b32 v126, v100, v101 offset0:4 offset1:6
	ds_write2st64_b32 v153, v102, v103 offset0:32 offset1:34
	ds_write2st64_b32 v153, v104, v105 offset0:36 offset1:38
	ds_write2st64_b32 v126, v106, v107 offset0:32 offset1:34
	ds_write2st64_b32 v126, v108, v109 offset0:36 offset1:38
	ds_write2st64_b32 v153, v110, v111 offset0:64 offset1:66
	ds_write2st64_b32 v153, v112, v113 offset0:68 offset1:70
	ds_write2st64_b32 v126, v114, v115 offset0:64 offset1:66
	ds_write2st64_b32 v126, v116, v117 offset0:68 offset1:70
	ds_write2st64_b32 v153, v118, v119 offset0:96 offset1:98
	ds_write2st64_b32 v153, v120, v121 offset0:100 offset1:102
	ds_write2st64_b32 v126, v122, v123 offset0:96 offset1:98
	ds_write2st64_b32 v126, v124, v125 offset0:100 offset1:102
	s_waitcnt lgkmcnt(0)
	s_barrier
	ds_read_b128 v[98:101], v147
	ds_read_b128 v[102:105], v148
	v_or_b32_e32 v110, s46, v190
	v_mov_b32_e32 v111, s47
	s_lshl_b64 s[0:1], s[0:1], 2
	s_mov_b64 s[46:47], 0
	s_andn2_b64 vcc, exec, s[44:45]
	s_waitcnt vmcnt(0) lgkmcnt(0)
	v_pk_add_f32 v[156:157], v[156:157], v[194:195] op_sel_hi:[1,0] neg_lo:[0,1] neg_hi:[0,1]
	v_pk_mul_f32 v[156:157], v[156:157], v[194:195] op_sel:[0,1]
	v_pk_fma_f32 v[156:157], v[208:209], v[156:157], v[216:217]
	v_pk_fma_f32 v[104:105], v[156:157], s[42:43], v[104:105] op_sel_hi:[1,0,1]
	v_pk_add_f32 v[160:161], v[160:161], v[194:195] op_sel_hi:[1,0] neg_lo:[0,1] neg_hi:[0,1]
	v_pk_mul_f32 v[160:161], v[160:161], v[194:195] op_sel:[0,1]
	v_pk_fma_f32 v[160:161], v[204:205], v[160:161], v[212:213]
	v_pk_fma_f32 v[108:109], v[160:161], s[42:43], v[100:101] op_sel_hi:[1,0,1]
	v_pk_add_f32 v[158:159], v[158:159], v[194:195] op_sel_hi:[1,0] neg_lo:[0,1] neg_hi:[0,1]
	v_pk_mul_f32 v[158:159], v[158:159], v[194:195] op_sel:[0,1]
	v_pk_fma_f32 v[158:159], v[202:203], v[158:159], v[210:211]
	v_pk_fma_f32 v[106:107], v[158:159], s[42:43], v[98:99] op_sel_hi:[1,0,1]
	v_lshl_add_u64 v[100:101], s[66:67], 0, v[134:135]
	v_lshlrev_b64 v[98:99], 2, v[110:111]
	v_lshl_add_u64 v[100:101], v[100:101], 0, v[98:99]
	v_pk_add_f32 v[154:155], v[154:155], v[194:195] op_sel_hi:[1,0] neg_lo:[0,1] neg_hi:[0,1]
	v_pk_mul_f32 v[154:155], v[154:155], v[194:195] op_sel:[0,1]
	v_pk_fma_f32 v[154:155], v[206:207], v[154:155], v[214:215]
	v_pk_fma_f32 v[102:103], v[154:155], s[42:43], v[102:103] op_sel_hi:[1,0,1]
	global_store_dwordx4 v[100:101], v[106:109], off
	global_store_dwordx4 v[100:101], v[102:105], off offset:16
	ds_read_b128 v[100:103], v146
	ds_read_b128 v[104:107], v145
	v_add_u32_e32 v108, s73, v151
	v_ashrrev_i32_e32 v109, 31, v108
	v_lshlrev_b64 v[108:109], 12, v[108:109]
	v_lshl_add_u64 v[108:109], s[66:67], 0, v[108:109]
	s_waitcnt lgkmcnt(1)
	v_pk_add_f32 v[168:169], v[168:169], v[196:197] op_sel_hi:[1,0] neg_lo:[0,1] neg_hi:[0,1]
	v_pk_mul_f32 v[168:169], v[168:169], v[196:197] op_sel:[0,1]
	v_pk_fma_f32 v[168:169], v[204:205], v[168:169], v[212:213]
	v_pk_fma_f32 v[102:103], v[168:169], s[42:43], v[102:103] op_sel_hi:[1,0,1]
	v_pk_add_f32 v[166:167], v[166:167], v[196:197] op_sel_hi:[1,0] neg_lo:[0,1] neg_hi:[0,1]
	v_pk_mul_f32 v[166:167], v[166:167], v[196:197] op_sel:[0,1]
	v_pk_fma_f32 v[166:167], v[202:203], v[166:167], v[210:211]
	v_pk_fma_f32 v[100:101], v[166:167], s[42:43], v[100:101] op_sel_hi:[1,0,1]
	v_lshl_add_u64 v[108:109], v[108:109], 0, v[98:99]
	global_store_dwordx4 v[108:109], v[100:103], off
	s_waitcnt lgkmcnt(0)
	s_nop 0
	v_pk_add_f32 v[164:165], v[164:165], v[196:197] op_sel_hi:[1,0] neg_lo:[0,1] neg_hi:[0,1]
	v_pk_mul_f32 v[164:165], v[164:165], v[196:197] op_sel:[0,1]
	v_pk_fma_f32 v[164:165], v[208:209], v[164:165], v[216:217]
	v_pk_fma_f32 v[102:103], v[164:165], s[42:43], v[106:107] op_sel_hi:[1,0,1]
	v_pk_add_f32 v[162:163], v[162:163], v[196:197] op_sel_hi:[1,0] neg_lo:[0,1] neg_hi:[0,1]
	v_pk_mul_f32 v[162:163], v[162:163], v[196:197] op_sel:[0,1]
	v_pk_fma_f32 v[162:163], v[206:207], v[162:163], v[214:215]
	v_pk_fma_f32 v[100:101], v[162:163], s[42:43], v[104:105] op_sel_hi:[1,0,1]
	global_store_dwordx4 v[108:109], v[100:103], off offset:16
	ds_read_b128 v[100:103], v144
	ds_read_b128 v[104:107], v143
	v_add_u32_e32 v108, s73, v150
	v_ashrrev_i32_e32 v109, 31, v108
	v_lshlrev_b64 v[108:109], 12, v[108:109]
	v_lshl_add_u64 v[108:109], s[66:67], 0, v[108:109]
	s_waitcnt lgkmcnt(1)
	v_pk_add_f32 v[176:177], v[176:177], v[198:199] op_sel_hi:[1,0] neg_lo:[0,1] neg_hi:[0,1]
	v_pk_mul_f32 v[176:177], v[176:177], v[198:199] op_sel:[0,1]
	v_pk_fma_f32 v[176:177], v[204:205], v[176:177], v[212:213]
	v_pk_fma_f32 v[102:103], v[176:177], s[42:43], v[102:103] op_sel_hi:[1,0,1]
	v_pk_add_f32 v[174:175], v[174:175], v[198:199] op_sel_hi:[1,0] neg_lo:[0,1] neg_hi:[0,1]
	v_pk_mul_f32 v[174:175], v[174:175], v[198:199] op_sel:[0,1]
	v_pk_fma_f32 v[174:175], v[202:203], v[174:175], v[210:211]
	v_pk_fma_f32 v[100:101], v[174:175], s[42:43], v[100:101] op_sel_hi:[1,0,1]
	v_lshl_add_u64 v[108:109], v[108:109], 0, v[98:99]
	global_store_dwordx4 v[108:109], v[100:103], off
	s_waitcnt lgkmcnt(0)
	s_nop 0
	v_pk_add_f32 v[172:173], v[172:173], v[198:199] op_sel_hi:[1,0] neg_lo:[0,1] neg_hi:[0,1]
	v_pk_mul_f32 v[172:173], v[172:173], v[198:199] op_sel:[0,1]
	v_pk_fma_f32 v[172:173], v[208:209], v[172:173], v[216:217]
	v_pk_fma_f32 v[102:103], v[172:173], s[42:43], v[106:107] op_sel_hi:[1,0,1]
	v_pk_add_f32 v[170:171], v[170:171], v[198:199] op_sel_hi:[1,0] neg_lo:[0,1] neg_hi:[0,1]
	v_pk_mul_f32 v[170:171], v[170:171], v[198:199] op_sel:[0,1]
	v_pk_fma_f32 v[170:171], v[206:207], v[170:171], v[214:215]
	v_pk_fma_f32 v[100:101], v[170:171], s[42:43], v[104:105] op_sel_hi:[1,0,1]
	global_store_dwordx4 v[108:109], v[100:103], off offset:16
	ds_read_b128 v[100:103], v141
	ds_read_b128 v[104:107], v140
	v_add_u32_e32 v108, s73, v149
	v_ashrrev_i32_e32 v109, 31, v108
	v_lshlrev_b64 v[108:109], 12, v[108:109]
	v_lshl_add_u64 v[108:109], s[66:67], 0, v[108:109]
	s_waitcnt lgkmcnt(1)
	v_pk_add_f32 v[184:185], v[184:185], v[200:201] op_sel_hi:[1,0] neg_lo:[0,1] neg_hi:[0,1]
	v_pk_mul_f32 v[184:185], v[184:185], v[200:201] op_sel:[0,1]
	v_pk_fma_f32 v[184:185], v[204:205], v[184:185], v[212:213]
	v_pk_fma_f32 v[102:103], v[184:185], s[42:43], v[102:103] op_sel_hi:[1,0,1]
	v_pk_add_f32 v[182:183], v[182:183], v[200:201] op_sel_hi:[1,0] neg_lo:[0,1] neg_hi:[0,1]
	v_pk_mul_f32 v[182:183], v[182:183], v[200:201] op_sel:[0,1]
	v_pk_fma_f32 v[182:183], v[202:203], v[182:183], v[210:211]
	v_pk_fma_f32 v[100:101], v[182:183], s[42:43], v[100:101] op_sel_hi:[1,0,1]
	v_lshl_add_u64 v[108:109], v[108:109], 0, v[98:99]
	global_store_dwordx4 v[108:109], v[100:103], off
	s_waitcnt lgkmcnt(0)
	s_nop 0
	v_pk_add_f32 v[180:181], v[180:181], v[200:201] op_sel_hi:[1,0] neg_lo:[0,1] neg_hi:[0,1]
	v_pk_mul_f32 v[180:181], v[180:181], v[200:201] op_sel:[0,1]
	v_pk_fma_f32 v[180:181], v[208:209], v[180:181], v[216:217]
	v_pk_fma_f32 v[102:103], v[180:181], s[42:43], v[106:107] op_sel_hi:[1,0,1]
	v_pk_add_f32 v[178:179], v[178:179], v[200:201] op_sel_hi:[1,0] neg_lo:[0,1] neg_hi:[0,1]
	v_pk_mul_f32 v[178:179], v[178:179], v[200:201] op_sel:[0,1]
	v_pk_fma_f32 v[178:179], v[206:207], v[178:179], v[214:215]
	v_pk_fma_f32 v[100:101], v[178:179], s[42:43], v[104:105] op_sel_hi:[1,0,1]
	global_store_dwordx4 v[108:109], v[100:103], off offset:16
	s_waitcnt lgkmcnt(0)
	s_barrier
	s_nop 0
	v_lshl_add_u64 v[100:101], s[66:67], 0, v[130:131]
	v_lshl_add_u64 v[128:129], v[100:101], 0, v[134:135]
	v_lshl_add_u64 v[106:107], v[128:129], 0, s[0:1]
	global_load_dwordx2 v[194:195], v[238:239], off offset:0
	global_load_dwordx2 v[196:197], v[238:239], off offset:256
	global_load_dwordx2 v[198:199], v[238:239], off offset:512
	global_load_dwordx2 v[200:201], v[238:239], off offset:768
	global_load_dwordx4 v[202:205], v[240:241], off offset:512
	global_load_dwordx4 v[206:209], v[240:241], off offset:528
	global_load_dwordx4 v[210:213], v[242:243], off offset:512
	global_load_dwordx4 v[214:217], v[242:243], off offset:528
	global_load_dwordx4 v[102:105], v[106:107], off offset:16
	s_nop 0
	global_load_dwordx4 v[106:109], v[106:107], off
	v_lshl_add_u64 v[158:159], v[100:101], 0, v[136:137]
	v_lshl_add_u64 v[114:115], v[158:159], 0, s[0:1]
	global_load_dwordx4 v[110:113], v[114:115], off offset:16
	s_nop 0
	global_load_dwordx4 v[114:117], v[114:115], off
	v_lshl_add_u64 v[138:139], v[100:101], 0, v[138:139]
	v_lshl_add_u64 v[122:123], v[138:139], 0, s[0:1]
	global_load_dwordx4 v[118:121], v[122:123], off offset:16
	s_nop 0
	global_load_dwordx4 v[122:125], v[122:123], off
	v_lshl_add_u64 v[160:161], v[100:101], 0, v[186:187]
	v_lshl_add_u64 v[154:155], v[160:161], 0, s[0:1]
	global_load_dwordx4 v[134:137], v[154:155], off offset:16
	s_nop 0
	global_load_dwordx4 v[154:157], v[154:155], off
	ds_write2st64_b32 v153, v66, v67 offset1:2
	ds_write2st64_b32 v153, v68, v69 offset0:4 offset1:6
	ds_write2st64_b32 v126, v70, v71 offset1:2
	ds_write2st64_b32 v126, v72, v73 offset0:4 offset1:6
	ds_write2st64_b32 v153, v74, v75 offset0:32 offset1:34
	ds_write2st64_b32 v153, v76, v77 offset0:36 offset1:38
	ds_write2st64_b32 v126, v78, v79 offset0:32 offset1:34
	ds_write2st64_b32 v126, v80, v81 offset0:36 offset1:38
	ds_write2st64_b32 v153, v82, v83 offset0:64 offset1:66
	ds_write2st64_b32 v153, v84, v85 offset0:68 offset1:70
	ds_write2st64_b32 v126, v86, v87 offset0:64 offset1:66
	ds_write2st64_b32 v126, v88, v89 offset0:68 offset1:70
	ds_write2st64_b32 v153, v90, v91 offset0:96 offset1:98
	ds_write2st64_b32 v153, v92, v93 offset0:100 offset1:102
	ds_write2st64_b32 v126, v94, v95 offset0:96 offset1:98
	ds_write2st64_b32 v126, v96, v97 offset0:100 offset1:102
	s_waitcnt lgkmcnt(0)
	s_barrier
	ds_read_b128 v[66:69], v147
	ds_read_b128 v[70:73], v148
	v_lshl_add_u64 v[74:75], v[128:129], 0, s[50:51]
	s_waitcnt vmcnt(6) lgkmcnt(1)
	v_pk_add_f32 v[108:109], v[108:109], v[194:195] op_sel_hi:[1,0] neg_lo:[0,1] neg_hi:[0,1]
	v_pk_mul_f32 v[108:109], v[108:109], v[194:195] op_sel:[0,1]
	v_pk_fma_f32 v[108:109], v[204:205], v[108:109], v[212:213]
	v_pk_fma_f32 v[68:69], v[108:109], s[42:43], v[68:69] op_sel_hi:[1,0,1]
	v_pk_add_f32 v[106:107], v[106:107], v[194:195] op_sel_hi:[1,0] neg_lo:[0,1] neg_hi:[0,1]
	v_pk_mul_f32 v[106:107], v[106:107], v[194:195] op_sel:[0,1]
	v_pk_fma_f32 v[106:107], v[202:203], v[106:107], v[210:211]
	v_pk_fma_f32 v[66:67], v[106:107], s[42:43], v[66:67] op_sel_hi:[1,0,1]
	global_store_dwordx4 v[74:75], v[66:69], off offset:512
	s_waitcnt lgkmcnt(0)
	s_nop 0
	v_pk_add_f32 v[104:105], v[104:105], v[194:195] op_sel_hi:[1,0] neg_lo:[0,1] neg_hi:[0,1]
	v_pk_mul_f32 v[104:105], v[104:105], v[194:195] op_sel:[0,1]
	v_pk_fma_f32 v[104:105], v[208:209], v[104:105], v[216:217]
	v_pk_fma_f32 v[68:69], v[104:105], s[42:43], v[72:73] op_sel_hi:[1,0,1]
	v_pk_add_f32 v[102:103], v[102:103], v[194:195] op_sel_hi:[1,0] neg_lo:[0,1] neg_hi:[0,1]
	v_pk_mul_f32 v[102:103], v[102:103], v[194:195] op_sel:[0,1]
	v_pk_fma_f32 v[102:103], v[206:207], v[102:103], v[214:215]
	v_pk_fma_f32 v[66:67], v[102:103], s[42:43], v[70:71] op_sel_hi:[1,0,1]
	global_store_dwordx4 v[74:75], v[66:69], off offset:528
	ds_read_b128 v[66:69], v146
	ds_read_b128 v[70:73], v145
	v_lshl_add_u64 v[74:75], v[158:159], 0, s[50:51]
	s_waitcnt vmcnt(6) lgkmcnt(1)
	v_pk_add_f32 v[116:117], v[116:117], v[196:197] op_sel_hi:[1,0] neg_lo:[0,1] neg_hi:[0,1]
	v_pk_mul_f32 v[116:117], v[116:117], v[196:197] op_sel:[0,1]
	v_pk_fma_f32 v[116:117], v[204:205], v[116:117], v[212:213]
	v_pk_fma_f32 v[68:69], v[116:117], s[42:43], v[68:69] op_sel_hi:[1,0,1]
	v_pk_add_f32 v[114:115], v[114:115], v[196:197] op_sel_hi:[1,0] neg_lo:[0,1] neg_hi:[0,1]
	v_pk_mul_f32 v[114:115], v[114:115], v[196:197] op_sel:[0,1]
	v_pk_fma_f32 v[114:115], v[202:203], v[114:115], v[210:211]
	v_pk_fma_f32 v[66:67], v[114:115], s[42:43], v[66:67] op_sel_hi:[1,0,1]
	global_store_dwordx4 v[74:75], v[66:69], off offset:512
	s_waitcnt lgkmcnt(0)
	s_nop 0
	v_pk_add_f32 v[112:113], v[112:113], v[196:197] op_sel_hi:[1,0] neg_lo:[0,1] neg_hi:[0,1]
	v_pk_mul_f32 v[112:113], v[112:113], v[196:197] op_sel:[0,1]
	v_pk_fma_f32 v[112:113], v[208:209], v[112:113], v[216:217]
	v_pk_fma_f32 v[68:69], v[112:113], s[42:43], v[72:73] op_sel_hi:[1,0,1]
	v_pk_add_f32 v[110:111], v[110:111], v[196:197] op_sel_hi:[1,0] neg_lo:[0,1] neg_hi:[0,1]
	v_pk_mul_f32 v[110:111], v[110:111], v[196:197] op_sel:[0,1]
	v_pk_fma_f32 v[110:111], v[206:207], v[110:111], v[214:215]
	v_pk_fma_f32 v[66:67], v[110:111], s[42:43], v[70:71] op_sel_hi:[1,0,1]
	global_store_dwordx4 v[74:75], v[66:69], off offset:528
	ds_read_b128 v[66:69], v144
	ds_read_b128 v[70:73], v143
	v_lshl_add_u64 v[74:75], v[138:139], 0, s[50:51]
	s_waitcnt vmcnt(6) lgkmcnt(1)
	v_pk_add_f32 v[124:125], v[124:125], v[198:199] op_sel_hi:[1,0] neg_lo:[0,1] neg_hi:[0,1]
	v_pk_mul_f32 v[124:125], v[124:125], v[198:199] op_sel:[0,1]
	v_pk_fma_f32 v[124:125], v[204:205], v[124:125], v[212:213]
	v_pk_fma_f32 v[68:69], v[124:125], s[42:43], v[68:69] op_sel_hi:[1,0,1]
	v_pk_add_f32 v[122:123], v[122:123], v[198:199] op_sel_hi:[1,0] neg_lo:[0,1] neg_hi:[0,1]
	v_pk_mul_f32 v[122:123], v[122:123], v[198:199] op_sel:[0,1]
	v_pk_fma_f32 v[122:123], v[202:203], v[122:123], v[210:211]
	v_pk_fma_f32 v[66:67], v[122:123], s[42:43], v[66:67] op_sel_hi:[1,0,1]
	global_store_dwordx4 v[74:75], v[66:69], off offset:512
	s_waitcnt lgkmcnt(0)
	s_nop 0
	v_pk_add_f32 v[120:121], v[120:121], v[198:199] op_sel_hi:[1,0] neg_lo:[0,1] neg_hi:[0,1]
	v_pk_mul_f32 v[120:121], v[120:121], v[198:199] op_sel:[0,1]
	v_pk_fma_f32 v[120:121], v[208:209], v[120:121], v[216:217]
	v_pk_fma_f32 v[68:69], v[120:121], s[42:43], v[72:73] op_sel_hi:[1,0,1]
	v_pk_add_f32 v[118:119], v[118:119], v[198:199] op_sel_hi:[1,0] neg_lo:[0,1] neg_hi:[0,1]
	v_pk_mul_f32 v[118:119], v[118:119], v[198:199] op_sel:[0,1]
	v_pk_fma_f32 v[118:119], v[206:207], v[118:119], v[214:215]
	v_pk_fma_f32 v[66:67], v[118:119], s[42:43], v[70:71] op_sel_hi:[1,0,1]
	global_store_dwordx4 v[74:75], v[66:69], off offset:528
	ds_read_b128 v[66:69], v141
	ds_read_b128 v[70:73], v140
	v_lshl_add_u64 v[74:75], v[160:161], 0, s[50:51]
	s_waitcnt vmcnt(6) lgkmcnt(1)
	v_pk_add_f32 v[156:157], v[156:157], v[200:201] op_sel_hi:[1,0] neg_lo:[0,1] neg_hi:[0,1]
	v_pk_mul_f32 v[156:157], v[156:157], v[200:201] op_sel:[0,1]
	v_pk_fma_f32 v[156:157], v[204:205], v[156:157], v[212:213]
	v_pk_fma_f32 v[68:69], v[156:157], s[42:43], v[68:69] op_sel_hi:[1,0,1]
	v_pk_add_f32 v[154:155], v[154:155], v[200:201] op_sel_hi:[1,0] neg_lo:[0,1] neg_hi:[0,1]
	v_pk_mul_f32 v[154:155], v[154:155], v[200:201] op_sel:[0,1]
	v_pk_fma_f32 v[154:155], v[202:203], v[154:155], v[210:211]
	v_pk_fma_f32 v[66:67], v[154:155], s[42:43], v[66:67] op_sel_hi:[1,0,1]
	global_store_dwordx4 v[74:75], v[66:69], off offset:512
	s_waitcnt lgkmcnt(0)
	s_nop 0
	v_pk_add_f32 v[136:137], v[136:137], v[200:201] op_sel_hi:[1,0] neg_lo:[0,1] neg_hi:[0,1]
	v_pk_mul_f32 v[136:137], v[136:137], v[200:201] op_sel:[0,1]
	v_pk_fma_f32 v[136:137], v[208:209], v[136:137], v[216:217]
	v_pk_fma_f32 v[68:69], v[136:137], s[42:43], v[72:73] op_sel_hi:[1,0,1]
	v_pk_add_f32 v[134:135], v[134:135], v[200:201] op_sel_hi:[1,0] neg_lo:[0,1] neg_hi:[0,1]
	v_pk_mul_f32 v[134:135], v[134:135], v[200:201] op_sel:[0,1]
	v_pk_fma_f32 v[134:135], v[206:207], v[134:135], v[214:215]
	v_pk_fma_f32 v[66:67], v[134:135], s[42:43], v[70:71] op_sel_hi:[1,0,1]
	global_store_dwordx4 v[74:75], v[66:69], off offset:528
	s_waitcnt lgkmcnt(0)
	s_barrier
	s_nop 0
	v_add_u32_e32 v66, s54, v152
	v_ashrrev_i32_e32 v67, 31, v66
	v_lshlrev_b64 v[102:103], 12, v[66:67]
	v_lshl_add_u64 v[70:71], v[132:133], 0, v[102:103]
	global_load_dwordx2 v[194:195], v[238:239], off offset:1024
	global_load_dwordx2 v[196:197], v[238:239], off offset:1280
	global_load_dwordx2 v[198:199], v[238:239], off offset:1536
	global_load_dwordx2 v[200:201], v[238:239], off offset:1792
	global_load_dwordx4 v[202:205], v[240:241], off offset:0
	global_load_dwordx4 v[206:209], v[240:241], off offset:16
	global_load_dwordx4 v[210:213], v[242:243], off offset:0
	global_load_dwordx4 v[214:217], v[242:243], off offset:16
	global_load_dwordx4 v[66:69], v[70:71], off offset:16
	s_nop 0
	global_load_dwordx4 v[70:73], v[70:71], off
	v_lshl_add_u64 v[104:105], v[102:103], 0, s[36:37]
	v_lshl_add_u64 v[78:79], v[132:133], 0, v[104:105]
	global_load_dwordx4 v[74:77], v[78:79], off offset:16
	s_nop 0
	global_load_dwordx4 v[78:81], v[78:79], off
	v_lshl_add_u64 v[106:107], v[102:103], 0, s[38:39]
	v_lshl_add_u64 v[86:87], v[132:133], 0, v[106:107]
	global_load_dwordx4 v[82:85], v[86:87], off offset:16
	s_nop 0
	global_load_dwordx4 v[86:89], v[86:87], off
	v_lshl_add_u64 v[108:109], v[102:103], 0, s[40:41]
	v_lshl_add_u64 v[94:95], v[132:133], 0, v[108:109]
	global_load_dwordx4 v[90:93], v[94:95], off offset:16
	s_nop 0
	global_load_dwordx4 v[94:97], v[94:95], off
	ds_write2st64_b32 v153, v34, v35 offset1:2
	ds_write2st64_b32 v153, v36, v37 offset0:4 offset1:6
	ds_write2st64_b32 v126, v38, v39 offset1:2
	ds_write2st64_b32 v126, v40, v41 offset0:4 offset1:6
	ds_write2st64_b32 v153, v42, v43 offset0:32 offset1:34
	ds_write2st64_b32 v153, v44, v45 offset0:36 offset1:38
	ds_write2st64_b32 v126, v46, v47 offset0:32 offset1:34
	ds_write2st64_b32 v126, v48, v49 offset0:36 offset1:38
	ds_write2st64_b32 v153, v50, v51 offset0:64 offset1:66
	ds_write2st64_b32 v153, v52, v53 offset0:68 offset1:70
	ds_write2st64_b32 v126, v54, v55 offset0:64 offset1:66
	ds_write2st64_b32 v126, v56, v57 offset0:68 offset1:70
	ds_write2st64_b32 v153, v58, v59 offset0:96 offset1:98
	ds_write2st64_b32 v153, v60, v61 offset0:100 offset1:102
	ds_write2st64_b32 v126, v62, v63 offset0:96 offset1:98
	ds_write2st64_b32 v126, v64, v65 offset0:100 offset1:102
	s_waitcnt lgkmcnt(0)
	s_barrier
	ds_read_b128 v[34:37], v147
	ds_read_b128 v[38:41], v148
	v_lshl_add_u64 v[42:43], s[66:67], 0, v[102:103]
	v_lshl_add_u64 v[42:43], v[42:43], 0, v[98:99]
	s_waitcnt vmcnt(6) lgkmcnt(1)
	v_pk_add_f32 v[72:73], v[72:73], v[194:195] op_sel_hi:[1,0] neg_lo:[0,1] neg_hi:[0,1]
	v_pk_mul_f32 v[72:73], v[72:73], v[194:195] op_sel:[0,1]
	v_pk_fma_f32 v[72:73], v[204:205], v[72:73], v[212:213]
	v_pk_fma_f32 v[36:37], v[72:73], s[42:43], v[36:37] op_sel_hi:[1,0,1]
	v_pk_add_f32 v[70:71], v[70:71], v[194:195] op_sel_hi:[1,0] neg_lo:[0,1] neg_hi:[0,1]
	v_pk_mul_f32 v[70:71], v[70:71], v[194:195] op_sel:[0,1]
	v_pk_fma_f32 v[70:71], v[202:203], v[70:71], v[210:211]
	v_pk_fma_f32 v[34:35], v[70:71], s[42:43], v[34:35] op_sel_hi:[1,0,1]
	global_store_dwordx4 v[42:43], v[34:37], off
	v_lshl_add_u64 v[70:71], v[100:101], 0, v[106:107]
	v_lshl_add_u64 v[54:55], v[70:71], 0, s[0:1]
	s_waitcnt lgkmcnt(0)
	v_pk_add_f32 v[68:69], v[68:69], v[194:195] op_sel_hi:[1,0] neg_lo:[0,1] neg_hi:[0,1]
	v_pk_mul_f32 v[68:69], v[68:69], v[194:195] op_sel:[0,1]
	v_pk_fma_f32 v[68:69], v[208:209], v[68:69], v[216:217]
	v_pk_fma_f32 v[36:37], v[68:69], s[42:43], v[40:41] op_sel_hi:[1,0,1]
	v_pk_add_f32 v[66:67], v[66:67], v[194:195] op_sel_hi:[1,0] neg_lo:[0,1] neg_hi:[0,1]
	v_pk_mul_f32 v[66:67], v[66:67], v[194:195] op_sel:[0,1]
	v_pk_fma_f32 v[66:67], v[206:207], v[66:67], v[214:215]
	v_pk_fma_f32 v[34:35], v[66:67], s[42:43], v[38:39] op_sel_hi:[1,0,1]
	global_store_dwordx4 v[42:43], v[34:37], off offset:16
	ds_read_b128 v[34:37], v146
	ds_read_b128 v[38:41], v145
	v_add_u32_e32 v42, s54, v151
	v_ashrrev_i32_e32 v43, 31, v42
	v_lshlrev_b64 v[42:43], 12, v[42:43]
	v_lshl_add_u64 v[42:43], s[66:67], 0, v[42:43]
	s_waitcnt vmcnt(6) lgkmcnt(1)
	v_pk_add_f32 v[80:81], v[80:81], v[196:197] op_sel_hi:[1,0] neg_lo:[0,1] neg_hi:[0,1]
	v_pk_mul_f32 v[80:81], v[80:81], v[196:197] op_sel:[0,1]
	v_pk_fma_f32 v[80:81], v[204:205], v[80:81], v[212:213]
	v_pk_fma_f32 v[36:37], v[80:81], s[42:43], v[36:37] op_sel_hi:[1,0,1]
	v_pk_add_f32 v[78:79], v[78:79], v[196:197] op_sel_hi:[1,0] neg_lo:[0,1] neg_hi:[0,1]
	v_pk_mul_f32 v[78:79], v[78:79], v[196:197] op_sel:[0,1]
	v_pk_fma_f32 v[78:79], v[202:203], v[78:79], v[210:211]
	v_pk_fma_f32 v[34:35], v[78:79], s[42:43], v[34:35] op_sel_hi:[1,0,1]
	v_lshl_add_u64 v[42:43], v[42:43], 0, v[98:99]
	global_store_dwordx4 v[42:43], v[34:37], off
	v_lshl_add_u64 v[66:67], v[100:101], 0, v[102:103]
	v_lshl_add_u64 v[68:69], v[100:101], 0, v[104:105]
	s_waitcnt lgkmcnt(0)
	v_pk_add_f32 v[76:77], v[76:77], v[196:197] op_sel_hi:[1,0] neg_lo:[0,1] neg_hi:[0,1]
	v_pk_mul_f32 v[76:77], v[76:77], v[196:197] op_sel:[0,1]
	v_pk_fma_f32 v[76:77], v[208:209], v[76:77], v[216:217]
	v_pk_fma_f32 v[36:37], v[76:77], s[42:43], v[40:41] op_sel_hi:[1,0,1]
	v_pk_add_f32 v[74:75], v[74:75], v[196:197] op_sel_hi:[1,0] neg_lo:[0,1] neg_hi:[0,1]
	v_pk_mul_f32 v[74:75], v[74:75], v[196:197] op_sel:[0,1]
	v_pk_fma_f32 v[74:75], v[206:207], v[74:75], v[214:215]
	v_pk_fma_f32 v[34:35], v[74:75], s[42:43], v[38:39] op_sel_hi:[1,0,1]
	global_store_dwordx4 v[42:43], v[34:37], off offset:16
	ds_read_b128 v[34:37], v144
	ds_read_b128 v[38:41], v143
	v_add_u32_e32 v42, s54, v150
	v_ashrrev_i32_e32 v43, 31, v42
	v_lshlrev_b64 v[42:43], 12, v[42:43]
	v_lshl_add_u64 v[42:43], s[66:67], 0, v[42:43]
	s_waitcnt vmcnt(6) lgkmcnt(1)
	v_pk_add_f32 v[88:89], v[88:89], v[198:199] op_sel_hi:[1,0] neg_lo:[0,1] neg_hi:[0,1]
	v_pk_mul_f32 v[88:89], v[88:89], v[198:199] op_sel:[0,1]
	v_pk_fma_f32 v[88:89], v[204:205], v[88:89], v[212:213]
	v_pk_fma_f32 v[36:37], v[88:89], s[42:43], v[36:37] op_sel_hi:[1,0,1]
	v_pk_add_f32 v[86:87], v[86:87], v[198:199] op_sel_hi:[1,0] neg_lo:[0,1] neg_hi:[0,1]
	v_pk_mul_f32 v[86:87], v[86:87], v[198:199] op_sel:[0,1]
	v_pk_fma_f32 v[86:87], v[202:203], v[86:87], v[210:211]
	v_pk_fma_f32 v[34:35], v[86:87], s[42:43], v[34:35] op_sel_hi:[1,0,1]
	v_lshl_add_u64 v[42:43], v[42:43], 0, v[98:99]
	global_store_dwordx4 v[42:43], v[34:37], off
	v_lshl_add_u64 v[46:47], v[68:69], 0, s[0:1]
	v_lshl_add_u64 v[72:73], v[100:101], 0, v[108:109]
	s_waitcnt lgkmcnt(0)
	v_pk_add_f32 v[84:85], v[84:85], v[198:199] op_sel_hi:[1,0] neg_lo:[0,1] neg_hi:[0,1]
	v_pk_mul_f32 v[84:85], v[84:85], v[198:199] op_sel:[0,1]
	v_pk_fma_f32 v[84:85], v[208:209], v[84:85], v[216:217]
	v_pk_fma_f32 v[36:37], v[84:85], s[42:43], v[40:41] op_sel_hi:[1,0,1]
	v_pk_add_f32 v[82:83], v[82:83], v[198:199] op_sel_hi:[1,0] neg_lo:[0,1] neg_hi:[0,1]
	v_pk_mul_f32 v[82:83], v[82:83], v[198:199] op_sel:[0,1]
	v_pk_fma_f32 v[82:83], v[206:207], v[82:83], v[214:215]
	v_pk_fma_f32 v[34:35], v[82:83], s[42:43], v[38:39] op_sel_hi:[1,0,1]
	global_store_dwordx4 v[42:43], v[34:37], off offset:16
	ds_read_b128 v[34:37], v141
	ds_read_b128 v[38:41], v140
	v_add_u32_e32 v42, s54, v149
	v_ashrrev_i32_e32 v43, 31, v42
	v_lshlrev_b64 v[42:43], 12, v[42:43]
	v_lshl_add_u64 v[42:43], s[66:67], 0, v[42:43]
	s_waitcnt vmcnt(6) lgkmcnt(1)
	v_pk_add_f32 v[96:97], v[96:97], v[200:201] op_sel_hi:[1,0] neg_lo:[0,1] neg_hi:[0,1]
	v_pk_mul_f32 v[96:97], v[96:97], v[200:201] op_sel:[0,1]
	v_pk_fma_f32 v[96:97], v[204:205], v[96:97], v[212:213]
	v_pk_fma_f32 v[36:37], v[96:97], s[42:43], v[36:37] op_sel_hi:[1,0,1]
	v_pk_add_f32 v[94:95], v[94:95], v[200:201] op_sel_hi:[1,0] neg_lo:[0,1] neg_hi:[0,1]
	v_pk_mul_f32 v[94:95], v[94:95], v[200:201] op_sel:[0,1]
	v_pk_fma_f32 v[94:95], v[202:203], v[94:95], v[210:211]
	v_pk_fma_f32 v[34:35], v[94:95], s[42:43], v[34:35] op_sel_hi:[1,0,1]
	v_lshl_add_u64 v[42:43], v[42:43], 0, v[98:99]
	global_store_dwordx4 v[42:43], v[34:37], off
	v_lshl_add_u64 v[62:63], v[72:73], 0, s[0:1]
	s_waitcnt lgkmcnt(0)
	v_pk_add_f32 v[92:93], v[92:93], v[200:201] op_sel_hi:[1,0] neg_lo:[0,1] neg_hi:[0,1]
	v_pk_mul_f32 v[92:93], v[92:93], v[200:201] op_sel:[0,1]
	v_pk_fma_f32 v[92:93], v[208:209], v[92:93], v[216:217]
	v_pk_fma_f32 v[36:37], v[92:93], s[42:43], v[40:41] op_sel_hi:[1,0,1]
	v_pk_add_f32 v[90:91], v[90:91], v[200:201] op_sel_hi:[1,0] neg_lo:[0,1] neg_hi:[0,1]
	v_pk_mul_f32 v[90:91], v[90:91], v[200:201] op_sel:[0,1]
	v_pk_fma_f32 v[90:91], v[206:207], v[90:91], v[214:215]
	v_pk_fma_f32 v[34:35], v[90:91], s[42:43], v[38:39] op_sel_hi:[1,0,1]
	global_store_dwordx4 v[42:43], v[34:37], off offset:16
	v_lshl_add_u64 v[38:39], v[66:67], 0, s[0:1]
	s_waitcnt lgkmcnt(0)
	s_barrier
	global_load_dwordx2 v[194:195], v[238:239], off offset:1024
	global_load_dwordx2 v[196:197], v[238:239], off offset:1280
	global_load_dwordx2 v[198:199], v[238:239], off offset:1536
	global_load_dwordx2 v[200:201], v[238:239], off offset:1792
	global_load_dwordx4 v[202:205], v[240:241], off offset:512
	global_load_dwordx4 v[206:209], v[240:241], off offset:528
	global_load_dwordx4 v[210:213], v[242:243], off offset:512
	global_load_dwordx4 v[214:217], v[242:243], off offset:528
	global_load_dwordx4 v[34:37], v[38:39], off offset:16
	s_nop 0
	global_load_dwordx4 v[38:41], v[38:39], off
	s_nop 0
	global_load_dwordx4 v[42:45], v[46:47], off offset:16
	s_nop 0
	global_load_dwordx4 v[46:49], v[46:47], off
	s_nop 0
	global_load_dwordx4 v[50:53], v[54:55], off offset:16
	s_nop 0
	global_load_dwordx4 v[54:57], v[54:55], off
	s_nop 0
	global_load_dwordx4 v[58:61], v[62:63], off offset:16
	s_nop 0
	global_load_dwordx4 v[62:65], v[62:63], off
	ds_write2st64_b32 v153, v2, v3 offset1:2
	ds_write2st64_b32 v153, v4, v5 offset0:4 offset1:6
	ds_write2st64_b32 v126, v6, v7 offset1:2
	ds_write2st64_b32 v126, v8, v9 offset0:4 offset1:6
	ds_write2st64_b32 v153, v10, v11 offset0:32 offset1:34
	ds_write2st64_b32 v153, v12, v13 offset0:36 offset1:38
	ds_write2st64_b32 v126, v14, v15 offset0:32 offset1:34
	ds_write2st64_b32 v126, v16, v17 offset0:36 offset1:38
	ds_write2st64_b32 v153, v18, v19 offset0:64 offset1:66
	ds_write2st64_b32 v153, v20, v21 offset0:68 offset1:70
	ds_write2st64_b32 v126, v22, v23 offset0:64 offset1:66
	ds_write2st64_b32 v126, v24, v25 offset0:68 offset1:70
	ds_write2st64_b32 v153, v26, v27 offset0:96 offset1:98
	ds_write2st64_b32 v153, v28, v29 offset0:100 offset1:102
	ds_write2st64_b32 v126, v30, v31 offset0:96 offset1:98
	ds_write2st64_b32 v126, v32, v33 offset0:100 offset1:102
	s_waitcnt lgkmcnt(0)
	s_barrier
	ds_read_b128 v[2:5], v147
	ds_read_b128 v[6:9], v148
	v_lshl_add_u64 v[10:11], v[66:67], 0, s[50:51]
	s_mov_b32 s0, s72
	s_waitcnt vmcnt(6) lgkmcnt(1)
	v_pk_add_f32 v[40:41], v[40:41], v[194:195] op_sel_hi:[1,0] neg_lo:[0,1] neg_hi:[0,1]
	v_pk_mul_f32 v[40:41], v[40:41], v[194:195] op_sel:[0,1]
	v_pk_fma_f32 v[40:41], v[204:205], v[40:41], v[212:213]
	v_pk_fma_f32 v[4:5], v[40:41], s[42:43], v[4:5] op_sel_hi:[1,0,1]
	v_pk_add_f32 v[38:39], v[38:39], v[194:195] op_sel_hi:[1,0] neg_lo:[0,1] neg_hi:[0,1]
	v_pk_mul_f32 v[38:39], v[38:39], v[194:195] op_sel:[0,1]
	v_pk_fma_f32 v[38:39], v[202:203], v[38:39], v[210:211]
	v_pk_fma_f32 v[2:3], v[38:39], s[42:43], v[2:3] op_sel_hi:[1,0,1]
	global_store_dwordx4 v[10:11], v[2:5], off offset:512
	s_waitcnt lgkmcnt(0)
	s_nop 0
	v_pk_add_f32 v[36:37], v[36:37], v[194:195] op_sel_hi:[1,0] neg_lo:[0,1] neg_hi:[0,1]
	v_pk_mul_f32 v[36:37], v[36:37], v[194:195] op_sel:[0,1]
	v_pk_fma_f32 v[36:37], v[208:209], v[36:37], v[216:217]
	v_pk_fma_f32 v[4:5], v[36:37], s[42:43], v[8:9] op_sel_hi:[1,0,1]
	v_pk_add_f32 v[34:35], v[34:35], v[194:195] op_sel_hi:[1,0] neg_lo:[0,1] neg_hi:[0,1]
	v_pk_mul_f32 v[34:35], v[34:35], v[194:195] op_sel:[0,1]
	v_pk_fma_f32 v[34:35], v[206:207], v[34:35], v[214:215]
	v_pk_fma_f32 v[2:3], v[34:35], s[42:43], v[6:7] op_sel_hi:[1,0,1]
	global_store_dwordx4 v[10:11], v[2:5], off offset:528
	ds_read_b128 v[2:5], v146
	ds_read_b128 v[6:9], v145
	v_lshl_add_u64 v[10:11], v[68:69], 0, s[50:51]
	s_waitcnt vmcnt(6) lgkmcnt(1)
	v_pk_add_f32 v[48:49], v[48:49], v[196:197] op_sel_hi:[1,0] neg_lo:[0,1] neg_hi:[0,1]
	v_pk_mul_f32 v[48:49], v[48:49], v[196:197] op_sel:[0,1]
	v_pk_fma_f32 v[48:49], v[204:205], v[48:49], v[212:213]
	v_pk_fma_f32 v[4:5], v[48:49], s[42:43], v[4:5] op_sel_hi:[1,0,1]
	v_pk_add_f32 v[46:47], v[46:47], v[196:197] op_sel_hi:[1,0] neg_lo:[0,1] neg_hi:[0,1]
	v_pk_mul_f32 v[46:47], v[46:47], v[196:197] op_sel:[0,1]
	v_pk_fma_f32 v[46:47], v[202:203], v[46:47], v[210:211]
	v_pk_fma_f32 v[2:3], v[46:47], s[42:43], v[2:3] op_sel_hi:[1,0,1]
	global_store_dwordx4 v[10:11], v[2:5], off offset:512
	s_waitcnt lgkmcnt(0)
	s_nop 0
	v_pk_add_f32 v[44:45], v[44:45], v[196:197] op_sel_hi:[1,0] neg_lo:[0,1] neg_hi:[0,1]
	v_pk_mul_f32 v[44:45], v[44:45], v[196:197] op_sel:[0,1]
	v_pk_fma_f32 v[44:45], v[208:209], v[44:45], v[216:217]
	v_pk_fma_f32 v[4:5], v[44:45], s[42:43], v[8:9] op_sel_hi:[1,0,1]
	v_pk_add_f32 v[42:43], v[42:43], v[196:197] op_sel_hi:[1,0] neg_lo:[0,1] neg_hi:[0,1]
	v_pk_mul_f32 v[42:43], v[42:43], v[196:197] op_sel:[0,1]
	v_pk_fma_f32 v[42:43], v[206:207], v[42:43], v[214:215]
	v_pk_fma_f32 v[2:3], v[42:43], s[42:43], v[6:7] op_sel_hi:[1,0,1]
	global_store_dwordx4 v[10:11], v[2:5], off offset:528
	ds_read_b128 v[2:5], v144
	ds_read_b128 v[6:9], v143
	v_lshl_add_u64 v[10:11], v[70:71], 0, s[50:51]
	s_waitcnt vmcnt(6) lgkmcnt(1)
	v_pk_add_f32 v[56:57], v[56:57], v[198:199] op_sel_hi:[1,0] neg_lo:[0,1] neg_hi:[0,1]
	v_pk_mul_f32 v[56:57], v[56:57], v[198:199] op_sel:[0,1]
	v_pk_fma_f32 v[56:57], v[204:205], v[56:57], v[212:213]
	v_pk_fma_f32 v[4:5], v[56:57], s[42:43], v[4:5] op_sel_hi:[1,0,1]
	v_pk_add_f32 v[54:55], v[54:55], v[198:199] op_sel_hi:[1,0] neg_lo:[0,1] neg_hi:[0,1]
	v_pk_mul_f32 v[54:55], v[54:55], v[198:199] op_sel:[0,1]
	v_pk_fma_f32 v[54:55], v[202:203], v[54:55], v[210:211]
	v_pk_fma_f32 v[2:3], v[54:55], s[42:43], v[2:3] op_sel_hi:[1,0,1]
	global_store_dwordx4 v[10:11], v[2:5], off offset:512
	s_waitcnt lgkmcnt(0)
	s_nop 0
	v_pk_add_f32 v[52:53], v[52:53], v[198:199] op_sel_hi:[1,0] neg_lo:[0,1] neg_hi:[0,1]
	v_pk_mul_f32 v[52:53], v[52:53], v[198:199] op_sel:[0,1]
	v_pk_fma_f32 v[52:53], v[208:209], v[52:53], v[216:217]
	v_pk_fma_f32 v[4:5], v[52:53], s[42:43], v[8:9] op_sel_hi:[1,0,1]
	v_pk_add_f32 v[50:51], v[50:51], v[198:199] op_sel_hi:[1,0] neg_lo:[0,1] neg_hi:[0,1]
	v_pk_mul_f32 v[50:51], v[50:51], v[198:199] op_sel:[0,1]
	v_pk_fma_f32 v[50:51], v[206:207], v[50:51], v[214:215]
	v_pk_fma_f32 v[2:3], v[50:51], s[42:43], v[6:7] op_sel_hi:[1,0,1]
	global_store_dwordx4 v[10:11], v[2:5], off offset:528
	ds_read_b128 v[2:5], v141
	ds_read_b128 v[6:9], v140
	v_lshl_add_u64 v[10:11], v[72:73], 0, s[50:51]
	s_waitcnt vmcnt(6) lgkmcnt(1)
	v_pk_add_f32 v[64:65], v[64:65], v[200:201] op_sel_hi:[1,0] neg_lo:[0,1] neg_hi:[0,1]
	v_pk_mul_f32 v[64:65], v[64:65], v[200:201] op_sel:[0,1]
	v_pk_fma_f32 v[64:65], v[204:205], v[64:65], v[212:213]
	v_pk_fma_f32 v[4:5], v[64:65], s[42:43], v[4:5] op_sel_hi:[1,0,1]
	v_pk_add_f32 v[62:63], v[62:63], v[200:201] op_sel_hi:[1,0] neg_lo:[0,1] neg_hi:[0,1]
	v_pk_mul_f32 v[62:63], v[62:63], v[200:201] op_sel:[0,1]
	v_pk_fma_f32 v[62:63], v[202:203], v[62:63], v[210:211]
	v_pk_fma_f32 v[2:3], v[62:63], s[42:43], v[2:3] op_sel_hi:[1,0,1]
	global_store_dwordx4 v[10:11], v[2:5], off offset:512
	s_waitcnt lgkmcnt(0)
	s_nop 0
	v_pk_add_f32 v[60:61], v[60:61], v[200:201] op_sel_hi:[1,0] neg_lo:[0,1] neg_hi:[0,1]
	v_pk_mul_f32 v[60:61], v[60:61], v[200:201] op_sel:[0,1]
	v_pk_fma_f32 v[60:61], v[208:209], v[60:61], v[216:217]
	v_pk_fma_f32 v[4:5], v[60:61], s[42:43], v[8:9] op_sel_hi:[1,0,1]
	v_pk_add_f32 v[58:59], v[58:59], v[200:201] op_sel_hi:[1,0] neg_lo:[0,1] neg_hi:[0,1]
	v_pk_mul_f32 v[58:59], v[58:59], v[200:201] op_sel:[0,1]
	v_pk_fma_f32 v[58:59], v[206:207], v[58:59], v[214:215]
	v_pk_fma_f32 v[2:3], v[58:59], s[42:43], v[6:7] op_sel_hi:[1,0,1]
	global_store_dwordx4 v[10:11], v[2:5], off offset:528
	s_waitcnt lgkmcnt(0)
	s_barrier
	s_cbranch_vccz .LBB0_1475

.LBB0_1595:
	v_add_u32_e32 v2, s1, v168
	v_ashrrev_i32_e32 v3, 31, v2
	v_add_u32_e32 v4, 16, v2
	v_lshlrev_b64 v[2:3], 11, v[2:3]
	v_ashrrev_i32_e32 v5, 31, v4
	v_lshl_add_u64 v[2:3], v[156:157], 0, v[2:3]
	v_lshlrev_b64 v[6:7], 11, v[4:5]
	global_load_dwordx4 v[2:5], v[2:3], off
	v_lshl_add_u64 v[6:7], v[156:157], 0, v[6:7]
	global_load_dwordx4 v[114:117], v[6:7], off
	s_add_i32 s1, s1, 32
	s_cmpk_eq_i32 s1, 0x80
	s_waitcnt vmcnt(1)
	v_mfma_f32_32x32x16_bf16 v[176:191], v[2:5], v[130:133], 0
	v_mfma_f32_32x32x16_bf16 v[192:207], v[2:5], v[134:137], 0
	v_mfma_f32_32x32x16_bf16 v[208:223], v[2:5], v[138:141], 0
	v_mfma_f32_32x32x16_bf16 v[224:239], v[2:5], v[142:145], 0
	s_waitcnt vmcnt(0)
	v_mfma_f32_32x32x16_bf16 v[50:65], v[114:117], v[130:133], 0
	v_mfma_f32_32x32x16_bf16 v[66:81], v[114:117], v[134:137], 0
	v_mfma_f32_32x32x16_bf16 v[82:97], v[114:117], v[138:141], 0
	v_mfma_f32_32x32x16_bf16 v[98:113], v[114:117], v[142:145], 0
	s_nop 7
	v_fma_f32 v244, -v153, v35, v176
	v_fma_f32 v245, v153, v34, v192
	v_fma_f32 v246, -v155, v119, v208
	v_fma_f32 v247, v155, v118, v224
	v_fma_f32 v240, v152, v34, v244
	v_fma_f32 v241, v152, v35, v245
	v_fma_f32 v242, v154, v118, v246
	v_fma_f32 v243, v154, v119, v247
	v_fma_f32 v244, -v153, v241, v177
	v_fma_f32 v245, v153, v240, v193
	v_fma_f32 v246, -v155, v243, v209
	v_fma_f32 v247, v155, v242, v225
	v_fma_f32 v34, v152, v240, v244
	v_fma_f32 v35, v152, v241, v245
	v_fma_f32 v118, v154, v242, v246
	v_fma_f32 v119, v154, v243, v247
	v_fma_f32 v244, -v153, v35, v178
	v_fma_f32 v245, v153, v34, v194
	v_fma_f32 v246, -v155, v119, v210
	v_fma_f32 v247, v155, v118, v226
	v_fma_f32 v240, v152, v34, v244
	v_fma_f32 v241, v152, v35, v245
	v_fma_f32 v242, v154, v118, v246
	v_fma_f32 v243, v154, v119, v247
	v_fma_f32 v244, -v153, v241, v179
	v_fma_f32 v245, v153, v240, v195
	v_fma_f32 v246, -v155, v243, v211
	v_fma_f32 v247, v155, v242, v227
	v_fma_f32 v34, v152, v240, v244
	v_fma_f32 v35, v152, v241, v245
	v_fma_f32 v118, v154, v242, v246
	v_fma_f32 v119, v154, v243, v247
	v_fma_f32 v244, -v153, v35, v180
	v_fma_f32 v245, v153, v34, v196
	v_fma_f32 v246, -v155, v119, v212
	v_fma_f32 v247, v155, v118, v228
	v_fma_f32 v240, v152, v34, v244
	v_fma_f32 v241, v152, v35, v245
	v_fma_f32 v242, v154, v118, v246
	v_fma_f32 v243, v154, v119, v247
	v_fma_f32 v244, -v153, v241, v181
	v_fma_f32 v245, v153, v240, v197
	v_fma_f32 v246, -v155, v243, v213
	v_fma_f32 v247, v155, v242, v229
	v_fma_f32 v34, v152, v240, v244
	v_fma_f32 v35, v152, v241, v245
	v_fma_f32 v118, v154, v242, v246
	v_fma_f32 v119, v154, v243, v247
	v_fma_f32 v244, -v153, v35, v182
	v_fma_f32 v245, v153, v34, v198
	v_fma_f32 v246, -v155, v119, v214
	v_fma_f32 v247, v155, v118, v230
	v_fma_f32 v240, v152, v34, v244
	v_fma_f32 v241, v152, v35, v245
	v_fma_f32 v242, v154, v118, v246
	v_fma_f32 v243, v154, v119, v247
	v_fma_f32 v244, -v153, v241, v183
	v_fma_f32 v245, v153, v240, v199
	v_fma_f32 v246, -v155, v243, v215
	v_fma_f32 v247, v155, v242, v231
	v_fma_f32 v34, v152, v240, v244
	v_fma_f32 v35, v152, v241, v245
	v_fma_f32 v118, v154, v242, v246
	v_fma_f32 v119, v154, v243, v247
	v_fma_f32 v244, -v153, v35, v184
	v_fma_f32 v245, v153, v34, v200
	v_fma_f32 v246, -v155, v119, v216
	v_fma_f32 v247, v155, v118, v232
	v_fma_f32 v240, v152, v34, v244
	v_fma_f32 v241, v152, v35, v245
	v_fma_f32 v242, v154, v118, v246
	v_fma_f32 v243, v154, v119, v247
	v_fma_f32 v244, -v153, v241, v185
	v_fma_f32 v245, v153, v240, v201
	v_fma_f32 v246, -v155, v243, v217
	v_fma_f32 v247, v155, v242, v233
	v_fma_f32 v34, v152, v240, v244
	v_fma_f32 v35, v152, v241, v245
	v_fma_f32 v118, v154, v242, v246
	v_fma_f32 v119, v154, v243, v247
	v_fma_f32 v244, -v153, v35, v186
	v_fma_f32 v245, v153, v34, v202
	v_fma_f32 v246, -v155, v119, v218
	v_fma_f32 v247, v155, v118, v234
	v_fma_f32 v240, v152, v34, v244
	v_fma_f32 v241, v152, v35, v245
	v_fma_f32 v242, v154, v118, v246
	v_fma_f32 v243, v154, v119, v247
	v_fma_f32 v244, -v153, v241, v187
	v_fma_f32 v245, v153, v240, v203
	v_fma_f32 v246, -v155, v243, v219
	v_fma_f32 v247, v155, v242, v235
	v_fma_f32 v34, v152, v240, v244
	v_fma_f32 v35, v152, v241, v245
	v_fma_f32 v118, v154, v242, v246
	v_fma_f32 v119, v154, v243, v247
	v_fma_f32 v244, -v153, v35, v188
	v_fma_f32 v245, v153, v34, v204
	v_fma_f32 v246, -v155, v119, v220
	v_fma_f32 v247, v155, v118, v236
	v_fma_f32 v240, v152, v34, v244
	v_fma_f32 v241, v152, v35, v245
	v_fma_f32 v242, v154, v118, v246
	v_fma_f32 v243, v154, v119, v247
	v_fma_f32 v244, -v153, v241, v189
	v_fma_f32 v245, v153, v240, v205
	v_fma_f32 v246, -v155, v243, v221
	v_fma_f32 v247, v155, v242, v237
	v_fma_f32 v34, v152, v240, v244
	v_fma_f32 v35, v152, v241, v245
	v_fma_f32 v118, v154, v242, v246
	v_fma_f32 v119, v154, v243, v247
	v_fma_f32 v244, -v153, v35, v190
	v_fma_f32 v245, v153, v34, v206
	v_fma_f32 v246, -v155, v119, v222
	v_fma_f32 v247, v155, v118, v238
	v_fma_f32 v240, v152, v34, v244
	v_fma_f32 v241, v152, v35, v245
	v_fma_f32 v242, v154, v118, v246
	v_fma_f32 v243, v154, v119, v247
	v_fma_f32 v244, -v153, v241, v191
	v_fma_f32 v245, v153, v240, v207
	v_fma_f32 v246, -v155, v243, v223
	v_fma_f32 v247, v155, v242, v239
	v_fma_f32 v34, v152, v240, v244
	v_fma_f32 v35, v152, v241, v245
	v_fma_f32 v118, v154, v242, v246
	v_fma_f32 v119, v154, v243, v247
	v_fma_f32 v244, -v153, v35, v50
	v_fma_f32 v245, v153, v34, v66
	v_fma_f32 v246, -v155, v119, v82
	v_fma_f32 v247, v155, v118, v98
	v_fma_f32 v240, v152, v34, v244
	v_fma_f32 v241, v152, v35, v245
	v_fma_f32 v242, v154, v118, v246
	v_fma_f32 v243, v154, v119, v247
	v_fma_f32 v244, -v153, v241, v51
	v_fma_f32 v245, v153, v240, v67
	v_fma_f32 v246, -v155, v243, v83
	v_fma_f32 v247, v155, v242, v99
	v_fma_f32 v34, v152, v240, v244
	v_fma_f32 v35, v152, v241, v245
	v_fma_f32 v118, v154, v242, v246
	v_fma_f32 v119, v154, v243, v247
	v_fma_f32 v244, -v153, v35, v52
	v_fma_f32 v245, v153, v34, v68
	v_fma_f32 v246, -v155, v119, v84
	v_fma_f32 v247, v155, v118, v100
	v_fma_f32 v240, v152, v34, v244
	v_fma_f32 v241, v152, v35, v245
	v_fma_f32 v242, v154, v118, v246
	v_fma_f32 v243, v154, v119, v247
	v_fma_f32 v244, -v153, v241, v53
	v_fma_f32 v245, v153, v240, v69
	v_fma_f32 v246, -v155, v243, v85
	v_fma_f32 v247, v155, v242, v101
	v_fma_f32 v34, v152, v240, v244
	v_fma_f32 v35, v152, v241, v245
	v_fma_f32 v118, v154, v242, v246
	v_fma_f32 v119, v154, v243, v247
	v_fma_f32 v244, -v153, v35, v54
	v_fma_f32 v245, v153, v34, v70
	v_fma_f32 v246, -v155, v119, v86
	v_fma_f32 v247, v155, v118, v102
	v_fma_f32 v240, v152, v34, v244
	v_fma_f32 v241, v152, v35, v245
	v_fma_f32 v242, v154, v118, v246
	v_fma_f32 v243, v154, v119, v247
	v_fma_f32 v244, -v153, v241, v55
	v_fma_f32 v245, v153, v240, v71
	v_fma_f32 v246, -v155, v243, v87
	v_fma_f32 v247, v155, v242, v103
	v_fma_f32 v34, v152, v240, v244
	v_fma_f32 v35, v152, v241, v245
	v_fma_f32 v118, v154, v242, v246
	v_fma_f32 v119, v154, v243, v247
	v_fma_f32 v244, -v153, v35, v56
	v_fma_f32 v245, v153, v34, v72
	v_fma_f32 v246, -v155, v119, v88
	v_fma_f32 v247, v155, v118, v104
	v_fma_f32 v240, v152, v34, v244
	v_fma_f32 v241, v152, v35, v245
	v_fma_f32 v242, v154, v118, v246
	v_fma_f32 v243, v154, v119, v247
	v_fma_f32 v244, -v153, v241, v57
	v_fma_f32 v245, v153, v240, v73
	v_fma_f32 v246, -v155, v243, v89
	v_fma_f32 v247, v155, v242, v105
	v_fma_f32 v34, v152, v240, v244
	v_fma_f32 v35, v152, v241, v245
	v_fma_f32 v118, v154, v242, v246
	v_fma_f32 v119, v154, v243, v247
	v_fma_f32 v244, -v153, v35, v58
	v_fma_f32 v245, v153, v34, v74
	v_fma_f32 v246, -v155, v119, v90
	v_fma_f32 v247, v155, v118, v106
	v_fma_f32 v240, v152, v34, v244
	v_fma_f32 v241, v152, v35, v245
	v_fma_f32 v242, v154, v118, v246
	v_fma_f32 v243, v154, v119, v247
	v_fma_f32 v244, -v153, v241, v59
	v_fma_f32 v245, v153, v240, v75
	v_fma_f32 v246, -v155, v243, v91
	v_fma_f32 v247, v155, v242, v107
	v_fma_f32 v34, v152, v240, v244
	v_fma_f32 v35, v152, v241, v245
	v_fma_f32 v118, v154, v242, v246
	v_fma_f32 v119, v154, v243, v247
	v_fma_f32 v244, -v153, v35, v60
	v_fma_f32 v245, v153, v34, v76
	v_fma_f32 v246, -v155, v119, v92
	v_fma_f32 v247, v155, v118, v108
	v_fma_f32 v240, v152, v34, v244
	v_fma_f32 v241, v152, v35, v245
	v_fma_f32 v242, v154, v118, v246
	v_fma_f32 v243, v154, v119, v247
	v_fma_f32 v244, -v153, v241, v61
	v_fma_f32 v245, v153, v240, v77
	v_fma_f32 v246, -v155, v243, v93
	v_fma_f32 v247, v155, v242, v109
	v_fma_f32 v34, v152, v240, v244
	v_fma_f32 v35, v152, v241, v245
	v_fma_f32 v118, v154, v242, v246
	v_fma_f32 v119, v154, v243, v247
	v_fma_f32 v244, -v153, v35, v62
	v_fma_f32 v245, v153, v34, v78
	v_fma_f32 v246, -v155, v119, v94
	v_fma_f32 v247, v155, v118, v110
	v_fma_f32 v240, v152, v34, v244
	v_fma_f32 v241, v152, v35, v245
	v_fma_f32 v242, v154, v118, v246
	v_fma_f32 v243, v154, v119, v247
	v_fma_f32 v244, -v153, v241, v63
	v_fma_f32 v245, v153, v240, v79
	v_fma_f32 v246, -v155, v243, v95
	v_fma_f32 v247, v155, v242, v111
	v_fma_f32 v34, v152, v240, v244
	v_fma_f32 v35, v152, v241, v245
	v_fma_f32 v118, v154, v242, v246
	v_fma_f32 v119, v154, v243, v247
	v_fma_f32 v244, -v153, v35, v64
	v_fma_f32 v245, v153, v34, v80
	v_fma_f32 v246, -v155, v119, v96
	v_fma_f32 v247, v155, v118, v112
	v_fma_f32 v240, v152, v34, v244
	v_fma_f32 v241, v152, v35, v245
	v_fma_f32 v242, v154, v118, v246
	v_fma_f32 v243, v154, v119, v247
	v_fma_f32 v244, -v153, v241, v65
	v_fma_f32 v245, v153, v240, v81
	v_fma_f32 v246, -v155, v243, v97
	v_fma_f32 v247, v155, v242, v113
	v_fma_f32 v34, v152, v240, v244
	v_fma_f32 v35, v152, v241, v245
	v_fma_f32 v118, v154, v242, v246
	v_fma_f32 v119, v154, v243, v247
	s_cbranch_scc0 .LBB0_1595
	s_nop 0
	s_nop 0
	s_nop 0
	s_nop 0
	s_nop 0
	s_nop 0
	s_nop 0
	v_lshlrev_b32_e32 v2, 7, v167
	v_or3_b32 v2, v2, v163, v166
	v_ashrrev_i32_e32 v3, 31, v2
	v_lshlrev_b64 v[2:3], 9, v[2:3]
	s_add_i32 s0, s0, s96
	v_lshl_add_u64 v[2:3], v[150:151], 0, v[2:3]
	s_cmpk_gt_i32 s0, 0x1ff
	global_store_dwordx2 v[2:3], v[34:35], off
	global_store_dwordx2 v[2:3], v[118:119], off offset:256
	s_cbranch_scc0 .LBB0_1594

.LBB0_1843:
	v_mbcnt_lo_u32_b32 v148, -1, 0
	v_mbcnt_hi_u32_b32 v148, -1, v148
	v_xor_b32_e32 v149, 32, v148
	v_lshlrev_b32_e32 v149, 2, v149
	v_mov_b32_e32 v150, 0x3727c5ac
	v_lshlrev_b32_e32 v151, 3, v148
	global_load_dwordx4 v[64:67], v[12:13], off
	global_load_dwordx4 v[68:71], v[12:13], off offset:1024
	global_load_dwordx4 v[72:75], v[12:13], off offset:2048
	global_load_dwordx4 v[76:79], v[12:13], off offset:3072
	global_load_dwordx4 v[80:83], v[14:15], off
	global_load_dwordx4 v[84:87], v[14:15], off offset:1024
	global_load_dwordx4 v[88:91], v[14:15], off offset:2048
	global_load_dwordx4 v[92:95], v[14:15], off offset:3072
	v_ashrrev_i32_e32 v159, 31, v16
	v_mov_b32_e32 v158, v16
	v_lshlrev_b64 v[158:159], 12, v[158:159]
	v_lshl_add_u64 v[152:153], v[10:11], 0, v[158:159]
	global_load_dwordx4 v[96:99], v[152:153], off
	global_load_dwordx4 v[100:103], v[152:153], off offset:1024
	global_load_dwordx4 v[104:107], v[152:153], off offset:2048
	global_load_dwordx4 v[108:111], v[152:153], off offset:3072
	s_add_i32 s99, s8, s96
	s_cmpk_lt_i32 s99, 0x800
	s_cselect_b32 s99, s2, 0
	v_add_u32_e32 v156, s99, v16
	v_ashrrev_i32_e32 v159, 31, v156
	v_mov_b32_e32 v158, v156
	v_lshlrev_b64 v[158:159], 12, v[158:159]
	v_lshl_add_u64 v[154:155], v[10:11], 0, v[158:159]
	global_load_dwordx4 v[112:115], v[154:155], off
	global_load_dwordx4 v[116:119], v[154:155], off offset:1024
	global_load_dwordx4 v[120:123], v[154:155], off offset:2048
	global_load_dwordx4 v[124:127], v[154:155], off offset:3072
	s_waitcnt vmcnt(4)
	s_branch .Lln_p15_procA
.Lln_p15_loopA:
	s_add_i32 s99, s8, s96
	s_cmpk_lt_i32 s99, 0x800
	s_cselect_b32 s99, s2, 0
	v_add_u32_e32 v156, s99, v16
	v_ashrrev_i32_e32 v159, 31, v156
	v_mov_b32_e32 v158, v156
	v_lshlrev_b64 v[158:159], 12, v[158:159]
	v_lshl_add_u64 v[154:155], v[10:11], 0, v[158:159]
	global_load_dwordx4 v[112:115], v[154:155], off
	global_load_dwordx4 v[116:119], v[154:155], off offset:1024
	global_load_dwordx4 v[120:123], v[154:155], off offset:2048
	global_load_dwordx4 v[124:127], v[154:155], off offset:3072
	s_waitcnt vmcnt(9)
.Lln_p15_procA:
	v_add_f32_e32 v128, v96, v97
	v_add_f32_e32 v129, v100, v101
	v_add_f32_e32 v130, v104, v105
	v_add_f32_e32 v131, v108, v109
	v_add_f32_e32 v128, v98, v128
	v_add_f32_e32 v129, v102, v129
	v_add_f32_e32 v130, v106, v130
	v_add_f32_e32 v131, v110, v131
	v_add_f32_e32 v128, v99, v128
	v_add_f32_e32 v129, v103, v129
	v_add_f32_e32 v130, v107, v130
	v_add_f32_e32 v131, v111, v131
	v_add_f32_e32 v132, v128, v129
	v_add_f32_e32 v132, v132, v130
	v_add_f32_e32 v132, v132, v131
	s_nop 1
	v_add_f32_dpp v132, v132, v132 quad_perm:[1,0,3,2] row_mask:0xf bank_mask:0xf
	s_nop 1
	v_add_f32_dpp v132, v132, v132 quad_perm:[2,3,0,1] row_mask:0xf bank_mask:0xf
	s_nop 1
	v_add_f32_dpp v132, v132, v132 row_half_mirror row_mask:0xf bank_mask:0xf
	s_nop 1
	v_add_f32_dpp v132, v132, v132 row_mirror row_mask:0xf bank_mask:0xf
	ds_swizzle_b32 v147, v132 offset:0x401f
	s_waitcnt lgkmcnt(0)
	v_add_f32_e32 v132, v132, v147
	ds_bpermute_b32 v147, v149, v132
	s_waitcnt lgkmcnt(0)
	v_add_f32_e32 v132, v132, v147
	v_mul_f32_e32 v133, 0x3a800000, v132
	v_sub_f32_e32 v96, v96, v133
	v_sub_f32_e32 v97, v97, v133
	v_sub_f32_e32 v98, v98, v133
	v_sub_f32_e32 v99, v99, v133
	v_sub_f32_e32 v100, v100, v133
	v_sub_f32_e32 v101, v101, v133
	v_sub_f32_e32 v102, v102, v133
	v_sub_f32_e32 v103, v103, v133
	v_sub_f32_e32 v104, v104, v133
	v_sub_f32_e32 v105, v105, v133
	v_sub_f32_e32 v106, v106, v133
	v_sub_f32_e32 v107, v107, v133
	v_sub_f32_e32 v108, v108, v133
	v_sub_f32_e32 v109, v109, v133
	v_sub_f32_e32 v110, v110, v133
	v_sub_f32_e32 v111, v111, v133
	v_mul_f32_e32 v134, v96, v96
	v_mul_f32_e32 v135, v97, v97
	v_add_f32_e32 v134, v134, v135
	v_mul_f32_e32 v135, v98, v98
	v_add_f32_e32 v134, v135, v134
	v_mul_f32_e32 v135, v99, v99
	v_add_f32_e32 v134, v135, v134
	v_mul_f32_e32 v135, v100, v100
	v_add_f32_e32 v134, v135, v134
	v_mul_f32_e32 v135, v101, v101
	v_add_f32_e32 v134, v135, v134
	v_mul_f32_e32 v135, v102, v102
	v_add_f32_e32 v134, v135, v134
	v_mul_f32_e32 v135, v103, v103
	v_add_f32_e32 v134, v135, v134
	v_mul_f32_e32 v135, v104, v104
	v_add_f32_e32 v134, v135, v134
	v_mul_f32_e32 v135, v105, v105
	v_add_f32_e32 v134, v135, v134
	v_mul_f32_e32 v135, v106, v106
	v_add_f32_e32 v134, v135, v134
	v_mul_f32_e32 v135, v107, v107
	v_add_f32_e32 v134, v135, v134
	v_mul_f32_e32 v135, v108, v108
	v_add_f32_e32 v134, v135, v134
	v_mul_f32_e32 v135, v109, v109
	v_add_f32_e32 v134, v135, v134
	v_mul_f32_e32 v135, v110, v110
	v_add_f32_e32 v134, v135, v134
	v_mul_f32_e32 v135, v111, v111
	v_add_f32_e32 v134, v135, v134
	s_nop 1
	v_add_f32_dpp v134, v134, v134 quad_perm:[1,0,3,2] row_mask:0xf bank_mask:0xf
	s_nop 1
	v_add_f32_dpp v134, v134, v134 quad_perm:[2,3,0,1] row_mask:0xf bank_mask:0xf
	s_nop 1
	v_add_f32_dpp v134, v134, v134 row_half_mirror row_mask:0xf bank_mask:0xf
	s_nop 1
	v_add_f32_dpp v134, v134, v134 row_mirror row_mask:0xf bank_mask:0xf
	ds_swizzle_b32 v147, v134 offset:0x401f
	s_waitcnt lgkmcnt(0)
	v_add_f32_e32 v134, v134, v147
	ds_bpermute_b32 v147, v149, v134
	s_waitcnt lgkmcnt(0)
	v_add_f32_e32 v134, v134, v147
	v_fmamk_f32 v134, v134, 0x3a800000, v150
	v_rsq_f32_e32 v134, v134
	s_nop 0
	v_mul_f32_e32 v96, v96, v134
	v_mul_f32_e32 v97, v97, v134
	v_mul_f32_e32 v98, v98, v134
	v_mul_f32_e32 v99, v99, v134
	v_mul_f32_e32 v100, v100, v134
	v_mul_f32_e32 v101, v101, v134
	v_mul_f32_e32 v102, v102, v134
	v_mul_f32_e32 v103, v103, v134
	v_mul_f32_e32 v104, v104, v134
	v_mul_f32_e32 v105, v105, v134
	v_mul_f32_e32 v106, v106, v134
	v_mul_f32_e32 v107, v107, v134
	v_mul_f32_e32 v108, v108, v134
	v_mul_f32_e32 v109, v109, v134
	v_mul_f32_e32 v110, v110, v134
	v_mul_f32_e32 v111, v111, v134
	v_fma_f32 v96, v64, v96, v80
	v_fma_f32 v97, v65, v97, v81
	v_fma_f32 v98, v66, v98, v82
	v_fma_f32 v99, v67, v99, v83
	v_fma_f32 v100, v68, v100, v84
	v_fma_f32 v101, v69, v101, v85
	v_fma_f32 v102, v70, v102, v86
	v_fma_f32 v103, v71, v103, v87
	v_fma_f32 v104, v72, v104, v88
	v_fma_f32 v105, v73, v105, v89
	v_fma_f32 v106, v74, v106, v90
	v_fma_f32 v107, v75, v107, v91
	v_fma_f32 v108, v76, v108, v92
	v_fma_f32 v109, v77, v109, v93
	v_fma_f32 v110, v78, v110, v94
	v_fma_f32 v111, v79, v111, v95
	v_lshlrev_b32_e32 v162, 3, v16
	v_add_u32_e32 v162, 0xf000000, v162
	v_mov_b32_e32 v164, v133
	v_mov_b32_e32 v165, v134
	s_mov_b64 exec, 1
	global_store_dwordx2 v162, v[164:165], s[62:63]
	s_mov_b64 exec, -1
	v_ashrrev_i32_e32 v159, 31, v16
	v_mov_b32_e32 v158, v16
	v_lshlrev_b64 v[158:159], 11, v[158:159]
	v_lshl_add_u64 v[160:161], s[60:61], 0, v[158:159]
	v_mov_b32_e32 v158, v151
	v_mov_b32_e32 v159, 0
	v_lshl_add_u64 v[160:161], v[160:161], 0, v[158:159]
	v_cvt_pk_bf16_f32 v136, v96, v97
	v_cvt_pk_bf16_f32 v137, v98, v99
	v_cvt_pk_bf16_f32 v138, v100, v101
	v_cvt_pk_bf16_f32 v139, v102, v103
	v_cvt_pk_bf16_f32 v140, v104, v105
	v_cvt_pk_bf16_f32 v141, v106, v107
	v_cvt_pk_bf16_f32 v142, v108, v109
	v_cvt_pk_bf16_f32 v143, v110, v111
	global_store_dwordx2 v[160:161], v[136:137], off
	global_store_dwordx2 v[160:161], v[138:139], off offset:512
	global_store_dwordx2 v[160:161], v[140:141], off offset:1024
	global_store_dwordx2 v[160:161], v[142:143], off offset:1536
	v_mov_b32_e32 v16, v156
	v_mov_b32_e32 v152, v154
	v_mov_b32_e32 v153, v155
	s_add_i32 s8, s8, s96
	s_cmpk_lt_i32 s8, 0x800
	s_cbranch_scc0 .LBB0_1851
	s_add_i32 s99, s8, s96
	s_cmpk_lt_i32 s99, 0x800
	s_cselect_b32 s99, s2, 0
	v_add_u32_e32 v156, s99, v16
	v_ashrrev_i32_e32 v159, 31, v156
	v_mov_b32_e32 v158, v156
	v_lshlrev_b64 v[158:159], 12, v[158:159]
	v_lshl_add_u64 v[154:155], v[10:11], 0, v[158:159]
	global_load_dwordx4 v[96:99], v[154:155], off
	global_load_dwordx4 v[100:103], v[154:155], off offset:1024
	global_load_dwordx4 v[104:107], v[154:155], off offset:2048
	global_load_dwordx4 v[108:111], v[154:155], off offset:3072
	s_waitcnt vmcnt(9)
	v_add_f32_e32 v128, v112, v113
	v_add_f32_e32 v129, v116, v117
	v_add_f32_e32 v130, v120, v121
	v_add_f32_e32 v131, v124, v125
	v_add_f32_e32 v128, v114, v128
	v_add_f32_e32 v129, v118, v129
	v_add_f32_e32 v130, v122, v130
	v_add_f32_e32 v131, v126, v131
	v_add_f32_e32 v128, v115, v128
	v_add_f32_e32 v129, v119, v129
	v_add_f32_e32 v130, v123, v130
	v_add_f32_e32 v131, v127, v131
	v_add_f32_e32 v132, v128, v129
	v_add_f32_e32 v132, v132, v130
	v_add_f32_e32 v132, v132, v131
	s_nop 1
	v_add_f32_dpp v132, v132, v132 quad_perm:[1,0,3,2] row_mask:0xf bank_mask:0xf
	s_nop 1
	v_add_f32_dpp v132, v132, v132 quad_perm:[2,3,0,1] row_mask:0xf bank_mask:0xf
	s_nop 1
	v_add_f32_dpp v132, v132, v132 row_half_mirror row_mask:0xf bank_mask:0xf
	s_nop 1
	v_add_f32_dpp v132, v132, v132 row_mirror row_mask:0xf bank_mask:0xf
	ds_swizzle_b32 v147, v132 offset:0x401f
	s_waitcnt lgkmcnt(0)
	v_add_f32_e32 v132, v132, v147
	ds_bpermute_b32 v147, v149, v132
	s_waitcnt lgkmcnt(0)
	v_add_f32_e32 v132, v132, v147
	v_mul_f32_e32 v133, 0x3a800000, v132
	v_sub_f32_e32 v112, v112, v133
	v_sub_f32_e32 v113, v113, v133
	v_sub_f32_e32 v114, v114, v133
	v_sub_f32_e32 v115, v115, v133
	v_sub_f32_e32 v116, v116, v133
	v_sub_f32_e32 v117, v117, v133
	v_sub_f32_e32 v118, v118, v133
	v_sub_f32_e32 v119, v119, v133
	v_sub_f32_e32 v120, v120, v133
	v_sub_f32_e32 v121, v121, v133
	v_sub_f32_e32 v122, v122, v133
	v_sub_f32_e32 v123, v123, v133
	v_sub_f32_e32 v124, v124, v133
	v_sub_f32_e32 v125, v125, v133
	v_sub_f32_e32 v126, v126, v133
	v_sub_f32_e32 v127, v127, v133
	v_mul_f32_e32 v134, v112, v112
	v_mul_f32_e32 v135, v113, v113
	v_add_f32_e32 v134, v134, v135
	v_mul_f32_e32 v135, v114, v114
	v_add_f32_e32 v134, v135, v134
	v_mul_f32_e32 v135, v115, v115
	v_add_f32_e32 v134, v135, v134
	v_mul_f32_e32 v135, v116, v116
	v_add_f32_e32 v134, v135, v134
	v_mul_f32_e32 v135, v117, v117
	v_add_f32_e32 v134, v135, v134
	v_mul_f32_e32 v135, v118, v118
	v_add_f32_e32 v134, v135, v134
	v_mul_f32_e32 v135, v119, v119
	v_add_f32_e32 v134, v135, v134
	v_mul_f32_e32 v135, v120, v120
	v_add_f32_e32 v134, v135, v134
	v_mul_f32_e32 v135, v121, v121
	v_add_f32_e32 v134, v135, v134
	v_mul_f32_e32 v135, v122, v122
	v_add_f32_e32 v134, v135, v134
	v_mul_f32_e32 v135, v123, v123
	v_add_f32_e32 v134, v135, v134
	v_mul_f32_e32 v135, v124, v124
	v_add_f32_e32 v134, v135, v134
	v_mul_f32_e32 v135, v125, v125
	v_add_f32_e32 v134, v135, v134
	v_mul_f32_e32 v135, v126, v126
	v_add_f32_e32 v134, v135, v134
	v_mul_f32_e32 v135, v127, v127
	v_add_f32_e32 v134, v135, v134
	s_nop 1
	v_add_f32_dpp v134, v134, v134 quad_perm:[1,0,3,2] row_mask:0xf bank_mask:0xf
	s_nop 1
	v_add_f32_dpp v134, v134, v134 quad_perm:[2,3,0,1] row_mask:0xf bank_mask:0xf
	s_nop 1
	v_add_f32_dpp v134, v134, v134 row_half_mirror row_mask:0xf bank_mask:0xf
	s_nop 1
	v_add_f32_dpp v134, v134, v134 row_mirror row_mask:0xf bank_mask:0xf
	ds_swizzle_b32 v147, v134 offset:0x401f
	s_waitcnt lgkmcnt(0)
	v_add_f32_e32 v134, v134, v147
	ds_bpermute_b32 v147, v149, v134
	s_waitcnt lgkmcnt(0)
	v_add_f32_e32 v134, v134, v147
	v_fmamk_f32 v134, v134, 0x3a800000, v150
	v_rsq_f32_e32 v134, v134
	s_nop 0
	v_mul_f32_e32 v112, v112, v134
	v_mul_f32_e32 v113, v113, v134
	v_mul_f32_e32 v114, v114, v134
	v_mul_f32_e32 v115, v115, v134
	v_mul_f32_e32 v116, v116, v134
	v_mul_f32_e32 v117, v117, v134
	v_mul_f32_e32 v118, v118, v134
	v_mul_f32_e32 v119, v119, v134
	v_mul_f32_e32 v120, v120, v134
	v_mul_f32_e32 v121, v121, v134
	v_mul_f32_e32 v122, v122, v134
	v_mul_f32_e32 v123, v123, v134
	v_mul_f32_e32 v124, v124, v134
	v_mul_f32_e32 v125, v125, v134
	v_mul_f32_e32 v126, v126, v134
	v_mul_f32_e32 v127, v127, v134
	v_fma_f32 v112, v64, v112, v80
	v_fma_f32 v113, v65, v113, v81
	v_fma_f32 v114, v66, v114, v82
	v_fma_f32 v115, v67, v115, v83
	v_fma_f32 v116, v68, v116, v84
	v_fma_f32 v117, v69, v117, v85
	v_fma_f32 v118, v70, v118, v86
	v_fma_f32 v119, v71, v119, v87
	v_fma_f32 v120, v72, v120, v88
	v_fma_f32 v121, v73, v121, v89
	v_fma_f32 v122, v74, v122, v90
	v_fma_f32 v123, v75, v123, v91
	v_fma_f32 v124, v76, v124, v92
	v_fma_f32 v125, v77, v125, v93
	v_fma_f32 v126, v78, v126, v94
	v_fma_f32 v127, v79, v127, v95
	v_lshlrev_b32_e32 v162, 3, v16
	v_add_u32_e32 v162, 0xf000000, v162
	v_mov_b32_e32 v164, v133
	v_mov_b32_e32 v165, v134
	s_mov_b64 exec, 1
	global_store_dwordx2 v162, v[164:165], s[62:63]
	s_mov_b64 exec, -1
	v_ashrrev_i32_e32 v159, 31, v16
	v_mov_b32_e32 v158, v16
	v_lshlrev_b64 v[158:159], 11, v[158:159]
	v_lshl_add_u64 v[160:161], s[60:61], 0, v[158:159]
	v_mov_b32_e32 v158, v151
	v_mov_b32_e32 v159, 0
	v_lshl_add_u64 v[160:161], v[160:161], 0, v[158:159]
	v_cvt_pk_bf16_f32 v136, v112, v113
	v_cvt_pk_bf16_f32 v137, v114, v115
	v_cvt_pk_bf16_f32 v138, v116, v117
	v_cvt_pk_bf16_f32 v139, v118, v119
	v_cvt_pk_bf16_f32 v140, v120, v121
	v_cvt_pk_bf16_f32 v141, v122, v123
	v_cvt_pk_bf16_f32 v142, v124, v125
	v_cvt_pk_bf16_f32 v143, v126, v127
	global_store_dwordx2 v[160:161], v[136:137], off
	global_store_dwordx2 v[160:161], v[138:139], off offset:512
	global_store_dwordx2 v[160:161], v[140:141], off offset:1024
	global_store_dwordx2 v[160:161], v[142:143], off offset:1536
	v_mov_b32_e32 v16, v156
	v_mov_b32_e32 v152, v154
	v_mov_b32_e32 v153, v155
	s_add_i32 s8, s8, s96
	s_cmpk_lt_i32 s8, 0x800
	s_cbranch_scc0 .LBB0_1851
	s_branch .Lln_p15_loopA

.LBB0_1913:
	v_add_u32_e32 v169, s35, v161
	ds_read_b128 v[172:175], v169 offset:32768
	ds_read_b128 v[176:179], v169 offset:33792
	ds_read_b128 v[180:183], v169 offset:34816
	ds_read_b128 v[184:187], v169 offset:35840
	v_add_u32_e32 v170, s48, v142
	v_lshl_add_u64 v[224:225], v[138:139], 0, s[0:1]
	v_readfirstlane_b32 s53, v170
	v_add_u32_e32 v171, 0x2000, v170
	v_add_u32_e32 v165, s37, v161
	v_add_u32_e32 v166, s41, v162
	v_add_u32_e32 v167, s44, v162
	v_add_u32_e32 v168, s45, v162
	v_lshl_add_u64 v[220:221], v[224:225], 0, s[6:7]
	s_mov_b32 m0, s53
	v_lshl_add_u64 v[246:247], v[140:141], 0, s[0:1]
	v_readfirstlane_b32 s53, v171
	ds_read_b128 v[188:191], v165
	ds_read_b128 v[192:195], v165 offset:1024
	ds_read_b128 v[196:199], v166
	ds_read_b128 v[200:203], v166 offset:1024
	ds_read_b128 v[204:207], v167
	ds_read_b128 v[208:211], v167 offset:1024
	ds_read_b128 v[212:215], v168
	ds_read_b128 v[216:219], v168 offset:1024
	global_load_lds_dwordx4 v[220:221], off
	v_lshl_add_u64 v[220:221], v[246:247], 0, s[6:7]
	s_mov_b32 m0, s53
	s_nop 0
	global_load_lds_dwordx4 v[220:221], off
	s_waitcnt lgkmcnt(8)
	s_barrier
	s_waitcnt lgkmcnt(0)
	s_setprio 1
	s_waitcnt lgkmcnt(0)
	v_mfma_f32_16x16x32_bf16 v[126:129], v[172:175], v[188:191], v[126:129]
	v_mfma_f32_16x16x32_bf16 v[122:125], v[180:183], v[188:191], v[122:125]
	v_mfma_f32_16x16x32_bf16 v[118:121], v[172:175], v[196:199], v[118:121]
	v_mfma_f32_16x16x32_bf16 v[114:117], v[180:183], v[196:199], v[114:117]
	v_mfma_f32_16x16x32_bf16 v[110:113], v[172:175], v[204:207], v[110:113]
	v_mfma_f32_16x16x32_bf16 v[106:109], v[180:183], v[204:207], v[106:109]
	v_mfma_f32_16x16x32_bf16 v[102:105], v[172:175], v[212:215], v[102:105]
	v_mfma_f32_16x16x32_bf16 v[98:101], v[180:183], v[212:215], v[98:101]
	v_mfma_f32_16x16x32_bf16 v[126:129], v[176:179], v[192:195], v[126:129]
	v_mfma_f32_16x16x32_bf16 v[122:125], v[184:187], v[192:195], v[122:125]
	v_mfma_f32_16x16x32_bf16 v[118:121], v[176:179], v[200:203], v[118:121]
	v_mfma_f32_16x16x32_bf16 v[114:117], v[184:187], v[200:203], v[114:117]
	v_mfma_f32_16x16x32_bf16 v[110:113], v[176:179], v[208:211], v[110:113]
	v_mfma_f32_16x16x32_bf16 v[106:109], v[184:187], v[208:211], v[106:109]
	v_mfma_f32_16x16x32_bf16 v[102:105], v[176:179], v[216:219], v[102:105]
	v_mfma_f32_16x16x32_bf16 v[98:101], v[184:187], v[216:219], v[98:101]
	s_setprio 0
	s_barrier
	v_lshl_add_u64 v[248:249], v[134:135], 0, s[0:1]
	v_readfirstlane_b32 s53, v144
	v_lshl_add_u64 v[238:239], v[248:249], 0, s[8:9]
	s_mov_b32 m0, s53
	v_lshl_add_u64 v[250:251], v[136:137], 0, s[0:1]
	v_readfirstlane_b32 s53, v145
	ds_read_b128 v[220:223], v169 offset:49152
	ds_read_b128 v[226:229], v169 offset:50176
	ds_read_b128 v[230:233], v169 offset:51200
	ds_read_b128 v[234:237], v169 offset:52224
	global_load_lds_dwordx4 v[238:239], off
	v_lshl_add_u64 v[238:239], v[250:251], 0, s[8:9]
	s_mov_b32 m0, s53
	s_nop 0
	global_load_lds_dwordx4 v[238:239], off
	s_barrier
	s_waitcnt lgkmcnt(0)
	s_setprio 1
	s_waitcnt lgkmcnt(0)
	v_mfma_f32_16x16x32_bf16 v[94:97], v[220:223], v[188:191], v[94:97]
	v_mfma_f32_16x16x32_bf16 v[90:93], v[230:233], v[188:191], v[90:93]
	v_mfma_f32_16x16x32_bf16 v[82:85], v[220:223], v[196:199], v[82:85]
	v_mfma_f32_16x16x32_bf16 v[66:69], v[230:233], v[196:199], v[66:69]
	v_mfma_f32_16x16x32_bf16 v[62:65], v[220:223], v[204:207], v[62:65]
	v_mfma_f32_16x16x32_bf16 v[58:61], v[230:233], v[204:207], v[58:61]
	v_mfma_f32_16x16x32_bf16 v[54:57], v[220:223], v[212:215], v[54:57]
	v_mfma_f32_16x16x32_bf16 v[50:53], v[230:233], v[212:215], v[50:53]
	v_mfma_f32_16x16x32_bf16 v[94:97], v[226:229], v[192:195], v[94:97]
	v_mfma_f32_16x16x32_bf16 v[90:93], v[234:237], v[192:195], v[90:93]
	v_mfma_f32_16x16x32_bf16 v[82:85], v[226:229], v[200:203], v[82:85]
	v_mfma_f32_16x16x32_bf16 v[66:69], v[234:237], v[200:203], v[66:69]
	v_mfma_f32_16x16x32_bf16 v[62:65], v[226:229], v[208:211], v[62:65]
	v_mfma_f32_16x16x32_bf16 v[58:61], v[234:237], v[208:211], v[58:61]
	v_mfma_f32_16x16x32_bf16 v[54:57], v[226:229], v[216:219], v[54:57]
	v_mfma_f32_16x16x32_bf16 v[50:53], v[234:237], v[216:219], v[50:53]
	s_setprio 0
	v_readfirstlane_b32 s53, v143
	v_lshl_add_u64 v[238:239], v[224:225], 0, s[10:11]
	s_mov_b32 m0, s53
	v_readfirstlane_b32 s53, v146
	s_barrier
	ds_read_b128 v[188:191], v165 offset:16384
	ds_read_b128 v[192:195], v165 offset:17408
	ds_read_b128 v[196:199], v166 offset:16384
	ds_read_b128 v[200:203], v166 offset:17408
	ds_read_b128 v[204:207], v167 offset:16384
	ds_read_b128 v[208:211], v167 offset:17408
	ds_read_b128 v[212:215], v168 offset:16384
	ds_read_b128 v[216:219], v168 offset:17408
	global_load_lds_dwordx4 v[238:239], off
	v_lshl_add_u64 v[238:239], v[246:247], 0, s[10:11]
	s_mov_b32 m0, s53
	s_nop 0
	global_load_lds_dwordx4 v[238:239], off
	s_barrier
	s_waitcnt lgkmcnt(0)
	s_setprio 1
	s_waitcnt lgkmcnt(0)
	v_mfma_f32_16x16x32_bf16 v[46:49], v[172:175], v[188:191], v[46:49]
	v_mfma_f32_16x16x32_bf16 v[42:45], v[180:183], v[188:191], v[42:45]
	v_mfma_f32_16x16x32_bf16 v[38:41], v[172:175], v[196:199], v[38:41]
	v_mfma_f32_16x16x32_bf16 v[34:37], v[180:183], v[196:199], v[34:37]
	v_mfma_f32_16x16x32_bf16 v[30:33], v[172:175], v[204:207], v[30:33]
	v_mfma_f32_16x16x32_bf16 v[26:29], v[180:183], v[204:207], v[26:29]
	v_mfma_f32_16x16x32_bf16 v[22:25], v[172:175], v[212:215], v[22:25]
	v_mfma_f32_16x16x32_bf16 v[18:21], v[180:183], v[212:215], v[18:21]
	v_mfma_f32_16x16x32_bf16 v[46:49], v[176:179], v[192:195], v[46:49]
	v_mfma_f32_16x16x32_bf16 v[42:45], v[184:187], v[192:195], v[42:45]
	v_mfma_f32_16x16x32_bf16 v[38:41], v[176:179], v[200:203], v[38:41]
	v_mfma_f32_16x16x32_bf16 v[34:37], v[184:187], v[200:203], v[34:37]
	v_mfma_f32_16x16x32_bf16 v[30:33], v[176:179], v[208:211], v[30:33]
	v_mfma_f32_16x16x32_bf16 v[26:29], v[184:187], v[208:211], v[26:29]
	v_mfma_f32_16x16x32_bf16 v[22:25], v[176:179], v[216:219], v[22:25]
	v_mfma_f32_16x16x32_bf16 v[18:21], v[184:187], v[216:219], v[18:21]
	s_setprio 0
	s_barrier
	v_readfirstlane_b32 s53, v147
	v_lshl_add_u64 v[172:173], v[248:249], 0, s[12:13]
	s_mov_b32 m0, s53
	v_readfirstlane_b32 s53, v148
	global_load_lds_dwordx4 v[172:173], off
	v_lshl_add_u64 v[172:173], v[250:251], 0, s[12:13]
	s_mov_b32 m0, s53
	s_nop 0
	global_load_lds_dwordx4 v[172:173], off
	s_waitcnt vmcnt(6)
	s_barrier
	s_setprio 1
	v_mfma_f32_16x16x32_bf16 v[14:17], v[220:223], v[188:191], v[14:17]
	v_mfma_f32_16x16x32_bf16 v[10:13], v[230:233], v[188:191], v[10:13]
	v_mfma_f32_16x16x32_bf16 v[6:9], v[220:223], v[196:199], v[6:9]
	v_mfma_f32_16x16x32_bf16 v[2:5], v[230:233], v[196:199], v[2:5]
	v_mfma_f32_16x16x32_bf16 v[70:73], v[220:223], v[204:207], v[70:73]
	v_mfma_f32_16x16x32_bf16 v[74:77], v[230:233], v[204:207], v[74:77]
	v_mfma_f32_16x16x32_bf16 v[78:81], v[220:223], v[212:215], v[78:81]
	v_mfma_f32_16x16x32_bf16 v[86:89], v[230:233], v[212:215], v[86:89]
	v_mfma_f32_16x16x32_bf16 v[14:17], v[226:229], v[192:195], v[14:17]
	v_mfma_f32_16x16x32_bf16 v[10:13], v[234:237], v[192:195], v[10:13]
	v_mfma_f32_16x16x32_bf16 v[6:9], v[226:229], v[200:203], v[6:9]
	v_mfma_f32_16x16x32_bf16 v[2:5], v[234:237], v[200:203], v[2:5]
	v_mfma_f32_16x16x32_bf16 v[70:73], v[226:229], v[208:211], v[70:73]
	v_mfma_f32_16x16x32_bf16 v[74:77], v[234:237], v[208:211], v[74:77]
	v_mfma_f32_16x16x32_bf16 v[78:81], v[226:229], v[216:219], v[78:81]
	v_mfma_f32_16x16x32_bf16 v[86:89], v[234:237], v[216:219], v[86:89]
	s_setprio 0
	s_barrier
	ds_read_b128 v[178:181], v154
	ds_read_b128 v[182:185], v154 offset:1024
	ds_read_b128 v[186:189], v154 offset:2048
	ds_read_b128 v[190:193], v154 offset:3072
	v_readfirstlane_b32 s53, v149
	v_add_u32_e32 v172, s41, v163
	v_add_u32_e32 v173, s44, v163
	v_add_u32_e32 v174, s45, v163
	v_lshl_add_u64 v[176:177], v[224:225], 0, s[18:19]
	s_mov_b32 m0, s53
	v_readfirstlane_b32 s53, v150
	ds_read_b128 v[194:197], v153
	ds_read_b128 v[198:201], v153 offset:1024
	ds_read_b128 v[202:205], v172
	ds_read_b128 v[206:209], v172 offset:1024
	ds_read_b128 v[210:213], v173
	ds_read_b128 v[214:217], v173 offset:1024
	ds_read_b128 v[218:221], v174
	ds_read_b128 v[226:229], v174 offset:1024
	global_load_lds_dwordx4 v[176:177], off
	v_lshl_add_u64 v[176:177], v[246:247], 0, s[18:19]
	s_mov_b32 m0, s53
	s_nop 0
	global_load_lds_dwordx4 v[176:177], off
	s_waitcnt lgkmcnt(8)
	s_barrier
	s_waitcnt lgkmcnt(0)
	s_setprio 1
	s_waitcnt lgkmcnt(0)
	v_mfma_f32_16x16x32_bf16 v[126:129], v[178:181], v[194:197], v[126:129]
	v_mfma_f32_16x16x32_bf16 v[122:125], v[186:189], v[194:197], v[122:125]
	v_mfma_f32_16x16x32_bf16 v[118:121], v[178:181], v[202:205], v[118:121]
	v_mfma_f32_16x16x32_bf16 v[114:117], v[186:189], v[202:205], v[114:117]
	v_mfma_f32_16x16x32_bf16 v[110:113], v[178:181], v[210:213], v[110:113]
	v_mfma_f32_16x16x32_bf16 v[106:109], v[186:189], v[210:213], v[106:109]
	v_mfma_f32_16x16x32_bf16 v[102:105], v[178:181], v[218:221], v[102:105]
	v_mfma_f32_16x16x32_bf16 v[98:101], v[186:189], v[218:221], v[98:101]
	v_mfma_f32_16x16x32_bf16 v[126:129], v[182:185], v[198:201], v[126:129]
	v_mfma_f32_16x16x32_bf16 v[122:125], v[190:193], v[198:201], v[122:125]
	v_mfma_f32_16x16x32_bf16 v[118:121], v[182:185], v[206:209], v[118:121]
	v_mfma_f32_16x16x32_bf16 v[114:117], v[190:193], v[206:209], v[114:117]
	v_mfma_f32_16x16x32_bf16 v[110:113], v[182:185], v[214:217], v[110:113]
	v_mfma_f32_16x16x32_bf16 v[106:109], v[190:193], v[214:217], v[106:109]
	v_mfma_f32_16x16x32_bf16 v[102:105], v[182:185], v[226:229], v[102:105]
	v_mfma_f32_16x16x32_bf16 v[98:101], v[190:193], v[226:229], v[98:101]
	s_setprio 0
	s_barrier
	v_readfirstlane_b32 s53, v155
	v_lshl_add_u64 v[176:177], v[248:249], 0, s[22:23]
	s_mov_b32 m0, s53
	v_readfirstlane_b32 s53, v156
	ds_read_b128 v[230:233], v152
	ds_read_b128 v[234:237], v152 offset:1024
	ds_read_b128 v[238:241], v152 offset:2048
	ds_read_b128 v[242:245], v152 offset:3072
	global_load_lds_dwordx4 v[176:177], off
	v_lshl_add_u64 v[176:177], v[250:251], 0, s[22:23]
	s_mov_b32 m0, s53
	s_nop 0
	global_load_lds_dwordx4 v[176:177], off
	s_barrier
	s_waitcnt lgkmcnt(0)
	s_setprio 1
	s_waitcnt lgkmcnt(0)
	v_mfma_f32_16x16x32_bf16 v[94:97], v[230:233], v[194:197], v[94:97]
	v_mfma_f32_16x16x32_bf16 v[90:93], v[238:241], v[194:197], v[90:93]
	v_mfma_f32_16x16x32_bf16 v[82:85], v[230:233], v[202:205], v[82:85]
	v_mfma_f32_16x16x32_bf16 v[66:69], v[238:241], v[202:205], v[66:69]
	v_mfma_f32_16x16x32_bf16 v[62:65], v[230:233], v[210:213], v[62:65]
	v_mfma_f32_16x16x32_bf16 v[58:61], v[238:241], v[210:213], v[58:61]
	v_mfma_f32_16x16x32_bf16 v[54:57], v[230:233], v[218:221], v[54:57]
	v_mfma_f32_16x16x32_bf16 v[50:53], v[238:241], v[218:221], v[50:53]
	v_mfma_f32_16x16x32_bf16 v[94:97], v[234:237], v[198:201], v[94:97]
	v_mfma_f32_16x16x32_bf16 v[90:93], v[242:245], v[198:201], v[90:93]
	v_mfma_f32_16x16x32_bf16 v[82:85], v[234:237], v[206:209], v[82:85]
	v_mfma_f32_16x16x32_bf16 v[66:69], v[242:245], v[206:209], v[66:69]
	v_mfma_f32_16x16x32_bf16 v[62:65], v[234:237], v[214:217], v[62:65]
	v_mfma_f32_16x16x32_bf16 v[58:61], v[242:245], v[214:217], v[58:61]
	v_mfma_f32_16x16x32_bf16 v[54:57], v[234:237], v[226:229], v[54:57]
	v_mfma_f32_16x16x32_bf16 v[50:53], v[242:245], v[226:229], v[50:53]
	s_setprio 0
	v_readfirstlane_b32 s53, v157
	v_add_u32_e32 v175, s41, v164
	v_add_u32_e32 v176, s44, v164
	v_add_u32_e32 v177, s45, v164
	v_lshl_add_u64 v[222:223], v[224:225], 0, s[24:25]
	s_mov_b32 m0, s53
	v_readfirstlane_b32 s53, v158
	s_barrier
	ds_read_b128 v[194:197], v151
	ds_read_b128 v[198:201], v151 offset:1024
	ds_read_b128 v[202:205], v175
	ds_read_b128 v[206:209], v175 offset:1024
	ds_read_b128 v[210:213], v176
	ds_read_b128 v[214:217], v176 offset:1024
	ds_read_b128 v[218:221], v177
	ds_read_b128 v[226:229], v177 offset:1024
	global_load_lds_dwordx4 v[222:223], off
	v_lshl_add_u64 v[222:223], v[246:247], 0, s[24:25]
	s_mov_b32 m0, s53
	s_nop 0
	global_load_lds_dwordx4 v[222:223], off
	s_barrier
	s_waitcnt lgkmcnt(0)
	s_setprio 1
	s_waitcnt lgkmcnt(0)
	v_mfma_f32_16x16x32_bf16 v[46:49], v[178:181], v[194:197], v[46:49]
	v_mfma_f32_16x16x32_bf16 v[42:45], v[186:189], v[194:197], v[42:45]
	v_mfma_f32_16x16x32_bf16 v[38:41], v[178:181], v[202:205], v[38:41]
	v_mfma_f32_16x16x32_bf16 v[34:37], v[186:189], v[202:205], v[34:37]
	v_mfma_f32_16x16x32_bf16 v[30:33], v[178:181], v[210:213], v[30:33]
	v_mfma_f32_16x16x32_bf16 v[26:29], v[186:189], v[210:213], v[26:29]
	v_mfma_f32_16x16x32_bf16 v[22:25], v[178:181], v[218:221], v[22:25]
	v_mfma_f32_16x16x32_bf16 v[18:21], v[186:189], v[218:221], v[18:21]
	v_mfma_f32_16x16x32_bf16 v[46:49], v[182:185], v[198:201], v[46:49]
	v_mfma_f32_16x16x32_bf16 v[42:45], v[190:193], v[198:201], v[42:45]
	v_mfma_f32_16x16x32_bf16 v[38:41], v[182:185], v[206:209], v[38:41]
	v_mfma_f32_16x16x32_bf16 v[34:37], v[190:193], v[206:209], v[34:37]
	v_mfma_f32_16x16x32_bf16 v[30:33], v[182:185], v[214:217], v[30:33]
	v_mfma_f32_16x16x32_bf16 v[26:29], v[190:193], v[214:217], v[26:29]
	v_mfma_f32_16x16x32_bf16 v[22:25], v[182:185], v[226:229], v[22:25]
	v_mfma_f32_16x16x32_bf16 v[18:21], v[190:193], v[226:229], v[18:21]
	s_setprio 0
	s_barrier
	v_readfirstlane_b32 s53, v159
	v_lshl_add_u64 v[178:179], v[248:249], 0, s[26:27]
	s_mov_b32 m0, s53
	v_readfirstlane_b32 s53, v160
	global_load_lds_dwordx4 v[178:179], off
	v_lshl_add_u64 v[178:179], v[250:251], 0, s[26:27]
	s_mov_b32 m0, s53
	s_nop 0
	global_load_lds_dwordx4 v[178:179], off
	s_waitcnt vmcnt(6)
	s_barrier
	s_setprio 1
	v_mfma_f32_16x16x32_bf16 v[14:17], v[230:233], v[194:197], v[14:17]
	v_mfma_f32_16x16x32_bf16 v[10:13], v[238:241], v[194:197], v[10:13]
	v_mfma_f32_16x16x32_bf16 v[6:9], v[230:233], v[202:205], v[6:9]
	v_mfma_f32_16x16x32_bf16 v[2:5], v[238:241], v[202:205], v[2:5]
	v_mfma_f32_16x16x32_bf16 v[70:73], v[230:233], v[210:213], v[70:73]
	v_mfma_f32_16x16x32_bf16 v[74:77], v[238:241], v[210:213], v[74:77]
	v_mfma_f32_16x16x32_bf16 v[78:81], v[230:233], v[218:221], v[78:81]
	v_mfma_f32_16x16x32_bf16 v[86:89], v[238:241], v[218:221], v[86:89]
	v_mfma_f32_16x16x32_bf16 v[14:17], v[234:237], v[198:201], v[14:17]
	v_mfma_f32_16x16x32_bf16 v[10:13], v[242:245], v[198:201], v[10:13]
	v_mfma_f32_16x16x32_bf16 v[6:9], v[234:237], v[206:209], v[6:9]
	v_mfma_f32_16x16x32_bf16 v[2:5], v[242:245], v[206:209], v[2:5]
	v_mfma_f32_16x16x32_bf16 v[70:73], v[234:237], v[214:217], v[70:73]
	v_mfma_f32_16x16x32_bf16 v[74:77], v[242:245], v[214:217], v[74:77]
	v_mfma_f32_16x16x32_bf16 v[78:81], v[234:237], v[226:229], v[78:81]
	v_mfma_f32_16x16x32_bf16 v[86:89], v[242:245], v[226:229], v[86:89]
	s_setprio 0
	s_add_i32 s52, s52, 2
	s_add_u32 s0, s0, 0x100
	s_addc_u32 s1, s1, 0
	s_cmp_lt_u32 s52, 12
	s_barrier
	s_cbranch_scc1 .LBB0_1913
	s_or_b32 s0, s34, 0x80
	s_ashr_i32 s1, s0, 31
	s_lshl_b64 s[44:45], s[0:1], 11
	s_add_u32 s44, s60, s44
	s_addc_u32 s45, s61, s45
	v_lshl_add_u64 v[202:203], v[130:131], 1, s[44:45]
	v_readfirstlane_b32 s1, v170
	v_lshl_add_u64 v[202:203], v[202:203], 0, s[28:29]
	s_mov_b32 m0, s1
	v_lshl_add_u64 v[132:133], v[132:133], 1, s[44:45]
	v_readfirstlane_b32 s1, v171
	ds_read_b128 v[134:137], v169 offset:32768
	ds_read_b128 v[138:141], v169 offset:33792
	ds_read_b128 v[142:145], v169 offset:34816
	ds_read_b128 v[146:149], v169 offset:35840
	ds_read_b128 v[156:159], v165
	ds_read_b128 v[160:163], v165 offset:1024
	ds_read_b128 v[178:181], v166
	ds_read_b128 v[182:185], v166 offset:1024
	ds_read_b128 v[186:189], v167
	ds_read_b128 v[190:193], v167 offset:1024
	ds_read_b128 v[194:197], v168
	ds_read_b128 v[198:201], v168 offset:1024
	global_load_lds_dwordx4 v[202:203], off
	v_lshl_add_u64 v[132:133], v[132:133], 0, s[28:29]
	s_mov_b32 m0, s1
	s_nop 0
	global_load_lds_dwordx4 v[132:133], off
	s_barrier
	s_waitcnt lgkmcnt(0)
	s_setprio 1
	s_waitcnt lgkmcnt(0)
	v_mfma_f32_16x16x32_bf16 v[126:129], v[134:137], v[156:159], v[126:129]
	v_mfma_f32_16x16x32_bf16 v[122:125], v[142:145], v[156:159], v[122:125]
	v_mfma_f32_16x16x32_bf16 v[118:121], v[134:137], v[178:181], v[118:121]
	v_mfma_f32_16x16x32_bf16 v[114:117], v[142:145], v[178:181], v[114:117]
	v_mfma_f32_16x16x32_bf16 v[110:113], v[134:137], v[186:189], v[110:113]
	v_mfma_f32_16x16x32_bf16 v[126:129], v[138:141], v[160:163], v[126:129]
	v_mfma_f32_16x16x32_bf16 v[122:125], v[146:149], v[160:163], v[122:125]
	v_mfma_f32_16x16x32_bf16 v[118:121], v[138:141], v[182:185], v[118:121]
	v_mfma_f32_16x16x32_bf16 v[114:117], v[146:149], v[182:185], v[114:117]
	v_mfma_f32_16x16x32_bf16 v[110:113], v[138:141], v[190:193], v[110:113]
	v_mfma_f32_16x16x32_bf16 v[106:109], v[142:145], v[186:189], v[106:109]
	v_mfma_f32_16x16x32_bf16 v[102:105], v[134:137], v[194:197], v[102:105]
	v_mfma_f32_16x16x32_bf16 v[98:101], v[142:145], v[194:197], v[98:101]
	v_mfma_f32_16x16x32_bf16 v[202:205], v[146:149], v[190:193], v[106:109]
	v_mfma_f32_16x16x32_bf16 v[206:209], v[138:141], v[198:201], v[102:105]
	v_mfma_f32_16x16x32_bf16 v[210:213], v[146:149], v[198:201], v[98:101]
	s_setprio 0
	s_barrier
	s_nop 2
	ds_read_b128 v[98:101], v169 offset:49152
	ds_read_b128 v[102:105], v169 offset:50176
	ds_read_b128 v[106:109], v169 offset:51200
	ds_read_b128 v[214:217], v169 offset:52224
	s_barrier
	s_waitcnt lgkmcnt(0)
	s_setprio 1
	s_waitcnt lgkmcnt(0)
	v_mfma_f32_16x16x32_bf16 v[94:97], v[98:101], v[156:159], v[94:97]
	v_mfma_f32_16x16x32_bf16 v[90:93], v[106:109], v[156:159], v[90:93]
	v_mfma_f32_16x16x32_bf16 v[82:85], v[98:101], v[178:181], v[82:85]
	v_mfma_f32_16x16x32_bf16 v[62:65], v[98:101], v[186:189], v[62:65]
	v_mfma_f32_16x16x32_bf16 v[58:61], v[106:109], v[186:189], v[58:61]
	v_mfma_f32_16x16x32_bf16 v[54:57], v[98:101], v[194:197], v[54:57]
	v_mfma_f32_16x16x32_bf16 v[50:53], v[106:109], v[194:197], v[50:53]
	v_mfma_f32_16x16x32_bf16 v[94:97], v[102:105], v[160:163], v[94:97]
	v_mfma_f32_16x16x32_bf16 v[90:93], v[214:217], v[160:163], v[90:93]
	v_mfma_f32_16x16x32_bf16 v[82:85], v[102:105], v[182:185], v[82:85]
	v_mfma_f32_16x16x32_bf16 v[66:69], v[106:109], v[178:181], v[66:69]
	v_mfma_f32_16x16x32_bf16 v[62:65], v[102:105], v[190:193], v[62:65]
	v_mfma_f32_16x16x32_bf16 v[58:61], v[214:217], v[190:193], v[58:61]
	v_mfma_f32_16x16x32_bf16 v[54:57], v[102:105], v[198:201], v[54:57]
	v_mfma_f32_16x16x32_bf16 v[50:53], v[214:217], v[198:201], v[50:53]
	v_mfma_f32_16x16x32_bf16 v[156:159], v[214:217], v[182:185], v[66:69]
	s_setprio 0
	s_barrier
	s_nop 0
	ds_read_b128 v[66:69], v165 offset:16384
	ds_read_b128 v[160:163], v165 offset:17408
	ds_read_b128 v[178:181], v166 offset:16384
	ds_read_b128 v[182:185], v166 offset:17408
	ds_read_b128 v[186:189], v167 offset:16384
	ds_read_b128 v[164:167], v167 offset:17408
	ds_read_b128 v[190:193], v168 offset:16384
	ds_read_b128 v[168:171], v168 offset:17408
	s_waitcnt vmcnt(4)
	s_barrier
	s_waitcnt lgkmcnt(0)
	s_setprio 1
	s_waitcnt lgkmcnt(0)
	v_mfma_f32_16x16x32_bf16 v[46:49], v[134:137], v[66:69], v[46:49]
	v_mfma_f32_16x16x32_bf16 v[42:45], v[142:145], v[66:69], v[42:45]
	v_mfma_f32_16x16x32_bf16 v[30:33], v[134:137], v[186:189], v[30:33]
	v_mfma_f32_16x16x32_bf16 v[26:29], v[142:145], v[186:189], v[26:29]
	v_mfma_f32_16x16x32_bf16 v[22:25], v[134:137], v[190:193], v[22:25]
	v_mfma_f32_16x16x32_bf16 v[18:21], v[142:145], v[190:193], v[18:21]
	v_mfma_f32_16x16x32_bf16 v[46:49], v[138:141], v[160:163], v[46:49]
	v_mfma_f32_16x16x32_bf16 v[42:45], v[146:149], v[160:163], v[42:45]
	v_mfma_f32_16x16x32_bf16 v[38:41], v[134:137], v[178:181], v[38:41]
	v_mfma_f32_16x16x32_bf16 v[34:37], v[142:145], v[178:181], v[34:37]
	v_mfma_f32_16x16x32_bf16 v[30:33], v[138:141], v[164:167], v[30:33]
	v_mfma_f32_16x16x32_bf16 v[26:29], v[146:149], v[164:167], v[26:29]
	v_mfma_f32_16x16x32_bf16 v[22:25], v[138:141], v[168:171], v[22:25]
	v_mfma_f32_16x16x32_bf16 v[18:21], v[146:149], v[168:171], v[18:21]
	v_mfma_f32_16x16x32_bf16 v[194:197], v[138:141], v[182:185], v[38:41]
	v_mfma_f32_16x16x32_bf16 v[198:201], v[146:149], v[182:185], v[34:37]
	s_setprio 0
	s_setprio 1
	v_mfma_f32_16x16x32_bf16 v[2:5], v[106:109], v[178:181], v[2:5]
	v_mfma_f32_16x16x32_bf16 v[136:139], v[214:217], v[182:185], v[2:5]
	v_mfma_f32_16x16x32_bf16 v[2:5], v[98:101], v[186:189], v[70:73]
	v_mfma_f32_16x16x32_bf16 v[140:143], v[102:105], v[164:167], v[2:5]
	v_mfma_f32_16x16x32_bf16 v[2:5], v[106:109], v[186:189], v[74:77]
	v_mfma_f32_16x16x32_bf16 v[14:17], v[98:101], v[66:69], v[14:17]
	v_mfma_f32_16x16x32_bf16 v[10:13], v[106:109], v[66:69], v[10:13]
	v_mfma_f32_16x16x32_bf16 v[144:147], v[214:217], v[164:167], v[2:5]
	v_mfma_f32_16x16x32_bf16 v[2:5], v[98:101], v[190:193], v[78:81]
	v_mfma_f32_16x16x32_bf16 v[14:17], v[102:105], v[160:163], v[14:17]
	v_mfma_f32_16x16x32_bf16 v[10:13], v[214:217], v[160:163], v[10:13]
	v_mfma_f32_16x16x32_bf16 v[6:9], v[98:101], v[178:181], v[6:9]
	v_mfma_f32_16x16x32_bf16 v[160:163], v[102:105], v[168:171], v[2:5]
	v_mfma_f32_16x16x32_bf16 v[2:5], v[106:109], v[190:193], v[86:89]
	v_mfma_f32_16x16x32_bf16 v[132:135], v[102:105], v[182:185], v[6:9]
	v_mfma_f32_16x16x32_bf16 v[164:167], v[214:217], v[168:171], v[2:5]
	s_setprio 0
	s_barrier
	s_nop 3
	ds_read_b128 v[2:5], v154
	ds_read_b128 v[6:9], v154 offset:1024
	ds_read_b128 v[168:171], v154 offset:2048
	ds_read_b128 v[178:181], v154 offset:3072
	ds_read_b128 v[34:37], v153
	ds_read_b128 v[38:41], v153 offset:1024
	ds_read_b128 v[78:81], v172
	ds_read_b128 v[86:89], v172 offset:1024
	ds_read_b128 v[182:185], v173
	ds_read_b128 v[186:189], v173 offset:1024
	ds_read_b128 v[190:193], v174
	ds_read_b128 v[214:217], v174 offset:1024
	s_waitcnt vmcnt(2)
	s_barrier
	s_waitcnt lgkmcnt(0)
	s_setprio 1
	s_waitcnt lgkmcnt(0)
	v_mfma_f32_16x16x32_bf16 v[66:69], v[2:5], v[34:37], v[126:129]
	v_mfma_f32_16x16x32_bf16 v[126:129], v[6:9], v[38:41], v[66:69]
	v_mfma_f32_16x16x32_bf16 v[66:69], v[168:171], v[34:37], v[122:125]
	v_mfma_f32_16x16x32_bf16 v[98:101], v[178:181], v[38:41], v[66:69]
	v_mfma_f32_16x16x32_bf16 v[66:69], v[2:5], v[78:81], v[118:121]
	v_mfma_f32_16x16x32_bf16 v[102:105], v[6:9], v[86:89], v[66:69]
	v_mfma_f32_16x16x32_bf16 v[66:69], v[168:171], v[78:81], v[114:117]
	v_mfma_f32_16x16x32_bf16 v[106:109], v[178:181], v[86:89], v[66:69]
	v_mfma_f32_16x16x32_bf16 v[66:69], v[2:5], v[182:185], v[110:113]
	v_mfma_f32_16x16x32_bf16 v[110:113], v[6:9], v[186:189], v[66:69]
	v_mfma_f32_16x16x32_bf16 v[66:69], v[168:171], v[182:185], v[202:205]
	v_mfma_f32_16x16x32_bf16 v[114:117], v[178:181], v[186:189], v[66:69]
	v_mfma_f32_16x16x32_bf16 v[66:69], v[2:5], v[190:193], v[206:209]
	v_mfma_f32_16x16x32_bf16 v[118:121], v[6:9], v[214:217], v[66:69]
	v_mfma_f32_16x16x32_bf16 v[66:69], v[168:171], v[190:193], v[210:213]
	v_mfma_f32_16x16x32_bf16 v[122:125], v[178:181], v[214:217], v[66:69]
	s_setprio 0
	s_barrier
	ds_read_b128 v[202:205], v152
	ds_read_b128 v[206:209], v152 offset:1024
	ds_read_b128 v[210:213], v152 offset:2048
	ds_read_b128 v[152:155], v152 offset:3072
	s_waitcnt vmcnt(0)
	s_barrier
	s_waitcnt lgkmcnt(0)
	s_setprio 1
	s_waitcnt lgkmcnt(0)
	v_mfma_f32_16x16x32_bf16 v[66:69], v[202:205], v[34:37], v[94:97]
	v_mfma_f32_16x16x32_bf16 v[34:37], v[210:213], v[34:37], v[90:93]
	v_mfma_f32_16x16x32_bf16 v[70:73], v[152:155], v[38:41], v[34:37]
	v_mfma_f32_16x16x32_bf16 v[34:37], v[202:205], v[78:81], v[82:85]
	v_mfma_f32_16x16x32_bf16 v[74:77], v[206:209], v[86:89], v[34:37]
	v_mfma_f32_16x16x32_bf16 v[34:37], v[210:213], v[78:81], v[156:159]
	v_mfma_f32_16x16x32_bf16 v[78:81], v[152:155], v[86:89], v[34:37]
	v_mfma_f32_16x16x32_bf16 v[34:37], v[202:205], v[182:185], v[62:65]
	v_mfma_f32_16x16x32_bf16 v[82:85], v[206:209], v[186:189], v[34:37]
	v_mfma_f32_16x16x32_bf16 v[34:37], v[210:213], v[182:185], v[58:61]
	v_mfma_f32_16x16x32_bf16 v[86:89], v[152:155], v[186:189], v[34:37]
	v_mfma_f32_16x16x32_bf16 v[34:37], v[202:205], v[190:193], v[54:57]
	v_mfma_f32_16x16x32_bf16 v[90:93], v[206:209], v[214:217], v[34:37]
	v_mfma_f32_16x16x32_bf16 v[34:37], v[210:213], v[190:193], v[50:53]
	v_mfma_f32_16x16x32_bf16 v[66:69], v[206:209], v[38:41], v[66:69]
	v_mfma_f32_16x16x32_bf16 v[94:97], v[152:155], v[214:217], v[34:37]
	s_setprio 0
	s_barrier
	ds_read_b128 v[156:159], v151
	ds_read_b128 v[148:151], v151 offset:1024
	ds_read_b128 v[182:185], v175
	ds_read_b128 v[172:175], v175 offset:1024
	ds_read_b128 v[186:189], v176
	ds_read_b128 v[190:193], v176 offset:1024
	ds_read_b128 v[214:217], v177
	ds_read_b128 v[218:221], v177 offset:1024
	s_barrier
	s_waitcnt lgkmcnt(0)
	s_setprio 1
	s_waitcnt lgkmcnt(0)
	v_mfma_f32_16x16x32_bf16 v[34:37], v[2:5], v[156:159], v[46:49]
	v_mfma_f32_16x16x32_bf16 v[38:41], v[168:171], v[156:159], v[42:45]
	v_mfma_f32_16x16x32_bf16 v[42:45], v[2:5], v[182:185], v[194:197]
	v_mfma_f32_16x16x32_bf16 v[30:33], v[2:5], v[186:189], v[30:33]
	v_mfma_f32_16x16x32_bf16 v[2:5], v[2:5], v[214:217], v[22:25]
	v_mfma_f32_16x16x32_bf16 v[46:49], v[168:171], v[182:185], v[198:201]
	v_mfma_f32_16x16x32_bf16 v[26:29], v[168:171], v[186:189], v[26:29]
	v_mfma_f32_16x16x32_bf16 v[58:61], v[6:9], v[218:221], v[2:5]
	v_mfma_f32_16x16x32_bf16 v[2:5], v[168:171], v[214:217], v[18:21]
	v_mfma_f32_16x16x32_bf16 v[34:37], v[6:9], v[148:151], v[34:37]
	v_mfma_f32_16x16x32_bf16 v[38:41], v[178:181], v[148:151], v[38:41]
	v_mfma_f32_16x16x32_bf16 v[42:45], v[6:9], v[172:175], v[42:45]
	v_mfma_f32_16x16x32_bf16 v[46:49], v[178:181], v[172:175], v[46:49]
	v_mfma_f32_16x16x32_bf16 v[50:53], v[6:9], v[190:193], v[30:33]
	v_mfma_f32_16x16x32_bf16 v[54:57], v[178:181], v[190:193], v[26:29]
	v_mfma_f32_16x16x32_bf16 v[62:65], v[178:181], v[218:221], v[2:5]
	s_setprio 0
	s_setprio 1
	v_mfma_f32_16x16x32_bf16 v[2:5], v[202:205], v[156:159], v[14:17]
	v_mfma_f32_16x16x32_bf16 v[6:9], v[210:213], v[156:159], v[10:13]
	v_mfma_f32_16x16x32_bf16 v[10:13], v[202:205], v[182:185], v[132:135]
	v_mfma_f32_16x16x32_bf16 v[14:17], v[210:213], v[182:185], v[136:139]
	v_mfma_f32_16x16x32_bf16 v[18:21], v[202:205], v[186:189], v[140:143]
	v_mfma_f32_16x16x32_bf16 v[22:25], v[210:213], v[186:189], v[144:147]
	v_mfma_f32_16x16x32_bf16 v[26:29], v[202:205], v[214:217], v[160:163]
	v_mfma_f32_16x16x32_bf16 v[30:33], v[210:213], v[214:217], v[164:167]
	v_mfma_f32_16x16x32_bf16 v[2:5], v[206:209], v[148:151], v[2:5]
	v_mfma_f32_16x16x32_bf16 v[6:9], v[152:155], v[148:151], v[6:9]
	v_mfma_f32_16x16x32_bf16 v[10:13], v[206:209], v[172:175], v[10:13]
	v_mfma_f32_16x16x32_bf16 v[14:17], v[152:155], v[172:175], v[14:17]
	v_mfma_f32_16x16x32_bf16 v[18:21], v[206:209], v[190:193], v[18:21]
	v_mfma_f32_16x16x32_bf16 v[22:25], v[152:155], v[190:193], v[22:25]
	v_mfma_f32_16x16x32_bf16 v[26:29], v[206:209], v[218:221], v[26:29]
	v_mfma_f32_16x16x32_bf16 v[30:33], v[152:155], v[218:221], v[30:33]
	s_setprio 0
	s_cmpk_gt_u32 s39, 0xff
	s_barrier
	s_cbranch_scc1 .LBB0_1916
	s_barrier

.LBB0_1918:
	v_and_b32_e32 v132, 15, v0
	v_lshrrev_b32_e32 v133, 8, v0
	v_lshl_add_u32 v132, v133, 6, v132
	v_add_u32_e32 v132, s34, v132
	v_mul_u32_u24_e32 v132, 0x1600, v132
	v_bfe_u32 v133, v0, 4, 4
	s_lshl_b32 s1, s51, 8
	v_lshl_add_u32 v132, v133, 3, v132
	v_add_u32_e32 v140, s1, v132
	v_mul_f32_e32 v132, 0xbfb8aa3b, v126
	v_mul_f32_e32 v133, 0xbfb8aa3b, v127
	v_mul_f32_e32 v134, 0xbfb8aa3b, v128
	v_mul_f32_e32 v135, 0xbfb8aa3b, v129
	v_mul_f32_e32 v136, 0xbfb8aa3b, v66
	v_mul_f32_e32 v137, 0xbfb8aa3b, v67
	v_mul_f32_e32 v138, 0xbfb8aa3b, v68
	v_mul_f32_e32 v139, 0xbfb8aa3b, v69
	v_exp_f32_e32 v132, v132
	v_exp_f32_e32 v133, v133
	v_exp_f32_e32 v134, v134
	v_exp_f32_e32 v135, v135
	v_exp_f32_e32 v136, v136
	v_exp_f32_e32 v137, v137
	v_exp_f32_e32 v138, v138
	v_exp_f32_e32 v139, v139
	v_add_f32_e32 v132, 1.0, v132
	v_add_f32_e32 v133, 1.0, v133
	v_add_f32_e32 v134, 1.0, v134
	v_add_f32_e32 v135, 1.0, v135
	v_add_f32_e32 v136, 1.0, v136
	v_add_f32_e32 v137, 1.0, v137
	v_add_f32_e32 v138, 1.0, v138
	v_add_f32_e32 v139, 1.0, v139
	v_rcp_f32_e32 v132, v132
	v_rcp_f32_e32 v133, v133
	v_rcp_f32_e32 v134, v134
	v_rcp_f32_e32 v135, v135
	v_rcp_f32_e32 v136, v136
	v_rcp_f32_e32 v137, v137
	v_rcp_f32_e32 v138, v138
	v_rcp_f32_e32 v139, v139
	v_pk_mul_f32 v[126:127], v[126:127], v[132:133]
	v_pk_mul_f32 v[128:129], v[128:129], v[134:135]
	v_pk_mul_f32 v[66:67], v[66:67], v[136:137]
	v_pk_mul_f32 v[68:69], v[68:69], v[138:139]
	v_pk_mul_f32 v[126:127], v[98:99], v[126:127]
	v_pk_mul_f32 v[128:129], v[100:101], v[128:129]
	v_pk_mul_f32 v[66:67], v[70:71], v[66:67]
	v_pk_mul_f32 v[68:69], v[72:73], v[68:69]
	v_cvt_pk_bf16_f32 v126, v126, v127
	v_cvt_pk_bf16_f32 v127, v128, v129
	v_cvt_pk_bf16_f32 v66, v66, v67
	v_cvt_pk_bf16_f32 v67, v68, v69
	global_store_dwordx2 v140, v[126:127], s[94:95]
	global_store_dwordx2 v140, v[66:67], s[94:95] offset:128
	v_add_u32_e32 v142, 0x16000, v140
	v_mul_f32_e32 v132, 0xbfb8aa3b, v102
	v_mul_f32_e32 v133, 0xbfb8aa3b, v103
	v_mul_f32_e32 v134, 0xbfb8aa3b, v104
	v_mul_f32_e32 v135, 0xbfb8aa3b, v105
	v_mul_f32_e32 v136, 0xbfb8aa3b, v74
	v_mul_f32_e32 v137, 0xbfb8aa3b, v75
	v_mul_f32_e32 v138, 0xbfb8aa3b, v76
	v_mul_f32_e32 v139, 0xbfb8aa3b, v77
	v_exp_f32_e32 v132, v132
	v_exp_f32_e32 v133, v133
	v_exp_f32_e32 v134, v134
	v_exp_f32_e32 v135, v135
	v_exp_f32_e32 v136, v136
	v_exp_f32_e32 v137, v137
	v_exp_f32_e32 v138, v138
	v_exp_f32_e32 v139, v139
	v_add_f32_e32 v132, 1.0, v132
	v_add_f32_e32 v133, 1.0, v133
	v_add_f32_e32 v134, 1.0, v134
	v_add_f32_e32 v135, 1.0, v135
	v_add_f32_e32 v136, 1.0, v136
	v_add_f32_e32 v137, 1.0, v137
	v_add_f32_e32 v138, 1.0, v138
	v_add_f32_e32 v139, 1.0, v139
	v_rcp_f32_e32 v132, v132
	v_rcp_f32_e32 v133, v133
	v_rcp_f32_e32 v134, v134
	v_rcp_f32_e32 v135, v135
	v_rcp_f32_e32 v136, v136
	v_rcp_f32_e32 v137, v137
	v_rcp_f32_e32 v138, v138
	v_rcp_f32_e32 v139, v139
	v_pk_mul_f32 v[102:103], v[102:103], v[132:133]
	v_pk_mul_f32 v[104:105], v[104:105], v[134:135]
	v_pk_mul_f32 v[74:75], v[74:75], v[136:137]
	v_pk_mul_f32 v[76:77], v[76:77], v[138:139]
	v_pk_mul_f32 v[102:103], v[106:107], v[102:103]
	v_pk_mul_f32 v[104:105], v[108:109], v[104:105]
	v_pk_mul_f32 v[74:75], v[78:79], v[74:75]
	v_pk_mul_f32 v[76:77], v[80:81], v[76:77]
	v_cvt_pk_bf16_f32 v102, v102, v103
	v_cvt_pk_bf16_f32 v103, v104, v105
	v_cvt_pk_bf16_f32 v74, v74, v75
	v_cvt_pk_bf16_f32 v75, v76, v77
	global_store_dwordx2 v142, v[102:103], s[94:95]
	global_store_dwordx2 v142, v[74:75], s[94:95] offset:128
	v_add_u32_e32 v141, 0x2c000, v140
	v_mul_f32_e32 v132, 0xbfb8aa3b, v110
	v_mul_f32_e32 v133, 0xbfb8aa3b, v111
	v_mul_f32_e32 v134, 0xbfb8aa3b, v112
	v_mul_f32_e32 v135, 0xbfb8aa3b, v113
	v_mul_f32_e32 v136, 0xbfb8aa3b, v82
	v_mul_f32_e32 v137, 0xbfb8aa3b, v83
	v_mul_f32_e32 v138, 0xbfb8aa3b, v84
	v_mul_f32_e32 v139, 0xbfb8aa3b, v85
	v_exp_f32_e32 v132, v132
	v_exp_f32_e32 v133, v133
	v_exp_f32_e32 v134, v134
	v_exp_f32_e32 v135, v135
	v_exp_f32_e32 v136, v136
	v_exp_f32_e32 v137, v137
	v_exp_f32_e32 v138, v138
	v_exp_f32_e32 v139, v139
	v_add_f32_e32 v132, 1.0, v132
	v_add_f32_e32 v133, 1.0, v133
	v_add_f32_e32 v134, 1.0, v134
	v_add_f32_e32 v135, 1.0, v135
	v_add_f32_e32 v136, 1.0, v136
	v_add_f32_e32 v137, 1.0, v137
	v_add_f32_e32 v138, 1.0, v138
	v_add_f32_e32 v139, 1.0, v139
	v_rcp_f32_e32 v132, v132
	v_rcp_f32_e32 v133, v133
	v_rcp_f32_e32 v134, v134
	v_rcp_f32_e32 v135, v135
	v_rcp_f32_e32 v136, v136
	v_rcp_f32_e32 v137, v137
	v_rcp_f32_e32 v138, v138
	v_rcp_f32_e32 v139, v139
	v_pk_mul_f32 v[110:111], v[110:111], v[132:133]
	v_pk_mul_f32 v[112:113], v[112:113], v[134:135]
	v_pk_mul_f32 v[82:83], v[82:83], v[136:137]
	v_pk_mul_f32 v[84:85], v[84:85], v[138:139]
	v_pk_mul_f32 v[110:111], v[114:115], v[110:111]
	v_pk_mul_f32 v[112:113], v[116:117], v[112:113]
	v_pk_mul_f32 v[82:83], v[86:87], v[82:83]
	v_pk_mul_f32 v[84:85], v[88:89], v[84:85]
	v_cvt_pk_bf16_f32 v110, v110, v111
	v_cvt_pk_bf16_f32 v111, v112, v113
	v_cvt_pk_bf16_f32 v82, v82, v83
	v_cvt_pk_bf16_f32 v83, v84, v85
	global_store_dwordx2 v141, v[110:111], s[94:95]
	global_store_dwordx2 v141, v[82:83], s[94:95] offset:128
	v_add_u32_e32 v142, 0x42000, v140
	v_mul_f32_e32 v132, 0xbfb8aa3b, v118
	v_mul_f32_e32 v133, 0xbfb8aa3b, v119
	v_mul_f32_e32 v134, 0xbfb8aa3b, v120
	v_mul_f32_e32 v135, 0xbfb8aa3b, v121
	v_mul_f32_e32 v136, 0xbfb8aa3b, v90
	v_mul_f32_e32 v137, 0xbfb8aa3b, v91
	v_mul_f32_e32 v138, 0xbfb8aa3b, v92
	v_mul_f32_e32 v139, 0xbfb8aa3b, v93
	v_exp_f32_e32 v132, v132
	v_exp_f32_e32 v133, v133
	v_exp_f32_e32 v134, v134
	v_exp_f32_e32 v135, v135
	v_exp_f32_e32 v136, v136
	v_exp_f32_e32 v137, v137
	v_exp_f32_e32 v138, v138
	v_exp_f32_e32 v139, v139
	v_add_f32_e32 v132, 1.0, v132
	v_add_f32_e32 v133, 1.0, v133
	v_add_f32_e32 v134, 1.0, v134
	v_add_f32_e32 v135, 1.0, v135
	v_add_f32_e32 v136, 1.0, v136
	v_add_f32_e32 v137, 1.0, v137
	v_add_f32_e32 v138, 1.0, v138
	v_add_f32_e32 v139, 1.0, v139
	v_rcp_f32_e32 v132, v132
	v_rcp_f32_e32 v133, v133
	v_rcp_f32_e32 v134, v134
	v_rcp_f32_e32 v135, v135
	v_rcp_f32_e32 v136, v136
	v_rcp_f32_e32 v137, v137
	v_rcp_f32_e32 v138, v138
	v_rcp_f32_e32 v139, v139
	v_pk_mul_f32 v[118:119], v[118:119], v[132:133]
	v_pk_mul_f32 v[120:121], v[120:121], v[134:135]
	v_pk_mul_f32 v[90:91], v[90:91], v[136:137]
	v_pk_mul_f32 v[92:93], v[92:93], v[138:139]
	v_pk_mul_f32 v[118:119], v[122:123], v[118:119]
	v_pk_mul_f32 v[120:121], v[124:125], v[120:121]
	v_pk_mul_f32 v[90:91], v[94:95], v[90:91]
	v_pk_mul_f32 v[92:93], v[96:97], v[92:93]
	v_cvt_pk_bf16_f32 v118, v118, v119
	v_cvt_pk_bf16_f32 v119, v120, v121
	v_cvt_pk_bf16_f32 v90, v90, v91
	v_cvt_pk_bf16_f32 v91, v92, v93
	global_store_dwordx2 v142, v[118:119], s[94:95]
	global_store_dwordx2 v142, v[90:91], s[94:95] offset:128
	v_add_u32_e32 v141, 0xb0000, v140
	v_mul_f32_e32 v132, 0xbfb8aa3b, v34
	v_mul_f32_e32 v133, 0xbfb8aa3b, v35
	v_mul_f32_e32 v134, 0xbfb8aa3b, v36
	v_mul_f32_e32 v135, 0xbfb8aa3b, v37
	v_mul_f32_e32 v136, 0xbfb8aa3b, v2
	v_mul_f32_e32 v137, 0xbfb8aa3b, v3
	v_mul_f32_e32 v138, 0xbfb8aa3b, v4
	v_mul_f32_e32 v139, 0xbfb8aa3b, v5
	v_exp_f32_e32 v132, v132
	v_exp_f32_e32 v133, v133
	v_exp_f32_e32 v134, v134
	v_exp_f32_e32 v135, v135
	v_exp_f32_e32 v136, v136
	v_exp_f32_e32 v137, v137
	v_exp_f32_e32 v138, v138
	v_exp_f32_e32 v139, v139
	v_add_f32_e32 v132, 1.0, v132
	v_add_f32_e32 v133, 1.0, v133
	v_add_f32_e32 v134, 1.0, v134
	v_add_f32_e32 v135, 1.0, v135
	v_add_f32_e32 v136, 1.0, v136
	v_add_f32_e32 v137, 1.0, v137
	v_add_f32_e32 v138, 1.0, v138
	v_add_f32_e32 v139, 1.0, v139
	v_rcp_f32_e32 v132, v132
	v_rcp_f32_e32 v133, v133
	v_rcp_f32_e32 v134, v134
	v_rcp_f32_e32 v135, v135
	v_rcp_f32_e32 v136, v136
	v_rcp_f32_e32 v137, v137
	v_rcp_f32_e32 v138, v138
	v_rcp_f32_e32 v139, v139
	v_pk_mul_f32 v[34:35], v[34:35], v[132:133]
	v_pk_mul_f32 v[36:37], v[36:37], v[134:135]
	v_pk_mul_f32 v[2:3], v[2:3], v[136:137]
	v_pk_mul_f32 v[4:5], v[4:5], v[138:139]
	v_pk_mul_f32 v[34:35], v[38:39], v[34:35]
	v_pk_mul_f32 v[36:37], v[40:41], v[36:37]
	v_pk_mul_f32 v[2:3], v[6:7], v[2:3]
	v_pk_mul_f32 v[4:5], v[8:9], v[4:5]
	v_cvt_pk_bf16_f32 v34, v34, v35
	v_cvt_pk_bf16_f32 v35, v36, v37
	v_cvt_pk_bf16_f32 v2, v2, v3
	v_cvt_pk_bf16_f32 v3, v4, v5
	global_store_dwordx2 v141, v[34:35], s[94:95]
	global_store_dwordx2 v141, v[2:3], s[94:95] offset:128
	v_add_u32_e32 v142, 0xc6000, v140
	v_mul_f32_e32 v132, 0xbfb8aa3b, v42
	v_mul_f32_e32 v133, 0xbfb8aa3b, v43
	v_mul_f32_e32 v134, 0xbfb8aa3b, v44
	v_mul_f32_e32 v135, 0xbfb8aa3b, v45
	v_mul_f32_e32 v136, 0xbfb8aa3b, v10
	v_mul_f32_e32 v137, 0xbfb8aa3b, v11
	v_mul_f32_e32 v138, 0xbfb8aa3b, v12
	v_mul_f32_e32 v139, 0xbfb8aa3b, v13
	v_exp_f32_e32 v132, v132
	v_exp_f32_e32 v133, v133
	v_exp_f32_e32 v134, v134
	v_exp_f32_e32 v135, v135
	v_exp_f32_e32 v136, v136
	v_exp_f32_e32 v137, v137
	v_exp_f32_e32 v138, v138
	v_exp_f32_e32 v139, v139
	v_add_f32_e32 v132, 1.0, v132
	v_add_f32_e32 v133, 1.0, v133
	v_add_f32_e32 v134, 1.0, v134
	v_add_f32_e32 v135, 1.0, v135
	v_add_f32_e32 v136, 1.0, v136
	v_add_f32_e32 v137, 1.0, v137
	v_add_f32_e32 v138, 1.0, v138
	v_add_f32_e32 v139, 1.0, v139
	v_rcp_f32_e32 v132, v132
	v_rcp_f32_e32 v133, v133
	v_rcp_f32_e32 v134, v134
	v_rcp_f32_e32 v135, v135
	v_rcp_f32_e32 v136, v136
	v_rcp_f32_e32 v137, v137
	v_rcp_f32_e32 v138, v138
	v_rcp_f32_e32 v139, v139
	v_pk_mul_f32 v[42:43], v[42:43], v[132:133]
	v_pk_mul_f32 v[44:45], v[44:45], v[134:135]
	v_pk_mul_f32 v[10:11], v[10:11], v[136:137]
	v_pk_mul_f32 v[12:13], v[12:13], v[138:139]
	v_pk_mul_f32 v[42:43], v[46:47], v[42:43]
	v_pk_mul_f32 v[44:45], v[48:49], v[44:45]
	v_pk_mul_f32 v[10:11], v[14:15], v[10:11]
	v_pk_mul_f32 v[12:13], v[16:17], v[12:13]
	v_cvt_pk_bf16_f32 v42, v42, v43
	v_cvt_pk_bf16_f32 v43, v44, v45
	v_cvt_pk_bf16_f32 v10, v10, v11
	v_cvt_pk_bf16_f32 v11, v12, v13
	global_store_dwordx2 v142, v[42:43], s[94:95]
	global_store_dwordx2 v142, v[10:11], s[94:95] offset:128
	v_add_u32_e32 v141, 0xdc000, v140
	v_mul_f32_e32 v132, 0xbfb8aa3b, v50
	v_mul_f32_e32 v133, 0xbfb8aa3b, v51
	v_mul_f32_e32 v134, 0xbfb8aa3b, v52
	v_mul_f32_e32 v135, 0xbfb8aa3b, v53
	v_mul_f32_e32 v136, 0xbfb8aa3b, v18
	v_mul_f32_e32 v137, 0xbfb8aa3b, v19
	v_mul_f32_e32 v138, 0xbfb8aa3b, v20
	v_mul_f32_e32 v139, 0xbfb8aa3b, v21
	v_exp_f32_e32 v132, v132
	v_exp_f32_e32 v133, v133
	v_exp_f32_e32 v134, v134
	v_exp_f32_e32 v135, v135
	v_exp_f32_e32 v136, v136
	v_exp_f32_e32 v137, v137
	v_exp_f32_e32 v138, v138
	v_exp_f32_e32 v139, v139
	v_add_f32_e32 v132, 1.0, v132
	v_add_f32_e32 v133, 1.0, v133
	v_add_f32_e32 v134, 1.0, v134
	v_add_f32_e32 v135, 1.0, v135
	v_add_f32_e32 v136, 1.0, v136
	v_add_f32_e32 v137, 1.0, v137
	v_add_f32_e32 v138, 1.0, v138
	v_add_f32_e32 v139, 1.0, v139
	v_rcp_f32_e32 v132, v132
	v_rcp_f32_e32 v133, v133
	v_rcp_f32_e32 v134, v134
	v_rcp_f32_e32 v135, v135
	v_rcp_f32_e32 v136, v136
	v_rcp_f32_e32 v137, v137
	v_rcp_f32_e32 v138, v138
	v_rcp_f32_e32 v139, v139
	v_pk_mul_f32 v[50:51], v[50:51], v[132:133]
	v_pk_mul_f32 v[52:53], v[52:53], v[134:135]
	v_pk_mul_f32 v[18:19], v[18:19], v[136:137]
	v_pk_mul_f32 v[20:21], v[20:21], v[138:139]
	v_pk_mul_f32 v[50:51], v[54:55], v[50:51]
	v_pk_mul_f32 v[52:53], v[56:57], v[52:53]
	v_pk_mul_f32 v[18:19], v[22:23], v[18:19]
	v_pk_mul_f32 v[20:21], v[24:25], v[20:21]
	v_cvt_pk_bf16_f32 v50, v50, v51
	v_cvt_pk_bf16_f32 v51, v52, v53
	v_cvt_pk_bf16_f32 v18, v18, v19
	v_cvt_pk_bf16_f32 v19, v20, v21
	global_store_dwordx2 v141, v[50:51], s[94:95]
	global_store_dwordx2 v141, v[18:19], s[94:95] offset:128
	v_add_u32_e32 v142, 0xf2000, v140
	v_mul_f32_e32 v132, 0xbfb8aa3b, v58
	v_mul_f32_e32 v133, 0xbfb8aa3b, v59
	v_mul_f32_e32 v134, 0xbfb8aa3b, v60
	v_mul_f32_e32 v135, 0xbfb8aa3b, v61
	v_mul_f32_e32 v136, 0xbfb8aa3b, v26
	v_mul_f32_e32 v137, 0xbfb8aa3b, v27
	v_mul_f32_e32 v138, 0xbfb8aa3b, v28
	v_mul_f32_e32 v139, 0xbfb8aa3b, v29
	v_exp_f32_e32 v132, v132
	v_exp_f32_e32 v133, v133
	v_exp_f32_e32 v134, v134
	v_exp_f32_e32 v135, v135
	v_exp_f32_e32 v136, v136
	v_exp_f32_e32 v137, v137
	v_exp_f32_e32 v138, v138
	v_exp_f32_e32 v139, v139
	v_add_f32_e32 v132, 1.0, v132
	v_add_f32_e32 v133, 1.0, v133
	v_add_f32_e32 v134, 1.0, v134
	v_add_f32_e32 v135, 1.0, v135
	v_add_f32_e32 v136, 1.0, v136
	v_add_f32_e32 v137, 1.0, v137
	v_add_f32_e32 v138, 1.0, v138
	v_add_f32_e32 v139, 1.0, v139
	v_rcp_f32_e32 v132, v132
	v_rcp_f32_e32 v133, v133
	v_rcp_f32_e32 v134, v134
	v_rcp_f32_e32 v135, v135
	v_rcp_f32_e32 v136, v136
	v_rcp_f32_e32 v137, v137
	v_rcp_f32_e32 v138, v138
	v_rcp_f32_e32 v139, v139
	v_pk_mul_f32 v[58:59], v[58:59], v[132:133]
	v_pk_mul_f32 v[60:61], v[60:61], v[134:135]
	v_pk_mul_f32 v[26:27], v[26:27], v[136:137]
	v_pk_mul_f32 v[28:29], v[28:29], v[138:139]
	v_pk_mul_f32 v[58:59], v[62:63], v[58:59]
	v_pk_mul_f32 v[60:61], v[64:65], v[60:61]
	v_pk_mul_f32 v[26:27], v[30:31], v[26:27]
	v_pk_mul_f32 v[28:29], v[32:33], v[28:29]
	v_cvt_pk_bf16_f32 v58, v58, v59
	v_cvt_pk_bf16_f32 v59, v60, v61
	v_cvt_pk_bf16_f32 v26, v26, v27
	v_cvt_pk_bf16_f32 v27, v28, v29
	global_store_dwordx2 v142, v[58:59], s[94:95]
	global_store_dwordx2 v142, v[26:27], s[94:95] offset:128
	s_waitcnt lgkmcnt(0)
	s_mov_b64 s[44:45], 0
	s_andn2_b64 vcc, exec, s[30:31]
	s_mov_b32 s0, s50
	s_barrier
	s_cbranch_vccnz .LBB0_1906
	s_branch .LBB0_1929

.LBB0_1984:
	v_and_b32_e32 v246, 15, v0
	v_lshlrev_b32_e32 v246, 5, v246
	s_lshl_b32 s98, s36, 2
	v_mov_b32_e32 v247, 0
	v_add_u32_e32 v246, s98, v246
	v_lshrrev_b32_e32 v244, 4, v0
	v_add_u32_e32 v244, s49, v244
	v_mov_b32_e32 v245, 0
	v_lshlrev_b32_e32 v244, 3, v244
	v_readlane_b32 s98, v253, 46
	v_readlane_b32 s99, v253, 47
	s_nop 1
	v_lshl_add_u64 v[240:241], s[98:99], 0, v[246:247]
	v_readlane_b32 s98, v255, 40
	v_readlane_b32 s99, v255, 41
	s_nop 1
	v_lshl_add_u64 v[242:243], s[98:99], 0, v[246:247]
	s_add_u32 s98, s62, 0xf000000
	s_addc_u32 s99, s63, 0
	v_lshl_add_u64 v[238:239], s[98:99], 0, v[244:245]
	v_lshlrev_b32_e32 v130, 3, v153
	v_and_b32_e32 v190, 0x78, v130
	v_ashrrev_i32_e32 v152, 4, v153
	v_lshrrev_b32_e32 v130, 1, v153
	v_and_b32_e32 v191, 0x60, v130
	v_or_b32_e32 v130, 4, v190
	v_lshlrev_b32_e32 v132, 2, v152
	v_bitop3_b32 v133, v132, v190, 48 bitop3:0x6c
	v_bitop3_b32 v132, v132, v130, 48 bitop3:0x6c
	v_lshlrev_b32_e32 v134, 9, v152
	v_lshlrev_b32_e32 v132, 2, v132
	v_add_u32_e32 v151, 32, v152
	v_lshlrev_b32_e32 v133, 2, v133
	v_add3_u32 v148, s44, v132, v134
	v_lshlrev_b32_e32 v132, 2, v151
	v_add3_u32 v147, s44, v133, v134
	v_bitop3_b32 v133, v132, v190, 48 bitop3:0x6c
	v_bitop3_b32 v132, v132, v130, 48 bitop3:0x6c
	v_lshlrev_b32_e32 v134, 9, v151
	v_lshlrev_b32_e32 v132, 2, v132
	v_add_u32_e32 v150, 64, v152
	v_lshlrev_b32_e32 v133, 2, v133
	v_add3_u32 v145, s44, v132, v134
	v_lshlrev_b32_e32 v132, 2, v150
	v_add3_u32 v146, s44, v133, v134
	v_bitop3_b32 v133, v132, v190, 48 bitop3:0x6c
	v_bitop3_b32 v132, v132, v130, 48 bitop3:0x6c
	v_lshlrev_b32_e32 v134, 9, v150
	v_lshlrev_b32_e32 v132, 2, v132
	v_add_u32_e32 v149, 0x60, v152
	v_lshlrev_b32_e32 v133, 2, v133
	v_add3_u32 v143, s44, v132, v134
	v_lshlrev_b32_e32 v132, 2, v149
	v_add3_u32 v144, s44, v133, v134
	v_bitop3_b32 v133, v132, v190, 48 bitop3:0x6c
	v_bitop3_b32 v130, v132, v130, 48 bitop3:0x6c
	v_lshlrev_b32_e32 v133, 2, v133
	v_lshlrev_b32_e32 v134, 9, v149
	v_lshlrev_b32_e32 v130, 2, v130
	s_lshl_b64 s[38:39], s[36:37], 2
	v_add3_u32 v141, s44, v133, v134
	v_add3_u32 v140, s44, v130, v134
	v_add_u32_e32 v134, s49, v152
	s_add_u32 s40, s66, s38
	s_addc_u32 s41, s67, s39
	v_lshlrev_b32_e32 v130, 2, v190
	v_ashrrev_i32_e32 v135, 31, v134
	v_lshl_add_u64 v[132:133], s[40:41], 0, v[130:131]
	v_lshlrev_b64 v[134:135], 12, v[134:135]
	v_lshl_add_u64 v[136:137], v[132:133], 0, v[134:135]
	global_load_dwordx2 v[194:195], v[238:239], off offset:0
	global_load_dwordx2 v[196:197], v[238:239], off offset:256
	global_load_dwordx2 v[198:199], v[238:239], off offset:512
	global_load_dwordx2 v[200:201], v[238:239], off offset:768
	global_load_dwordx4 v[202:205], v[240:241], off offset:0
	global_load_dwordx4 v[206:209], v[240:241], off offset:16
	global_load_dwordx4 v[210:213], v[242:243], off offset:0
	global_load_dwordx4 v[214:217], v[242:243], off offset:16
	global_load_dwordx4 v[154:157], v[136:137], off offset:16
	global_load_dwordx4 v[158:161], v[136:137], off
	v_lshl_add_u64 v[136:137], v[134:135], 0, s[24:25]
	v_lshl_add_u64 v[138:139], v[132:133], 0, v[136:137]
	global_load_dwordx4 v[162:165], v[138:139], off offset:16
	global_load_dwordx4 v[166:169], v[138:139], off
	v_lshl_add_u64 v[138:139], v[134:135], 0, s[26:27]
	v_lshl_add_u64 v[174:175], v[132:133], 0, v[138:139]
	global_load_dwordx4 v[170:173], v[174:175], off offset:16
	s_nop 0
	global_load_dwordx4 v[174:177], v[174:175], off
	v_lshl_add_u64 v[186:187], v[134:135], 0, s[28:29]
	v_lshl_add_u64 v[182:183], v[132:133], 0, v[186:187]
	global_load_dwordx4 v[178:181], v[182:183], off offset:16
	s_nop 0
	global_load_dwordx4 v[182:185], v[182:183], off
	v_bfe_u32 v189, v153, 4, 2
	v_and_b32_e32 v188, 15, v153
	v_lshlrev_b32_e32 v193, 4, v189
	v_lshlrev_b32_e32 v153, 7, v153
	v_or_b32_e32 v192, v191, v188
	v_bitop3_b32 v188, v191, v193, v188 bitop3:0x36
	v_and_b32_e32 v153, 0xffff8000, v153
	v_lshlrev_b32_e32 v188, 2, v188
	v_lshl_or_b32 v189, v189, 11, v153
	v_add3_u32 v153, s44, v188, v189
	ds_write2st64_b32 v153, v126, v127 offset1:2
	ds_write2st64_b32 v153, v128, v129 offset0:4 offset1:6
	v_bitop3_b32 v126, v192, v193, 16 bitop3:0x36
	v_lshlrev_b32_e32 v126, 2, v126
	v_add3_u32 v126, s44, v126, v189
	ds_write2st64_b32 v126, v98, v99 offset1:2
	ds_write2st64_b32 v126, v100, v101 offset0:4 offset1:6
	ds_write2st64_b32 v153, v102, v103 offset0:32 offset1:34
	ds_write2st64_b32 v153, v104, v105 offset0:36 offset1:38
	ds_write2st64_b32 v126, v106, v107 offset0:32 offset1:34
	ds_write2st64_b32 v126, v108, v109 offset0:36 offset1:38
	ds_write2st64_b32 v153, v110, v111 offset0:64 offset1:66
	ds_write2st64_b32 v153, v112, v113 offset0:68 offset1:70
	ds_write2st64_b32 v126, v114, v115 offset0:64 offset1:66
	ds_write2st64_b32 v126, v116, v117 offset0:68 offset1:70
	ds_write2st64_b32 v153, v118, v119 offset0:96 offset1:98
	ds_write2st64_b32 v153, v120, v121 offset0:100 offset1:102
	ds_write2st64_b32 v126, v122, v123 offset0:96 offset1:98
	ds_write2st64_b32 v126, v124, v125 offset0:100 offset1:102
	s_waitcnt lgkmcnt(0)
	s_barrier
	ds_read_b128 v[98:101], v147
	ds_read_b128 v[102:105], v148
	v_or_b32_e32 v110, s36, v190
	v_mov_b32_e32 v111, s37
	s_lshl_b64 s[0:1], s[0:1], 2
	s_mov_b64 s[36:37], 0
	s_andn2_b64 vcc, exec, s[34:35]
	s_waitcnt vmcnt(0) lgkmcnt(0)
	v_pk_add_f32 v[156:157], v[156:157], v[194:195] op_sel_hi:[1,0] neg_lo:[0,1] neg_hi:[0,1]
	v_pk_mul_f32 v[156:157], v[156:157], v[194:195] op_sel:[0,1]
	v_pk_fma_f32 v[156:157], v[208:209], v[156:157], v[216:217]
	v_pk_fma_f32 v[104:105], v[156:157], s[30:31], v[104:105] op_sel_hi:[1,0,1]
	v_pk_add_f32 v[160:161], v[160:161], v[194:195] op_sel_hi:[1,0] neg_lo:[0,1] neg_hi:[0,1]
	v_pk_mul_f32 v[160:161], v[160:161], v[194:195] op_sel:[0,1]
	v_pk_fma_f32 v[160:161], v[204:205], v[160:161], v[212:213]
	v_pk_fma_f32 v[108:109], v[160:161], s[30:31], v[100:101] op_sel_hi:[1,0,1]
	v_pk_add_f32 v[158:159], v[158:159], v[194:195] op_sel_hi:[1,0] neg_lo:[0,1] neg_hi:[0,1]
	v_pk_mul_f32 v[158:159], v[158:159], v[194:195] op_sel:[0,1]
	v_pk_fma_f32 v[158:159], v[202:203], v[158:159], v[210:211]
	v_pk_fma_f32 v[106:107], v[158:159], s[30:31], v[98:99] op_sel_hi:[1,0,1]
	v_lshl_add_u64 v[100:101], s[66:67], 0, v[134:135]
	v_lshlrev_b64 v[98:99], 2, v[110:111]
	v_lshl_add_u64 v[100:101], v[100:101], 0, v[98:99]
	v_pk_add_f32 v[154:155], v[154:155], v[194:195] op_sel_hi:[1,0] neg_lo:[0,1] neg_hi:[0,1]
	v_pk_mul_f32 v[154:155], v[154:155], v[194:195] op_sel:[0,1]
	v_pk_fma_f32 v[154:155], v[206:207], v[154:155], v[214:215]
	v_pk_fma_f32 v[102:103], v[154:155], s[30:31], v[102:103] op_sel_hi:[1,0,1]
	global_store_dwordx4 v[100:101], v[106:109], off
	global_store_dwordx4 v[100:101], v[102:105], off offset:16
	ds_read_b128 v[100:103], v146
	ds_read_b128 v[104:107], v145
	v_add_u32_e32 v108, s49, v151
	v_ashrrev_i32_e32 v109, 31, v108
	v_lshlrev_b64 v[108:109], 12, v[108:109]
	v_lshl_add_u64 v[108:109], s[66:67], 0, v[108:109]
	s_waitcnt lgkmcnt(1)
	v_pk_add_f32 v[168:169], v[168:169], v[196:197] op_sel_hi:[1,0] neg_lo:[0,1] neg_hi:[0,1]
	v_pk_mul_f32 v[168:169], v[168:169], v[196:197] op_sel:[0,1]
	v_pk_fma_f32 v[168:169], v[204:205], v[168:169], v[212:213]
	v_pk_fma_f32 v[102:103], v[168:169], s[30:31], v[102:103] op_sel_hi:[1,0,1]
	v_pk_add_f32 v[166:167], v[166:167], v[196:197] op_sel_hi:[1,0] neg_lo:[0,1] neg_hi:[0,1]
	v_pk_mul_f32 v[166:167], v[166:167], v[196:197] op_sel:[0,1]
	v_pk_fma_f32 v[166:167], v[202:203], v[166:167], v[210:211]
	v_pk_fma_f32 v[100:101], v[166:167], s[30:31], v[100:101] op_sel_hi:[1,0,1]
	v_lshl_add_u64 v[108:109], v[108:109], 0, v[98:99]
	global_store_dwordx4 v[108:109], v[100:103], off
	s_waitcnt lgkmcnt(0)
	s_nop 0
	v_pk_add_f32 v[164:165], v[164:165], v[196:197] op_sel_hi:[1,0] neg_lo:[0,1] neg_hi:[0,1]
	v_pk_mul_f32 v[164:165], v[164:165], v[196:197] op_sel:[0,1]
	v_pk_fma_f32 v[164:165], v[208:209], v[164:165], v[216:217]
	v_pk_fma_f32 v[102:103], v[164:165], s[30:31], v[106:107] op_sel_hi:[1,0,1]
	v_pk_add_f32 v[162:163], v[162:163], v[196:197] op_sel_hi:[1,0] neg_lo:[0,1] neg_hi:[0,1]
	v_pk_mul_f32 v[162:163], v[162:163], v[196:197] op_sel:[0,1]
	v_pk_fma_f32 v[162:163], v[206:207], v[162:163], v[214:215]
	v_pk_fma_f32 v[100:101], v[162:163], s[30:31], v[104:105] op_sel_hi:[1,0,1]
	global_store_dwordx4 v[108:109], v[100:103], off offset:16
	ds_read_b128 v[100:103], v144
	ds_read_b128 v[104:107], v143
	v_add_u32_e32 v108, s49, v150
	v_ashrrev_i32_e32 v109, 31, v108
	v_lshlrev_b64 v[108:109], 12, v[108:109]
	v_lshl_add_u64 v[108:109], s[66:67], 0, v[108:109]
	s_waitcnt lgkmcnt(1)
	v_pk_add_f32 v[176:177], v[176:177], v[198:199] op_sel_hi:[1,0] neg_lo:[0,1] neg_hi:[0,1]
	v_pk_mul_f32 v[176:177], v[176:177], v[198:199] op_sel:[0,1]
	v_pk_fma_f32 v[176:177], v[204:205], v[176:177], v[212:213]
	v_pk_fma_f32 v[102:103], v[176:177], s[30:31], v[102:103] op_sel_hi:[1,0,1]
	v_pk_add_f32 v[174:175], v[174:175], v[198:199] op_sel_hi:[1,0] neg_lo:[0,1] neg_hi:[0,1]
	v_pk_mul_f32 v[174:175], v[174:175], v[198:199] op_sel:[0,1]
	v_pk_fma_f32 v[174:175], v[202:203], v[174:175], v[210:211]
	v_pk_fma_f32 v[100:101], v[174:175], s[30:31], v[100:101] op_sel_hi:[1,0,1]
	v_lshl_add_u64 v[108:109], v[108:109], 0, v[98:99]
	global_store_dwordx4 v[108:109], v[100:103], off
	s_waitcnt lgkmcnt(0)
	s_nop 0
	v_pk_add_f32 v[172:173], v[172:173], v[198:199] op_sel_hi:[1,0] neg_lo:[0,1] neg_hi:[0,1]
	v_pk_mul_f32 v[172:173], v[172:173], v[198:199] op_sel:[0,1]
	v_pk_fma_f32 v[172:173], v[208:209], v[172:173], v[216:217]
	v_pk_fma_f32 v[102:103], v[172:173], s[30:31], v[106:107] op_sel_hi:[1,0,1]
	v_pk_add_f32 v[170:171], v[170:171], v[198:199] op_sel_hi:[1,0] neg_lo:[0,1] neg_hi:[0,1]
	v_pk_mul_f32 v[170:171], v[170:171], v[198:199] op_sel:[0,1]
	v_pk_fma_f32 v[170:171], v[206:207], v[170:171], v[214:215]
	v_pk_fma_f32 v[100:101], v[170:171], s[30:31], v[104:105] op_sel_hi:[1,0,1]
	global_store_dwordx4 v[108:109], v[100:103], off offset:16
	ds_read_b128 v[100:103], v141
	ds_read_b128 v[104:107], v140
	v_add_u32_e32 v108, s49, v149
	v_ashrrev_i32_e32 v109, 31, v108
	v_lshlrev_b64 v[108:109], 12, v[108:109]
	v_lshl_add_u64 v[108:109], s[66:67], 0, v[108:109]
	s_waitcnt lgkmcnt(1)
	v_pk_add_f32 v[184:185], v[184:185], v[200:201] op_sel_hi:[1,0] neg_lo:[0,1] neg_hi:[0,1]
	v_pk_mul_f32 v[184:185], v[184:185], v[200:201] op_sel:[0,1]
	v_pk_fma_f32 v[184:185], v[204:205], v[184:185], v[212:213]
	v_pk_fma_f32 v[102:103], v[184:185], s[30:31], v[102:103] op_sel_hi:[1,0,1]
	v_pk_add_f32 v[182:183], v[182:183], v[200:201] op_sel_hi:[1,0] neg_lo:[0,1] neg_hi:[0,1]
	v_pk_mul_f32 v[182:183], v[182:183], v[200:201] op_sel:[0,1]
	v_pk_fma_f32 v[182:183], v[202:203], v[182:183], v[210:211]
	v_pk_fma_f32 v[100:101], v[182:183], s[30:31], v[100:101] op_sel_hi:[1,0,1]
	v_lshl_add_u64 v[108:109], v[108:109], 0, v[98:99]
	global_store_dwordx4 v[108:109], v[100:103], off
	s_waitcnt lgkmcnt(0)
	s_nop 0
	v_pk_add_f32 v[180:181], v[180:181], v[200:201] op_sel_hi:[1,0] neg_lo:[0,1] neg_hi:[0,1]
	v_pk_mul_f32 v[180:181], v[180:181], v[200:201] op_sel:[0,1]
	v_pk_fma_f32 v[180:181], v[208:209], v[180:181], v[216:217]
	v_pk_fma_f32 v[102:103], v[180:181], s[30:31], v[106:107] op_sel_hi:[1,0,1]
	v_pk_add_f32 v[178:179], v[178:179], v[200:201] op_sel_hi:[1,0] neg_lo:[0,1] neg_hi:[0,1]
	v_pk_mul_f32 v[178:179], v[178:179], v[200:201] op_sel:[0,1]
	v_pk_fma_f32 v[178:179], v[206:207], v[178:179], v[214:215]
	v_pk_fma_f32 v[100:101], v[178:179], s[30:31], v[104:105] op_sel_hi:[1,0,1]
	global_store_dwordx4 v[108:109], v[100:103], off offset:16
	s_waitcnt lgkmcnt(0)
	s_barrier
	s_nop 0
	v_lshl_add_u64 v[100:101], s[66:67], 0, v[130:131]
	v_lshl_add_u64 v[128:129], v[100:101], 0, v[134:135]
	v_lshl_add_u64 v[106:107], v[128:129], 0, s[0:1]
	global_load_dwordx2 v[194:195], v[238:239], off offset:0
	global_load_dwordx2 v[196:197], v[238:239], off offset:256
	global_load_dwordx2 v[198:199], v[238:239], off offset:512
	global_load_dwordx2 v[200:201], v[238:239], off offset:768
	global_load_dwordx4 v[202:205], v[240:241], off offset:512
	global_load_dwordx4 v[206:209], v[240:241], off offset:528
	global_load_dwordx4 v[210:213], v[242:243], off offset:512
	global_load_dwordx4 v[214:217], v[242:243], off offset:528
	global_load_dwordx4 v[102:105], v[106:107], off offset:16
	s_nop 0
	global_load_dwordx4 v[106:109], v[106:107], off
	v_lshl_add_u64 v[158:159], v[100:101], 0, v[136:137]
	v_lshl_add_u64 v[114:115], v[158:159], 0, s[0:1]
	global_load_dwordx4 v[110:113], v[114:115], off offset:16
	s_nop 0
	global_load_dwordx4 v[114:117], v[114:115], off
	v_lshl_add_u64 v[138:139], v[100:101], 0, v[138:139]
	v_lshl_add_u64 v[122:123], v[138:139], 0, s[0:1]
	global_load_dwordx4 v[118:121], v[122:123], off offset:16
	s_nop 0
	global_load_dwordx4 v[122:125], v[122:123], off
	v_lshl_add_u64 v[160:161], v[100:101], 0, v[186:187]
	v_lshl_add_u64 v[154:155], v[160:161], 0, s[0:1]
	global_load_dwordx4 v[134:137], v[154:155], off offset:16
	s_nop 0
	global_load_dwordx4 v[154:157], v[154:155], off
	ds_write2st64_b32 v153, v66, v67 offset1:2
	ds_write2st64_b32 v153, v68, v69 offset0:4 offset1:6
	ds_write2st64_b32 v126, v70, v71 offset1:2
	ds_write2st64_b32 v126, v72, v73 offset0:4 offset1:6
	ds_write2st64_b32 v153, v74, v75 offset0:32 offset1:34
	ds_write2st64_b32 v153, v76, v77 offset0:36 offset1:38
	ds_write2st64_b32 v126, v78, v79 offset0:32 offset1:34
	ds_write2st64_b32 v126, v80, v81 offset0:36 offset1:38
	ds_write2st64_b32 v153, v82, v83 offset0:64 offset1:66
	ds_write2st64_b32 v153, v84, v85 offset0:68 offset1:70
	ds_write2st64_b32 v126, v86, v87 offset0:64 offset1:66
	ds_write2st64_b32 v126, v88, v89 offset0:68 offset1:70
	ds_write2st64_b32 v153, v90, v91 offset0:96 offset1:98
	ds_write2st64_b32 v153, v92, v93 offset0:100 offset1:102
	ds_write2st64_b32 v126, v94, v95 offset0:96 offset1:98
	ds_write2st64_b32 v126, v96, v97 offset0:100 offset1:102
	s_waitcnt lgkmcnt(0)
	s_barrier
	ds_read_b128 v[66:69], v147
	ds_read_b128 v[70:73], v148
	v_lshl_add_u64 v[74:75], v[128:129], 0, s[38:39]
	s_waitcnt vmcnt(6) lgkmcnt(1)
	v_pk_add_f32 v[108:109], v[108:109], v[194:195] op_sel_hi:[1,0] neg_lo:[0,1] neg_hi:[0,1]
	v_pk_mul_f32 v[108:109], v[108:109], v[194:195] op_sel:[0,1]
	v_pk_fma_f32 v[108:109], v[204:205], v[108:109], v[212:213]
	v_pk_fma_f32 v[68:69], v[108:109], s[30:31], v[68:69] op_sel_hi:[1,0,1]
	v_pk_add_f32 v[106:107], v[106:107], v[194:195] op_sel_hi:[1,0] neg_lo:[0,1] neg_hi:[0,1]
	v_pk_mul_f32 v[106:107], v[106:107], v[194:195] op_sel:[0,1]
	v_pk_fma_f32 v[106:107], v[202:203], v[106:107], v[210:211]
	v_pk_fma_f32 v[66:67], v[106:107], s[30:31], v[66:67] op_sel_hi:[1,0,1]
	global_store_dwordx4 v[74:75], v[66:69], off offset:512
	s_waitcnt lgkmcnt(0)
	s_nop 0
	v_pk_add_f32 v[104:105], v[104:105], v[194:195] op_sel_hi:[1,0] neg_lo:[0,1] neg_hi:[0,1]
	v_pk_mul_f32 v[104:105], v[104:105], v[194:195] op_sel:[0,1]
	v_pk_fma_f32 v[104:105], v[208:209], v[104:105], v[216:217]
	v_pk_fma_f32 v[68:69], v[104:105], s[30:31], v[72:73] op_sel_hi:[1,0,1]
	v_pk_add_f32 v[102:103], v[102:103], v[194:195] op_sel_hi:[1,0] neg_lo:[0,1] neg_hi:[0,1]
	v_pk_mul_f32 v[102:103], v[102:103], v[194:195] op_sel:[0,1]
	v_pk_fma_f32 v[102:103], v[206:207], v[102:103], v[214:215]
	v_pk_fma_f32 v[66:67], v[102:103], s[30:31], v[70:71] op_sel_hi:[1,0,1]
	global_store_dwordx4 v[74:75], v[66:69], off offset:528
	ds_read_b128 v[66:69], v146
	ds_read_b128 v[70:73], v145
	v_lshl_add_u64 v[74:75], v[158:159], 0, s[38:39]
	s_waitcnt vmcnt(6) lgkmcnt(1)
	v_pk_add_f32 v[116:117], v[116:117], v[196:197] op_sel_hi:[1,0] neg_lo:[0,1] neg_hi:[0,1]
	v_pk_mul_f32 v[116:117], v[116:117], v[196:197] op_sel:[0,1]
	v_pk_fma_f32 v[116:117], v[204:205], v[116:117], v[212:213]
	v_pk_fma_f32 v[68:69], v[116:117], s[30:31], v[68:69] op_sel_hi:[1,0,1]
	v_pk_add_f32 v[114:115], v[114:115], v[196:197] op_sel_hi:[1,0] neg_lo:[0,1] neg_hi:[0,1]
	v_pk_mul_f32 v[114:115], v[114:115], v[196:197] op_sel:[0,1]
	v_pk_fma_f32 v[114:115], v[202:203], v[114:115], v[210:211]
	v_pk_fma_f32 v[66:67], v[114:115], s[30:31], v[66:67] op_sel_hi:[1,0,1]
	global_store_dwordx4 v[74:75], v[66:69], off offset:512
	s_waitcnt lgkmcnt(0)
	s_nop 0
	v_pk_add_f32 v[112:113], v[112:113], v[196:197] op_sel_hi:[1,0] neg_lo:[0,1] neg_hi:[0,1]
	v_pk_mul_f32 v[112:113], v[112:113], v[196:197] op_sel:[0,1]
	v_pk_fma_f32 v[112:113], v[208:209], v[112:113], v[216:217]
	v_pk_fma_f32 v[68:69], v[112:113], s[30:31], v[72:73] op_sel_hi:[1,0,1]
	v_pk_add_f32 v[110:111], v[110:111], v[196:197] op_sel_hi:[1,0] neg_lo:[0,1] neg_hi:[0,1]
	v_pk_mul_f32 v[110:111], v[110:111], v[196:197] op_sel:[0,1]
	v_pk_fma_f32 v[110:111], v[206:207], v[110:111], v[214:215]
	v_pk_fma_f32 v[66:67], v[110:111], s[30:31], v[70:71] op_sel_hi:[1,0,1]
	global_store_dwordx4 v[74:75], v[66:69], off offset:528
	ds_read_b128 v[66:69], v144
	ds_read_b128 v[70:73], v143
	v_lshl_add_u64 v[74:75], v[138:139], 0, s[38:39]
	s_waitcnt vmcnt(6) lgkmcnt(1)
	v_pk_add_f32 v[124:125], v[124:125], v[198:199] op_sel_hi:[1,0] neg_lo:[0,1] neg_hi:[0,1]
	v_pk_mul_f32 v[124:125], v[124:125], v[198:199] op_sel:[0,1]
	v_pk_fma_f32 v[124:125], v[204:205], v[124:125], v[212:213]
	v_pk_fma_f32 v[68:69], v[124:125], s[30:31], v[68:69] op_sel_hi:[1,0,1]
	v_pk_add_f32 v[122:123], v[122:123], v[198:199] op_sel_hi:[1,0] neg_lo:[0,1] neg_hi:[0,1]
	v_pk_mul_f32 v[122:123], v[122:123], v[198:199] op_sel:[0,1]
	v_pk_fma_f32 v[122:123], v[202:203], v[122:123], v[210:211]
	v_pk_fma_f32 v[66:67], v[122:123], s[30:31], v[66:67] op_sel_hi:[1,0,1]
	global_store_dwordx4 v[74:75], v[66:69], off offset:512
	s_waitcnt lgkmcnt(0)
	s_nop 0
	v_pk_add_f32 v[120:121], v[120:121], v[198:199] op_sel_hi:[1,0] neg_lo:[0,1] neg_hi:[0,1]
	v_pk_mul_f32 v[120:121], v[120:121], v[198:199] op_sel:[0,1]
	v_pk_fma_f32 v[120:121], v[208:209], v[120:121], v[216:217]
	v_pk_fma_f32 v[68:69], v[120:121], s[30:31], v[72:73] op_sel_hi:[1,0,1]
	v_pk_add_f32 v[118:119], v[118:119], v[198:199] op_sel_hi:[1,0] neg_lo:[0,1] neg_hi:[0,1]
	v_pk_mul_f32 v[118:119], v[118:119], v[198:199] op_sel:[0,1]
	v_pk_fma_f32 v[118:119], v[206:207], v[118:119], v[214:215]
	v_pk_fma_f32 v[66:67], v[118:119], s[30:31], v[70:71] op_sel_hi:[1,0,1]
	global_store_dwordx4 v[74:75], v[66:69], off offset:528
	ds_read_b128 v[66:69], v141
	ds_read_b128 v[70:73], v140
	v_lshl_add_u64 v[74:75], v[160:161], 0, s[38:39]
	s_waitcnt vmcnt(6) lgkmcnt(1)
	v_pk_add_f32 v[156:157], v[156:157], v[200:201] op_sel_hi:[1,0] neg_lo:[0,1] neg_hi:[0,1]
	v_pk_mul_f32 v[156:157], v[156:157], v[200:201] op_sel:[0,1]
	v_pk_fma_f32 v[156:157], v[204:205], v[156:157], v[212:213]
	v_pk_fma_f32 v[68:69], v[156:157], s[30:31], v[68:69] op_sel_hi:[1,0,1]
	v_pk_add_f32 v[154:155], v[154:155], v[200:201] op_sel_hi:[1,0] neg_lo:[0,1] neg_hi:[0,1]
	v_pk_mul_f32 v[154:155], v[154:155], v[200:201] op_sel:[0,1]
	v_pk_fma_f32 v[154:155], v[202:203], v[154:155], v[210:211]
	v_pk_fma_f32 v[66:67], v[154:155], s[30:31], v[66:67] op_sel_hi:[1,0,1]
	global_store_dwordx4 v[74:75], v[66:69], off offset:512
	s_waitcnt lgkmcnt(0)
	s_nop 0
	v_pk_add_f32 v[136:137], v[136:137], v[200:201] op_sel_hi:[1,0] neg_lo:[0,1] neg_hi:[0,1]
	v_pk_mul_f32 v[136:137], v[136:137], v[200:201] op_sel:[0,1]
	v_pk_fma_f32 v[136:137], v[208:209], v[136:137], v[216:217]
	v_pk_fma_f32 v[68:69], v[136:137], s[30:31], v[72:73] op_sel_hi:[1,0,1]
	v_pk_add_f32 v[134:135], v[134:135], v[200:201] op_sel_hi:[1,0] neg_lo:[0,1] neg_hi:[0,1]
	v_pk_mul_f32 v[134:135], v[134:135], v[200:201] op_sel:[0,1]
	v_pk_fma_f32 v[134:135], v[206:207], v[134:135], v[214:215]
	v_pk_fma_f32 v[66:67], v[134:135], s[30:31], v[70:71] op_sel_hi:[1,0,1]
	global_store_dwordx4 v[74:75], v[66:69], off offset:528
	s_waitcnt lgkmcnt(0)
	s_barrier
	s_nop 0
	v_add_u32_e32 v66, s42, v152
	v_ashrrev_i32_e32 v67, 31, v66
	v_lshlrev_b64 v[102:103], 12, v[66:67]
	v_lshl_add_u64 v[70:71], v[132:133], 0, v[102:103]
	global_load_dwordx2 v[194:195], v[238:239], off offset:1024
	global_load_dwordx2 v[196:197], v[238:239], off offset:1280
	global_load_dwordx2 v[198:199], v[238:239], off offset:1536
	global_load_dwordx2 v[200:201], v[238:239], off offset:1792
	global_load_dwordx4 v[202:205], v[240:241], off offset:0
	global_load_dwordx4 v[206:209], v[240:241], off offset:16
	global_load_dwordx4 v[210:213], v[242:243], off offset:0
	global_load_dwordx4 v[214:217], v[242:243], off offset:16
	global_load_dwordx4 v[66:69], v[70:71], off offset:16
	s_nop 0
	global_load_dwordx4 v[70:73], v[70:71], off
	v_lshl_add_u64 v[104:105], v[102:103], 0, s[24:25]
	v_lshl_add_u64 v[78:79], v[132:133], 0, v[104:105]
	global_load_dwordx4 v[74:77], v[78:79], off offset:16
	s_nop 0
	global_load_dwordx4 v[78:81], v[78:79], off
	v_lshl_add_u64 v[106:107], v[102:103], 0, s[26:27]
	v_lshl_add_u64 v[86:87], v[132:133], 0, v[106:107]
	global_load_dwordx4 v[82:85], v[86:87], off offset:16
	s_nop 0
	global_load_dwordx4 v[86:89], v[86:87], off
	v_lshl_add_u64 v[108:109], v[102:103], 0, s[28:29]
	v_lshl_add_u64 v[94:95], v[132:133], 0, v[108:109]
	global_load_dwordx4 v[90:93], v[94:95], off offset:16
	s_nop 0
	global_load_dwordx4 v[94:97], v[94:95], off
	ds_write2st64_b32 v153, v34, v35 offset1:2
	ds_write2st64_b32 v153, v36, v37 offset0:4 offset1:6
	ds_write2st64_b32 v126, v38, v39 offset1:2
	ds_write2st64_b32 v126, v40, v41 offset0:4 offset1:6
	ds_write2st64_b32 v153, v42, v43 offset0:32 offset1:34
	ds_write2st64_b32 v153, v44, v45 offset0:36 offset1:38
	ds_write2st64_b32 v126, v46, v47 offset0:32 offset1:34
	ds_write2st64_b32 v126, v48, v49 offset0:36 offset1:38
	ds_write2st64_b32 v153, v50, v51 offset0:64 offset1:66
	ds_write2st64_b32 v153, v52, v53 offset0:68 offset1:70
	ds_write2st64_b32 v126, v54, v55 offset0:64 offset1:66
	ds_write2st64_b32 v126, v56, v57 offset0:68 offset1:70
	ds_write2st64_b32 v153, v58, v59 offset0:96 offset1:98
	ds_write2st64_b32 v153, v60, v61 offset0:100 offset1:102
	ds_write2st64_b32 v126, v62, v63 offset0:96 offset1:98
	ds_write2st64_b32 v126, v64, v65 offset0:100 offset1:102
	s_waitcnt lgkmcnt(0)
	s_barrier
	ds_read_b128 v[34:37], v147
	ds_read_b128 v[38:41], v148
	v_lshl_add_u64 v[42:43], s[66:67], 0, v[102:103]
	v_lshl_add_u64 v[42:43], v[42:43], 0, v[98:99]
	s_waitcnt vmcnt(6) lgkmcnt(1)
	v_pk_add_f32 v[72:73], v[72:73], v[194:195] op_sel_hi:[1,0] neg_lo:[0,1] neg_hi:[0,1]
	v_pk_mul_f32 v[72:73], v[72:73], v[194:195] op_sel:[0,1]
	v_pk_fma_f32 v[72:73], v[204:205], v[72:73], v[212:213]
	v_pk_fma_f32 v[36:37], v[72:73], s[30:31], v[36:37] op_sel_hi:[1,0,1]
	v_pk_add_f32 v[70:71], v[70:71], v[194:195] op_sel_hi:[1,0] neg_lo:[0,1] neg_hi:[0,1]
	v_pk_mul_f32 v[70:71], v[70:71], v[194:195] op_sel:[0,1]
	v_pk_fma_f32 v[70:71], v[202:203], v[70:71], v[210:211]
	v_pk_fma_f32 v[34:35], v[70:71], s[30:31], v[34:35] op_sel_hi:[1,0,1]
	global_store_dwordx4 v[42:43], v[34:37], off
	v_lshl_add_u64 v[70:71], v[100:101], 0, v[106:107]
	v_lshl_add_u64 v[54:55], v[70:71], 0, s[0:1]
	s_waitcnt lgkmcnt(0)
	v_pk_add_f32 v[68:69], v[68:69], v[194:195] op_sel_hi:[1,0] neg_lo:[0,1] neg_hi:[0,1]
	v_pk_mul_f32 v[68:69], v[68:69], v[194:195] op_sel:[0,1]
	v_pk_fma_f32 v[68:69], v[208:209], v[68:69], v[216:217]
	v_pk_fma_f32 v[36:37], v[68:69], s[30:31], v[40:41] op_sel_hi:[1,0,1]
	v_pk_add_f32 v[66:67], v[66:67], v[194:195] op_sel_hi:[1,0] neg_lo:[0,1] neg_hi:[0,1]
	v_pk_mul_f32 v[66:67], v[66:67], v[194:195] op_sel:[0,1]
	v_pk_fma_f32 v[66:67], v[206:207], v[66:67], v[214:215]
	v_pk_fma_f32 v[34:35], v[66:67], s[30:31], v[38:39] op_sel_hi:[1,0,1]
	global_store_dwordx4 v[42:43], v[34:37], off offset:16
	ds_read_b128 v[34:37], v146
	ds_read_b128 v[38:41], v145
	v_add_u32_e32 v42, s42, v151
	v_ashrrev_i32_e32 v43, 31, v42
	v_lshlrev_b64 v[42:43], 12, v[42:43]
	v_lshl_add_u64 v[42:43], s[66:67], 0, v[42:43]
	s_waitcnt vmcnt(6) lgkmcnt(1)
	v_pk_add_f32 v[80:81], v[80:81], v[196:197] op_sel_hi:[1,0] neg_lo:[0,1] neg_hi:[0,1]
	v_pk_mul_f32 v[80:81], v[80:81], v[196:197] op_sel:[0,1]
	v_pk_fma_f32 v[80:81], v[204:205], v[80:81], v[212:213]
	v_pk_fma_f32 v[36:37], v[80:81], s[30:31], v[36:37] op_sel_hi:[1,0,1]
	v_pk_add_f32 v[78:79], v[78:79], v[196:197] op_sel_hi:[1,0] neg_lo:[0,1] neg_hi:[0,1]
	v_pk_mul_f32 v[78:79], v[78:79], v[196:197] op_sel:[0,1]
	v_pk_fma_f32 v[78:79], v[202:203], v[78:79], v[210:211]
	v_pk_fma_f32 v[34:35], v[78:79], s[30:31], v[34:35] op_sel_hi:[1,0,1]
	v_lshl_add_u64 v[42:43], v[42:43], 0, v[98:99]
	global_store_dwordx4 v[42:43], v[34:37], off
	v_lshl_add_u64 v[66:67], v[100:101], 0, v[102:103]
	v_lshl_add_u64 v[68:69], v[100:101], 0, v[104:105]
	s_waitcnt lgkmcnt(0)
	v_pk_add_f32 v[76:77], v[76:77], v[196:197] op_sel_hi:[1,0] neg_lo:[0,1] neg_hi:[0,1]
	v_pk_mul_f32 v[76:77], v[76:77], v[196:197] op_sel:[0,1]
	v_pk_fma_f32 v[76:77], v[208:209], v[76:77], v[216:217]
	v_pk_fma_f32 v[36:37], v[76:77], s[30:31], v[40:41] op_sel_hi:[1,0,1]
	v_pk_add_f32 v[74:75], v[74:75], v[196:197] op_sel_hi:[1,0] neg_lo:[0,1] neg_hi:[0,1]
	v_pk_mul_f32 v[74:75], v[74:75], v[196:197] op_sel:[0,1]
	v_pk_fma_f32 v[74:75], v[206:207], v[74:75], v[214:215]
	v_pk_fma_f32 v[34:35], v[74:75], s[30:31], v[38:39] op_sel_hi:[1,0,1]
	global_store_dwordx4 v[42:43], v[34:37], off offset:16
	ds_read_b128 v[34:37], v144
	ds_read_b128 v[38:41], v143
	v_add_u32_e32 v42, s42, v150
	v_ashrrev_i32_e32 v43, 31, v42
	v_lshlrev_b64 v[42:43], 12, v[42:43]
	v_lshl_add_u64 v[42:43], s[66:67], 0, v[42:43]
	s_waitcnt vmcnt(6) lgkmcnt(1)
	v_pk_add_f32 v[88:89], v[88:89], v[198:199] op_sel_hi:[1,0] neg_lo:[0,1] neg_hi:[0,1]
	v_pk_mul_f32 v[88:89], v[88:89], v[198:199] op_sel:[0,1]
	v_pk_fma_f32 v[88:89], v[204:205], v[88:89], v[212:213]
	v_pk_fma_f32 v[36:37], v[88:89], s[30:31], v[36:37] op_sel_hi:[1,0,1]
	v_pk_add_f32 v[86:87], v[86:87], v[198:199] op_sel_hi:[1,0] neg_lo:[0,1] neg_hi:[0,1]
	v_pk_mul_f32 v[86:87], v[86:87], v[198:199] op_sel:[0,1]
	v_pk_fma_f32 v[86:87], v[202:203], v[86:87], v[210:211]
	v_pk_fma_f32 v[34:35], v[86:87], s[30:31], v[34:35] op_sel_hi:[1,0,1]
	v_lshl_add_u64 v[42:43], v[42:43], 0, v[98:99]
	global_store_dwordx4 v[42:43], v[34:37], off
	v_lshl_add_u64 v[46:47], v[68:69], 0, s[0:1]
	v_lshl_add_u64 v[72:73], v[100:101], 0, v[108:109]
	s_waitcnt lgkmcnt(0)
	v_pk_add_f32 v[84:85], v[84:85], v[198:199] op_sel_hi:[1,0] neg_lo:[0,1] neg_hi:[0,1]
	v_pk_mul_f32 v[84:85], v[84:85], v[198:199] op_sel:[0,1]
	v_pk_fma_f32 v[84:85], v[208:209], v[84:85], v[216:217]
	v_pk_fma_f32 v[36:37], v[84:85], s[30:31], v[40:41] op_sel_hi:[1,0,1]
	v_pk_add_f32 v[82:83], v[82:83], v[198:199] op_sel_hi:[1,0] neg_lo:[0,1] neg_hi:[0,1]
	v_pk_mul_f32 v[82:83], v[82:83], v[198:199] op_sel:[0,1]
	v_pk_fma_f32 v[82:83], v[206:207], v[82:83], v[214:215]
	v_pk_fma_f32 v[34:35], v[82:83], s[30:31], v[38:39] op_sel_hi:[1,0,1]
	global_store_dwordx4 v[42:43], v[34:37], off offset:16
	ds_read_b128 v[34:37], v141
	ds_read_b128 v[38:41], v140
	v_add_u32_e32 v42, s42, v149
	v_ashrrev_i32_e32 v43, 31, v42
	v_lshlrev_b64 v[42:43], 12, v[42:43]
	v_lshl_add_u64 v[42:43], s[66:67], 0, v[42:43]
	s_waitcnt vmcnt(6) lgkmcnt(1)
	v_pk_add_f32 v[96:97], v[96:97], v[200:201] op_sel_hi:[1,0] neg_lo:[0,1] neg_hi:[0,1]
	v_pk_mul_f32 v[96:97], v[96:97], v[200:201] op_sel:[0,1]
	v_pk_fma_f32 v[96:97], v[204:205], v[96:97], v[212:213]
	v_pk_fma_f32 v[36:37], v[96:97], s[30:31], v[36:37] op_sel_hi:[1,0,1]
	v_pk_add_f32 v[94:95], v[94:95], v[200:201] op_sel_hi:[1,0] neg_lo:[0,1] neg_hi:[0,1]
	v_pk_mul_f32 v[94:95], v[94:95], v[200:201] op_sel:[0,1]
	v_pk_fma_f32 v[94:95], v[202:203], v[94:95], v[210:211]
	v_pk_fma_f32 v[34:35], v[94:95], s[30:31], v[34:35] op_sel_hi:[1,0,1]
	v_lshl_add_u64 v[42:43], v[42:43], 0, v[98:99]
	global_store_dwordx4 v[42:43], v[34:37], off
	v_lshl_add_u64 v[62:63], v[72:73], 0, s[0:1]
	s_waitcnt lgkmcnt(0)
	v_pk_add_f32 v[92:93], v[92:93], v[200:201] op_sel_hi:[1,0] neg_lo:[0,1] neg_hi:[0,1]
	v_pk_mul_f32 v[92:93], v[92:93], v[200:201] op_sel:[0,1]
	v_pk_fma_f32 v[92:93], v[208:209], v[92:93], v[216:217]
	v_pk_fma_f32 v[36:37], v[92:93], s[30:31], v[40:41] op_sel_hi:[1,0,1]
	v_pk_add_f32 v[90:91], v[90:91], v[200:201] op_sel_hi:[1,0] neg_lo:[0,1] neg_hi:[0,1]
	v_pk_mul_f32 v[90:91], v[90:91], v[200:201] op_sel:[0,1]
	v_pk_fma_f32 v[90:91], v[206:207], v[90:91], v[214:215]
	v_pk_fma_f32 v[34:35], v[90:91], s[30:31], v[38:39] op_sel_hi:[1,0,1]
	global_store_dwordx4 v[42:43], v[34:37], off offset:16
	v_lshl_add_u64 v[38:39], v[66:67], 0, s[0:1]
	s_waitcnt lgkmcnt(0)
	s_barrier
	global_load_dwordx2 v[194:195], v[238:239], off offset:1024
	global_load_dwordx2 v[196:197], v[238:239], off offset:1280
	global_load_dwordx2 v[198:199], v[238:239], off offset:1536
	global_load_dwordx2 v[200:201], v[238:239], off offset:1792
	global_load_dwordx4 v[202:205], v[240:241], off offset:512
	global_load_dwordx4 v[206:209], v[240:241], off offset:528
	global_load_dwordx4 v[210:213], v[242:243], off offset:512
	global_load_dwordx4 v[214:217], v[242:243], off offset:528
	global_load_dwordx4 v[34:37], v[38:39], off offset:16
	s_nop 0
	global_load_dwordx4 v[38:41], v[38:39], off
	s_nop 0
	global_load_dwordx4 v[42:45], v[46:47], off offset:16
	s_nop 0
	global_load_dwordx4 v[46:49], v[46:47], off
	s_nop 0
	global_load_dwordx4 v[50:53], v[54:55], off offset:16
	s_nop 0
	global_load_dwordx4 v[54:57], v[54:55], off
	s_nop 0
	global_load_dwordx4 v[58:61], v[62:63], off offset:16
	s_nop 0
	global_load_dwordx4 v[62:65], v[62:63], off
	ds_write2st64_b32 v153, v2, v3 offset1:2
	ds_write2st64_b32 v153, v4, v5 offset0:4 offset1:6
	ds_write2st64_b32 v126, v6, v7 offset1:2
	ds_write2st64_b32 v126, v8, v9 offset0:4 offset1:6
	ds_write2st64_b32 v153, v10, v11 offset0:32 offset1:34
	ds_write2st64_b32 v153, v12, v13 offset0:36 offset1:38
	ds_write2st64_b32 v126, v14, v15 offset0:32 offset1:34
	ds_write2st64_b32 v126, v16, v17 offset0:36 offset1:38
	ds_write2st64_b32 v153, v18, v19 offset0:64 offset1:66
	ds_write2st64_b32 v153, v20, v21 offset0:68 offset1:70
	ds_write2st64_b32 v126, v22, v23 offset0:64 offset1:66
	ds_write2st64_b32 v126, v24, v25 offset0:68 offset1:70
	ds_write2st64_b32 v153, v26, v27 offset0:96 offset1:98
	ds_write2st64_b32 v153, v28, v29 offset0:100 offset1:102
	ds_write2st64_b32 v126, v30, v31 offset0:96 offset1:98
	ds_write2st64_b32 v126, v32, v33 offset0:100 offset1:102
	s_waitcnt lgkmcnt(0)
	s_barrier
	ds_read_b128 v[2:5], v147
	ds_read_b128 v[6:9], v148
	v_lshl_add_u64 v[10:11], v[66:67], 0, s[38:39]
	s_mov_b32 s0, s48
	s_waitcnt vmcnt(6) lgkmcnt(1)
	v_pk_add_f32 v[40:41], v[40:41], v[194:195] op_sel_hi:[1,0] neg_lo:[0,1] neg_hi:[0,1]
	v_pk_mul_f32 v[40:41], v[40:41], v[194:195] op_sel:[0,1]
	v_pk_fma_f32 v[40:41], v[204:205], v[40:41], v[212:213]
	v_pk_fma_f32 v[4:5], v[40:41], s[30:31], v[4:5] op_sel_hi:[1,0,1]
	v_pk_add_f32 v[38:39], v[38:39], v[194:195] op_sel_hi:[1,0] neg_lo:[0,1] neg_hi:[0,1]
	v_pk_mul_f32 v[38:39], v[38:39], v[194:195] op_sel:[0,1]
	v_pk_fma_f32 v[38:39], v[202:203], v[38:39], v[210:211]
	v_pk_fma_f32 v[2:3], v[38:39], s[30:31], v[2:3] op_sel_hi:[1,0,1]
	global_store_dwordx4 v[10:11], v[2:5], off offset:512
	s_waitcnt lgkmcnt(0)
	s_nop 0
	v_pk_add_f32 v[36:37], v[36:37], v[194:195] op_sel_hi:[1,0] neg_lo:[0,1] neg_hi:[0,1]
	v_pk_mul_f32 v[36:37], v[36:37], v[194:195] op_sel:[0,1]
	v_pk_fma_f32 v[36:37], v[208:209], v[36:37], v[216:217]
	v_pk_fma_f32 v[4:5], v[36:37], s[30:31], v[8:9] op_sel_hi:[1,0,1]
	v_pk_add_f32 v[34:35], v[34:35], v[194:195] op_sel_hi:[1,0] neg_lo:[0,1] neg_hi:[0,1]
	v_pk_mul_f32 v[34:35], v[34:35], v[194:195] op_sel:[0,1]
	v_pk_fma_f32 v[34:35], v[206:207], v[34:35], v[214:215]
	v_pk_fma_f32 v[2:3], v[34:35], s[30:31], v[6:7] op_sel_hi:[1,0,1]
	global_store_dwordx4 v[10:11], v[2:5], off offset:528
	ds_read_b128 v[2:5], v146
	ds_read_b128 v[6:9], v145
	v_lshl_add_u64 v[10:11], v[68:69], 0, s[38:39]
	s_waitcnt vmcnt(6) lgkmcnt(1)
	v_pk_add_f32 v[48:49], v[48:49], v[196:197] op_sel_hi:[1,0] neg_lo:[0,1] neg_hi:[0,1]
	v_pk_mul_f32 v[48:49], v[48:49], v[196:197] op_sel:[0,1]
	v_pk_fma_f32 v[48:49], v[204:205], v[48:49], v[212:213]
	v_pk_fma_f32 v[4:5], v[48:49], s[30:31], v[4:5] op_sel_hi:[1,0,1]
	v_pk_add_f32 v[46:47], v[46:47], v[196:197] op_sel_hi:[1,0] neg_lo:[0,1] neg_hi:[0,1]
	v_pk_mul_f32 v[46:47], v[46:47], v[196:197] op_sel:[0,1]
	v_pk_fma_f32 v[46:47], v[202:203], v[46:47], v[210:211]
	v_pk_fma_f32 v[2:3], v[46:47], s[30:31], v[2:3] op_sel_hi:[1,0,1]
	global_store_dwordx4 v[10:11], v[2:5], off offset:512
	s_waitcnt lgkmcnt(0)
	s_nop 0
	v_pk_add_f32 v[44:45], v[44:45], v[196:197] op_sel_hi:[1,0] neg_lo:[0,1] neg_hi:[0,1]
	v_pk_mul_f32 v[44:45], v[44:45], v[196:197] op_sel:[0,1]
	v_pk_fma_f32 v[44:45], v[208:209], v[44:45], v[216:217]
	v_pk_fma_f32 v[4:5], v[44:45], s[30:31], v[8:9] op_sel_hi:[1,0,1]
	v_pk_add_f32 v[42:43], v[42:43], v[196:197] op_sel_hi:[1,0] neg_lo:[0,1] neg_hi:[0,1]
	v_pk_mul_f32 v[42:43], v[42:43], v[196:197] op_sel:[0,1]
	v_pk_fma_f32 v[42:43], v[206:207], v[42:43], v[214:215]
	v_pk_fma_f32 v[2:3], v[42:43], s[30:31], v[6:7] op_sel_hi:[1,0,1]
	global_store_dwordx4 v[10:11], v[2:5], off offset:528
	ds_read_b128 v[2:5], v144
	ds_read_b128 v[6:9], v143
	v_lshl_add_u64 v[10:11], v[70:71], 0, s[38:39]
	s_waitcnt vmcnt(6) lgkmcnt(1)
	v_pk_add_f32 v[56:57], v[56:57], v[198:199] op_sel_hi:[1,0] neg_lo:[0,1] neg_hi:[0,1]
	v_pk_mul_f32 v[56:57], v[56:57], v[198:199] op_sel:[0,1]
	v_pk_fma_f32 v[56:57], v[204:205], v[56:57], v[212:213]
	v_pk_fma_f32 v[4:5], v[56:57], s[30:31], v[4:5] op_sel_hi:[1,0,1]
	v_pk_add_f32 v[54:55], v[54:55], v[198:199] op_sel_hi:[1,0] neg_lo:[0,1] neg_hi:[0,1]
	v_pk_mul_f32 v[54:55], v[54:55], v[198:199] op_sel:[0,1]
	v_pk_fma_f32 v[54:55], v[202:203], v[54:55], v[210:211]
	v_pk_fma_f32 v[2:3], v[54:55], s[30:31], v[2:3] op_sel_hi:[1,0,1]
	global_store_dwordx4 v[10:11], v[2:5], off offset:512
	s_waitcnt lgkmcnt(0)
	s_nop 0
	v_pk_add_f32 v[52:53], v[52:53], v[198:199] op_sel_hi:[1,0] neg_lo:[0,1] neg_hi:[0,1]
	v_pk_mul_f32 v[52:53], v[52:53], v[198:199] op_sel:[0,1]
	v_pk_fma_f32 v[52:53], v[208:209], v[52:53], v[216:217]
	v_pk_fma_f32 v[4:5], v[52:53], s[30:31], v[8:9] op_sel_hi:[1,0,1]
	v_pk_add_f32 v[50:51], v[50:51], v[198:199] op_sel_hi:[1,0] neg_lo:[0,1] neg_hi:[0,1]
	v_pk_mul_f32 v[50:51], v[50:51], v[198:199] op_sel:[0,1]
	v_pk_fma_f32 v[50:51], v[206:207], v[50:51], v[214:215]
	v_pk_fma_f32 v[2:3], v[50:51], s[30:31], v[6:7] op_sel_hi:[1,0,1]
	global_store_dwordx4 v[10:11], v[2:5], off offset:528
	ds_read_b128 v[2:5], v141
	ds_read_b128 v[6:9], v140
	v_lshl_add_u64 v[10:11], v[72:73], 0, s[38:39]
	s_waitcnt vmcnt(6) lgkmcnt(1)
	v_pk_add_f32 v[64:65], v[64:65], v[200:201] op_sel_hi:[1,0] neg_lo:[0,1] neg_hi:[0,1]
	v_pk_mul_f32 v[64:65], v[64:65], v[200:201] op_sel:[0,1]
	v_pk_fma_f32 v[64:65], v[204:205], v[64:65], v[212:213]
	v_pk_fma_f32 v[4:5], v[64:65], s[30:31], v[4:5] op_sel_hi:[1,0,1]
	v_pk_add_f32 v[62:63], v[62:63], v[200:201] op_sel_hi:[1,0] neg_lo:[0,1] neg_hi:[0,1]
	v_pk_mul_f32 v[62:63], v[62:63], v[200:201] op_sel:[0,1]
	v_pk_fma_f32 v[62:63], v[202:203], v[62:63], v[210:211]
	v_pk_fma_f32 v[2:3], v[62:63], s[30:31], v[2:3] op_sel_hi:[1,0,1]
	global_store_dwordx4 v[10:11], v[2:5], off offset:512
	s_waitcnt lgkmcnt(0)
	s_nop 0
	v_pk_add_f32 v[60:61], v[60:61], v[200:201] op_sel_hi:[1,0] neg_lo:[0,1] neg_hi:[0,1]
	v_pk_mul_f32 v[60:61], v[60:61], v[200:201] op_sel:[0,1]
	v_pk_fma_f32 v[60:61], v[208:209], v[60:61], v[216:217]
	v_pk_fma_f32 v[4:5], v[60:61], s[30:31], v[8:9] op_sel_hi:[1,0,1]
	v_pk_add_f32 v[58:59], v[58:59], v[200:201] op_sel_hi:[1,0] neg_lo:[0,1] neg_hi:[0,1]
	v_pk_mul_f32 v[58:59], v[58:59], v[200:201] op_sel:[0,1]
	v_pk_fma_f32 v[58:59], v[206:207], v[58:59], v[214:215]
	v_pk_fma_f32 v[2:3], v[58:59], s[30:31], v[6:7] op_sel_hi:[1,0,1]
	global_store_dwordx4 v[10:11], v[2:5], off offset:528
	s_waitcnt lgkmcnt(0)
	s_barrier
	s_cbranch_vccz .LBB0_1999
